# added: EpiRes first-unit row-stat loads issued together (were 8 serialized round trips); relaxed counted waits on first K trip after an epilogue (store acks no longer gate the first LDS-DMA waits)
# baseline (speedup 1.0000x reference)
.LBB0_200:
	s_add_u32 s10, s58, 0x370a000
	s_mov_b64 s[12:13], 0x80
	s_addc_u32 s11, s59, 0
	s_and_b32 s34, s5, 3
	s_add_i32 m0, s66, 0x18000
	v_lshl_add_u64 v[6:7], v[6:7], 0, s[12:13]
	s_lshl_b32 s78, s4, 6
	s_lshl_b32 s15, s4, 13
	s_lshl_b32 s79, s34, 5
	s_lshl_b32 s37, s34, 12
	s_waitcnt vmcnt(2)
	s_barrier
	global_load_lds_dwordx4 v[6:7], off
	v_lshl_add_u64 v[4:5], v[4:5], 0, s[12:13]
	s_add_i32 m0, s66, 0x1a000
	s_add_i32 s80, s66, 0x8000
	s_add_i32 s81, s66, 0xa000
	global_load_lds_dwordx4 v[4:5], off
	v_lshl_add_u64 v[0:1], v[0:1], 0, s[12:13]
	s_mov_b32 m0, s80
	s_add_u32 s60, s74, 0x40080
	global_load_lds_dwordx4 v[0:1], off
	v_lshl_add_u64 v[0:1], v[2:3], 0, s[12:13]
	s_mov_b32 m0, s81
	s_addc_u32 s61, s75, 0
	global_load_lds_dwordx4 v[0:1], off
	s_add_i32 m0, s66, 0x1c000
	v_lshl_add_u64 v[0:1], s[60:61], 0, v[146:147]
	global_load_lds_dwordx4 v[0:1], off
	v_lshl_add_u64 v[0:1], s[60:61], 0, v[150:151]
	s_add_i32 m0, s66, 0x1e000
	v_and_b32_e32 v168, 15, v8
	global_load_lds_dwordx4 v[0:1], off
	v_and_b32_e32 v0, 48, v8
	v_lshlrev_b32_e32 v1, 2, v8
	v_lshl_or_b32 v0, v168, 6, v0
	v_and_b32_e32 v2, 32, v1
	v_bitop3_b32 v3, v0, s15, v2 bitop3:0xde
	v_bitop3_b32 v170, v0, s37, v2 bitop3:0xde
	v_and_b32_e32 v0, 0x80, v1
	v_and_b32_e32 v1, 31, v8
	v_or3_b32 v171, v1, v0, s79
	v_lshlrev_b32_e32 v0, 14, v9
	v_and_b32_e32 v0, 0xffff8000, v0
	v_lshl_add_u32 v0, v10, 11, v0
	v_and_b32_e32 v1, 1, v9
	v_lshl_or_b32 v0, v1, 6, v0
	s_lshl_b32 s82, s5, 9
	v_lshl_add_u32 v152, v11, 1, v0
	v_lshlrev_b32_e32 v0, 14, v12
	s_cmpk_lt_u32 s14, 0x100
	v_and_b32_e32 v0, 0xffff8000, v0
	s_waitcnt vmcnt(6)
	s_cselect_b64 s[14:15], -1, 0
	s_lshl_b32 s4, s4, 11
	s_lshl_b32 s5, s34, 9
	v_lshl_add_u32 v0, v13, 11, v0
	v_and_b32_e32 v1, 1, v12
	s_or_b32 s83, s4, s5
	v_lshl_or_b32 v0, v1, 6, v0
	v_bfe_u32 v169, v8, 4, 2
	s_add_i32 s83, s83, 0x22400
	v_mov_b32_e32 v153, v147
	v_lshl_add_u32 v154, v14, 1, v0
	v_mov_b32_e32 v155, v147
	v_mov_b64_e32 v[156:157], 0xa00
	v_mov_b64_e32 v[158:159], 0x9ff
	s_add_i32 s84, s82, 0x22500
	s_add_i32 s85, 0, 0x10000
	s_add_i32 s86, 0, 0x14000
	v_add_u32_e32 v172, 0, v3
	s_mov_b32 s34, 0x3e38aa3b
	s_mov_b32 s87, 0
	s_barrier
	s_mov_b32 s99, 0
	s_branch .LBB0_203

.Lrlx2a:
	s_waitcnt vmcnt(24)
	s_branch .Lrlx2a_done

.LBB0_206:
	v_add_u32_e32 v160, s85, v170
	v_add_u32_e32 v173, s86, v170
	ds_read_b128 v[132:135], v160
	ds_read_b128 v[136:139], v160 offset:1024
	ds_read_b128 v[140:143], v160 offset:2048
	ds_read_b128 v[160:163], v160 offset:3072
	ds_read_b128 v[164:167], v173
	ds_read_b128 v[174:177], v173 offset:1024
	ds_read_b128 v[178:181], v173 offset:2048
	ds_read_b128 v[182:185], v173 offset:3072
	s_add_u32 s76, s46, 0xfffc0080
	s_addc_u32 s77, s47, -1
	s_and_b64 s[74:75], s[74:75], exec
	s_cselect_b32 s77, s37, s77
	s_cselect_b32 s76, s63, s76
	s_cselect_b32 s75, s61, s89
	s_cselect_b32 s74, s73, s88
	v_lshl_add_u64 v[220:221], s[46:47], 0, v[152:153]
	s_add_i32 m0, s66, 0xc000
	ds_read_b128 v[186:189], v172
	ds_read_b128 v[190:193], v172 offset:1024
	ds_read_b128 v[194:197], v172 offset:2048
	ds_read_b128 v[198:201], v172 offset:3072
	ds_read_b128 v[202:205], v172 offset:4096
	ds_read_b128 v[206:209], v172 offset:5120
	ds_read_b128 v[212:215], v172 offset:6144
	ds_read_b128 v[216:219], v172 offset:7168
	global_load_lds_dwordx4 v[220:221], off
	v_lshl_add_u64 v[220:221], s[46:47], 0, v[154:155]
	s_add_i32 m0, s66, 0xe000
	s_nop 0
	global_load_lds_dwordx4 v[220:221], off
	s_cmp_lg_u32 s99, 0
	s_cbranch_scc1 .Lrlx2a
	s_waitcnt vmcnt(8)
.Lrlx2a_done:
	s_waitcnt lgkmcnt(0)
	s_barrier
	s_setprio 1
	s_waitcnt lgkmcnt(0)
	v_mfma_f32_16x16x32_f16 v[124:127], v[132:135], v[186:189], v[124:127]
	v_mfma_f32_16x16x32_f16 v[120:123], v[140:143], v[186:189], v[120:123]
	v_mfma_f32_16x16x32_f16 v[108:111], v[132:135], v[194:197], v[108:111]
	v_mfma_f32_16x16x32_f16 v[104:107], v[140:143], v[194:197], v[104:107]
	v_mfma_f32_16x16x32_f16 v[92:95], v[132:135], v[202:205], v[92:95]
	v_mfma_f32_16x16x32_f16 v[88:91], v[140:143], v[202:205], v[88:91]
	v_mfma_f32_16x16x32_f16 v[76:79], v[132:135], v[212:215], v[76:79]
	v_mfma_f32_16x16x32_f16 v[72:75], v[140:143], v[212:215], v[72:75]
	v_mfma_f32_16x16x32_f16 v[124:127], v[136:139], v[190:193], v[124:127]
	v_mfma_f32_16x16x32_f16 v[120:123], v[160:163], v[190:193], v[120:123]
	v_mfma_f32_16x16x32_f16 v[108:111], v[136:139], v[198:201], v[108:111]
	v_mfma_f32_16x16x32_f16 v[104:107], v[160:163], v[198:201], v[104:107]
	v_mfma_f32_16x16x32_f16 v[92:95], v[136:139], v[206:209], v[92:95]
	v_mfma_f32_16x16x32_f16 v[88:91], v[160:163], v[206:209], v[88:91]
	v_mfma_f32_16x16x32_f16 v[76:79], v[136:139], v[216:219], v[76:79]
	v_mfma_f32_16x16x32_f16 v[72:75], v[160:163], v[216:219], v[72:75]
	s_setprio 0
	s_setprio 1
	v_mfma_f32_16x16x32_f16 v[116:119], v[164:167], v[186:189], v[116:119]
	v_mfma_f32_16x16x32_f16 v[112:115], v[178:181], v[186:189], v[112:115]
	v_mfma_f32_16x16x32_f16 v[100:103], v[164:167], v[194:197], v[100:103]
	v_mfma_f32_16x16x32_f16 v[96:99], v[178:181], v[194:197], v[96:99]
	v_mfma_f32_16x16x32_f16 v[84:87], v[164:167], v[202:205], v[84:87]
	v_mfma_f32_16x16x32_f16 v[80:83], v[178:181], v[202:205], v[80:83]
	v_mfma_f32_16x16x32_f16 v[68:71], v[164:167], v[212:215], v[68:71]
	v_mfma_f32_16x16x32_f16 v[64:67], v[178:181], v[212:215], v[64:67]
	v_mfma_f32_16x16x32_f16 v[116:119], v[174:177], v[190:193], v[116:119]
	v_mfma_f32_16x16x32_f16 v[112:115], v[182:185], v[190:193], v[112:115]
	v_mfma_f32_16x16x32_f16 v[100:103], v[174:177], v[198:201], v[100:103]
	v_mfma_f32_16x16x32_f16 v[96:99], v[182:185], v[198:201], v[96:99]
	v_mfma_f32_16x16x32_f16 v[84:87], v[174:177], v[206:209], v[84:87]
	v_mfma_f32_16x16x32_f16 v[80:83], v[182:185], v[206:209], v[80:83]
	v_mfma_f32_16x16x32_f16 v[68:71], v[174:177], v[216:219], v[68:71]
	v_mfma_f32_16x16x32_f16 v[64:67], v[182:185], v[216:219], v[64:67]
	s_setprio 0
	s_barrier
	s_add_i32 s91, s85, s35
	v_lshl_add_u64 v[220:221], s[74:75], 0, v[146:147]
	s_mov_b32 m0, s91
	ds_read_b128 v[186:189], v172 offset:16384
	ds_read_b128 v[190:193], v172 offset:17408
	ds_read_b128 v[194:197], v172 offset:18432
	ds_read_b128 v[198:201], v172 offset:19456
	ds_read_b128 v[202:205], v172 offset:20480
	ds_read_b128 v[206:209], v172 offset:21504
	ds_read_b128 v[212:215], v172 offset:22528
	ds_read_b128 v[216:219], v172 offset:23552
	global_load_lds_dwordx4 v[220:221], off
	s_add_i32 m0, s91, 0x2000
	s_add_u32 s92, s74, 0x40000
	v_lshl_add_u64 v[222:223], s[74:75], 0, v[150:151]
	s_addc_u32 s93, s75, 0
	s_add_i32 s91, s86, s35
	global_load_lds_dwordx4 v[222:223], off
	v_lshl_add_u64 v[224:225], s[92:93], 0, v[146:147]
	s_mov_b32 m0, s91
	v_lshl_add_u64 v[226:227], s[76:77], 0, v[148:149]
	global_load_lds_dwordx4 v[224:225], off
	v_lshl_add_u64 v[224:225], s[92:93], 0, v[150:151]
	s_add_i32 m0, s91, 0x2000
	s_nop 0
	global_load_lds_dwordx4 v[224:225], off
	v_lshl_add_u64 v[224:225], s[76:77], 0, v[144:145]
	s_mov_b32 m0, s66
	s_nop 0
	global_load_lds_dwordx4 v[224:225], off
	s_mov_b32 m0, s67
	s_nop 0
	global_load_lds_dwordx4 v[226:227], off
	s_cmp_lg_u32 s99, 0
	s_cbranch_scc1 .Lrlx2b
	s_waitcnt vmcnt(8)
.Lrlx2b_done:
	s_mov_b32 s99, 0
	s_waitcnt lgkmcnt(0)
	s_barrier
	s_setprio 1
	s_waitcnt lgkmcnt(0)
	v_mfma_f32_16x16x32_f16 v[60:63], v[132:135], v[186:189], v[60:63]
	v_mfma_f32_16x16x32_f16 v[56:59], v[140:143], v[186:189], v[56:59]
	v_mfma_f32_16x16x32_f16 v[44:47], v[132:135], v[194:197], v[44:47]
	v_mfma_f32_16x16x32_f16 v[40:43], v[140:143], v[194:197], v[40:43]
	v_mfma_f32_16x16x32_f16 v[28:31], v[132:135], v[202:205], v[28:31]
	v_mfma_f32_16x16x32_f16 v[24:27], v[140:143], v[202:205], v[24:27]
	v_mfma_f32_16x16x32_f16 v[12:15], v[132:135], v[212:215], v[12:15]
	v_mfma_f32_16x16x32_f16 v[8:11], v[140:143], v[212:215], v[8:11]
	v_mfma_f32_16x16x32_f16 v[60:63], v[136:139], v[190:193], v[60:63]
	v_mfma_f32_16x16x32_f16 v[56:59], v[160:163], v[190:193], v[56:59]
	v_mfma_f32_16x16x32_f16 v[44:47], v[136:139], v[198:201], v[44:47]
	v_mfma_f32_16x16x32_f16 v[40:43], v[160:163], v[198:201], v[40:43]
	v_mfma_f32_16x16x32_f16 v[28:31], v[136:139], v[206:209], v[28:31]
	v_mfma_f32_16x16x32_f16 v[24:27], v[160:163], v[206:209], v[24:27]
	v_mfma_f32_16x16x32_f16 v[12:15], v[136:139], v[216:219], v[12:15]
	v_mfma_f32_16x16x32_f16 v[8:11], v[160:163], v[216:219], v[8:11]
	s_setprio 0
	s_setprio 1
	v_mfma_f32_16x16x32_f16 v[52:55], v[164:167], v[186:189], v[52:55]
	v_mfma_f32_16x16x32_f16 v[48:51], v[178:181], v[186:189], v[48:51]
	v_mfma_f32_16x16x32_f16 v[36:39], v[164:167], v[194:197], v[36:39]
	v_mfma_f32_16x16x32_f16 v[32:35], v[178:181], v[194:197], v[32:35]
	v_mfma_f32_16x16x32_f16 v[20:23], v[164:167], v[202:205], v[20:23]
	v_mfma_f32_16x16x32_f16 v[16:19], v[178:181], v[202:205], v[16:19]
	v_mfma_f32_16x16x32_f16 v[4:7], v[164:167], v[212:215], v[4:7]
	v_mfma_f32_16x16x32_f16 v[0:3], v[178:181], v[212:215], v[0:3]
	v_mfma_f32_16x16x32_f16 v[52:55], v[174:177], v[190:193], v[52:55]
	v_mfma_f32_16x16x32_f16 v[48:51], v[182:185], v[190:193], v[48:51]
	v_mfma_f32_16x16x32_f16 v[36:39], v[174:177], v[198:201], v[36:39]
	v_mfma_f32_16x16x32_f16 v[32:35], v[182:185], v[198:201], v[32:35]
	v_mfma_f32_16x16x32_f16 v[20:23], v[174:177], v[206:209], v[20:23]
	v_mfma_f32_16x16x32_f16 v[16:19], v[182:185], v[206:209], v[16:19]
	v_mfma_f32_16x16x32_f16 v[4:7], v[174:177], v[216:219], v[4:7]
	v_mfma_f32_16x16x32_f16 v[0:3], v[182:185], v[216:219], v[0:3]
	s_setprio 0
	s_barrier
	s_add_i32 s91, 0, 0x18000
	s_add_i32 s92, 0, 0x1c000
	v_add_u32_e32 v160, s91, v170
	v_add_u32_e32 v173, s92, v170
	ds_read_b128 v[132:135], v160
	ds_read_b128 v[136:139], v160 offset:1024
	ds_read_b128 v[140:143], v160 offset:2048
	ds_read_b128 v[160:163], v160 offset:3072
	ds_read_b128 v[164:167], v173
	ds_read_b128 v[174:177], v173 offset:1024
	ds_read_b128 v[178:181], v173 offset:2048
	ds_read_b128 v[182:185], v173 offset:3072
	s_add_u32 s76, s76, 0x40000
	s_addc_u32 s77, s77, 0
	s_mov_b32 m0, s68
	v_lshl_add_u64 v[228:229], s[76:77], 0, v[144:145]
	ds_read_b128 v[186:189], v172 offset:32768
	ds_read_b128 v[190:193], v172 offset:33792
	ds_read_b128 v[194:197], v172 offset:34816
	ds_read_b128 v[198:201], v172 offset:35840
	ds_read_b128 v[202:205], v172 offset:36864
	ds_read_b128 v[206:209], v172 offset:37888
	ds_read_b128 v[212:215], v172 offset:38912
	ds_read_b128 v[216:219], v172 offset:39936
	global_load_lds_dwordx4 v[228:229], off
	v_lshl_add_u64 v[228:229], s[76:77], 0, v[148:149]
	s_mov_b32 m0, s69
	s_nop 0
	global_load_lds_dwordx4 v[228:229], off
	s_waitcnt vmcnt(8)
	s_waitcnt lgkmcnt(0)
	s_barrier
	s_setprio 1
	s_waitcnt lgkmcnt(0)
	v_mfma_f32_16x16x32_f16 v[124:127], v[132:135], v[186:189], v[124:127]
	v_mfma_f32_16x16x32_f16 v[120:123], v[140:143], v[186:189], v[120:123]
	v_mfma_f32_16x16x32_f16 v[108:111], v[132:135], v[194:197], v[108:111]
	v_mfma_f32_16x16x32_f16 v[104:107], v[140:143], v[194:197], v[104:107]
	v_mfma_f32_16x16x32_f16 v[92:95], v[132:135], v[202:205], v[92:95]
	v_mfma_f32_16x16x32_f16 v[88:91], v[140:143], v[202:205], v[88:91]
	v_mfma_f32_16x16x32_f16 v[76:79], v[132:135], v[212:215], v[76:79]
	v_mfma_f32_16x16x32_f16 v[72:75], v[140:143], v[212:215], v[72:75]
	v_mfma_f32_16x16x32_f16 v[124:127], v[136:139], v[190:193], v[124:127]
	v_mfma_f32_16x16x32_f16 v[120:123], v[160:163], v[190:193], v[120:123]
	v_mfma_f32_16x16x32_f16 v[108:111], v[136:139], v[198:201], v[108:111]
	v_mfma_f32_16x16x32_f16 v[104:107], v[160:163], v[198:201], v[104:107]
	v_mfma_f32_16x16x32_f16 v[92:95], v[136:139], v[206:209], v[92:95]
	v_mfma_f32_16x16x32_f16 v[88:91], v[160:163], v[206:209], v[88:91]
	v_mfma_f32_16x16x32_f16 v[76:79], v[136:139], v[216:219], v[76:79]
	v_mfma_f32_16x16x32_f16 v[72:75], v[160:163], v[216:219], v[72:75]
	s_setprio 0
	s_setprio 1
	v_mfma_f32_16x16x32_f16 v[116:119], v[164:167], v[186:189], v[116:119]
	v_mfma_f32_16x16x32_f16 v[112:115], v[178:181], v[186:189], v[112:115]
	v_mfma_f32_16x16x32_f16 v[100:103], v[164:167], v[194:197], v[100:103]
	v_mfma_f32_16x16x32_f16 v[96:99], v[178:181], v[194:197], v[96:99]
	v_mfma_f32_16x16x32_f16 v[84:87], v[164:167], v[202:205], v[84:87]
	v_mfma_f32_16x16x32_f16 v[80:83], v[178:181], v[202:205], v[80:83]
	v_mfma_f32_16x16x32_f16 v[68:71], v[164:167], v[212:215], v[68:71]
	v_mfma_f32_16x16x32_f16 v[64:67], v[178:181], v[212:215], v[64:67]
	v_mfma_f32_16x16x32_f16 v[116:119], v[174:177], v[190:193], v[116:119]
	v_mfma_f32_16x16x32_f16 v[112:115], v[182:185], v[190:193], v[112:115]
	v_mfma_f32_16x16x32_f16 v[100:103], v[174:177], v[198:201], v[100:103]
	v_mfma_f32_16x16x32_f16 v[96:99], v[182:185], v[198:201], v[96:99]
	v_mfma_f32_16x16x32_f16 v[84:87], v[174:177], v[206:209], v[84:87]
	v_mfma_f32_16x16x32_f16 v[80:83], v[182:185], v[206:209], v[80:83]
	v_mfma_f32_16x16x32_f16 v[68:71], v[174:177], v[216:219], v[68:71]
	v_mfma_f32_16x16x32_f16 v[64:67], v[182:185], v[216:219], v[64:67]
	s_setprio 0
	s_barrier
	s_add_i32 s76, s91, s35
	v_lshl_add_u64 v[220:221], v[220:221], 0, s[12:13]
	s_mov_b32 m0, s76
	ds_read_b128 v[186:189], v172 offset:49152
	ds_read_b128 v[190:193], v172 offset:50176
	ds_read_b128 v[194:197], v172 offset:51200
	ds_read_b128 v[198:201], v172 offset:52224
	ds_read_b128 v[202:205], v172 offset:53248
	ds_read_b128 v[206:209], v172 offset:54272
	ds_read_b128 v[212:215], v172 offset:55296
	ds_read_b128 v[216:219], v172 offset:56320
	global_load_lds_dwordx4 v[220:221], off
	s_add_i32 m0, s76, 0x2000
	s_add_u32 s74, s74, 0x40080
	v_lshl_add_u64 v[220:221], v[222:223], 0, s[12:13]
	s_addc_u32 s75, s75, 0
	s_add_i32 s76, s92, s35
	global_load_lds_dwordx4 v[220:221], off
	v_lshl_add_u64 v[220:221], s[74:75], 0, v[146:147]
	s_mov_b32 m0, s76
	s_nop 0
	global_load_lds_dwordx4 v[220:221], off
	v_lshl_add_u64 v[220:221], s[74:75], 0, v[150:151]
	s_add_i32 m0, s76, 0x2000
	s_nop 0
	global_load_lds_dwordx4 v[220:221], off
	v_lshl_add_u64 v[220:221], v[224:225], 0, s[12:13]
	s_mov_b32 m0, s80
	s_nop 0
	global_load_lds_dwordx4 v[220:221], off
	v_lshl_add_u64 v[220:221], v[226:227], 0, s[12:13]
	s_mov_b32 m0, s81
	s_nop 0
	global_load_lds_dwordx4 v[220:221], off
	s_waitcnt vmcnt(8)
	s_waitcnt lgkmcnt(0)
	s_barrier
	s_setprio 1
	s_waitcnt lgkmcnt(0)
	v_mfma_f32_16x16x32_f16 v[60:63], v[132:135], v[186:189], v[60:63]
	v_mfma_f32_16x16x32_f16 v[56:59], v[140:143], v[186:189], v[56:59]
	v_mfma_f32_16x16x32_f16 v[44:47], v[132:135], v[194:197], v[44:47]
	v_mfma_f32_16x16x32_f16 v[40:43], v[140:143], v[194:197], v[40:43]
	v_mfma_f32_16x16x32_f16 v[28:31], v[132:135], v[202:205], v[28:31]
	v_mfma_f32_16x16x32_f16 v[24:27], v[140:143], v[202:205], v[24:27]
	v_mfma_f32_16x16x32_f16 v[12:15], v[132:135], v[212:215], v[12:15]
	v_mfma_f32_16x16x32_f16 v[8:11], v[140:143], v[212:215], v[8:11]
	v_mfma_f32_16x16x32_f16 v[60:63], v[136:139], v[190:193], v[60:63]
	v_mfma_f32_16x16x32_f16 v[56:59], v[160:163], v[190:193], v[56:59]
	v_mfma_f32_16x16x32_f16 v[44:47], v[136:139], v[198:201], v[44:47]
	v_mfma_f32_16x16x32_f16 v[40:43], v[160:163], v[198:201], v[40:43]
	v_mfma_f32_16x16x32_f16 v[28:31], v[136:139], v[206:209], v[28:31]
	v_mfma_f32_16x16x32_f16 v[24:27], v[160:163], v[206:209], v[24:27]
	v_mfma_f32_16x16x32_f16 v[12:15], v[136:139], v[216:219], v[12:15]
	v_mfma_f32_16x16x32_f16 v[8:11], v[160:163], v[216:219], v[8:11]
	s_setprio 0
	s_setprio 1
	v_mfma_f32_16x16x32_f16 v[52:55], v[164:167], v[186:189], v[52:55]
	v_mfma_f32_16x16x32_f16 v[48:51], v[178:181], v[186:189], v[48:51]
	v_mfma_f32_16x16x32_f16 v[36:39], v[164:167], v[194:197], v[36:39]
	v_mfma_f32_16x16x32_f16 v[32:35], v[178:181], v[194:197], v[32:35]
	v_mfma_f32_16x16x32_f16 v[20:23], v[164:167], v[202:205], v[20:23]
	v_mfma_f32_16x16x32_f16 v[16:19], v[178:181], v[202:205], v[16:19]
	v_mfma_f32_16x16x32_f16 v[4:7], v[164:167], v[212:215], v[4:7]
	v_mfma_f32_16x16x32_f16 v[0:3], v[178:181], v[212:215], v[0:3]
	v_mfma_f32_16x16x32_f16 v[52:55], v[174:177], v[190:193], v[52:55]
	v_mfma_f32_16x16x32_f16 v[48:51], v[182:185], v[190:193], v[48:51]
	v_mfma_f32_16x16x32_f16 v[36:39], v[174:177], v[198:201], v[36:39]
	v_mfma_f32_16x16x32_f16 v[32:35], v[182:185], v[198:201], v[32:35]
	v_mfma_f32_16x16x32_f16 v[20:23], v[174:177], v[206:209], v[20:23]
	v_mfma_f32_16x16x32_f16 v[16:19], v[182:185], v[206:209], v[16:19]
	v_mfma_f32_16x16x32_f16 v[4:7], v[174:177], v[216:219], v[4:7]
	v_mfma_f32_16x16x32_f16 v[0:3], v[182:185], v[216:219], v[0:3]
	s_setprio 0
	s_barrier
	s_add_i32 s90, s90, 2
	s_add_u32 s46, s46, 0x100
	s_addc_u32 s47, s47, 0
	s_add_u32 s88, s88, 0x100
	s_addc_u32 s89, s89, 0
	s_cmp_gt_u32 s90, 13
	s_cbranch_scc1 .LBB0_209

.LBB0_307:
	s_andn2_b64 vcc, exec, s[4:5]
	s_mov_b64 s[4:5], -1
	v_cvt_pk_bf16_f32 v0, v10, v12
	v_cvt_pk_bf16_f32 v1, v14, v17
	v_cvt_pk_bf16_f32 v2, v11, v13
	v_cvt_pk_bf16_f32 v3, v15, v16
	global_store_dwordx4 v[8:9], v[0:3], off offset:256
	s_mov_b32 s99, 1
	s_cbranch_vccnz .LBB0_202
	s_andn2_b64 vcc, exec, s[8:9]
	s_cbranch_vccnz .LBB0_201
	s_barrier
	s_branch .LBB0_201

.LBB0_740:
	s_sext_i32_i16 s86, s4
	s_add_u32 s4, s58, 0x3714000
	s_addc_u32 s5, s59, 0
	s_add_u32 s6, s58, 0x371f000
	v_and_b32_e32 v194, 15, v9
	v_and_b32_e32 v15, 48, v9
	v_lshlrev_b32_e32 v16, 2, v9
	s_addc_u32 s7, s59, 0
	s_and_b32 s34, s12, 3
	s_lshl_b32 s10, s9, 13
	v_lshl_or_b32 v15, v194, 6, v15
	v_and_b32_e32 v17, 32, v16
	v_bitop3_b32 v18, v15, s10, v17 bitop3:0xde
	s_lshl_b32 s10, s34, 12
	v_bitop3_b32 v196, v15, s10, v17 bitop3:0xde
	s_mov_b64 s[10:11], 0x80
	s_add_i32 m0, s61, 0x18000
	v_lshl_add_u64 v[6:7], v[6:7], 0, s[10:11]
	s_lshl_b32 s73, s9, 6
	s_lshl_b32 s78, s34, 5
	s_waitcnt vmcnt(2)
	s_barrier
	global_load_lds_dwordx4 v[6:7], off
	v_lshl_add_u64 v[4:5], v[4:5], 0, s[10:11]
	s_add_i32 m0, s61, 0x1a000
	s_add_i32 s79, s61, 0x8000
	s_add_i32 s80, s61, 0xa000
	global_load_lds_dwordx4 v[4:5], off
	v_lshl_add_u64 v[0:1], v[0:1], 0, s[10:11]
	s_mov_b32 m0, s79
	s_add_u32 s14, s74, 0x40080
	global_load_lds_dwordx4 v[0:1], off
	v_lshl_add_u64 v[0:1], v[2:3], 0, s[10:11]
	s_mov_b32 m0, s80
	s_addc_u32 s15, s75, 0
	global_load_lds_dwordx4 v[0:1], off
	s_add_i32 m0, s61, 0x1c000
	v_lshl_add_u64 v[0:1], s[14:15], 0, v[172:173]
	global_load_lds_dwordx4 v[0:1], off
	v_lshl_add_u64 v[0:1], s[14:15], 0, v[168:169]
	s_add_i32 m0, s61, 0x1e000
	s_lshl_b32 s81, s12, 9
	global_load_lds_dwordx4 v[0:1], off
	v_and_b32_e32 v0, 0x80, v16
	v_and_b32_e32 v1, 31, v9
	v_or3_b32 v197, v1, v0, s78
	v_lshlrev_b32_e32 v0, 14, v13
	v_and_b32_e32 v0, 0xffff8000, v0
	v_lshl_add_u32 v0, v12, 11, v0
	v_and_b32_e32 v1, 1, v13
	v_lshl_or_b32 v0, v1, 6, v0
	v_lshl_add_u32 v176, v14, 1, v0
	v_lshlrev_b32_e32 v0, 14, v8
	s_cmpk_lt_u32 s8, 0x100
	v_and_b32_e32 v0, 0xffff8000, v0
	s_waitcnt vmcnt(6)
	s_cselect_b64 s[12:13], -1, 0
	s_lshl_b32 s8, s9, 11
	s_lshl_b32 s9, s34, 9
	v_lshl_add_u32 v0, v10, 11, v0
	v_and_b32_e32 v1, 1, v8
	s_or_b32 s82, s8, s9
	v_lshl_or_b32 v0, v1, 6, v0
	v_bfe_u32 v195, v9, 4, 2
	s_add_i32 s82, s82, 0x22400
	v_mov_b32_e32 v177, v173
	v_lshl_add_u32 v178, v11, 1, v0
	v_mov_b32_e32 v179, v173
	v_mov_b64_e32 v[180:181], 0xb00
	v_mov_b64_e32 v[182:183], 0xaff
	s_movk_i32 s83, 0x1600
	s_add_i32 s84, s81, 0x22500
	s_add_i32 s85, 0, 0x10000
	s_add_i32 s88, 0, 0x14000
	v_add_u32_e32 v198, 0, v18
	v_mov_b32_e32 v199, 0x20400
	s_barrier
	s_mov_b32 s99, 0
	s_branch .LBB0_743

.Lrlx7a:
	s_waitcnt vmcnt(16)
	s_branch .Lrlx7a_done

.LBB0_746:
	v_add_u32_e32 v76, s85, v196
	v_add_u32_e32 v160, s88, v196
	ds_read_b128 v[56:59], v76
	ds_read_b128 v[64:67], v76 offset:1024
	ds_read_b128 v[72:75], v76 offset:2048
	ds_read_b128 v[76:79], v76 offset:3072
	ds_read_b128 v[100:103], v160
	ds_read_b128 v[136:139], v160 offset:1024
	ds_read_b128 v[156:159], v160 offset:2048
	ds_read_b128 v[160:163], v160 offset:3072
	s_add_u32 s76, s46, 0xfffc0080
	s_addc_u32 s77, s47, -1
	s_and_b64 s[74:75], s[74:75], exec
	s_cselect_b32 s77, s35, s77
	s_cselect_b32 s76, s87, s76
	s_cselect_b32 s75, s15, s91
	s_cselect_b32 s74, s89, s90
	v_lshl_add_u64 v[192:193], s[46:47], 0, v[176:177]
	s_add_i32 m0, s61, 0xc000
	ds_read_b128 v[164:167], v198
	ds_read_b128 v[184:187], v198 offset:1024
	ds_read_b128 v[188:191], v198 offset:2048
	ds_read_b128 v[200:203], v198 offset:3072
	ds_read_b128 v[204:207], v198 offset:4096
	ds_read_b128 v[212:215], v198 offset:5120
	ds_read_b128 v[216:219], v198 offset:6144
	ds_read_b128 v[220:223], v198 offset:7168
	global_load_lds_dwordx4 v[192:193], off
	v_lshl_add_u64 v[192:193], s[46:47], 0, v[178:179]
	s_add_i32 m0, s61, 0xe000
	s_nop 0
	global_load_lds_dwordx4 v[192:193], off
	s_cmp_lg_u32 s99, 0
	s_cbranch_scc1 .Lrlx7a
	s_waitcnt vmcnt(8)
.Lrlx7a_done:
	s_waitcnt lgkmcnt(0)
	s_barrier
	s_setprio 1
	s_waitcnt lgkmcnt(0)
	v_mfma_f32_16x16x32_f16 v[152:155], v[56:59], v[164:167], v[152:155]
	v_mfma_f32_16x16x32_f16 v[144:147], v[72:75], v[164:167], v[144:147]
	v_mfma_f32_16x16x32_f16 v[132:135], v[56:59], v[188:191], v[132:135]
	v_mfma_f32_16x16x32_f16 v[124:127], v[72:75], v[188:191], v[124:127]
	v_mfma_f32_16x16x32_f16 v[116:119], v[56:59], v[204:207], v[116:119]
	v_mfma_f32_16x16x32_f16 v[108:111], v[72:75], v[204:207], v[108:111]
	v_mfma_f32_16x16x32_f16 v[96:99], v[56:59], v[216:219], v[96:99]
	v_mfma_f32_16x16x32_f16 v[88:91], v[72:75], v[216:219], v[88:91]
	v_mfma_f32_16x16x32_f16 v[152:155], v[64:67], v[184:187], v[152:155]
	v_mfma_f32_16x16x32_f16 v[144:147], v[76:79], v[184:187], v[144:147]
	v_mfma_f32_16x16x32_f16 v[132:135], v[64:67], v[200:203], v[132:135]
	v_mfma_f32_16x16x32_f16 v[124:127], v[76:79], v[200:203], v[124:127]
	v_mfma_f32_16x16x32_f16 v[116:119], v[64:67], v[212:215], v[116:119]
	v_mfma_f32_16x16x32_f16 v[108:111], v[76:79], v[212:215], v[108:111]
	v_mfma_f32_16x16x32_f16 v[96:99], v[64:67], v[220:223], v[96:99]
	v_mfma_f32_16x16x32_f16 v[88:91], v[76:79], v[220:223], v[88:91]
	s_setprio 0
	s_setprio 1
	v_mfma_f32_16x16x32_f16 v[148:151], v[100:103], v[164:167], v[148:151]
	v_mfma_f32_16x16x32_f16 v[140:143], v[156:159], v[164:167], v[140:143]
	v_mfma_f32_16x16x32_f16 v[128:131], v[100:103], v[188:191], v[128:131]
	v_mfma_f32_16x16x32_f16 v[120:123], v[156:159], v[188:191], v[120:123]
	v_mfma_f32_16x16x32_f16 v[112:115], v[100:103], v[204:207], v[112:115]
	v_mfma_f32_16x16x32_f16 v[104:107], v[156:159], v[204:207], v[104:107]
	v_mfma_f32_16x16x32_f16 v[92:95], v[100:103], v[216:219], v[92:95]
	v_mfma_f32_16x16x32_f16 v[84:87], v[156:159], v[216:219], v[84:87]
	v_mfma_f32_16x16x32_f16 v[148:151], v[136:139], v[184:187], v[148:151]
	v_mfma_f32_16x16x32_f16 v[140:143], v[160:163], v[184:187], v[140:143]
	v_mfma_f32_16x16x32_f16 v[128:131], v[136:139], v[200:203], v[128:131]
	v_mfma_f32_16x16x32_f16 v[120:123], v[160:163], v[200:203], v[120:123]
	v_mfma_f32_16x16x32_f16 v[112:115], v[136:139], v[212:215], v[112:115]
	v_mfma_f32_16x16x32_f16 v[104:107], v[160:163], v[212:215], v[104:107]
	v_mfma_f32_16x16x32_f16 v[92:95], v[136:139], v[220:223], v[92:95]
	v_mfma_f32_16x16x32_f16 v[84:87], v[160:163], v[220:223], v[84:87]
	s_setprio 0
	s_barrier
	s_add_i32 s93, s85, s67
	v_lshl_add_u64 v[192:193], s[74:75], 0, v[172:173]
	s_mov_b32 m0, s93
	ds_read_b128 v[164:167], v198 offset:16384
	ds_read_b128 v[184:187], v198 offset:17408
	ds_read_b128 v[188:191], v198 offset:18432
	ds_read_b128 v[200:203], v198 offset:19456
	ds_read_b128 v[204:207], v198 offset:20480
	ds_read_b128 v[212:215], v198 offset:21504
	ds_read_b128 v[216:219], v198 offset:22528
	ds_read_b128 v[220:223], v198 offset:23552
	global_load_lds_dwordx4 v[192:193], off
	s_add_i32 m0, s93, 0x2000
	s_add_u32 s94, s74, 0x40000
	v_lshl_add_u64 v[208:209], s[74:75], 0, v[168:169]
	s_addc_u32 s95, s75, 0
	s_add_i32 s93, s88, s67
	global_load_lds_dwordx4 v[208:209], off
	v_lshl_add_u64 v[210:211], s[94:95], 0, v[172:173]
	s_mov_b32 m0, s93
	v_lshl_add_u64 v[224:225], s[76:77], 0, v[170:171]
	global_load_lds_dwordx4 v[210:211], off
	v_lshl_add_u64 v[210:211], s[94:95], 0, v[168:169]
	s_add_i32 m0, s93, 0x2000
	s_nop 0
	global_load_lds_dwordx4 v[210:211], off
	v_lshl_add_u64 v[210:211], s[76:77], 0, v[174:175]
	s_mov_b32 m0, s61
	s_nop 0
	global_load_lds_dwordx4 v[210:211], off
	s_mov_b32 m0, s69
	s_nop 0
	global_load_lds_dwordx4 v[224:225], off
	s_cmp_lg_u32 s99, 0
	s_cbranch_scc1 .Lrlx7b
	s_waitcnt vmcnt(8)
.Lrlx7b_done:
	s_mov_b32 s99, 0
	s_waitcnt lgkmcnt(0)
	s_barrier
	s_setprio 1
	s_waitcnt lgkmcnt(0)
	v_mfma_f32_16x16x32_f16 v[80:83], v[56:59], v[164:167], v[80:83]
	v_mfma_f32_16x16x32_f16 v[60:63], v[72:75], v[164:167], v[60:63]
	v_mfma_f32_16x16x32_f16 v[44:47], v[56:59], v[188:191], v[44:47]
	v_mfma_f32_16x16x32_f16 v[36:39], v[72:75], v[188:191], v[36:39]
	v_mfma_f32_16x16x32_f16 v[28:31], v[56:59], v[204:207], v[28:31]
	v_mfma_f32_16x16x32_f16 v[20:23], v[72:75], v[204:207], v[20:23]
	v_mfma_f32_16x16x32_f16 v[12:15], v[56:59], v[216:219], v[12:15]
	v_mfma_f32_16x16x32_f16 v[4:7], v[72:75], v[216:219], v[4:7]
	v_mfma_f32_16x16x32_f16 v[80:83], v[64:67], v[184:187], v[80:83]
	v_mfma_f32_16x16x32_f16 v[60:63], v[76:79], v[184:187], v[60:63]
	v_mfma_f32_16x16x32_f16 v[44:47], v[64:67], v[200:203], v[44:47]
	v_mfma_f32_16x16x32_f16 v[36:39], v[76:79], v[200:203], v[36:39]
	v_mfma_f32_16x16x32_f16 v[28:31], v[64:67], v[212:215], v[28:31]
	v_mfma_f32_16x16x32_f16 v[20:23], v[76:79], v[212:215], v[20:23]
	v_mfma_f32_16x16x32_f16 v[12:15], v[64:67], v[220:223], v[12:15]
	v_mfma_f32_16x16x32_f16 v[4:7], v[76:79], v[220:223], v[4:7]
	s_setprio 0
	s_setprio 1
	v_mfma_f32_16x16x32_f16 v[48:51], v[156:159], v[164:167], v[48:51]
	v_mfma_f32_16x16x32_f16 v[40:43], v[100:103], v[188:191], v[40:43]
	v_mfma_f32_16x16x32_f16 v[32:35], v[156:159], v[188:191], v[32:35]
	v_mfma_f32_16x16x32_f16 v[24:27], v[100:103], v[204:207], v[24:27]
	v_mfma_f32_16x16x32_f16 v[16:19], v[156:159], v[204:207], v[16:19]
	v_mfma_f32_16x16x32_f16 v[8:11], v[100:103], v[216:219], v[8:11]
	v_mfma_f32_16x16x32_f16 v[0:3], v[156:159], v[216:219], v[0:3]
	v_mfma_f32_16x16x32_f16 v[56:59], v[100:103], v[164:167], v[68:71]
	v_mfma_f32_16x16x32_f16 v[48:51], v[160:163], v[184:187], v[48:51]
	v_mfma_f32_16x16x32_f16 v[40:43], v[136:139], v[200:203], v[40:43]
	v_mfma_f32_16x16x32_f16 v[32:35], v[160:163], v[200:203], v[32:35]
	v_mfma_f32_16x16x32_f16 v[24:27], v[136:139], v[212:215], v[24:27]
	v_mfma_f32_16x16x32_f16 v[16:19], v[160:163], v[212:215], v[16:19]
	v_mfma_f32_16x16x32_f16 v[8:11], v[136:139], v[220:223], v[8:11]
	v_mfma_f32_16x16x32_f16 v[0:3], v[160:163], v[220:223], v[0:3]
	v_mfma_f32_16x16x32_f16 v[56:59], v[136:139], v[184:187], v[56:59]
	s_setprio 0
	s_barrier
	s_add_i32 s93, 0, 0x18000
	s_add_i32 s94, 0, 0x1c000
	v_add_u32_e32 v76, s93, v196
	v_add_u32_e32 v160, s94, v196
	ds_read_b128 v[64:67], v76
	ds_read_b128 v[68:71], v76 offset:1024
	ds_read_b128 v[72:75], v76 offset:2048
	ds_read_b128 v[76:79], v76 offset:3072
	ds_read_b128 v[100:103], v160
	ds_read_b128 v[136:139], v160 offset:1024
	ds_read_b128 v[156:159], v160 offset:2048
	ds_read_b128 v[160:163], v160 offset:3072
	s_add_u32 s76, s76, 0x40000
	s_addc_u32 s77, s77, 0
	s_mov_b32 m0, s70
	v_lshl_add_u64 v[226:227], s[76:77], 0, v[174:175]
	ds_read_b128 v[164:167], v198 offset:32768
	ds_read_b128 v[184:187], v198 offset:33792
	ds_read_b128 v[188:191], v198 offset:34816
	ds_read_b128 v[200:203], v198 offset:35840
	ds_read_b128 v[204:207], v198 offset:36864
	ds_read_b128 v[212:215], v198 offset:37888
	ds_read_b128 v[216:219], v198 offset:38912
	ds_read_b128 v[220:223], v198 offset:39936
	global_load_lds_dwordx4 v[226:227], off
	v_lshl_add_u64 v[226:227], s[76:77], 0, v[170:171]
	s_mov_b32 m0, s71
	s_nop 0
	global_load_lds_dwordx4 v[226:227], off
	s_waitcnt vmcnt(8)
	s_waitcnt lgkmcnt(0)
	s_barrier
	s_setprio 1
	s_waitcnt lgkmcnt(0)
	v_mfma_f32_16x16x32_f16 v[152:155], v[64:67], v[164:167], v[152:155]
	v_mfma_f32_16x16x32_f16 v[144:147], v[72:75], v[164:167], v[144:147]
	v_mfma_f32_16x16x32_f16 v[132:135], v[64:67], v[188:191], v[132:135]
	v_mfma_f32_16x16x32_f16 v[124:127], v[72:75], v[188:191], v[124:127]
	v_mfma_f32_16x16x32_f16 v[116:119], v[64:67], v[204:207], v[116:119]
	v_mfma_f32_16x16x32_f16 v[108:111], v[72:75], v[204:207], v[108:111]
	v_mfma_f32_16x16x32_f16 v[96:99], v[64:67], v[216:219], v[96:99]
	v_mfma_f32_16x16x32_f16 v[88:91], v[72:75], v[216:219], v[88:91]
	v_mfma_f32_16x16x32_f16 v[152:155], v[68:71], v[184:187], v[152:155]
	v_mfma_f32_16x16x32_f16 v[144:147], v[76:79], v[184:187], v[144:147]
	v_mfma_f32_16x16x32_f16 v[132:135], v[68:71], v[200:203], v[132:135]
	v_mfma_f32_16x16x32_f16 v[124:127], v[76:79], v[200:203], v[124:127]
	v_mfma_f32_16x16x32_f16 v[116:119], v[68:71], v[212:215], v[116:119]
	v_mfma_f32_16x16x32_f16 v[108:111], v[76:79], v[212:215], v[108:111]
	v_mfma_f32_16x16x32_f16 v[96:99], v[68:71], v[220:223], v[96:99]
	v_mfma_f32_16x16x32_f16 v[88:91], v[76:79], v[220:223], v[88:91]
	s_setprio 0
	s_setprio 1
	v_mfma_f32_16x16x32_f16 v[148:151], v[100:103], v[164:167], v[148:151]
	v_mfma_f32_16x16x32_f16 v[140:143], v[156:159], v[164:167], v[140:143]
	v_mfma_f32_16x16x32_f16 v[128:131], v[100:103], v[188:191], v[128:131]
	v_mfma_f32_16x16x32_f16 v[120:123], v[156:159], v[188:191], v[120:123]
	v_mfma_f32_16x16x32_f16 v[112:115], v[100:103], v[204:207], v[112:115]
	v_mfma_f32_16x16x32_f16 v[104:107], v[156:159], v[204:207], v[104:107]
	v_mfma_f32_16x16x32_f16 v[92:95], v[100:103], v[216:219], v[92:95]
	v_mfma_f32_16x16x32_f16 v[84:87], v[156:159], v[216:219], v[84:87]
	v_mfma_f32_16x16x32_f16 v[148:151], v[136:139], v[184:187], v[148:151]
	v_mfma_f32_16x16x32_f16 v[140:143], v[160:163], v[184:187], v[140:143]
	v_mfma_f32_16x16x32_f16 v[128:131], v[136:139], v[200:203], v[128:131]
	v_mfma_f32_16x16x32_f16 v[120:123], v[160:163], v[200:203], v[120:123]
	v_mfma_f32_16x16x32_f16 v[112:115], v[136:139], v[212:215], v[112:115]
	v_mfma_f32_16x16x32_f16 v[104:107], v[160:163], v[212:215], v[104:107]
	v_mfma_f32_16x16x32_f16 v[92:95], v[136:139], v[220:223], v[92:95]
	v_mfma_f32_16x16x32_f16 v[84:87], v[160:163], v[220:223], v[84:87]
	s_setprio 0
	s_barrier
	s_add_i32 s76, s93, s67
	v_lshl_add_u64 v[192:193], v[192:193], 0, s[10:11]
	s_mov_b32 m0, s76
	ds_read_b128 v[164:167], v198 offset:49152
	ds_read_b128 v[184:187], v198 offset:50176
	ds_read_b128 v[188:191], v198 offset:51200
	ds_read_b128 v[200:203], v198 offset:52224
	ds_read_b128 v[204:207], v198 offset:53248
	ds_read_b128 v[212:215], v198 offset:54272
	ds_read_b128 v[216:219], v198 offset:55296
	ds_read_b128 v[220:223], v198 offset:56320
	global_load_lds_dwordx4 v[192:193], off
	s_add_i32 m0, s76, 0x2000
	s_add_u32 s74, s74, 0x40080
	v_lshl_add_u64 v[192:193], v[208:209], 0, s[10:11]
	s_addc_u32 s75, s75, 0
	s_add_i32 s76, s94, s67
	global_load_lds_dwordx4 v[192:193], off
	v_lshl_add_u64 v[192:193], s[74:75], 0, v[172:173]
	s_mov_b32 m0, s76
	s_nop 0
	global_load_lds_dwordx4 v[192:193], off
	v_lshl_add_u64 v[192:193], s[74:75], 0, v[168:169]
	s_add_i32 m0, s76, 0x2000
	s_nop 0
	global_load_lds_dwordx4 v[192:193], off
	v_lshl_add_u64 v[192:193], v[210:211], 0, s[10:11]
	s_mov_b32 m0, s79
	s_nop 0
	global_load_lds_dwordx4 v[192:193], off
	v_lshl_add_u64 v[192:193], v[224:225], 0, s[10:11]
	s_mov_b32 m0, s80
	s_nop 0
	global_load_lds_dwordx4 v[192:193], off
	s_waitcnt vmcnt(8)
	s_waitcnt lgkmcnt(0)
	s_barrier
	s_setprio 1
	s_waitcnt lgkmcnt(0)
	v_mfma_f32_16x16x32_f16 v[80:83], v[64:67], v[164:167], v[80:83]
	v_mfma_f32_16x16x32_f16 v[60:63], v[72:75], v[164:167], v[60:63]
	v_mfma_f32_16x16x32_f16 v[44:47], v[64:67], v[188:191], v[44:47]
	v_mfma_f32_16x16x32_f16 v[36:39], v[72:75], v[188:191], v[36:39]
	v_mfma_f32_16x16x32_f16 v[28:31], v[64:67], v[204:207], v[28:31]
	v_mfma_f32_16x16x32_f16 v[20:23], v[72:75], v[204:207], v[20:23]
	v_mfma_f32_16x16x32_f16 v[12:15], v[64:67], v[216:219], v[12:15]
	v_mfma_f32_16x16x32_f16 v[4:7], v[72:75], v[216:219], v[4:7]
	v_mfma_f32_16x16x32_f16 v[80:83], v[68:71], v[184:187], v[80:83]
	v_mfma_f32_16x16x32_f16 v[60:63], v[76:79], v[184:187], v[60:63]
	v_mfma_f32_16x16x32_f16 v[44:47], v[68:71], v[200:203], v[44:47]
	v_mfma_f32_16x16x32_f16 v[36:39], v[76:79], v[200:203], v[36:39]
	v_mfma_f32_16x16x32_f16 v[28:31], v[68:71], v[212:215], v[28:31]
	v_mfma_f32_16x16x32_f16 v[20:23], v[76:79], v[212:215], v[20:23]
	v_mfma_f32_16x16x32_f16 v[12:15], v[68:71], v[220:223], v[12:15]
	v_mfma_f32_16x16x32_f16 v[4:7], v[76:79], v[220:223], v[4:7]
	s_setprio 0
	s_setprio 1
	v_mfma_f32_16x16x32_f16 v[56:59], v[100:103], v[164:167], v[56:59]
	v_mfma_f32_16x16x32_f16 v[48:51], v[156:159], v[164:167], v[48:51]
	v_mfma_f32_16x16x32_f16 v[40:43], v[100:103], v[188:191], v[40:43]
	v_mfma_f32_16x16x32_f16 v[32:35], v[156:159], v[188:191], v[32:35]
	v_mfma_f32_16x16x32_f16 v[24:27], v[100:103], v[204:207], v[24:27]
	v_mfma_f32_16x16x32_f16 v[16:19], v[156:159], v[204:207], v[16:19]
	v_mfma_f32_16x16x32_f16 v[8:11], v[100:103], v[216:219], v[8:11]
	v_mfma_f32_16x16x32_f16 v[0:3], v[156:159], v[216:219], v[0:3]
	v_mfma_f32_16x16x32_f16 v[68:71], v[136:139], v[184:187], v[56:59]
	v_mfma_f32_16x16x32_f16 v[48:51], v[160:163], v[184:187], v[48:51]
	v_mfma_f32_16x16x32_f16 v[40:43], v[136:139], v[200:203], v[40:43]
	v_mfma_f32_16x16x32_f16 v[32:35], v[160:163], v[200:203], v[32:35]
	v_mfma_f32_16x16x32_f16 v[24:27], v[136:139], v[212:215], v[24:27]
	v_mfma_f32_16x16x32_f16 v[16:19], v[160:163], v[212:215], v[16:19]
	v_mfma_f32_16x16x32_f16 v[8:11], v[136:139], v[220:223], v[8:11]
	v_mfma_f32_16x16x32_f16 v[0:3], v[160:163], v[220:223], v[0:3]
	s_setprio 0
	s_barrier
	s_add_i32 s92, s92, 2
	s_add_u32 s46, s46, 0x100
	s_addc_u32 s47, s47, 0
	s_add_u32 s90, s90, 0x100
	s_addc_u32 s91, s91, 0
	s_cmp_gt_u32 s92, 13
	s_cbranch_scc1 .LBB0_749

.LBB0_751:
	s_cmp_eq_u32 s60, s66
	s_movk_i32 s15, 0x200
	s_cselect_b32 s15, s15, 0x300
	s_cmp_lg_u32 s60, s65
	s_cselect_b32 s15, s15, 0x100
	s_cmp_lg_u32 s60, s64
	v_mov_b32_e32 v64, v195
	v_mov_b32_e32 v65, v194
	s_cselect_b32 s15, s15, 0
	s_lshl_b32 s35, s86, 7
	s_or_b32 s35, s35, s78
	v_lshl_add_u32 v66, v64, 5, s82
	v_add_u32_e32 v184, s73, v65
	ds_read_b128 v[72:75], v66
	ds_read_b128 v[52:55], v66 offset:16
	ds_read_b128 v[76:79], v66 offset:256
	ds_read_b128 v[56:59], v66 offset:272
	ds_read_b128 v[202:205], v66 offset:128
	ds_read_b128 v[206:209], v66 offset:384
	ds_read_b128 v[160:163], v66 offset:144
	ds_read_b128 v[164:167], v66 offset:400
	v_lshl_add_u32 v190, v64, 3, s35
	v_add_u32_e32 v64, s15, v184
	v_lshl_add_u32 v64, v64, 3, v199
	ds_read2_b64 v[156:159], v64 offset1:16
	ds_read2_b64 v[136:139], v64 offset0:32 offset1:48
	ds_read2_b64 v[100:103], v64 offset0:128 offset1:144
	ds_read2_b64 v[64:67], v64 offset0:160 offset1:176
	s_waitcnt lgkmcnt(0)
	v_mov_b32_e32 v186, v202
	v_mov_b32_e32 v187, v72
	v_mov_b32_e32 v188, v206
	v_mov_b32_e32 v189, v76
	v_mov_b32_e32 v210, v148
	v_mov_b32_e32 v211, v152
	v_pk_fma_f32 v[212:213], v[186:187], v[156:157], v[188:189] op_sel:[0,1,0]
	v_mov_b32_e32 v76, v207
	v_pk_fma_f32 v[210:211], v[210:211], v[156:157], v[212:213] op_sel_hi:[1,0,1]
	v_mov_b32_e32 v152, v149
	v_mul_f32_e32 v72, 0xbfb8aa3b, v211
	v_exp_f32_e32 v72, v72
	v_mov_b32_e32 v202, v150
	v_lshl_add_u32 v200, s60, 8, v184
	v_ashrrev_i32_e32 v191, 31, v190
	v_add_f32_e32 v72, 1.0, v72
	v_rcp_f32_e32 v72, v72
	v_mov_b64_e32 v[184:185], s[42:43]
	v_mad_i64_i32 v[192:193], s[46:47], v200, s83, v[184:185]
	v_mul_f32_e32 v72, v211, v72
	v_mul_f32_e32 v201, v210, v72
	v_mov_b32_e32 v72, v203
	v_pk_fma_f32 v[148:149], v[72:73], v[156:157], v[76:77] op_sel:[0,1,0]
	v_mov_b32_e32 v203, v154
	v_pk_fma_f32 v[148:149], v[152:153], v[156:157], v[148:149] op_sel_hi:[1,0,1]
	v_mov_b32_e32 v153, v78
	v_mul_f32_e32 v152, 0xbfb8aa3b, v149
	v_exp_f32_e32 v152, v152
	v_mov_b32_e32 v78, v209
	v_mov_b32_e32 v154, v151
	s_andn2_b64 vcc, exec, s[8:9]
	v_add_f32_e32 v152, 1.0, v152
	v_rcp_f32_e32 v152, v152
	s_nop 0
	v_mul_f32_e32 v149, v149, v152
	v_mul_f32_e32 v210, v148, v149
	v_mov_b32_e32 v148, v204
	v_mov_b32_e32 v149, v74
	v_mov_b32_e32 v152, v208
	v_pk_fma_f32 v[206:207], v[148:149], v[156:157], v[152:153] op_sel:[0,1,0]
	s_nop 0
	v_pk_fma_f32 v[202:203], v[202:203], v[156:157], v[206:207] op_sel_hi:[1,0,1]
	s_nop 0
	v_mul_f32_e32 v74, 0xbfb8aa3b, v203
	v_exp_f32_e32 v74, v74
	s_nop 0
	v_add_f32_e32 v74, 1.0, v74
	v_rcp_f32_e32 v74, v74
	s_nop 0
	v_mul_f32_e32 v74, v203, v74
	v_mul_f32_e32 v206, v202, v74
	v_mov_b32_e32 v74, v205
	v_pk_fma_f32 v[150:151], v[74:75], v[156:157], v[78:79] op_sel:[0,1,0]
	v_mov_b32_e32 v202, v140
	v_pk_fma_f32 v[150:151], v[154:155], v[156:157], v[150:151] op_sel_hi:[1,0,1]
	v_mov_b32_e32 v155, v56
	v_mul_f32_e32 v154, 0xbfb8aa3b, v151
	v_exp_f32_e32 v154, v154
	v_mov_b32_e32 v203, v144
	v_mov_b32_e32 v56, v165
	v_mov_b32_e32 v144, v141
	v_add_f32_e32 v154, 1.0, v154
	v_rcp_f32_e32 v154, v154
	s_nop 0
	v_mul_f32_e32 v151, v151, v154
	v_mul_f32_e32 v207, v150, v151
	v_mov_b32_e32 v150, v160
	v_mov_b32_e32 v151, v52
	v_mov_b32_e32 v154, v164
	v_pk_fma_f32 v[204:205], v[150:151], v[156:157], v[154:155] op_sel:[0,1,0]
	v_mov_b32_e32 v160, v142
	v_pk_fma_f32 v[202:203], v[202:203], v[156:157], v[204:205] op_sel_hi:[1,0,1]
	s_nop 0
	v_mul_f32_e32 v52, 0xbfb8aa3b, v203
	v_exp_f32_e32 v52, v52
	s_nop 0
	v_add_f32_e32 v52, 1.0, v52
	v_rcp_f32_e32 v52, v52
	s_nop 0
	v_mul_f32_e32 v52, v203, v52
	v_mul_f32_e32 v202, v202, v52
	v_mov_b32_e32 v52, v161
	v_pk_fma_f32 v[140:141], v[52:53], v[156:157], v[56:57] op_sel:[0,1,0]
	v_mov_b32_e32 v161, v146
	v_pk_fma_f32 v[140:141], v[144:145], v[156:157], v[140:141] op_sel_hi:[1,0,1]
	v_mov_b32_e32 v145, v58
	v_mul_f32_e32 v144, 0xbfb8aa3b, v141
	v_exp_f32_e32 v144, v144
	v_mov_b32_e32 v58, v167
	v_mov_b32_e32 v146, v143
	v_add_f32_e32 v144, 1.0, v144
	v_rcp_f32_e32 v144, v144
	s_nop 0
	v_mul_f32_e32 v141, v141, v144
	v_mul_f32_e32 v203, v140, v141
	v_mov_b32_e32 v140, v162
	v_mov_b32_e32 v141, v54
	v_mov_b32_e32 v144, v166
	v_pk_fma_f32 v[164:165], v[140:141], v[156:157], v[144:145] op_sel:[0,1,0]
	s_nop 0
	v_pk_fma_f32 v[160:161], v[160:161], v[156:157], v[164:165] op_sel_hi:[1,0,1]
	s_nop 0
	v_mul_f32_e32 v54, 0xbfb8aa3b, v161
	v_exp_f32_e32 v54, v54
	s_nop 0
	v_add_f32_e32 v54, 1.0, v54
	v_rcp_f32_e32 v54, v54
	s_nop 0
	v_mul_f32_e32 v54, v161, v54
	v_mul_f32_e32 v164, v160, v54
	v_mov_b32_e32 v54, v163
	v_pk_fma_f32 v[142:143], v[54:55], v[156:157], v[58:59] op_sel:[0,1,0]
	v_cvt_pk_bf16_f32 v160, v201, v210
	v_cvt_pk_bf16_f32 v161, v206, v207
	v_cvt_pk_bf16_f32 v162, v202, v203
	s_nop 0
	v_pk_fma_f32 v[142:143], v[146:147], v[156:157], v[142:143] op_sel_hi:[1,0,1]
	v_mov_b32_e32 v157, v132
	v_mul_f32_e32 v146, 0xbfb8aa3b, v143
	v_exp_f32_e32 v146, v146
	v_mov_b32_e32 v132, v129
	v_add_f32_e32 v146, 1.0, v146
	v_rcp_f32_e32 v146, v146
	s_nop 0
	v_mul_f32_e32 v143, v143, v146
	v_mul_f32_e32 v156, v142, v143
	v_lshlrev_b64 v[142:143], 1, v[190:191]
	v_lshl_add_u64 v[146:147], v[192:193], 0, v[142:143]
	v_cvt_pk_bf16_f32 v163, v164, v156
	global_store_dwordx4 v[146:147], v[160:163], off
	v_mov_b32_e32 v156, v128
	v_add_u32_e32 v146, 16, v200
	v_pk_fma_f32 v[160:161], v[186:187], v[158:159], v[188:189] op_sel:[0,1,0]
	v_mad_i64_i32 v[146:147], s[46:47], v146, s83, v[184:185]
	v_pk_fma_f32 v[156:157], v[156:157], v[158:159], v[160:161] op_sel_hi:[1,0,1]
	s_nop 0
	v_mul_f32_e32 v128, 0xbfb8aa3b, v157
	v_exp_f32_e32 v128, v128
	s_nop 0
	v_add_f32_e32 v128, 1.0, v128
	v_rcp_f32_e32 v128, v128
	s_nop 0
	v_mul_f32_e32 v128, v157, v128
	v_mul_f32_e32 v156, v156, v128
	v_pk_fma_f32 v[128:129], v[72:73], v[158:159], v[76:77] op_sel:[0,1,0]
	s_nop 0
	v_pk_fma_f32 v[128:129], v[132:133], v[158:159], v[128:129] op_sel_hi:[1,0,1]
	s_nop 0
	v_mul_f32_e32 v132, 0xbfb8aa3b, v129
	v_exp_f32_e32 v132, v132
	s_nop 0
	v_add_f32_e32 v132, 1.0, v132
	v_rcp_f32_e32 v132, v132
	s_nop 0
	v_mul_f32_e32 v129, v129, v132
	v_mul_f32_e32 v157, v128, v129
	v_mov_b32_e32 v128, v130
	v_mov_b32_e32 v129, v134
	v_pk_fma_f32 v[132:133], v[148:149], v[158:159], v[152:153] op_sel:[0,1,0]
	v_mov_b32_e32 v134, v131
	v_pk_fma_f32 v[128:129], v[128:129], v[158:159], v[132:133] op_sel_hi:[1,0,1]
	s_nop 0
	v_mul_f32_e32 v130, 0xbfb8aa3b, v129
	v_exp_f32_e32 v130, v130
	s_nop 0
	v_add_f32_e32 v130, 1.0, v130
	v_rcp_f32_e32 v130, v130
	s_nop 0
	v_mul_f32_e32 v129, v129, v130
	v_mul_f32_e32 v132, v128, v129
	v_pk_fma_f32 v[128:129], v[74:75], v[158:159], v[78:79] op_sel:[0,1,0]
	s_nop 0
	v_pk_fma_f32 v[128:129], v[134:135], v[158:159], v[128:129] op_sel_hi:[1,0,1]
	s_nop 0
	v_mul_f32_e32 v130, 0xbfb8aa3b, v129
	v_exp_f32_e32 v130, v130
	s_nop 0
	v_add_f32_e32 v130, 1.0, v130
	v_rcp_f32_e32 v130, v130
	s_nop 0
	v_mul_f32_e32 v129, v129, v130
	v_mul_f32_e32 v133, v128, v129
	v_mov_b32_e32 v128, v120
	v_mov_b32_e32 v129, v124
	v_pk_fma_f32 v[130:131], v[150:151], v[158:159], v[154:155] op_sel:[0,1,0]
	v_mov_b32_e32 v124, v121
	v_pk_fma_f32 v[128:129], v[128:129], v[158:159], v[130:131] op_sel_hi:[1,0,1]
	s_nop 0
	v_mul_f32_e32 v120, 0xbfb8aa3b, v129
	v_exp_f32_e32 v120, v120
	s_nop 0
	v_add_f32_e32 v120, 1.0, v120
	v_rcp_f32_e32 v120, v120
	s_nop 0
	v_mul_f32_e32 v120, v129, v120
	v_mul_f32_e32 v128, v128, v120
	v_pk_fma_f32 v[120:121], v[52:53], v[158:159], v[56:57] op_sel:[0,1,0]
	s_nop 0
	v_pk_fma_f32 v[120:121], v[124:125], v[158:159], v[120:121] op_sel_hi:[1,0,1]
	s_nop 0
	v_mul_f32_e32 v124, 0xbfb8aa3b, v121
	v_exp_f32_e32 v124, v124
	s_nop 0
	v_add_f32_e32 v124, 1.0, v124
	v_rcp_f32_e32 v124, v124
	s_nop 0
	v_mul_f32_e32 v121, v121, v124
	v_mul_f32_e32 v129, v120, v121
	v_mov_b32_e32 v120, v122
	v_mov_b32_e32 v121, v126
	v_pk_fma_f32 v[124:125], v[140:141], v[158:159], v[144:145] op_sel:[0,1,0]
	v_mov_b32_e32 v126, v123
	v_pk_fma_f32 v[120:121], v[120:121], v[158:159], v[124:125] op_sel_hi:[1,0,1]
	v_lshl_add_u64 v[124:125], v[146:147], 0, v[142:143]
	v_mul_f32_e32 v122, 0xbfb8aa3b, v121
	v_exp_f32_e32 v122, v122
	s_nop 0
	v_add_f32_e32 v122, 1.0, v122
	v_rcp_f32_e32 v122, v122
	s_nop 0
	v_mul_f32_e32 v121, v121, v122
	v_mul_f32_e32 v130, v120, v121
	v_pk_fma_f32 v[120:121], v[54:55], v[158:159], v[58:59] op_sel:[0,1,0]
	s_nop 0
	v_pk_fma_f32 v[120:121], v[126:127], v[158:159], v[120:121] op_sel_hi:[1,0,1]
	s_nop 0
	v_mul_f32_e32 v122, 0xbfb8aa3b, v121
	v_exp_f32_e32 v122, v122
	s_nop 0
	v_add_f32_e32 v122, 1.0, v122
	v_rcp_f32_e32 v122, v122
	s_nop 0
	v_mul_f32_e32 v121, v121, v122
	v_mul_f32_e32 v123, v120, v121
	v_cvt_pk_bf16_f32 v120, v156, v157
	v_cvt_pk_bf16_f32 v121, v132, v133
	v_cvt_pk_bf16_f32 v122, v128, v129
	v_cvt_pk_bf16_f32 v123, v130, v123
	global_store_dwordx4 v[124:125], v[120:123], off
	v_pk_fma_f32 v[124:125], v[186:187], v[136:137], v[188:189] op_sel:[0,1,0]
	s_nop 0
	v_mov_b32_e32 v122, v112
	v_mov_b32_e32 v123, v116
	v_pk_fma_f32 v[122:123], v[122:123], v[136:137], v[124:125] op_sel_hi:[1,0,1]
	v_mov_b32_e32 v116, v113
	v_mul_f32_e32 v112, 0xbfb8aa3b, v123
	v_exp_f32_e32 v112, v112
	v_add_u32_e32 v120, 32, v200
	v_mad_i64_i32 v[120:121], s[46:47], v120, s83, v[184:185]
	v_add_f32_e32 v112, 1.0, v112
	v_rcp_f32_e32 v112, v112
	s_nop 0
	v_mul_f32_e32 v112, v123, v112
	v_mul_f32_e32 v122, v122, v112
	v_pk_fma_f32 v[112:113], v[72:73], v[136:137], v[76:77] op_sel:[0,1,0]
	s_nop 0
	v_pk_fma_f32 v[112:113], v[116:117], v[136:137], v[112:113] op_sel_hi:[1,0,1]
	s_nop 0
	v_mul_f32_e32 v116, 0xbfb8aa3b, v113
	v_exp_f32_e32 v116, v116
	s_nop 0
	v_add_f32_e32 v116, 1.0, v116
	v_rcp_f32_e32 v116, v116
	s_nop 0
	v_mul_f32_e32 v113, v113, v116
	v_mul_f32_e32 v123, v112, v113
	v_mov_b32_e32 v112, v114
	v_mov_b32_e32 v113, v118
	v_pk_fma_f32 v[116:117], v[148:149], v[136:137], v[152:153] op_sel:[0,1,0]
	v_mov_b32_e32 v118, v115
	v_pk_fma_f32 v[112:113], v[112:113], v[136:137], v[116:117] op_sel_hi:[1,0,1]
	s_nop 0
	v_mul_f32_e32 v114, 0xbfb8aa3b, v113
	v_exp_f32_e32 v114, v114
	s_nop 0
	v_add_f32_e32 v114, 1.0, v114
	v_rcp_f32_e32 v114, v114
	s_nop 0
	v_mul_f32_e32 v113, v113, v114
	v_mul_f32_e32 v116, v112, v113
	v_pk_fma_f32 v[112:113], v[74:75], v[136:137], v[78:79] op_sel:[0,1,0]
	s_nop 0
	v_pk_fma_f32 v[112:113], v[118:119], v[136:137], v[112:113] op_sel_hi:[1,0,1]
	s_nop 0
	v_mul_f32_e32 v114, 0xbfb8aa3b, v113
	v_exp_f32_e32 v114, v114
	s_nop 0
	v_add_f32_e32 v114, 1.0, v114
	v_rcp_f32_e32 v114, v114
	s_nop 0
	v_mul_f32_e32 v113, v113, v114
	v_mul_f32_e32 v117, v112, v113
	v_mov_b32_e32 v112, v104
	v_mov_b32_e32 v113, v108
	v_pk_fma_f32 v[114:115], v[150:151], v[136:137], v[154:155] op_sel:[0,1,0]
	v_mov_b32_e32 v108, v105
	v_pk_fma_f32 v[112:113], v[112:113], v[136:137], v[114:115] op_sel_hi:[1,0,1]
	s_nop 0
	v_mul_f32_e32 v104, 0xbfb8aa3b, v113
	v_exp_f32_e32 v104, v104
	s_nop 0
	v_add_f32_e32 v104, 1.0, v104
	v_rcp_f32_e32 v104, v104
	s_nop 0
	v_mul_f32_e32 v104, v113, v104
	v_mul_f32_e32 v112, v112, v104
	v_pk_fma_f32 v[104:105], v[52:53], v[136:137], v[56:57] op_sel:[0,1,0]
	s_nop 0
	v_pk_fma_f32 v[104:105], v[108:109], v[136:137], v[104:105] op_sel_hi:[1,0,1]
	s_nop 0
	v_mul_f32_e32 v108, 0xbfb8aa3b, v105
	v_exp_f32_e32 v108, v108
	s_nop 0
	v_add_f32_e32 v108, 1.0, v108
	v_rcp_f32_e32 v108, v108
	s_nop 0
	v_mul_f32_e32 v105, v105, v108
	v_mul_f32_e32 v113, v104, v105
	v_mov_b32_e32 v104, v106
	v_mov_b32_e32 v105, v110
	v_pk_fma_f32 v[108:109], v[140:141], v[136:137], v[144:145] op_sel:[0,1,0]
	v_mov_b32_e32 v110, v107
	v_pk_fma_f32 v[104:105], v[104:105], v[136:137], v[108:109] op_sel_hi:[1,0,1]
	v_lshl_add_u64 v[108:109], v[120:121], 0, v[142:143]
	v_mul_f32_e32 v106, 0xbfb8aa3b, v105
	v_exp_f32_e32 v106, v106
	s_nop 0
	v_add_f32_e32 v106, 1.0, v106
	v_rcp_f32_e32 v106, v106
	s_nop 0
	v_mul_f32_e32 v105, v105, v106
	v_mul_f32_e32 v114, v104, v105
	v_pk_fma_f32 v[104:105], v[54:55], v[136:137], v[58:59] op_sel:[0,1,0]
	s_nop 0
	v_pk_fma_f32 v[104:105], v[110:111], v[136:137], v[104:105] op_sel_hi:[1,0,1]
	s_nop 0
	v_mul_f32_e32 v106, 0xbfb8aa3b, v105
	v_exp_f32_e32 v106, v106
	s_nop 0
	v_add_f32_e32 v106, 1.0, v106
	v_rcp_f32_e32 v106, v106
	s_nop 0
	v_mul_f32_e32 v105, v105, v106
	v_mul_f32_e32 v107, v104, v105
	v_cvt_pk_bf16_f32 v104, v122, v123
	v_cvt_pk_bf16_f32 v105, v116, v117
	v_cvt_pk_bf16_f32 v106, v112, v113
	v_cvt_pk_bf16_f32 v107, v114, v107
	global_store_dwordx4 v[108:109], v[104:107], off
	v_pk_fma_f32 v[108:109], v[186:187], v[138:139], v[188:189] op_sel:[0,1,0]
	s_nop 0
	v_mov_b32_e32 v106, v92
	v_mov_b32_e32 v107, v96
	v_pk_fma_f32 v[106:107], v[106:107], v[138:139], v[108:109] op_sel_hi:[1,0,1]
	v_mov_b32_e32 v96, v93
	v_mul_f32_e32 v92, 0xbfb8aa3b, v107
	v_exp_f32_e32 v92, v92
	v_add_u32_e32 v104, 48, v200
	v_mad_i64_i32 v[104:105], s[46:47], v104, s83, v[184:185]
	v_add_f32_e32 v92, 1.0, v92
	v_rcp_f32_e32 v92, v92
	s_nop 0
	v_mul_f32_e32 v92, v107, v92
	v_mul_f32_e32 v106, v106, v92
	v_pk_fma_f32 v[92:93], v[72:73], v[138:139], v[76:77] op_sel:[0,1,0]
	s_nop 0
	v_pk_fma_f32 v[92:93], v[96:97], v[138:139], v[92:93] op_sel_hi:[1,0,1]
	s_nop 0
	v_mul_f32_e32 v96, 0xbfb8aa3b, v93
	v_exp_f32_e32 v96, v96
	s_nop 0
	v_add_f32_e32 v96, 1.0, v96
	v_rcp_f32_e32 v96, v96
	s_nop 0
	v_mul_f32_e32 v93, v93, v96
	v_mul_f32_e32 v107, v92, v93
	v_mov_b32_e32 v92, v94
	v_mov_b32_e32 v93, v98
	v_pk_fma_f32 v[96:97], v[148:149], v[138:139], v[152:153] op_sel:[0,1,0]
	v_mov_b32_e32 v98, v95
	v_pk_fma_f32 v[92:93], v[92:93], v[138:139], v[96:97] op_sel_hi:[1,0,1]
	s_nop 0
	v_mul_f32_e32 v94, 0xbfb8aa3b, v93
	v_exp_f32_e32 v94, v94
	s_nop 0
	v_add_f32_e32 v94, 1.0, v94
	v_rcp_f32_e32 v94, v94
	s_nop 0
	v_mul_f32_e32 v93, v93, v94
	v_mul_f32_e32 v96, v92, v93
	v_pk_fma_f32 v[92:93], v[74:75], v[138:139], v[78:79] op_sel:[0,1,0]
	s_nop 0
	v_pk_fma_f32 v[92:93], v[98:99], v[138:139], v[92:93] op_sel_hi:[1,0,1]
	s_nop 0
	v_mul_f32_e32 v94, 0xbfb8aa3b, v93
	v_exp_f32_e32 v94, v94
	s_nop 0
	v_add_f32_e32 v94, 1.0, v94
	v_rcp_f32_e32 v94, v94
	s_nop 0
	v_mul_f32_e32 v93, v93, v94
	v_mul_f32_e32 v97, v92, v93
	v_mov_b32_e32 v92, v84
	v_mov_b32_e32 v93, v88
	v_pk_fma_f32 v[94:95], v[150:151], v[138:139], v[154:155] op_sel:[0,1,0]
	v_mov_b32_e32 v88, v85
	v_pk_fma_f32 v[92:93], v[92:93], v[138:139], v[94:95] op_sel_hi:[1,0,1]
	s_nop 0
	v_mul_f32_e32 v84, 0xbfb8aa3b, v93
	v_exp_f32_e32 v84, v84
	s_nop 0
	v_add_f32_e32 v84, 1.0, v84
	v_rcp_f32_e32 v84, v84
	s_nop 0
	v_mul_f32_e32 v84, v93, v84
	v_mul_f32_e32 v92, v92, v84
	v_pk_fma_f32 v[84:85], v[52:53], v[138:139], v[56:57] op_sel:[0,1,0]
	s_nop 0
	v_pk_fma_f32 v[84:85], v[88:89], v[138:139], v[84:85] op_sel_hi:[1,0,1]
	s_nop 0
	v_mul_f32_e32 v88, 0xbfb8aa3b, v85
	v_exp_f32_e32 v88, v88
	s_nop 0
	v_add_f32_e32 v88, 1.0, v88
	v_rcp_f32_e32 v88, v88
	s_nop 0
	v_mul_f32_e32 v85, v85, v88
	v_mul_f32_e32 v93, v84, v85
	v_mov_b32_e32 v84, v86
	v_mov_b32_e32 v85, v90
	v_pk_fma_f32 v[88:89], v[140:141], v[138:139], v[144:145] op_sel:[0,1,0]
	v_mov_b32_e32 v90, v87
	v_pk_fma_f32 v[84:85], v[84:85], v[138:139], v[88:89] op_sel_hi:[1,0,1]
	v_lshl_add_u64 v[88:89], v[104:105], 0, v[142:143]
	v_mul_f32_e32 v86, 0xbfb8aa3b, v85
	v_exp_f32_e32 v86, v86
	s_nop 0
	v_add_f32_e32 v86, 1.0, v86
	v_rcp_f32_e32 v86, v86
	s_nop 0
	v_mul_f32_e32 v85, v85, v86
	v_mul_f32_e32 v94, v84, v85
	v_pk_fma_f32 v[84:85], v[54:55], v[138:139], v[58:59] op_sel:[0,1,0]
	s_nop 0
	v_pk_fma_f32 v[84:85], v[90:91], v[138:139], v[84:85] op_sel_hi:[1,0,1]
	s_nop 0
	v_mul_f32_e32 v86, 0xbfb8aa3b, v85
	v_exp_f32_e32 v86, v86
	s_nop 0
	v_add_f32_e32 v86, 1.0, v86
	v_rcp_f32_e32 v86, v86
	s_nop 0
	v_mul_f32_e32 v85, v85, v86
	v_mul_f32_e32 v87, v84, v85
	v_cvt_pk_bf16_f32 v84, v106, v107
	v_cvt_pk_bf16_f32 v85, v96, v97
	v_cvt_pk_bf16_f32 v86, v92, v93
	v_cvt_pk_bf16_f32 v87, v94, v87
	global_store_dwordx4 v[88:89], v[84:87], off
	v_pk_fma_f32 v[88:89], v[186:187], v[100:101], v[188:189] op_sel:[0,1,0]
	s_nop 0
	v_mov_b32_e32 v86, v68
	v_mov_b32_e32 v87, v80
	v_pk_fma_f32 v[86:87], v[86:87], v[100:101], v[88:89] op_sel_hi:[1,0,1]
	v_mov_b32_e32 v80, v69
	v_mul_f32_e32 v68, 0xbfb8aa3b, v87
	v_exp_f32_e32 v68, v68
	v_add_u32_e32 v84, 0x80, v200
	v_mad_i64_i32 v[84:85], s[46:47], v84, s83, v[184:185]
	v_add_f32_e32 v68, 1.0, v68
	v_rcp_f32_e32 v68, v68
	s_nop 0
	v_mul_f32_e32 v68, v87, v68
	v_mul_f32_e32 v86, v86, v68
	v_pk_fma_f32 v[68:69], v[72:73], v[100:101], v[76:77] op_sel:[0,1,0]
	s_nop 0
	v_pk_fma_f32 v[68:69], v[80:81], v[100:101], v[68:69] op_sel_hi:[1,0,1]
	s_nop 0
	v_mul_f32_e32 v80, 0xbfb8aa3b, v69
	v_exp_f32_e32 v80, v80
	s_nop 0
	v_add_f32_e32 v80, 1.0, v80
	v_rcp_f32_e32 v80, v80
	s_nop 0
	v_mul_f32_e32 v69, v69, v80
	v_mul_f32_e32 v87, v68, v69
	v_mov_b32_e32 v68, v70
	v_mov_b32_e32 v69, v82
	v_pk_fma_f32 v[80:81], v[148:149], v[100:101], v[152:153] op_sel:[0,1,0]
	v_mov_b32_e32 v82, v71
	v_pk_fma_f32 v[68:69], v[68:69], v[100:101], v[80:81] op_sel_hi:[1,0,1]
	s_nop 0
	v_mul_f32_e32 v70, 0xbfb8aa3b, v69
	v_exp_f32_e32 v70, v70
	s_nop 0
	v_add_f32_e32 v70, 1.0, v70
	v_rcp_f32_e32 v70, v70
	s_nop 0
	v_mul_f32_e32 v69, v69, v70
	v_mul_f32_e32 v80, v68, v69
	v_pk_fma_f32 v[68:69], v[74:75], v[100:101], v[78:79] op_sel:[0,1,0]
	s_nop 0
	v_pk_fma_f32 v[68:69], v[82:83], v[100:101], v[68:69] op_sel_hi:[1,0,1]
	s_nop 0
	v_mul_f32_e32 v70, 0xbfb8aa3b, v69
	v_exp_f32_e32 v70, v70
	s_nop 0
	v_add_f32_e32 v70, 1.0, v70
	v_rcp_f32_e32 v70, v70
	s_nop 0
	v_mul_f32_e32 v69, v69, v70
	v_mul_f32_e32 v81, v68, v69
	v_mov_b32_e32 v68, v48
	v_mov_b32_e32 v69, v60
	v_pk_fma_f32 v[70:71], v[150:151], v[100:101], v[154:155] op_sel:[0,1,0]
	v_mov_b32_e32 v60, v49
	v_pk_fma_f32 v[68:69], v[68:69], v[100:101], v[70:71] op_sel_hi:[1,0,1]
	s_nop 0
	v_mul_f32_e32 v48, 0xbfb8aa3b, v69
	v_exp_f32_e32 v48, v48
	s_nop 0
	v_add_f32_e32 v48, 1.0, v48
	v_rcp_f32_e32 v48, v48
	s_nop 0
	v_mul_f32_e32 v48, v69, v48
	v_mul_f32_e32 v68, v68, v48
	v_pk_fma_f32 v[48:49], v[52:53], v[100:101], v[56:57] op_sel:[0,1,0]
	s_nop 0
	v_pk_fma_f32 v[48:49], v[60:61], v[100:101], v[48:49] op_sel_hi:[1,0,1]
	s_nop 0
	v_mul_f32_e32 v60, 0xbfb8aa3b, v49
	v_exp_f32_e32 v60, v60
	s_nop 0
	v_add_f32_e32 v60, 1.0, v60
	v_rcp_f32_e32 v60, v60
	s_nop 0
	v_mul_f32_e32 v49, v49, v60
	v_mul_f32_e32 v69, v48, v49
	v_mov_b32_e32 v48, v50
	v_mov_b32_e32 v49, v62
	v_pk_fma_f32 v[60:61], v[140:141], v[100:101], v[144:145] op_sel:[0,1,0]
	v_mov_b32_e32 v62, v51
	v_pk_fma_f32 v[48:49], v[48:49], v[100:101], v[60:61] op_sel_hi:[1,0,1]
	v_lshl_add_u64 v[60:61], v[84:85], 0, v[142:143]
	v_mul_f32_e32 v50, 0xbfb8aa3b, v49
	v_exp_f32_e32 v50, v50
	s_nop 0
	v_add_f32_e32 v50, 1.0, v50
	v_rcp_f32_e32 v50, v50
	s_nop 0
	v_mul_f32_e32 v49, v49, v50
	v_mul_f32_e32 v70, v48, v49
	v_pk_fma_f32 v[48:49], v[54:55], v[100:101], v[58:59] op_sel:[0,1,0]
	s_nop 0
	v_pk_fma_f32 v[48:49], v[62:63], v[100:101], v[48:49] op_sel_hi:[1,0,1]
	s_nop 0
	v_mul_f32_e32 v50, 0xbfb8aa3b, v49
	v_exp_f32_e32 v50, v50
	s_nop 0
	v_add_f32_e32 v50, 1.0, v50
	v_rcp_f32_e32 v50, v50
	s_nop 0
	v_mul_f32_e32 v49, v49, v50
	v_mul_f32_e32 v51, v48, v49
	v_cvt_pk_bf16_f32 v48, v86, v87
	v_cvt_pk_bf16_f32 v49, v80, v81
	v_cvt_pk_bf16_f32 v50, v68, v69
	v_cvt_pk_bf16_f32 v51, v70, v51
	global_store_dwordx4 v[60:61], v[48:51], off
	v_pk_fma_f32 v[60:61], v[186:187], v[102:103], v[188:189] op_sel:[0,1,0]
	s_nop 0
	v_mov_b32_e32 v50, v40
	v_mov_b32_e32 v51, v44
	v_pk_fma_f32 v[50:51], v[50:51], v[102:103], v[60:61] op_sel_hi:[1,0,1]
	v_mov_b32_e32 v44, v41
	v_mul_f32_e32 v40, 0xbfb8aa3b, v51
	v_exp_f32_e32 v40, v40
	v_add_u32_e32 v48, 0x90, v200
	v_mad_i64_i32 v[48:49], s[46:47], v48, s83, v[184:185]
	v_add_f32_e32 v40, 1.0, v40
	v_rcp_f32_e32 v40, v40
	s_nop 0
	v_mul_f32_e32 v40, v51, v40
	v_mul_f32_e32 v50, v50, v40
	v_pk_fma_f32 v[40:41], v[72:73], v[102:103], v[76:77] op_sel:[0,1,0]
	s_nop 0
	v_pk_fma_f32 v[40:41], v[44:45], v[102:103], v[40:41] op_sel_hi:[1,0,1]
	s_nop 0
	v_mul_f32_e32 v44, 0xbfb8aa3b, v41
	v_exp_f32_e32 v44, v44
	s_nop 0
	v_add_f32_e32 v44, 1.0, v44
	v_rcp_f32_e32 v44, v44
	s_nop 0
	v_mul_f32_e32 v41, v41, v44
	v_mul_f32_e32 v51, v40, v41
	v_mov_b32_e32 v40, v42
	v_mov_b32_e32 v41, v46
	v_pk_fma_f32 v[44:45], v[148:149], v[102:103], v[152:153] op_sel:[0,1,0]
	v_mov_b32_e32 v46, v43
	v_pk_fma_f32 v[40:41], v[40:41], v[102:103], v[44:45] op_sel_hi:[1,0,1]
	s_nop 0
	v_mul_f32_e32 v42, 0xbfb8aa3b, v41
	v_exp_f32_e32 v42, v42
	s_nop 0
	v_add_f32_e32 v42, 1.0, v42
	v_rcp_f32_e32 v42, v42
	s_nop 0
	v_mul_f32_e32 v41, v41, v42
	v_mul_f32_e32 v44, v40, v41
	v_pk_fma_f32 v[40:41], v[74:75], v[102:103], v[78:79] op_sel:[0,1,0]
	s_nop 0
	v_pk_fma_f32 v[40:41], v[46:47], v[102:103], v[40:41] op_sel_hi:[1,0,1]
	s_nop 0
	v_mul_f32_e32 v42, 0xbfb8aa3b, v41
	v_exp_f32_e32 v42, v42
	s_nop 0
	v_add_f32_e32 v42, 1.0, v42
	v_rcp_f32_e32 v42, v42
	s_nop 0
	v_mul_f32_e32 v41, v41, v42
	v_mul_f32_e32 v45, v40, v41
	v_mov_b32_e32 v40, v32
	v_mov_b32_e32 v41, v36
	v_pk_fma_f32 v[42:43], v[150:151], v[102:103], v[154:155] op_sel:[0,1,0]
	v_mov_b32_e32 v36, v33
	v_pk_fma_f32 v[40:41], v[40:41], v[102:103], v[42:43] op_sel_hi:[1,0,1]
	s_nop 0
	v_mul_f32_e32 v32, 0xbfb8aa3b, v41
	v_exp_f32_e32 v32, v32
	s_nop 0
	v_add_f32_e32 v32, 1.0, v32
	v_rcp_f32_e32 v32, v32
	s_nop 0
	v_mul_f32_e32 v32, v41, v32
	v_mul_f32_e32 v40, v40, v32
	v_pk_fma_f32 v[32:33], v[52:53], v[102:103], v[56:57] op_sel:[0,1,0]
	s_nop 0
	v_pk_fma_f32 v[32:33], v[36:37], v[102:103], v[32:33] op_sel_hi:[1,0,1]
	s_nop 0
	v_mul_f32_e32 v36, 0xbfb8aa3b, v33
	v_exp_f32_e32 v36, v36
	s_nop 0
	v_add_f32_e32 v36, 1.0, v36
	v_rcp_f32_e32 v36, v36
	s_nop 0
	v_mul_f32_e32 v33, v33, v36
	v_mul_f32_e32 v41, v32, v33
	v_mov_b32_e32 v32, v34
	v_mov_b32_e32 v33, v38
	v_pk_fma_f32 v[36:37], v[140:141], v[102:103], v[144:145] op_sel:[0,1,0]
	v_mov_b32_e32 v38, v35
	v_pk_fma_f32 v[32:33], v[32:33], v[102:103], v[36:37] op_sel_hi:[1,0,1]
	v_lshl_add_u64 v[36:37], v[48:49], 0, v[142:143]
	v_mul_f32_e32 v34, 0xbfb8aa3b, v33
	v_exp_f32_e32 v34, v34
	s_nop 0
	v_add_f32_e32 v34, 1.0, v34
	v_rcp_f32_e32 v34, v34
	s_nop 0
	v_mul_f32_e32 v33, v33, v34
	v_mul_f32_e32 v42, v32, v33
	v_pk_fma_f32 v[32:33], v[54:55], v[102:103], v[58:59] op_sel:[0,1,0]
	s_nop 0
	v_pk_fma_f32 v[32:33], v[38:39], v[102:103], v[32:33] op_sel_hi:[1,0,1]
	s_nop 0
	v_mul_f32_e32 v34, 0xbfb8aa3b, v33
	v_exp_f32_e32 v34, v34
	s_nop 0
	v_add_f32_e32 v34, 1.0, v34
	v_rcp_f32_e32 v34, v34
	s_nop 0
	v_mul_f32_e32 v33, v33, v34
	v_mul_f32_e32 v35, v32, v33
	v_cvt_pk_bf16_f32 v32, v50, v51
	v_cvt_pk_bf16_f32 v33, v44, v45
	v_cvt_pk_bf16_f32 v34, v40, v41
	v_cvt_pk_bf16_f32 v35, v42, v35
	global_store_dwordx4 v[36:37], v[32:35], off
	v_pk_fma_f32 v[36:37], v[186:187], v[64:65], v[188:189] op_sel:[0,1,0]
	s_nop 0
	v_mov_b32_e32 v34, v24
	v_mov_b32_e32 v35, v28
	v_pk_fma_f32 v[34:35], v[34:35], v[64:65], v[36:37] op_sel_hi:[1,0,1]
	v_mov_b32_e32 v28, v25
	v_mul_f32_e32 v24, 0xbfb8aa3b, v35
	v_exp_f32_e32 v24, v24
	v_add_u32_e32 v32, 0xa0, v200
	v_mad_i64_i32 v[32:33], s[46:47], v32, s83, v[184:185]
	v_add_f32_e32 v24, 1.0, v24
	v_rcp_f32_e32 v24, v24
	s_nop 0
	v_mul_f32_e32 v24, v35, v24
	v_mul_f32_e32 v34, v34, v24
	v_pk_fma_f32 v[24:25], v[72:73], v[64:65], v[76:77] op_sel:[0,1,0]
	s_nop 0
	v_pk_fma_f32 v[24:25], v[28:29], v[64:65], v[24:25] op_sel_hi:[1,0,1]
	s_nop 0
	v_mul_f32_e32 v28, 0xbfb8aa3b, v25
	v_exp_f32_e32 v28, v28
	s_nop 0
	v_add_f32_e32 v28, 1.0, v28
	v_rcp_f32_e32 v28, v28
	s_nop 0
	v_mul_f32_e32 v25, v25, v28
	v_mul_f32_e32 v35, v24, v25
	v_mov_b32_e32 v24, v26
	v_mov_b32_e32 v25, v30
	v_pk_fma_f32 v[28:29], v[148:149], v[64:65], v[152:153] op_sel:[0,1,0]
	v_mov_b32_e32 v30, v27
	v_pk_fma_f32 v[24:25], v[24:25], v[64:65], v[28:29] op_sel_hi:[1,0,1]
	s_nop 0
	v_mul_f32_e32 v26, 0xbfb8aa3b, v25
	v_exp_f32_e32 v26, v26
	s_nop 0
	v_add_f32_e32 v26, 1.0, v26
	v_rcp_f32_e32 v26, v26
	s_nop 0
	v_mul_f32_e32 v25, v25, v26
	v_mul_f32_e32 v28, v24, v25
	v_pk_fma_f32 v[24:25], v[74:75], v[64:65], v[78:79] op_sel:[0,1,0]
	s_nop 0
	v_pk_fma_f32 v[24:25], v[30:31], v[64:65], v[24:25] op_sel_hi:[1,0,1]
	s_nop 0
	v_mul_f32_e32 v26, 0xbfb8aa3b, v25
	v_exp_f32_e32 v26, v26
	s_nop 0
	v_add_f32_e32 v26, 1.0, v26
	v_rcp_f32_e32 v26, v26
	s_nop 0
	v_mul_f32_e32 v25, v25, v26
	v_mul_f32_e32 v29, v24, v25
	v_mov_b32_e32 v24, v16
	v_mov_b32_e32 v25, v20
	v_pk_fma_f32 v[26:27], v[150:151], v[64:65], v[154:155] op_sel:[0,1,0]
	v_mov_b32_e32 v20, v17
	v_pk_fma_f32 v[24:25], v[24:25], v[64:65], v[26:27] op_sel_hi:[1,0,1]
	s_nop 0
	v_mul_f32_e32 v16, 0xbfb8aa3b, v25
	v_exp_f32_e32 v16, v16
	s_nop 0
	v_add_f32_e32 v16, 1.0, v16
	v_rcp_f32_e32 v16, v16
	s_nop 0
	v_mul_f32_e32 v16, v25, v16
	v_mul_f32_e32 v24, v24, v16
	v_pk_fma_f32 v[16:17], v[52:53], v[64:65], v[56:57] op_sel:[0,1,0]
	s_nop 0
	v_pk_fma_f32 v[16:17], v[20:21], v[64:65], v[16:17] op_sel_hi:[1,0,1]
	s_nop 0
	v_mul_f32_e32 v20, 0xbfb8aa3b, v17
	v_exp_f32_e32 v20, v20
	s_nop 0
	v_add_f32_e32 v20, 1.0, v20
	v_rcp_f32_e32 v20, v20
	s_nop 0
	v_mul_f32_e32 v17, v17, v20
	v_mul_f32_e32 v25, v16, v17
	v_mov_b32_e32 v16, v18
	v_mov_b32_e32 v17, v22
	v_pk_fma_f32 v[20:21], v[140:141], v[64:65], v[144:145] op_sel:[0,1,0]
	v_mov_b32_e32 v22, v19
	v_pk_fma_f32 v[16:17], v[16:17], v[64:65], v[20:21] op_sel_hi:[1,0,1]
	v_lshl_add_u64 v[20:21], v[32:33], 0, v[142:143]
	v_mul_f32_e32 v18, 0xbfb8aa3b, v17
	v_exp_f32_e32 v18, v18
	s_nop 0
	v_add_f32_e32 v18, 1.0, v18
	v_rcp_f32_e32 v18, v18
	s_nop 0
	v_mul_f32_e32 v17, v17, v18
	v_mul_f32_e32 v26, v16, v17
	v_pk_fma_f32 v[16:17], v[54:55], v[64:65], v[58:59] op_sel:[0,1,0]
	s_nop 0
	v_pk_fma_f32 v[16:17], v[22:23], v[64:65], v[16:17] op_sel_hi:[1,0,1]
	s_nop 0
	v_mul_f32_e32 v18, 0xbfb8aa3b, v17
	v_exp_f32_e32 v18, v18
	s_nop 0
	v_add_f32_e32 v18, 1.0, v18
	v_rcp_f32_e32 v18, v18
	s_nop 0
	v_mul_f32_e32 v17, v17, v18
	v_mul_f32_e32 v19, v16, v17
	v_cvt_pk_bf16_f32 v16, v34, v35
	v_cvt_pk_bf16_f32 v17, v28, v29
	v_cvt_pk_bf16_f32 v18, v24, v25
	v_cvt_pk_bf16_f32 v19, v26, v19
	global_store_dwordx4 v[20:21], v[16:19], off
	v_pk_fma_f32 v[20:21], v[186:187], v[66:67], v[188:189] op_sel:[0,1,0]
	s_nop 0
	v_mov_b32_e32 v18, v8
	v_mov_b32_e32 v19, v12
	v_pk_fma_f32 v[18:19], v[18:19], v[66:67], v[20:21] op_sel_hi:[1,0,1]
	v_mov_b32_e32 v12, v9
	v_mul_f32_e32 v8, 0xbfb8aa3b, v19
	v_exp_f32_e32 v8, v8
	v_add_u32_e32 v16, 0xb0, v200
	v_mad_i64_i32 v[16:17], s[46:47], v16, s83, v[184:185]
	v_add_f32_e32 v8, 1.0, v8
	v_rcp_f32_e32 v8, v8
	s_mov_b64 s[46:47], -1
	v_mul_f32_e32 v8, v19, v8
	v_mul_f32_e32 v18, v18, v8
	v_pk_fma_f32 v[8:9], v[72:73], v[66:67], v[76:77] op_sel:[0,1,0]
	s_nop 0
	v_pk_fma_f32 v[8:9], v[12:13], v[66:67], v[8:9] op_sel_hi:[1,0,1]
	s_nop 0
	v_mul_f32_e32 v12, 0xbfb8aa3b, v9
	v_exp_f32_e32 v12, v12
	s_nop 0
	v_add_f32_e32 v12, 1.0, v12
	v_rcp_f32_e32 v12, v12
	s_nop 0
	v_mul_f32_e32 v9, v9, v12
	v_mul_f32_e32 v19, v8, v9
	v_mov_b32_e32 v8, v10
	v_mov_b32_e32 v9, v14
	v_pk_fma_f32 v[12:13], v[148:149], v[66:67], v[152:153] op_sel:[0,1,0]
	v_mov_b32_e32 v14, v11
	v_pk_fma_f32 v[8:9], v[8:9], v[66:67], v[12:13] op_sel_hi:[1,0,1]
	s_nop 0
	v_mul_f32_e32 v10, 0xbfb8aa3b, v9
	v_exp_f32_e32 v10, v10
	s_nop 0
	v_add_f32_e32 v10, 1.0, v10
	v_rcp_f32_e32 v10, v10
	s_nop 0
	v_mul_f32_e32 v9, v9, v10
	v_mul_f32_e32 v12, v8, v9
	v_pk_fma_f32 v[8:9], v[74:75], v[66:67], v[78:79] op_sel:[0,1,0]
	s_nop 0
	v_pk_fma_f32 v[8:9], v[14:15], v[66:67], v[8:9] op_sel_hi:[1,0,1]
	s_nop 0
	v_mul_f32_e32 v10, 0xbfb8aa3b, v9
	v_exp_f32_e32 v10, v10
	s_nop 0
	v_add_f32_e32 v10, 1.0, v10
	v_rcp_f32_e32 v10, v10
	s_nop 0
	v_mul_f32_e32 v9, v9, v10
	v_mul_f32_e32 v13, v8, v9
	v_mov_b32_e32 v8, v0
	v_mov_b32_e32 v9, v4
	v_pk_fma_f32 v[10:11], v[150:151], v[66:67], v[154:155] op_sel:[0,1,0]
	v_mov_b32_e32 v4, v1
	v_pk_fma_f32 v[8:9], v[8:9], v[66:67], v[10:11] op_sel_hi:[1,0,1]
	s_nop 0
	v_mul_f32_e32 v0, 0xbfb8aa3b, v9
	v_exp_f32_e32 v0, v0
	s_nop 0
	v_add_f32_e32 v0, 1.0, v0
	v_rcp_f32_e32 v0, v0
	s_nop 0
	v_mul_f32_e32 v0, v9, v0
	v_mul_f32_e32 v8, v8, v0
	v_pk_fma_f32 v[0:1], v[52:53], v[66:67], v[56:57] op_sel:[0,1,0]
	s_nop 0
	v_pk_fma_f32 v[0:1], v[4:5], v[66:67], v[0:1] op_sel_hi:[1,0,1]
	s_nop 0
	v_mul_f32_e32 v4, 0xbfb8aa3b, v1
	v_exp_f32_e32 v4, v4
	s_nop 0
	v_add_f32_e32 v4, 1.0, v4
	v_rcp_f32_e32 v4, v4
	s_nop 0
	v_mul_f32_e32 v1, v1, v4
	v_mul_f32_e32 v9, v0, v1
	v_mov_b32_e32 v0, v2
	v_mov_b32_e32 v1, v6
	v_pk_fma_f32 v[4:5], v[140:141], v[66:67], v[144:145] op_sel:[0,1,0]
	v_mov_b32_e32 v6, v3
	v_pk_fma_f32 v[0:1], v[0:1], v[66:67], v[4:5] op_sel_hi:[1,0,1]
	v_lshl_add_u64 v[4:5], v[16:17], 0, v[142:143]
	v_mul_f32_e32 v2, 0xbfb8aa3b, v1
	v_exp_f32_e32 v2, v2
	s_nop 0
	v_add_f32_e32 v2, 1.0, v2
	v_rcp_f32_e32 v2, v2
	s_nop 0
	v_mul_f32_e32 v1, v1, v2
	v_mul_f32_e32 v10, v0, v1
	v_pk_fma_f32 v[0:1], v[54:55], v[66:67], v[58:59] op_sel:[0,1,0]
	s_nop 0
	v_pk_fma_f32 v[0:1], v[6:7], v[66:67], v[0:1] op_sel_hi:[1,0,1]
	s_nop 0
	v_mul_f32_e32 v2, 0xbfb8aa3b, v1
	v_exp_f32_e32 v2, v2
	s_nop 0
	v_add_f32_e32 v2, 1.0, v2
	v_rcp_f32_e32 v2, v2
	s_nop 0
	v_mul_f32_e32 v1, v1, v2
	v_mul_f32_e32 v3, v0, v1
	v_cvt_pk_bf16_f32 v0, v18, v19
	v_cvt_pk_bf16_f32 v1, v12, v13
	v_cvt_pk_bf16_f32 v2, v8, v9
	v_cvt_pk_bf16_f32 v3, v10, v3
	global_store_dwordx4 v[4:5], v[0:3], off
	s_mov_b32 s99, 1
	s_cbranch_vccnz .LBB0_742
	s_andn2_b64 vcc, exec, s[0:1]
	s_cbranch_vccnz .LBB0_741
	s_barrier
	s_branch .LBB0_741

.LBB0_813:
	s_add_u32 s0, s58, 0x3100000
	s_addc_u32 s1, s59, 0
	v_writelane_b32 v255, s0, 44
	s_nop 1
	v_writelane_b32 v255, s1, 45
	s_add_u32 s0, s58, 0x1f200000
	s_addc_u32 s1, s59, 0
	v_writelane_b32 v255, s0, 46
	s_add_u32 s76, s58, 0x3c00000
	s_addc_u32 s77, s59, 0
	v_writelane_b32 v255, s1, 47
	s_nop 0
	v_readlane_b32 s0, v255, 32
	v_readlane_b32 s1, v255, 33
	s_and_b64 vcc, exec, s[0:1]
	s_cbranch_vccnz .LBB0_853
	v_ashrrev_i32_e32 v2, 31, v0
	v_lshrrev_b32_e32 v2, 26, v2
	v_add_u32_e32 v2, v0, v2
	v_ashrrev_i32_e32 v137, 6, v2
	v_bfe_i32 v2, v0, 27, 1
	v_lshlrev_b32_e32 v1, 4, v0
	v_lshrrev_b32_e32 v2, 22, v2
	v_add_u32_e32 v2, v1, v2
	v_and_b32_e32 v2, 0xfffffc00, v2
	v_sub_u32_e32 v2, v1, v2
	v_lshrrev_b32_e32 v3, 4, v2
	v_bitop3_b32 v2, v3, v2, 32 bitop3:0x6c
	v_ashrrev_i32_e32 v4, 31, v2
	v_lshrrev_b32_e32 v4, 26, v4
	v_lshlrev_b32_e32 v3, 3, v137
	v_add_u32_e32 v4, v2, v4
	v_and_b32_e32 v3, -16, v3
	v_ashrrev_i32_e32 v149, 6, v4
	v_and_b32_e32 v4, 0xc0, v4
	v_add_u32_e32 v3, v149, v3
	v_lshlrev_b32_e32 v5, 5, v137
	v_sub_u32_e32 v2, v2, v4
	v_mov_b32_e32 v4, 1
	v_and_b32_e32 v147, 32, v5
	v_ashrrev_i16_sdwa v2, v4, sext(v2) dst_sel:DWORD dst_unused:UNUSED_PAD src0_sel:DWORD src1_sel:BYTE_0
	v_lshlrev_b32_e32 v5, 1, v3
	v_lshrrev_b32_e32 v6, 2, v3
	v_and_b32_e32 v7, 3, v149
	s_mov_b32 s4, 0xffffe0
	v_bfe_i32 v161, v2, 0, 16
	v_and_b32_e32 v5, 24, v5
	v_and_b32_e32 v6, 4, v6
	v_and_or_b32 v7, v3, s4, v7
	s_movk_i32 s9, 0xb00
	v_add_u32_e32 v2, v147, v161
	v_or3_b32 v5, v7, v6, v5
	v_mul_lo_u32 v3, v3, s9
	v_add_lshl_u32 v128, v2, v3, 1
	v_mul_u32_u24_e32 v3, 0xb00, v5
	v_add_u32_e32 v1, 0x2000, v1
	v_add_lshl_u32 v130, v3, v2, 1
	v_ashrrev_i32_e32 v2, 31, v1
	v_lshrrev_b32_e32 v2, 22, v2
	v_add_u32_e32 v2, v1, v2
	v_ashrrev_i32_e32 v163, 10, v2
	v_mul_i32_i24_e32 v2, 0x400, v163
	v_sub_u32_e32 v1, v1, v2
	v_lshrrev_b32_e32 v2, 4, v1
	v_bitop3_b32 v1, v2, v1, 32 bitop3:0x6c
	v_ashrrev_i32_e32 v3, 31, v1
	v_lshrrev_b32_e32 v3, 26, v3
	v_lshlrev_b32_e32 v2, 3, v163
	v_add_u32_e32 v3, v1, v3
	v_and_b32_e32 v2, -16, v2
	v_ashrrev_i32_e32 v165, 6, v3
	v_and_b32_e32 v3, 0xc0, v3
	v_add_u32_e32 v2, v165, v2
	v_lshlrev_b32_e32 v5, 5, v163
	v_sub_u32_e32 v1, v1, v3
	v_and_b32_e32 v167, 32, v5
	v_ashrrev_i16_sdwa v1, v4, sext(v1) dst_sel:DWORD dst_unused:UNUSED_PAD src0_sel:DWORD src1_sel:BYTE_0
	v_lshlrev_b32_e32 v3, 1, v2
	v_lshrrev_b32_e32 v4, 2, v2
	v_and_b32_e32 v5, 3, v165
	v_bfe_i32 v169, v1, 0, 16
	v_and_b32_e32 v3, 24, v3
	v_and_b32_e32 v4, 4, v4
	v_and_or_b32 v5, v2, s4, v5
	v_add_u32_e32 v1, v167, v169
	v_or3_b32 v3, v5, v4, v3
	v_mul_lo_u32 v2, v2, s9
	v_bfe_u32 v151, v0, 4, 2
	v_add_lshl_u32 v132, v1, v2, 1
	v_mul_u32_u24_e32 v2, 0xb00, v3
	v_and_b32_e32 v153, 15, v0
	v_add_lshl_u32 v134, v2, v1, 1
	v_mov_b32_e32 v1, v151
	v_mov_b32_e32 v0, v153
	s_ashr_i32 s1, s8, 6
	v_lshlrev_b32_e32 v2, 3, v1
	v_mbcnt_lo_u32_b32 v1, -1, 0
	v_mbcnt_hi_u32_b32 v1, -1, v1
	v_and_b32_e32 v5, 64, v1
	v_xor_b32_e32 v4, 16, v1
	v_add_u32_e32 v5, 64, v5
	v_cmp_lt_i32_e32 vcc, v4, v5
	s_ashr_i32 s10, s8, 8
	s_and_b32 s0, s1, 3
	v_cndmask_b32_e32 v4, v1, v4, vcc
	s_lshl_b32 s7, s1, 10
	s_lshl_b32 s13, s10, 6
	s_lshl_b32 s1, s80, 8
	v_lshlrev_b32_e32 v155, 2, v4
	v_xor_b32_e32 v4, 32, v1
	s_add_i32 s1, s1, s13
	v_cmp_lt_i32_e32 vcc, v4, v5
	v_add_u32_e32 v0, s1, v0
	v_ashrrev_i32_e32 v3, 31, v2
	v_cndmask_b32_e32 v1, v1, v4, vcc
	v_lshlrev_b32_e32 v157, 2, v1
	v_ashrrev_i32_e32 v1, 31, v0
	v_lshl_add_u64 v[4:5], v[2:3], 2, s[62:63]
	v_lshlrev_b64 v[6:7], 7, v[0:1]
	v_lshl_add_u64 v[10:11], v[4:5], 0, v[6:7]
	v_mov_b32_e32 v184, v0
	v_ashrrev_i32_e32 v185, 31, v184
	v_lshlrev_b64 v[184:185], 7, v[184:185]
	v_lshl_add_u64 v[184:185], v[4:5], 0, v[184:185]
	global_load_dwordx4 v[188:191], v[184:185], off offset:16
	global_load_dwordx4 v[192:195], v[184:185], off
	v_add_u32_e32 v184, 0x10, v0
	v_ashrrev_i32_e32 v185, 31, v184
	v_lshlrev_b64 v[184:185], 7, v[184:185]
	v_lshl_add_u64 v[184:185], v[4:5], 0, v[184:185]
	global_load_dwordx4 v[196:199], v[184:185], off offset:16
	global_load_dwordx4 v[200:203], v[184:185], off
	v_add_u32_e32 v184, 0x20, v0
	v_ashrrev_i32_e32 v185, 31, v184
	v_lshlrev_b64 v[184:185], 7, v[184:185]
	v_lshl_add_u64 v[184:185], v[4:5], 0, v[184:185]
	global_load_dwordx4 v[204:207], v[184:185], off offset:16
	global_load_dwordx4 v[208:211], v[184:185], off
	v_add_u32_e32 v184, 0x30, v0
	v_ashrrev_i32_e32 v185, 31, v184
	v_lshlrev_b64 v[184:185], 7, v[184:185]
	v_lshl_add_u64 v[184:185], v[4:5], 0, v[184:185]
	global_load_dwordx4 v[212:215], v[184:185], off offset:16
	global_load_dwordx4 v[216:219], v[184:185], off
	v_add_u32_e32 v184, 0x80, v0
	v_ashrrev_i32_e32 v185, 31, v184
	v_lshlrev_b64 v[184:185], 7, v[184:185]
	v_lshl_add_u64 v[184:185], v[4:5], 0, v[184:185]
	global_load_dwordx4 v[220:223], v[184:185], off offset:16
	global_load_dwordx4 v[224:227], v[184:185], off
	v_add_u32_e32 v184, 0x90, v0
	v_ashrrev_i32_e32 v185, 31, v184
	v_lshlrev_b64 v[184:185], 7, v[184:185]
	v_lshl_add_u64 v[184:185], v[4:5], 0, v[184:185]
	global_load_dwordx4 v[228:231], v[184:185], off offset:16
	global_load_dwordx4 v[232:235], v[184:185], off
	v_add_u32_e32 v184, 0xa0, v0
	v_ashrrev_i32_e32 v185, 31, v184
	v_lshlrev_b64 v[184:185], 7, v[184:185]
	v_lshl_add_u64 v[184:185], v[4:5], 0, v[184:185]
	global_load_dwordx4 v[236:239], v[184:185], off offset:16
	global_load_dwordx4 v[240:243], v[184:185], off
	v_add_u32_e32 v184, 0xb0, v0
	v_ashrrev_i32_e32 v185, 31, v184
	v_lshlrev_b64 v[184:185], 7, v[184:185]
	v_lshl_add_u64 v[184:185], v[4:5], 0, v[184:185]
	global_load_dwordx4 v[244:247], v[184:185], off offset:16
	global_load_dwordx4 v[248:251], v[184:185], off
	s_waitcnt vmcnt(0)
	v_mov_b32_e32 v6, v188
	v_mov_b32_e32 v7, v189
	v_mov_b32_e32 v8, v190
	v_mov_b32_e32 v9, v191
	s_nop 0
	v_mov_b32_e32 v10, v192
	v_mov_b32_e32 v11, v193
	v_mov_b32_e32 v12, v194
	v_mov_b32_e32 v13, v195
	v_add_u32_e32 v56, 0x90, v0
	v_ashrrev_i32_e32 v57, 31, v56
	v_add_u32_e32 v58, 0xa0, v0
	v_ashrrev_i32_e32 v59, 31, v58
	v_add_u32_e32 v60, 0xb0, v0
	v_ashrrev_i32_e32 v61, 31, v60
	s_lshl_b32 s66, s0, 5
	s_lshl_b32 s4, s79, 8
	s_or_b32 s4, s4, s66
	v_add_u32_e32 v2, s4, v2
	v_ashrrev_i32_e32 v3, 31, v2
	s_cmp_gt_i32 s80, 63
	v_readlane_b32 s14, v255, 44
	v_readlane_b32 s34, v255, 46
	v_readlane_b32 s15, v255, 45
	v_readlane_b32 s35, v255, 47
	s_cselect_b32 s5, s34, s14
	s_mul_i32 s14, s79, 0x160000
	s_cselect_b32 s4, s35, s15
	s_mul_hi_i32 s12, s79, 0x160000
	s_add_u32 s60, s5, s14
	s_addc_u32 s61, s4, s12
	s_add_i32 s67, s7, 0
	s_add_i32 m0, s67, 0x10000
	s_mul_i32 s11, s80, 0x160000
	s_mul_hi_i32 s6, s80, 0x160000
	v_mov_b32_e32 v136, 0
	v_mov_b32_e32 v131, v136
	v_mov_b32_e32 v135, v136
	v_mov_b32_e32 v129, v136
	v_mov_b32_e32 v133, v136
	s_mov_b32 s1, 0
	v_mov_b32_e32 v15, v6
	v_mov_b32_e32 v14, v10
	v_mov_b32_e32 v16, v12
	v_mov_b32_e32 v17, v8
	v_pk_add_f32 v[14:15], v[14:15], v[16:17]
	v_add_f32_e32 v6, v11, v13
	v_add_f32_e32 v8, v7, v9
	v_mov_b32_e32 v7, v14
	v_mov_b32_e32 v9, v15
	v_pk_add_f32 v[6:7], v[6:7], v[8:9]
	ds_bpermute_b32 v9, v155, v7
	ds_bpermute_b32 v8, v155, v6
	s_waitcnt lgkmcnt(0)
	v_pk_add_f32 v[48:49], v[6:7], v[8:9]
	v_add_u32_e32 v6, 16, v0
	v_ashrrev_i32_e32 v7, 31, v6
	v_lshlrev_b64 v[8:9], 7, v[6:7]
	v_lshl_add_u64 v[12:13], v[4:5], 0, v[8:9]
	v_mov_b32_e32 v8, v196
	v_mov_b32_e32 v9, v197
	v_mov_b32_e32 v10, v198
	v_mov_b32_e32 v11, v199
	s_nop 0
	v_mov_b32_e32 v12, v200
	v_mov_b32_e32 v13, v201
	v_mov_b32_e32 v14, v202
	v_mov_b32_e32 v15, v203
	ds_bpermute_b32 v51, v157, v49
	ds_bpermute_b32 v50, v157, v48
	v_mov_b32_e32 v17, v8
	v_mov_b32_e32 v16, v12
	v_mov_b32_e32 v18, v14
	v_mov_b32_e32 v19, v10
	v_pk_add_f32 v[16:17], v[16:17], v[18:19]
	v_add_f32_e32 v8, v13, v15
	v_add_f32_e32 v10, v9, v11
	v_mov_b32_e32 v9, v16
	v_mov_b32_e32 v11, v17
	v_pk_add_f32 v[8:9], v[8:9], v[10:11]
	ds_bpermute_b32 v11, v155, v9
	ds_bpermute_b32 v10, v155, v8
	s_waitcnt lgkmcnt(0)
	v_pk_add_f32 v[52:53], v[8:9], v[10:11]
	v_add_u32_e32 v8, 32, v0
	v_ashrrev_i32_e32 v9, 31, v8
	v_lshlrev_b64 v[10:11], 7, v[8:9]
	v_lshl_add_u64 v[14:15], v[4:5], 0, v[10:11]
	v_mov_b32_e32 v10, v204
	v_mov_b32_e32 v11, v205
	v_mov_b32_e32 v12, v206
	v_mov_b32_e32 v13, v207
	s_nop 0
	v_mov_b32_e32 v14, v208
	v_mov_b32_e32 v15, v209
	v_mov_b32_e32 v16, v210
	v_mov_b32_e32 v17, v211
	ds_bpermute_b32 v55, v157, v53
	ds_bpermute_b32 v54, v157, v52
	v_mov_b32_e32 v19, v10
	v_mov_b32_e32 v18, v14
	v_mov_b32_e32 v20, v16
	v_mov_b32_e32 v21, v12
	v_pk_add_f32 v[18:19], v[18:19], v[20:21]
	v_add_f32_e32 v10, v15, v17
	v_add_f32_e32 v12, v11, v13
	v_mov_b32_e32 v11, v18
	v_mov_b32_e32 v13, v19
	v_pk_add_f32 v[10:11], v[10:11], v[12:13]
	ds_bpermute_b32 v13, v155, v11
	ds_bpermute_b32 v12, v155, v10
	s_waitcnt lgkmcnt(0)
	v_pk_add_f32 v[64:65], v[10:11], v[12:13]
	v_add_u32_e32 v10, 48, v0
	v_ashrrev_i32_e32 v11, 31, v10
	v_lshlrev_b64 v[12:13], 7, v[10:11]
	v_lshl_add_u64 v[16:17], v[4:5], 0, v[12:13]
	v_mov_b32_e32 v12, v212
	v_mov_b32_e32 v13, v213
	v_mov_b32_e32 v14, v214
	v_mov_b32_e32 v15, v215
	s_nop 0
	v_mov_b32_e32 v16, v216
	v_mov_b32_e32 v17, v217
	v_mov_b32_e32 v18, v218
	v_mov_b32_e32 v19, v219
	ds_bpermute_b32 v67, v157, v65
	ds_bpermute_b32 v66, v157, v64
	v_mov_b32_e32 v21, v12
	v_mov_b32_e32 v20, v16
	v_mov_b32_e32 v22, v18
	v_mov_b32_e32 v23, v14
	v_pk_add_f32 v[20:21], v[20:21], v[22:23]
	v_add_f32_e32 v12, v17, v19
	v_add_f32_e32 v14, v13, v15
	v_mov_b32_e32 v13, v20
	v_mov_b32_e32 v15, v21
	v_pk_add_f32 v[12:13], v[12:13], v[14:15]
	ds_bpermute_b32 v15, v155, v13
	ds_bpermute_b32 v14, v155, v12
	s_waitcnt lgkmcnt(0)
	v_pk_add_f32 v[68:69], v[12:13], v[14:15]
	v_add_u32_e32 v12, 0x80, v0
	v_ashrrev_i32_e32 v13, 31, v12
	v_lshlrev_b64 v[14:15], 7, v[12:13]
	v_lshl_add_u64 v[18:19], v[4:5], 0, v[14:15]
	v_mov_b32_e32 v14, v220
	v_mov_b32_e32 v15, v221
	v_mov_b32_e32 v16, v222
	v_mov_b32_e32 v17, v223
	s_nop 0
	v_mov_b32_e32 v18, v224
	v_mov_b32_e32 v19, v225
	v_mov_b32_e32 v20, v226
	v_mov_b32_e32 v21, v227
	v_lshlrev_b64 v[0:1], 11, v[0:1]
	v_lshl_add_u64 v[0:1], s[44:45], 0, v[0:1]
	ds_bpermute_b32 v71, v157, v69
	ds_bpermute_b32 v70, v157, v68
	v_mov_b32_e32 v23, v14
	v_mov_b32_e32 v22, v18
	v_mov_b32_e32 v24, v20
	v_mov_b32_e32 v25, v16
	v_pk_add_f32 v[22:23], v[22:23], v[24:25]
	v_add_f32_e32 v14, v19, v21
	v_add_f32_e32 v16, v15, v17
	v_mov_b32_e32 v15, v22
	v_mov_b32_e32 v17, v23
	v_pk_add_f32 v[14:15], v[14:15], v[16:17]
	ds_bpermute_b32 v17, v155, v15
	ds_bpermute_b32 v16, v155, v14
	s_waitcnt lgkmcnt(0)
	v_pk_add_f32 v[112:113], v[14:15], v[16:17]
	v_lshlrev_b64 v[14:15], 7, v[56:57]
	v_lshl_add_u64 v[18:19], v[4:5], 0, v[14:15]
	v_mov_b32_e32 v14, v228
	v_mov_b32_e32 v15, v229
	v_mov_b32_e32 v16, v230
	v_mov_b32_e32 v17, v231
	s_nop 0
	v_mov_b32_e32 v18, v232
	v_mov_b32_e32 v19, v233
	v_mov_b32_e32 v20, v234
	v_mov_b32_e32 v21, v235
	ds_bpermute_b32 v115, v157, v113
	ds_bpermute_b32 v114, v157, v112
	v_mov_b32_e32 v23, v14
	v_mov_b32_e32 v22, v18
	v_mov_b32_e32 v24, v20
	v_mov_b32_e32 v25, v16
	v_pk_add_f32 v[22:23], v[22:23], v[24:25]
	v_add_f32_e32 v14, v19, v21
	v_add_f32_e32 v16, v15, v17
	v_mov_b32_e32 v15, v22
	v_mov_b32_e32 v17, v23
	v_pk_add_f32 v[14:15], v[14:15], v[16:17]
	ds_bpermute_b32 v17, v155, v15
	ds_bpermute_b32 v16, v155, v14
	s_waitcnt lgkmcnt(0)
	v_pk_add_f32 v[116:117], v[14:15], v[16:17]
	v_lshlrev_b64 v[14:15], 7, v[58:59]
	v_lshl_add_u64 v[18:19], v[4:5], 0, v[14:15]
	v_mov_b32_e32 v14, v236
	v_mov_b32_e32 v15, v237
	v_mov_b32_e32 v16, v238
	v_mov_b32_e32 v17, v239
	s_nop 0
	v_mov_b32_e32 v18, v240
	v_mov_b32_e32 v19, v241
	v_mov_b32_e32 v20, v242
	v_mov_b32_e32 v21, v243
	ds_bpermute_b32 v119, v157, v117
	ds_bpermute_b32 v118, v157, v116
	v_mov_b32_e32 v23, v14
	v_mov_b32_e32 v22, v18
	v_mov_b32_e32 v24, v20
	v_mov_b32_e32 v25, v16
	v_pk_add_f32 v[22:23], v[22:23], v[24:25]
	v_add_f32_e32 v14, v19, v21
	v_add_f32_e32 v16, v15, v17
	v_mov_b32_e32 v15, v22
	v_mov_b32_e32 v17, v23
	v_pk_add_f32 v[14:15], v[14:15], v[16:17]
	ds_bpermute_b32 v17, v155, v15
	ds_bpermute_b32 v16, v155, v14
	s_waitcnt lgkmcnt(0)
	v_pk_add_f32 v[120:121], v[14:15], v[16:17]
	v_lshlrev_b64 v[14:15], 7, v[60:61]
	v_lshl_add_u64 v[4:5], v[4:5], 0, v[14:15]
	v_mov_b32_e32 v14, v244
	v_mov_b32_e32 v15, v245
	v_mov_b32_e32 v16, v246
	v_mov_b32_e32 v17, v247
	v_mov_b32_e32 v18, v248
	v_mov_b32_e32 v19, v249
	v_mov_b32_e32 v20, v250
	v_mov_b32_e32 v21, v251
	ds_bpermute_b32 v123, v157, v121
	ds_bpermute_b32 v122, v157, v120
	v_mov_b32_e32 v5, v14
	v_mov_b32_e32 v4, v18
	v_mov_b32_e32 v22, v20
	v_mov_b32_e32 v23, v16
	v_pk_add_f32 v[4:5], v[4:5], v[22:23]
	v_add_f32_e32 v14, v19, v21
	v_add_f32_e32 v16, v15, v17
	v_mov_b32_e32 v15, v4
	v_mov_b32_e32 v17, v5
	v_pk_add_f32 v[4:5], v[14:15], v[16:17]
	ds_bpermute_b32 v15, v155, v5
	ds_bpermute_b32 v14, v155, v4
	s_waitcnt lgkmcnt(0)
	v_pk_add_f32 v[124:125], v[4:5], v[14:15]
	v_lshlrev_b64 v[4:5], 2, v[2:3]
	v_lshlrev_b64 v[2:3], 1, v[2:3]
	v_lshl_add_u64 v[74:75], v[0:1], 0, v[2:3]
	v_lshlrev_b64 v[0:1], 11, v[6:7]
	v_lshl_add_u64 v[0:1], s[44:45], 0, v[0:1]
	v_lshl_add_u64 v[76:77], v[0:1], 0, v[2:3]
	v_lshlrev_b64 v[0:1], 11, v[8:9]
	v_lshl_add_u64 v[0:1], s[44:45], 0, v[0:1]
	v_lshl_add_u64 v[78:79], v[0:1], 0, v[2:3]
	v_lshlrev_b64 v[0:1], 11, v[10:11]
	v_lshl_add_u64 v[0:1], s[44:45], 0, v[0:1]
	v_lshl_add_u64 v[80:81], v[0:1], 0, v[2:3]
	v_lshlrev_b64 v[0:1], 11, v[12:13]
	v_lshl_add_u64 v[0:1], s[44:45], 0, v[0:1]
	v_lshl_add_u64 v[138:139], v[0:1], 0, v[2:3]
	v_lshlrev_b64 v[0:1], 11, v[56:57]
	v_lshl_add_u64 v[0:1], s[44:45], 0, v[0:1]
	v_lshl_add_u64 v[56:57], v[0:1], 0, v[2:3]
	v_lshlrev_b64 v[0:1], 11, v[58:59]
	v_lshl_add_u64 v[0:1], s[44:45], 0, v[0:1]
	v_lshl_add_u64 v[58:59], v[0:1], 0, v[2:3]
	v_lshlrev_b64 v[0:1], 11, v[60:61]
	v_lshl_add_u64 v[0:1], s[44:45], 0, v[0:1]
	v_lshl_add_u64 v[62:63], s[18:19], 0, v[4:5]
	v_lshl_add_u64 v[72:73], s[20:21], 0, v[4:5]
	v_lshl_add_u64 v[140:141], v[0:1], 0, v[2:3]
	global_load_dwordx4 v[36:39], v[62:63], off offset:16
	global_load_dwordx4 v[44:47], v[62:63], off
	global_load_dwordx4 v[32:35], v[72:73], off offset:16
	global_load_dwordx4 v[40:43], v[72:73], off
	global_load_dwordx4 v[28:31], v[74:75], off
	global_load_dwordx4 v[24:27], v[76:77], off
	global_load_dwordx4 v[20:23], v[78:79], off
	global_load_dwordx4 v[16:19], v[80:81], off
	global_load_dwordx4 v[12:15], v[138:139], off
	global_load_dwordx4 v[8:11], v[56:57], off
	global_load_dwordx4 v[4:7], v[58:59], off
	global_load_dwordx4 v[0:3], v[140:141], off
	global_load_dwordx4 v[100:103], v[62:63], off offset:528
	global_load_dwordx4 v[108:111], v[62:63], off offset:512
	global_load_dwordx4 v[96:99], v[72:73], off offset:528
	global_load_dwordx4 v[104:107], v[72:73], off offset:512
	global_load_dwordx4 v[92:95], v[74:75], off offset:256
	global_load_dwordx4 v[88:91], v[76:77], off offset:256
	global_load_dwordx4 v[84:87], v[78:79], off offset:256
	s_nop 0
	global_load_dwordx4 v[80:83], v[80:81], off offset:256
	s_nop 0
	global_load_dwordx4 v[76:79], v[138:139], off offset:256
	global_load_dwordx4 v[72:75], v[56:57], off offset:256
	global_load_dwordx4 v[60:63], v[58:59], off offset:256
	s_nop 0
	global_load_dwordx4 v[56:59], v[140:141], off offset:256
	ds_bpermute_b32 v127, v157, v125
	global_load_lds_dwordx4 v130, s[60:61]
	s_add_i32 m0, s67, 0x12000
	s_add_u32 s4, s60, 0xb0000
	global_load_lds_dwordx4 v134, s[60:61]
	s_addc_u32 s5, s61, 0
	s_add_i32 m0, s67, 0x14000
	ds_bpermute_b32 v126, v157, v124
	global_load_lds_dwordx4 v130, s[4:5]
	s_add_i32 m0, s67, 0x16000
	s_add_u32 s40, s42, s11
	s_addc_u32 s41, s43, s6
	s_add_i32 s68, s67, 0x2000
	global_load_lds_dwordx4 v134, s[4:5]
	s_mov_b32 m0, s67
	s_add_u32 s4, s40, 0xb0000
	global_load_lds_dwordx4 v128, s[40:41]
	s_mov_b32 m0, s68
	s_addc_u32 s5, s41, 0
	s_add_i32 s69, s67, 0x4000
	global_load_lds_dwordx4 v132, s[40:41]
	s_mov_b32 m0, s69
	s_add_i32 s82, s67, 0x6000
	global_load_lds_dwordx4 v128, s[4:5]
	s_mov_b32 m0, s82
	s_cmp_eq_u32 s10, 1
	global_load_lds_dwordx4 v132, s[4:5]
	v_lshl_add_u64 v[138:139], s[60:61], 0, v[130:131]
	v_lshl_add_u64 v[140:141], s[60:61], 0, v[134:135]
	v_lshl_add_u64 v[142:143], s[40:41], 0, v[128:129]
	v_lshl_add_u64 v[144:145], s[40:41], 0, v[132:133]
	s_cselect_b64 s[4:5], -1, 0
	s_cmp_lg_u32 s10, 1
	s_cbranch_scc1 .LBB0_816
	s_barrier

.LBB0_1060:
	s_add_u32 s6, s58, 0x3734000
	v_and_b32_e32 v192, 15, v8
	v_and_b32_e32 v15, 48, v8
	v_lshlrev_b32_e32 v16, 2, v8
	s_addc_u32 s7, s59, 0
	s_and_b32 s34, s9, 3
	s_lshl_b32 s10, s8, 13
	v_lshl_or_b32 v15, v192, 6, v15
	v_and_b32_e32 v17, 32, v16
	s_lshl_b32 s70, s8, 6
	v_bitop3_b32 v18, v15, s10, v17 bitop3:0xde
	s_lshl_b32 s71, s34, 5
	s_lshl_b32 s10, s34, 12
	v_bitop3_b32 v194, v15, s10, v17 bitop3:0xde
	s_add_u32 s10, s58, 0x372a000
	s_mov_b64 s[12:13], 0x80
	s_addc_u32 s11, s59, 0
	s_add_i32 m0, s41, 0x18000
	v_lshl_add_u64 v[6:7], v[6:7], 0, s[12:13]
	s_waitcnt vmcnt(2)
	s_barrier
	global_load_lds_dwordx4 v[6:7], off
	v_lshl_add_u64 v[4:5], v[4:5], 0, s[12:13]
	s_add_i32 m0, s41, 0x1a000
	s_add_i32 s72, s41, 0x8000
	s_add_i32 s73, s41, 0xa000
	global_load_lds_dwordx4 v[4:5], off
	v_lshl_add_u64 v[0:1], v[0:1], 0, s[12:13]
	s_mov_b32 m0, s72
	s_add_u32 s14, s94, 0x40080
	global_load_lds_dwordx4 v[0:1], off
	v_lshl_add_u64 v[0:1], v[2:3], 0, s[12:13]
	s_mov_b32 m0, s73
	s_addc_u32 s15, s95, 0
	global_load_lds_dwordx4 v[0:1], off
	s_add_i32 m0, s41, 0x1c000
	v_lshl_add_u64 v[0:1], s[14:15], 0, v[178:179]
	global_load_lds_dwordx4 v[0:1], off
	v_lshl_add_u64 v[0:1], s[14:15], 0, v[182:183]
	s_add_i32 m0, s41, 0x1e000
	s_lshl_b32 s80, s9, 9
	global_load_lds_dwordx4 v[0:1], off
	v_and_b32_e32 v0, 0x80, v16
	v_and_b32_e32 v1, 31, v8
	v_or3_b32 v195, v1, v0, s71
	v_lshlrev_b32_e32 v0, 14, v9
	v_and_b32_e32 v0, 0xffff8000, v0
	v_lshl_add_u32 v0, v10, 11, v0
	v_and_b32_e32 v1, 1, v9
	v_lshl_or_b32 v0, v1, 6, v0
	v_lshl_add_u32 v184, v11, 1, v0
	v_lshlrev_b32_e32 v0, 14, v12
	s_cmpk_lt_u32 s0, 0x100
	v_and_b32_e32 v0, 0xffff8000, v0
	s_waitcnt vmcnt(6)
	s_cselect_b64 s[14:15], -1, 0
	s_lshl_b32 s0, s8, 11
	s_lshl_b32 s8, s34, 9
	v_lshl_add_u32 v0, v13, 11, v0
	v_and_b32_e32 v1, 1, v12
	s_or_b32 s79, s0, s8
	v_lshl_or_b32 v0, v1, 6, v0
	v_bfe_u32 v193, v8, 4, 2
	s_add_i32 s79, s79, 0x22400
	v_mov_b32_e32 v185, v179
	v_lshl_add_u32 v186, v14, 1, v0
	v_mov_b32_e32 v187, v179
	v_mov_b64_e32 v[188:189], 0xa00
	v_mov_b64_e32 v[190:191], 0x9ff
	s_add_i32 s78, s80, 0x22500
	s_add_i32 s81, 0, 0x10000
	s_add_i32 s84, 0, 0x14000
	v_add_u32_e32 v196, 0, v18
	s_mov_b32 s34, 0x3e38aa3b
	v_mov_b32_e32 v197, 0x20400
	s_mov_b32 s85, 0
	s_barrier
	s_mov_b32 s99, 0
	s_branch .LBB0_1063

.LBB0_1066:
	v_add_u32_e32 v56, s81, v194
	v_add_u32_e32 v72, s84, v194
	ds_read_b128 v[40:43], v56
	ds_read_b128 v[44:47], v56 offset:1024
	ds_read_b128 v[48:51], v56 offset:2048
	ds_read_b128 v[56:59], v56 offset:3072
	ds_read_b128 v[60:63], v72
	ds_read_b128 v[64:67], v72 offset:1024
	ds_read_b128 v[68:71], v72 offset:2048
	ds_read_b128 v[72:75], v72 offset:3072
	s_add_u32 s96, s46, 0xfffc0080
	s_addc_u32 s97, s47, -1
	s_and_b64 s[86:87], s[94:95], exec
	s_cselect_b32 s97, s0, s97
	s_cselect_b32 s96, s37, s96
	s_cselect_b32 s95, s61, s75
	s_cselect_b32 s94, s66, s67
	v_lshl_add_u64 v[210:211], s[46:47], 0, v[184:185]
	s_add_i32 m0, s41, 0xc000
	ds_read_b128 v[100:103], v196
	ds_read_b128 v[136:139], v196 offset:1024
	ds_read_b128 v[172:175], v196 offset:2048
	ds_read_b128 v[198:201], v196 offset:3072
	ds_read_b128 v[202:205], v196 offset:4096
	ds_read_b128 v[206:209], v196 offset:5120
	ds_read_b128 v[212:215], v196 offset:6144
	ds_read_b128 v[216:219], v196 offset:7168
	global_load_lds_dwordx4 v[210:211], off
	v_lshl_add_u64 v[210:211], s[46:47], 0, v[186:187]
	s_add_i32 m0, s41, 0xe000
	s_nop 0
	global_load_lds_dwordx4 v[210:211], off
	s_cmp_lg_u32 s99, 0
	s_cbranch_scc1 .Lrlx10a
	s_waitcnt vmcnt(8)
.Lrlx10a_done:
	s_waitcnt lgkmcnt(0)
	s_barrier
	s_setprio 1
	s_waitcnt lgkmcnt(0)
	v_mfma_f32_16x16x32_f16 v[168:171], v[40:43], v[100:103], v[168:171]
	v_mfma_f32_16x16x32_f16 v[164:167], v[48:51], v[100:103], v[164:167]
	v_mfma_f32_16x16x32_f16 v[152:155], v[40:43], v[172:175], v[152:155]
	v_mfma_f32_16x16x32_f16 v[148:151], v[48:51], v[172:175], v[148:151]
	v_mfma_f32_16x16x32_f16 v[132:135], v[40:43], v[202:205], v[132:135]
	v_mfma_f32_16x16x32_f16 v[128:131], v[48:51], v[202:205], v[128:131]
	v_mfma_f32_16x16x32_f16 v[116:119], v[40:43], v[212:215], v[116:119]
	v_mfma_f32_16x16x32_f16 v[112:115], v[48:51], v[212:215], v[112:115]
	v_mfma_f32_16x16x32_f16 v[168:171], v[44:47], v[136:139], v[168:171]
	v_mfma_f32_16x16x32_f16 v[164:167], v[56:59], v[136:139], v[164:167]
	v_mfma_f32_16x16x32_f16 v[152:155], v[44:47], v[198:201], v[152:155]
	v_mfma_f32_16x16x32_f16 v[148:151], v[56:59], v[198:201], v[148:151]
	v_mfma_f32_16x16x32_f16 v[132:135], v[44:47], v[206:209], v[132:135]
	v_mfma_f32_16x16x32_f16 v[128:131], v[56:59], v[206:209], v[128:131]
	v_mfma_f32_16x16x32_f16 v[116:119], v[44:47], v[216:219], v[116:119]
	v_mfma_f32_16x16x32_f16 v[112:115], v[56:59], v[216:219], v[112:115]
	s_setprio 0
	s_setprio 1
	v_mfma_f32_16x16x32_f16 v[160:163], v[60:63], v[100:103], v[160:163]
	v_mfma_f32_16x16x32_f16 v[100:103], v[68:71], v[100:103], v[156:159]
	v_mfma_f32_16x16x32_f16 v[140:143], v[68:71], v[172:175], v[140:143]
	v_mfma_f32_16x16x32_f16 v[124:127], v[60:63], v[202:205], v[124:127]
	v_mfma_f32_16x16x32_f16 v[120:123], v[68:71], v[202:205], v[120:123]
	v_mfma_f32_16x16x32_f16 v[108:111], v[60:63], v[212:215], v[108:111]
	v_mfma_f32_16x16x32_f16 v[104:107], v[68:71], v[212:215], v[104:107]
	v_mfma_f32_16x16x32_f16 v[160:163], v[64:67], v[136:139], v[160:163]
	v_mfma_f32_16x16x32_f16 v[100:103], v[72:75], v[136:139], v[100:103]
	v_mfma_f32_16x16x32_f16 v[136:139], v[60:63], v[172:175], v[144:147]
	v_mfma_f32_16x16x32_f16 v[140:143], v[72:75], v[198:201], v[140:143]
	v_mfma_f32_16x16x32_f16 v[124:127], v[64:67], v[206:209], v[124:127]
	v_mfma_f32_16x16x32_f16 v[120:123], v[72:75], v[206:209], v[120:123]
	v_mfma_f32_16x16x32_f16 v[108:111], v[64:67], v[216:219], v[108:111]
	v_mfma_f32_16x16x32_f16 v[104:107], v[72:75], v[216:219], v[104:107]
	v_mfma_f32_16x16x32_f16 v[136:139], v[64:67], v[198:201], v[136:139]
	s_setprio 0
	s_barrier
	s_add_i32 s86, s81, s90
	v_lshl_add_u64 v[210:211], s[94:95], 0, v[178:179]
	s_mov_b32 m0, s86
	ds_read_b128 v[144:147], v196 offset:16384
	ds_read_b128 v[156:159], v196 offset:17408
	ds_read_b128 v[172:175], v196 offset:18432
	ds_read_b128 v[198:201], v196 offset:19456
	ds_read_b128 v[202:205], v196 offset:20480
	ds_read_b128 v[206:209], v196 offset:21504
	ds_read_b128 v[212:215], v196 offset:22528
	ds_read_b128 v[216:219], v196 offset:23552
	global_load_lds_dwordx4 v[210:211], off
	s_add_i32 m0, s86, 0x2000
	s_add_u32 s86, s94, 0x40000
	v_lshl_add_u64 v[228:229], s[94:95], 0, v[182:183]
	s_addc_u32 s87, s95, 0
	s_add_i32 vcc_lo, s84, s90
	global_load_lds_dwordx4 v[228:229], off
	v_lshl_add_u64 v[220:221], s[86:87], 0, v[178:179]
	s_mov_b32 m0, vcc_lo
	v_lshl_add_u64 v[230:231], s[96:97], 0, v[176:177]
	global_load_lds_dwordx4 v[220:221], off
	v_lshl_add_u64 v[220:221], s[86:87], 0, v[182:183]
	s_add_i32 m0, vcc_lo, 0x2000
	v_lshl_add_u64 v[232:233], s[96:97], 0, v[180:181]
	global_load_lds_dwordx4 v[220:221], off
	s_mov_b32 m0, s41
	s_nop 0
	global_load_lds_dwordx4 v[230:231], off
	s_mov_b32 m0, s91
	s_nop 0
	global_load_lds_dwordx4 v[232:233], off
	s_cmp_lg_u32 s99, 0
	s_cbranch_scc1 .Lrlx10b
	s_waitcnt vmcnt(8)
.Lrlx10b_done:
	s_mov_b32 s99, 0
	s_waitcnt lgkmcnt(0)
	s_barrier
	s_setprio 1
	s_waitcnt lgkmcnt(0)
	v_mfma_f32_16x16x32_f16 v[96:99], v[40:43], v[144:147], v[96:99]
	v_mfma_f32_16x16x32_f16 v[92:95], v[48:51], v[144:147], v[92:95]
	v_mfma_f32_16x16x32_f16 v[80:83], v[40:43], v[172:175], v[80:83]
	v_mfma_f32_16x16x32_f16 v[76:79], v[48:51], v[172:175], v[76:79]
	v_mfma_f32_16x16x32_f16 v[28:31], v[40:43], v[202:205], v[28:31]
	v_mfma_f32_16x16x32_f16 v[24:27], v[48:51], v[202:205], v[24:27]
	v_mfma_f32_16x16x32_f16 v[12:15], v[40:43], v[212:215], v[12:15]
	v_mfma_f32_16x16x32_f16 v[8:11], v[48:51], v[212:215], v[8:11]
	v_mfma_f32_16x16x32_f16 v[96:99], v[44:47], v[156:159], v[96:99]
	v_mfma_f32_16x16x32_f16 v[92:95], v[56:59], v[156:159], v[92:95]
	v_mfma_f32_16x16x32_f16 v[80:83], v[44:47], v[198:201], v[80:83]
	v_mfma_f32_16x16x32_f16 v[76:79], v[56:59], v[198:201], v[76:79]
	v_mfma_f32_16x16x32_f16 v[28:31], v[44:47], v[206:209], v[28:31]
	v_mfma_f32_16x16x32_f16 v[24:27], v[56:59], v[206:209], v[24:27]
	v_mfma_f32_16x16x32_f16 v[12:15], v[44:47], v[216:219], v[12:15]
	v_mfma_f32_16x16x32_f16 v[8:11], v[56:59], v[216:219], v[8:11]
	s_setprio 0
	s_setprio 1
	v_mfma_f32_16x16x32_f16 v[36:39], v[68:71], v[172:175], v[36:39]
	v_mfma_f32_16x16x32_f16 v[20:23], v[60:63], v[202:205], v[20:23]
	v_mfma_f32_16x16x32_f16 v[16:19], v[68:71], v[202:205], v[16:19]
	v_mfma_f32_16x16x32_f16 v[4:7], v[60:63], v[212:215], v[4:7]
	v_mfma_f32_16x16x32_f16 v[0:3], v[68:71], v[212:215], v[0:3]
	v_mfma_f32_16x16x32_f16 v[40:43], v[60:63], v[144:147], v[88:91]
	v_mfma_f32_16x16x32_f16 v[44:47], v[68:71], v[144:147], v[84:87]
	v_mfma_f32_16x16x32_f16 v[48:51], v[60:63], v[172:175], v[52:55]
	v_mfma_f32_16x16x32_f16 v[36:39], v[72:75], v[198:201], v[36:39]
	v_mfma_f32_16x16x32_f16 v[20:23], v[64:67], v[206:209], v[20:23]
	v_mfma_f32_16x16x32_f16 v[16:19], v[72:75], v[206:209], v[16:19]
	v_mfma_f32_16x16x32_f16 v[4:7], v[64:67], v[216:219], v[4:7]
	v_mfma_f32_16x16x32_f16 v[0:3], v[72:75], v[216:219], v[0:3]
	v_mfma_f32_16x16x32_f16 v[40:43], v[64:67], v[156:159], v[40:43]
	v_mfma_f32_16x16x32_f16 v[44:47], v[72:75], v[156:159], v[44:47]
	v_mfma_f32_16x16x32_f16 v[48:51], v[64:67], v[198:201], v[48:51]
	s_setprio 0
	s_barrier
	s_add_i32 vcc_lo, 0, 0x18000
	s_add_i32 vcc_hi, 0, 0x1c000
	v_add_u32_e32 v64, vcc_lo, v194
	v_add_u32_e32 v84, vcc_hi, v194
	ds_read_b128 v[52:55], v64
	ds_read_b128 v[56:59], v64 offset:1024
	ds_read_b128 v[60:63], v64 offset:2048
	ds_read_b128 v[64:67], v64 offset:3072
	ds_read_b128 v[68:71], v84
	ds_read_b128 v[72:75], v84 offset:1024
	ds_read_b128 v[172:175], v84 offset:2048
	ds_read_b128 v[198:201], v84 offset:3072
	s_add_u32 s86, s96, 0x40000
	s_addc_u32 s87, s97, 0
	s_mov_b32 m0, s64
	v_lshl_add_u64 v[144:145], s[86:87], 0, v[176:177]
	ds_read_b128 v[84:87], v196 offset:32768
	ds_read_b128 v[88:91], v196 offset:33792
	ds_read_b128 v[202:205], v196 offset:34816
	ds_read_b128 v[206:209], v196 offset:35840
	ds_read_b128 v[212:215], v196 offset:36864
	ds_read_b128 v[216:219], v196 offset:37888
	ds_read_b128 v[220:223], v196 offset:38912
	ds_read_b128 v[224:227], v196 offset:39936
	global_load_lds_dwordx4 v[144:145], off
	v_lshl_add_u64 v[144:145], s[86:87], 0, v[180:181]
	s_mov_b32 m0, s65
	s_nop 0
	global_load_lds_dwordx4 v[144:145], off
	s_waitcnt vmcnt(8)
	s_waitcnt lgkmcnt(0)
	s_barrier
	s_setprio 1
	s_waitcnt lgkmcnt(0)
	v_mfma_f32_16x16x32_f16 v[144:147], v[52:55], v[84:87], v[168:171]
	v_mfma_f32_16x16x32_f16 v[168:171], v[56:59], v[88:91], v[144:147]
	v_mfma_f32_16x16x32_f16 v[144:147], v[60:63], v[84:87], v[164:167]
	v_mfma_f32_16x16x32_f16 v[164:167], v[64:67], v[88:91], v[144:147]
	v_mfma_f32_16x16x32_f16 v[144:147], v[52:55], v[202:205], v[152:155]
	v_mfma_f32_16x16x32_f16 v[152:155], v[56:59], v[206:209], v[144:147]
	v_mfma_f32_16x16x32_f16 v[144:147], v[60:63], v[202:205], v[148:151]
	v_mfma_f32_16x16x32_f16 v[132:135], v[52:55], v[212:215], v[132:135]
	v_mfma_f32_16x16x32_f16 v[128:131], v[60:63], v[212:215], v[128:131]
	v_mfma_f32_16x16x32_f16 v[116:119], v[52:55], v[220:223], v[116:119]
	v_mfma_f32_16x16x32_f16 v[112:115], v[60:63], v[220:223], v[112:115]
	v_mfma_f32_16x16x32_f16 v[148:151], v[64:67], v[206:209], v[144:147]
	v_mfma_f32_16x16x32_f16 v[132:135], v[56:59], v[216:219], v[132:135]
	v_mfma_f32_16x16x32_f16 v[128:131], v[64:67], v[216:219], v[128:131]
	v_mfma_f32_16x16x32_f16 v[116:119], v[56:59], v[224:227], v[116:119]
	v_mfma_f32_16x16x32_f16 v[112:115], v[64:67], v[224:227], v[112:115]
	s_setprio 0
	s_setprio 1
	v_mfma_f32_16x16x32_f16 v[144:147], v[68:71], v[84:87], v[160:163]
	v_mfma_f32_16x16x32_f16 v[84:87], v[172:175], v[84:87], v[100:103]
	v_mfma_f32_16x16x32_f16 v[156:159], v[198:201], v[88:91], v[84:87]
	v_mfma_f32_16x16x32_f16 v[84:87], v[68:71], v[202:205], v[136:139]
	v_mfma_f32_16x16x32_f16 v[160:163], v[72:75], v[88:91], v[144:147]
	v_mfma_f32_16x16x32_f16 v[144:147], v[72:75], v[206:209], v[84:87]
	v_mfma_f32_16x16x32_f16 v[84:87], v[172:175], v[202:205], v[140:143]
	v_mfma_f32_16x16x32_f16 v[140:143], v[198:201], v[206:209], v[84:87]
	v_mfma_f32_16x16x32_f16 v[84:87], v[68:71], v[212:215], v[124:127]
	v_mfma_f32_16x16x32_f16 v[124:127], v[72:75], v[216:219], v[84:87]
	v_mfma_f32_16x16x32_f16 v[84:87], v[172:175], v[212:215], v[120:123]
	v_mfma_f32_16x16x32_f16 v[120:123], v[198:201], v[216:219], v[84:87]
	v_mfma_f32_16x16x32_f16 v[84:87], v[68:71], v[220:223], v[108:111]
	v_mfma_f32_16x16x32_f16 v[108:111], v[72:75], v[224:227], v[84:87]
	v_mfma_f32_16x16x32_f16 v[84:87], v[172:175], v[220:223], v[104:107]
	v_mfma_f32_16x16x32_f16 v[104:107], v[198:201], v[224:227], v[84:87]
	s_setprio 0
	s_barrier
	s_add_i32 s86, vcc_lo, s90
	v_lshl_add_u64 v[88:89], v[210:211], 0, s[12:13]
	s_mov_b32 m0, s86
	s_nop 1
	ds_read_b128 v[84:87], v196 offset:49152
	ds_read_b128 v[100:103], v196 offset:50176
	ds_read_b128 v[136:139], v196 offset:51200
	ds_read_b128 v[202:205], v196 offset:52224
	ds_read_b128 v[206:209], v196 offset:53248
	ds_read_b128 v[212:215], v196 offset:54272
	ds_read_b128 v[216:219], v196 offset:55296
	ds_read_b128 v[220:223], v196 offset:56320
	global_load_lds_dwordx4 v[88:89], off
	s_add_i32 m0, s86, 0x2000
	s_add_u32 s86, s94, 0x40080
	v_lshl_add_u64 v[88:89], v[228:229], 0, s[12:13]
	s_addc_u32 s87, s95, 0
	s_add_i32 s94, vcc_hi, s90
	global_load_lds_dwordx4 v[88:89], off
	v_lshl_add_u64 v[88:89], s[86:87], 0, v[178:179]
	s_mov_b32 m0, s94
	s_nop 0
	global_load_lds_dwordx4 v[88:89], off
	v_lshl_add_u64 v[88:89], s[86:87], 0, v[182:183]
	s_add_i32 m0, s94, 0x2000
	s_nop 0
	global_load_lds_dwordx4 v[88:89], off
	v_lshl_add_u64 v[88:89], v[230:231], 0, s[12:13]
	s_mov_b32 m0, s72
	s_nop 0
	global_load_lds_dwordx4 v[88:89], off
	v_lshl_add_u64 v[88:89], v[232:233], 0, s[12:13]
	s_mov_b32 m0, s73
	s_nop 0
	global_load_lds_dwordx4 v[88:89], off
	s_waitcnt vmcnt(8)
	s_waitcnt lgkmcnt(0)
	s_barrier
	s_setprio 1
	s_waitcnt lgkmcnt(0)
	v_mfma_f32_16x16x32_f16 v[88:91], v[52:55], v[84:87], v[96:99]
	v_mfma_f32_16x16x32_f16 v[96:99], v[56:59], v[100:103], v[88:91]
	v_mfma_f32_16x16x32_f16 v[88:91], v[60:63], v[84:87], v[92:95]
	v_mfma_f32_16x16x32_f16 v[80:83], v[52:55], v[136:139], v[80:83]
	v_mfma_f32_16x16x32_f16 v[76:79], v[60:63], v[136:139], v[76:79]
	v_mfma_f32_16x16x32_f16 v[28:31], v[52:55], v[206:209], v[28:31]
	v_mfma_f32_16x16x32_f16 v[24:27], v[60:63], v[206:209], v[24:27]
	v_mfma_f32_16x16x32_f16 v[12:15], v[52:55], v[216:219], v[12:15]
	v_mfma_f32_16x16x32_f16 v[8:11], v[60:63], v[216:219], v[8:11]
	v_mfma_f32_16x16x32_f16 v[92:95], v[64:67], v[100:103], v[88:91]
	v_mfma_f32_16x16x32_f16 v[80:83], v[56:59], v[202:205], v[80:83]
	v_mfma_f32_16x16x32_f16 v[76:79], v[64:67], v[202:205], v[76:79]
	v_mfma_f32_16x16x32_f16 v[28:31], v[56:59], v[212:215], v[28:31]
	v_mfma_f32_16x16x32_f16 v[24:27], v[64:67], v[212:215], v[24:27]
	v_mfma_f32_16x16x32_f16 v[12:15], v[56:59], v[220:223], v[12:15]
	v_mfma_f32_16x16x32_f16 v[8:11], v[64:67], v[220:223], v[8:11]
	s_setprio 0
	s_setprio 1
	v_mfma_f32_16x16x32_f16 v[40:43], v[68:71], v[84:87], v[40:43]
	v_mfma_f32_16x16x32_f16 v[88:91], v[72:75], v[100:103], v[40:43]
	v_mfma_f32_16x16x32_f16 v[40:43], v[172:175], v[84:87], v[44:47]
	v_mfma_f32_16x16x32_f16 v[84:87], v[198:201], v[100:103], v[40:43]
	v_mfma_f32_16x16x32_f16 v[40:43], v[68:71], v[136:139], v[48:51]
	v_mfma_f32_16x16x32_f16 v[36:39], v[172:175], v[136:139], v[36:39]
	v_mfma_f32_16x16x32_f16 v[20:23], v[68:71], v[206:209], v[20:23]
	v_mfma_f32_16x16x32_f16 v[16:19], v[172:175], v[206:209], v[16:19]
	v_mfma_f32_16x16x32_f16 v[4:7], v[68:71], v[216:219], v[4:7]
	v_mfma_f32_16x16x32_f16 v[0:3], v[172:175], v[216:219], v[0:3]
	v_mfma_f32_16x16x32_f16 v[52:55], v[72:75], v[202:205], v[40:43]
	v_mfma_f32_16x16x32_f16 v[36:39], v[198:201], v[202:205], v[36:39]
	v_mfma_f32_16x16x32_f16 v[20:23], v[72:75], v[212:215], v[20:23]
	v_mfma_f32_16x16x32_f16 v[16:19], v[198:201], v[212:215], v[16:19]
	v_mfma_f32_16x16x32_f16 v[4:7], v[72:75], v[220:223], v[4:7]
	v_mfma_f32_16x16x32_f16 v[0:3], v[198:201], v[220:223], v[0:3]
	s_setprio 0
	s_barrier
	s_add_i32 s83, s83, 2
	s_add_u32 s46, s46, 0x100
	s_addc_u32 s47, s47, 0
	s_add_u32 s67, s67, 0x100
	s_addc_u32 s75, s75, 0
	s_cmp_gt_u32 s83, 13
	s_cbranch_scc1 .LBB0_1069

.LBB0_1167:
	s_andn2_b64 vcc, exec, s[8:9]
	s_mov_b64 s[8:9], -1
	v_cvt_pk_bf16_f32 v0, v10, v12
	v_cvt_pk_bf16_f32 v1, v14, v17
	v_cvt_pk_bf16_f32 v2, v11, v13
	v_cvt_pk_bf16_f32 v3, v15, v16
	global_store_dwordx4 v[8:9], v[0:3], off offset:256
	s_mov_b32 s99, 1
	s_cbranch_vccnz .LBB0_1062
	s_andn2_b64 vcc, exec, s[4:5]
	s_cbranch_vccnz .LBB0_1061
	s_barrier
	s_branch .LBB0_1061

.LBB0_1500:
	v_readlane_b32 s0, v255, 32
	v_readlane_b32 s1, v255, 33
	s_and_b64 vcc, exec, s[0:1]
	s_cbranch_vccnz .LBB0_1536
	v_ashrrev_i32_e32 v2, 31, v0
	v_lshrrev_b32_e32 v2, 26, v2
	v_add_u32_e32 v2, v0, v2
	v_ashrrev_i32_e32 v137, 6, v2
	v_bfe_i32 v2, v0, 27, 1
	v_lshlrev_b32_e32 v1, 4, v0
	v_lshrrev_b32_e32 v2, 22, v2
	v_add_u32_e32 v2, v1, v2
	v_and_b32_e32 v2, 0xfffffc00, v2
	v_sub_u32_e32 v2, v1, v2
	v_lshrrev_b32_e32 v3, 4, v2
	v_bitop3_b32 v2, v3, v2, 32 bitop3:0x6c
	v_ashrrev_i32_e32 v4, 31, v2
	v_lshrrev_b32_e32 v4, 26, v4
	v_add_u32_e32 v4, v2, v4
	v_lshlrev_b32_e32 v3, 3, v137
	v_ashrrev_i32_e32 v147, 6, v4
	v_and_b32_e32 v4, 0xc0, v4
	v_and_b32_e32 v3, -16, v3
	v_sub_u32_e32 v2, v2, v4
	v_mov_b32_e32 v4, 1
	v_add_u32_e32 v3, v147, v3
	v_ashrrev_i16_sdwa v2, v4, sext(v2) dst_sel:DWORD dst_unused:UNUSED_PAD src0_sel:DWORD src1_sel:BYTE_0
	v_lshlrev_b32_e32 v5, 5, v137
	v_bfe_i32 v149, v2, 0, 16
	v_lshlrev_b32_e32 v2, 1, v3
	v_lshrrev_b32_e32 v6, 2, v3
	v_and_b32_e32 v7, 3, v147
	s_mov_b32 s4, 0x1fffe0
	v_and_b32_e32 v5, 32, v5
	v_and_b32_e32 v2, 24, v2
	v_and_b32_e32 v6, 4, v6
	v_and_or_b32 v7, v3, s4, v7
	v_or3_b32 v2, v7, v6, v2
	v_add_lshl_u32 v5, v5, v149, 1
	v_add_u32_e32 v1, 0x2000, v1
	v_lshl_add_u32 v130, v2, 11, v5
	v_ashrrev_i32_e32 v2, 31, v1
	v_lshrrev_b32_e32 v2, 22, v2
	v_add_u32_e32 v2, v1, v2
	v_ashrrev_i32_e32 v161, 10, v2
	v_mul_i32_i24_e32 v2, 0x400, v161
	v_sub_u32_e32 v1, v1, v2
	v_lshrrev_b32_e32 v2, 4, v1
	v_bitop3_b32 v1, v2, v1, 32 bitop3:0x6c
	v_lshl_add_u32 v128, v3, 11, v5
	v_ashrrev_i32_e32 v3, 31, v1
	v_lshrrev_b32_e32 v3, 26, v3
	v_add_u32_e32 v3, v1, v3
	v_lshlrev_b32_e32 v2, 3, v161
	v_ashrrev_i32_e32 v163, 6, v3
	v_and_b32_e32 v3, 0xc0, v3
	v_and_b32_e32 v2, -16, v2
	v_sub_u32_e32 v1, v1, v3
	v_add_u32_e32 v2, v163, v2
	v_ashrrev_i16_sdwa v1, v4, sext(v1) dst_sel:DWORD dst_unused:UNUSED_PAD src0_sel:DWORD src1_sel:BYTE_0
	v_lshlrev_b32_e32 v5, 5, v161
	v_bfe_i32 v165, v1, 0, 16
	v_lshlrev_b32_e32 v1, 1, v2
	v_lshrrev_b32_e32 v3, 2, v2
	v_and_b32_e32 v4, 3, v163
	v_and_b32_e32 v5, 32, v5
	v_and_b32_e32 v1, 24, v1
	v_and_b32_e32 v3, 4, v3
	v_and_or_b32 v4, v2, s4, v4
	v_bfe_u32 v151, v0, 4, 2
	v_or3_b32 v1, v4, v3, v1
	v_add_lshl_u32 v3, v5, v165, 1
	v_and_b32_e32 v153, 15, v0
	v_lshl_add_u32 v134, v1, 11, v3
	v_mov_b32_e32 v0, v153
	v_mov_b32_e32 v1, v151
	v_lshl_add_u32 v132, v2, 11, v3
	v_lshlrev_b32_e32 v2, 3, v1
	v_mbcnt_lo_u32_b32 v1, -1, 0
	v_mbcnt_hi_u32_b32 v1, -1, v1
	v_and_b32_e32 v5, 64, v1
	v_xor_b32_e32 v4, 16, v1
	v_add_u32_e32 v5, 64, v5
	v_cmp_lt_i32_e32 vcc, v4, v5
	s_ashr_i32 s1, s8, 6
	s_ashr_i32 s9, s8, 8
	v_cndmask_b32_e32 v4, v1, v4, vcc
	s_and_b32 s0, s1, 3
	s_lshl_b32 s7, s1, 10
	s_lshl_b32 s11, s9, 6
	s_lshl_b32 s1, s92, 8
	v_lshlrev_b32_e32 v155, 2, v4
	v_xor_b32_e32 v4, 32, v1
	s_add_i32 s1, s1, s11
	v_cmp_lt_i32_e32 vcc, v4, v5
	v_add_u32_e32 v0, s1, v0
	v_ashrrev_i32_e32 v3, 31, v2
	v_cndmask_b32_e32 v1, v1, v4, vcc
	v_lshlrev_b32_e32 v157, 2, v1
	v_ashrrev_i32_e32 v1, 31, v0
	v_lshl_add_u64 v[4:5], v[2:3], 2, s[76:77]
	v_lshlrev_b64 v[6:7], 7, v[0:1]
	v_lshl_add_u64 v[10:11], v[4:5], 0, v[6:7]
	v_mov_b32_e32 v184, v0
	v_ashrrev_i32_e32 v185, 31, v184
	v_lshlrev_b64 v[184:185], 7, v[184:185]
	v_lshl_add_u64 v[184:185], v[4:5], 0, v[184:185]
	global_load_dwordx4 v[188:191], v[184:185], off offset:16
	global_load_dwordx4 v[192:195], v[184:185], off
	v_add_u32_e32 v184, 0x10, v0
	v_ashrrev_i32_e32 v185, 31, v184
	v_lshlrev_b64 v[184:185], 7, v[184:185]
	v_lshl_add_u64 v[184:185], v[4:5], 0, v[184:185]
	global_load_dwordx4 v[196:199], v[184:185], off offset:16
	global_load_dwordx4 v[200:203], v[184:185], off
	v_add_u32_e32 v184, 0x20, v0
	v_ashrrev_i32_e32 v185, 31, v184
	v_lshlrev_b64 v[184:185], 7, v[184:185]
	v_lshl_add_u64 v[184:185], v[4:5], 0, v[184:185]
	global_load_dwordx4 v[204:207], v[184:185], off offset:16
	global_load_dwordx4 v[208:211], v[184:185], off
	v_add_u32_e32 v184, 0x30, v0
	v_ashrrev_i32_e32 v185, 31, v184
	v_lshlrev_b64 v[184:185], 7, v[184:185]
	v_lshl_add_u64 v[184:185], v[4:5], 0, v[184:185]
	global_load_dwordx4 v[212:215], v[184:185], off offset:16
	global_load_dwordx4 v[216:219], v[184:185], off
	v_add_u32_e32 v184, 0x80, v0
	v_ashrrev_i32_e32 v185, 31, v184
	v_lshlrev_b64 v[184:185], 7, v[184:185]
	v_lshl_add_u64 v[184:185], v[4:5], 0, v[184:185]
	global_load_dwordx4 v[220:223], v[184:185], off offset:16
	global_load_dwordx4 v[224:227], v[184:185], off
	v_add_u32_e32 v184, 0x90, v0
	v_ashrrev_i32_e32 v185, 31, v184
	v_lshlrev_b64 v[184:185], 7, v[184:185]
	v_lshl_add_u64 v[184:185], v[4:5], 0, v[184:185]
	global_load_dwordx4 v[228:231], v[184:185], off offset:16
	global_load_dwordx4 v[232:235], v[184:185], off
	v_add_u32_e32 v184, 0xa0, v0
	v_ashrrev_i32_e32 v185, 31, v184
	v_lshlrev_b64 v[184:185], 7, v[184:185]
	v_lshl_add_u64 v[184:185], v[4:5], 0, v[184:185]
	global_load_dwordx4 v[236:239], v[184:185], off offset:16
	global_load_dwordx4 v[240:243], v[184:185], off
	v_add_u32_e32 v184, 0xb0, v0
	v_ashrrev_i32_e32 v185, 31, v184
	v_lshlrev_b64 v[184:185], 7, v[184:185]
	v_lshl_add_u64 v[184:185], v[4:5], 0, v[184:185]
	global_load_dwordx4 v[244:247], v[184:185], off offset:16
	global_load_dwordx4 v[248:251], v[184:185], off
	s_waitcnt vmcnt(0)
	v_mov_b32_e32 v6, v188
	v_mov_b32_e32 v7, v189
	v_mov_b32_e32 v8, v190
	v_mov_b32_e32 v9, v191
	s_nop 0
	v_mov_b32_e32 v10, v192
	v_mov_b32_e32 v11, v193
	v_mov_b32_e32 v12, v194
	v_mov_b32_e32 v13, v195
	s_waitcnt vmcnt(3)
	v_add_u32_e32 v56, 0x90, v0
	v_ashrrev_i32_e32 v57, 31, v56
	v_add_u32_e32 v58, 0xa0, v0
	v_ashrrev_i32_e32 v59, 31, v58
	s_waitcnt vmcnt(2)
	v_add_u32_e32 v60, 0xb0, v0
	v_ashrrev_i32_e32 v61, 31, v60
	s_lshl_b32 s66, s0, 5
	s_lshl_b32 s4, s88, 8
	s_or_b32 s4, s4, s66
	v_add_u32_e32 v2, s4, v2
	v_ashrrev_i32_e32 v3, 31, v2
	s_ashr_i32 s93, s92, 31
	s_lshl_b64 s[4:5], s[92:93], 19
	v_readlane_b32 s12, v255, 34
	v_readlane_b32 s14, v255, 36
	s_cmp_gt_i32 s92, 63
	v_readlane_b32 s13, v255, 35
	v_readlane_b32 s15, v255, 37
	s_cselect_b32 s6, s15, s13
	s_cselect_b32 s10, s14, s12
	s_ashr_i32 s89, s88, 31
	s_lshl_b64 s[12:13], s[88:89], 19
	s_add_u32 s40, s10, s12
	s_addc_u32 s41, s6, s13
	s_add_i32 s67, s7, 0
	s_add_i32 m0, s67, 0x10000
	v_mov_b32_e32 v136, 0
	v_mov_b32_e32 v131, v136
	v_mov_b32_e32 v135, v136
	v_mov_b32_e32 v129, v136
	v_mov_b32_e32 v133, v136
	s_mov_b32 s1, 0
	v_mov_b32_e32 v15, v6
	v_mov_b32_e32 v14, v10
	v_mov_b32_e32 v16, v12
	v_mov_b32_e32 v17, v8
	v_pk_add_f32 v[14:15], v[14:15], v[16:17]
	v_add_f32_e32 v6, v11, v13
	v_add_f32_e32 v8, v7, v9
	v_mov_b32_e32 v7, v14
	v_mov_b32_e32 v9, v15
	v_pk_add_f32 v[6:7], v[6:7], v[8:9]
	ds_bpermute_b32 v9, v155, v7
	ds_bpermute_b32 v8, v155, v6
	s_waitcnt lgkmcnt(0)
	v_pk_add_f32 v[48:49], v[6:7], v[8:9]
	v_add_u32_e32 v6, 16, v0
	v_ashrrev_i32_e32 v7, 31, v6
	v_lshlrev_b64 v[8:9], 7, v[6:7]
	v_lshl_add_u64 v[12:13], v[4:5], 0, v[8:9]
	v_mov_b32_e32 v8, v196
	v_mov_b32_e32 v9, v197
	v_mov_b32_e32 v10, v198
	v_mov_b32_e32 v11, v199
	s_nop 0
	v_mov_b32_e32 v12, v200
	v_mov_b32_e32 v13, v201
	v_mov_b32_e32 v14, v202
	v_mov_b32_e32 v15, v203
	ds_bpermute_b32 v51, v157, v49
	ds_bpermute_b32 v50, v157, v48
	v_mov_b32_e32 v17, v8
	v_mov_b32_e32 v16, v12
	v_mov_b32_e32 v18, v14
	v_mov_b32_e32 v19, v10
	v_pk_add_f32 v[16:17], v[16:17], v[18:19]
	v_add_f32_e32 v8, v13, v15
	v_add_f32_e32 v10, v9, v11
	v_mov_b32_e32 v9, v16
	v_mov_b32_e32 v11, v17
	v_pk_add_f32 v[8:9], v[8:9], v[10:11]
	ds_bpermute_b32 v11, v155, v9
	ds_bpermute_b32 v10, v155, v8
	s_waitcnt lgkmcnt(0)
	v_pk_add_f32 v[52:53], v[8:9], v[10:11]
	v_add_u32_e32 v8, 32, v0
	v_ashrrev_i32_e32 v9, 31, v8
	v_lshlrev_b64 v[10:11], 7, v[8:9]
	v_lshl_add_u64 v[14:15], v[4:5], 0, v[10:11]
	v_mov_b32_e32 v10, v204
	v_mov_b32_e32 v11, v205
	v_mov_b32_e32 v12, v206
	v_mov_b32_e32 v13, v207
	s_nop 0
	v_mov_b32_e32 v14, v208
	v_mov_b32_e32 v15, v209
	v_mov_b32_e32 v16, v210
	v_mov_b32_e32 v17, v211
	ds_bpermute_b32 v55, v157, v53
	ds_bpermute_b32 v54, v157, v52
	v_mov_b32_e32 v19, v10
	v_mov_b32_e32 v18, v14
	v_mov_b32_e32 v20, v16
	v_mov_b32_e32 v21, v12
	v_pk_add_f32 v[18:19], v[18:19], v[20:21]
	v_add_f32_e32 v10, v15, v17
	v_add_f32_e32 v12, v11, v13
	v_mov_b32_e32 v11, v18
	v_mov_b32_e32 v13, v19
	v_pk_add_f32 v[10:11], v[10:11], v[12:13]
	ds_bpermute_b32 v13, v155, v11
	ds_bpermute_b32 v12, v155, v10
	s_waitcnt lgkmcnt(0)
	v_pk_add_f32 v[64:65], v[10:11], v[12:13]
	v_add_u32_e32 v10, 48, v0
	v_ashrrev_i32_e32 v11, 31, v10
	v_lshlrev_b64 v[12:13], 7, v[10:11]
	v_lshl_add_u64 v[16:17], v[4:5], 0, v[12:13]
	v_mov_b32_e32 v12, v212
	v_mov_b32_e32 v13, v213
	v_mov_b32_e32 v14, v214
	v_mov_b32_e32 v15, v215
	s_nop 0
	v_mov_b32_e32 v16, v216
	v_mov_b32_e32 v17, v217
	v_mov_b32_e32 v18, v218
	v_mov_b32_e32 v19, v219
	ds_bpermute_b32 v67, v157, v65
	ds_bpermute_b32 v66, v157, v64
	v_mov_b32_e32 v21, v12
	v_mov_b32_e32 v20, v16
	v_mov_b32_e32 v22, v18
	v_mov_b32_e32 v23, v14
	v_pk_add_f32 v[20:21], v[20:21], v[22:23]
	v_add_f32_e32 v12, v17, v19
	v_add_f32_e32 v14, v13, v15
	v_mov_b32_e32 v13, v20
	v_mov_b32_e32 v15, v21
	v_pk_add_f32 v[12:13], v[12:13], v[14:15]
	ds_bpermute_b32 v15, v155, v13
	ds_bpermute_b32 v14, v155, v12
	s_waitcnt lgkmcnt(0)
	v_pk_add_f32 v[68:69], v[12:13], v[14:15]
	v_add_u32_e32 v12, 0x80, v0
	v_ashrrev_i32_e32 v13, 31, v12
	v_lshlrev_b64 v[14:15], 7, v[12:13]
	v_lshl_add_u64 v[18:19], v[4:5], 0, v[14:15]
	v_mov_b32_e32 v14, v220
	v_mov_b32_e32 v15, v221
	v_mov_b32_e32 v16, v222
	v_mov_b32_e32 v17, v223
	s_nop 0
	v_mov_b32_e32 v18, v224
	v_mov_b32_e32 v19, v225
	v_mov_b32_e32 v20, v226
	v_mov_b32_e32 v21, v227
	v_lshlrev_b64 v[0:1], 11, v[0:1]
	v_lshl_add_u64 v[0:1], s[44:45], 0, v[0:1]
	ds_bpermute_b32 v71, v157, v69
	ds_bpermute_b32 v70, v157, v68
	v_mov_b32_e32 v23, v14
	v_mov_b32_e32 v22, v18
	v_mov_b32_e32 v24, v20
	v_mov_b32_e32 v25, v16
	v_pk_add_f32 v[22:23], v[22:23], v[24:25]
	v_add_f32_e32 v14, v19, v21
	v_add_f32_e32 v16, v15, v17
	v_mov_b32_e32 v15, v22
	v_mov_b32_e32 v17, v23
	v_pk_add_f32 v[14:15], v[14:15], v[16:17]
	ds_bpermute_b32 v17, v155, v15
	ds_bpermute_b32 v16, v155, v14
	s_waitcnt lgkmcnt(0)
	v_pk_add_f32 v[112:113], v[14:15], v[16:17]
	v_lshlrev_b64 v[14:15], 7, v[56:57]
	v_lshl_add_u64 v[18:19], v[4:5], 0, v[14:15]
	v_mov_b32_e32 v14, v228
	v_mov_b32_e32 v15, v229
	v_mov_b32_e32 v16, v230
	v_mov_b32_e32 v17, v231
	s_nop 0
	v_mov_b32_e32 v18, v232
	v_mov_b32_e32 v19, v233
	v_mov_b32_e32 v20, v234
	v_mov_b32_e32 v21, v235
	ds_bpermute_b32 v115, v157, v113
	ds_bpermute_b32 v114, v157, v112
	v_mov_b32_e32 v23, v14
	v_mov_b32_e32 v22, v18
	v_mov_b32_e32 v24, v20
	v_mov_b32_e32 v25, v16
	v_pk_add_f32 v[22:23], v[22:23], v[24:25]
	v_add_f32_e32 v14, v19, v21
	v_add_f32_e32 v16, v15, v17
	v_mov_b32_e32 v15, v22
	v_mov_b32_e32 v17, v23
	v_pk_add_f32 v[14:15], v[14:15], v[16:17]
	ds_bpermute_b32 v17, v155, v15
	ds_bpermute_b32 v16, v155, v14
	s_waitcnt lgkmcnt(0)
	v_pk_add_f32 v[116:117], v[14:15], v[16:17]
	v_lshlrev_b64 v[14:15], 7, v[58:59]
	v_lshl_add_u64 v[18:19], v[4:5], 0, v[14:15]
	v_mov_b32_e32 v14, v236
	v_mov_b32_e32 v15, v237
	v_mov_b32_e32 v16, v238
	v_mov_b32_e32 v17, v239
	s_nop 0
	v_mov_b32_e32 v18, v240
	v_mov_b32_e32 v19, v241
	v_mov_b32_e32 v20, v242
	v_mov_b32_e32 v21, v243
	ds_bpermute_b32 v119, v157, v117
	ds_bpermute_b32 v118, v157, v116
	v_mov_b32_e32 v23, v14
	v_mov_b32_e32 v22, v18
	v_mov_b32_e32 v24, v20
	v_mov_b32_e32 v25, v16
	v_pk_add_f32 v[22:23], v[22:23], v[24:25]
	v_add_f32_e32 v14, v19, v21
	v_add_f32_e32 v16, v15, v17
	v_mov_b32_e32 v15, v22
	v_mov_b32_e32 v17, v23
	v_pk_add_f32 v[14:15], v[14:15], v[16:17]
	ds_bpermute_b32 v17, v155, v15
	ds_bpermute_b32 v16, v155, v14
	s_waitcnt lgkmcnt(0)
	v_pk_add_f32 v[120:121], v[14:15], v[16:17]
	v_lshlrev_b64 v[14:15], 7, v[60:61]
	v_lshl_add_u64 v[4:5], v[4:5], 0, v[14:15]
	v_mov_b32_e32 v14, v244
	v_mov_b32_e32 v15, v245
	v_mov_b32_e32 v16, v246
	v_mov_b32_e32 v17, v247
	v_mov_b32_e32 v18, v248
	v_mov_b32_e32 v19, v249
	v_mov_b32_e32 v20, v250
	v_mov_b32_e32 v21, v251
	ds_bpermute_b32 v123, v157, v121
	ds_bpermute_b32 v122, v157, v120
	v_mov_b32_e32 v5, v14
	v_mov_b32_e32 v4, v18
	v_mov_b32_e32 v22, v20
	v_mov_b32_e32 v23, v16
	v_pk_add_f32 v[4:5], v[4:5], v[22:23]
	v_add_f32_e32 v14, v19, v21
	v_add_f32_e32 v16, v15, v17
	v_mov_b32_e32 v15, v4
	v_mov_b32_e32 v17, v5
	v_pk_add_f32 v[4:5], v[14:15], v[16:17]
	ds_bpermute_b32 v15, v155, v5
	ds_bpermute_b32 v14, v155, v4
	s_waitcnt lgkmcnt(0)
	v_pk_add_f32 v[124:125], v[4:5], v[14:15]
	v_lshlrev_b64 v[4:5], 2, v[2:3]
	v_lshlrev_b64 v[2:3], 1, v[2:3]
	v_lshl_add_u64 v[74:75], v[0:1], 0, v[2:3]
	v_lshlrev_b64 v[0:1], 11, v[6:7]
	v_lshl_add_u64 v[0:1], s[44:45], 0, v[0:1]
	v_lshl_add_u64 v[76:77], v[0:1], 0, v[2:3]
	v_lshlrev_b64 v[0:1], 11, v[8:9]
	v_lshl_add_u64 v[0:1], s[44:45], 0, v[0:1]
	v_lshl_add_u64 v[78:79], v[0:1], 0, v[2:3]
	v_lshlrev_b64 v[0:1], 11, v[10:11]
	v_lshl_add_u64 v[0:1], s[44:45], 0, v[0:1]
	v_lshl_add_u64 v[80:81], v[0:1], 0, v[2:3]
	v_lshlrev_b64 v[0:1], 11, v[12:13]
	v_lshl_add_u64 v[0:1], s[44:45], 0, v[0:1]
	v_lshl_add_u64 v[138:139], v[0:1], 0, v[2:3]
	v_lshlrev_b64 v[0:1], 11, v[56:57]
	v_lshl_add_u64 v[0:1], s[44:45], 0, v[0:1]
	v_lshl_add_u64 v[56:57], v[0:1], 0, v[2:3]
	v_lshlrev_b64 v[0:1], 11, v[58:59]
	v_lshl_add_u64 v[0:1], s[44:45], 0, v[0:1]
	v_lshl_add_u64 v[58:59], v[0:1], 0, v[2:3]
	v_lshlrev_b64 v[0:1], 11, v[60:61]
	v_lshl_add_u64 v[0:1], s[44:45], 0, v[0:1]
	v_lshl_add_u64 v[62:63], s[28:29], 0, v[4:5]
	v_lshl_add_u64 v[72:73], s[30:31], 0, v[4:5]
	v_lshl_add_u64 v[140:141], v[0:1], 0, v[2:3]
	global_load_dwordx4 v[36:39], v[62:63], off offset:16
	global_load_dwordx4 v[44:47], v[62:63], off
	global_load_dwordx4 v[32:35], v[72:73], off offset:16
	global_load_dwordx4 v[40:43], v[72:73], off
	global_load_dwordx4 v[28:31], v[74:75], off
	global_load_dwordx4 v[24:27], v[76:77], off
	global_load_dwordx4 v[20:23], v[78:79], off
	global_load_dwordx4 v[16:19], v[80:81], off
	global_load_dwordx4 v[12:15], v[138:139], off
	global_load_dwordx4 v[8:11], v[56:57], off
	global_load_dwordx4 v[4:7], v[58:59], off
	global_load_dwordx4 v[0:3], v[140:141], off
	global_load_dwordx4 v[100:103], v[62:63], off offset:528
	global_load_dwordx4 v[108:111], v[62:63], off offset:512
	global_load_dwordx4 v[96:99], v[72:73], off offset:528
	global_load_dwordx4 v[104:107], v[72:73], off offset:512
	global_load_dwordx4 v[92:95], v[74:75], off offset:256
	global_load_dwordx4 v[88:91], v[76:77], off offset:256
	global_load_dwordx4 v[84:87], v[78:79], off offset:256
	s_nop 0
	global_load_dwordx4 v[80:83], v[80:81], off offset:256
	s_nop 0
	global_load_dwordx4 v[76:79], v[138:139], off offset:256
	global_load_dwordx4 v[72:75], v[56:57], off offset:256
	global_load_dwordx4 v[60:63], v[58:59], off offset:256
	s_nop 0
	global_load_dwordx4 v[56:59], v[140:141], off offset:256
	ds_bpermute_b32 v127, v157, v125
	global_load_lds_dwordx4 v130, s[40:41]
	s_add_i32 m0, s67, 0x12000
	s_add_u32 s12, s40, 0x40000
	global_load_lds_dwordx4 v134, s[40:41]
	s_addc_u32 s13, s41, 0
	s_add_i32 m0, s67, 0x14000
	ds_bpermute_b32 v126, v157, v124
	global_load_lds_dwordx4 v130, s[12:13]
	s_add_i32 m0, s67, 0x16000
	s_add_u32 s74, s42, s4
	s_addc_u32 s75, s43, s5
	s_add_i32 s68, s67, 0x2000
	global_load_lds_dwordx4 v134, s[12:13]
	s_mov_b32 m0, s67
	s_add_u32 s4, s74, 0x40000
	global_load_lds_dwordx4 v128, s[74:75]
	s_mov_b32 m0, s68
	s_addc_u32 s5, s75, 0
	s_add_i32 s69, s67, 0x4000
	global_load_lds_dwordx4 v132, s[74:75]
	s_mov_b32 m0, s69
	s_add_i32 s89, s67, 0x6000
	global_load_lds_dwordx4 v128, s[4:5]
	s_mov_b32 m0, s89
	s_cmp_eq_u32 s9, 1
	global_load_lds_dwordx4 v132, s[4:5]
	v_lshl_add_u64 v[138:139], s[40:41], 0, v[130:131]
	v_lshl_add_u64 v[140:141], s[40:41], 0, v[134:135]
	v_lshl_add_u64 v[142:143], s[74:75], 0, v[128:129]
	v_lshl_add_u64 v[144:145], s[74:75], 0, v[132:133]
	s_cselect_b64 s[4:5], -1, 0
	s_cmp_lg_u32 s9, 1
	s_cbranch_scc1 .LBB0_1503
	s_barrier

.LBB0_1600:
	s_sext_i32_i16 s41, s4
	s_add_u32 s4, s58, 0x373e000
	s_addc_u32 s5, s59, 0
	s_add_u32 s6, s58, 0x3749000
	v_and_b32_e32 v194, 15, v8
	v_and_b32_e32 v15, 48, v8
	v_lshlrev_b32_e32 v16, 2, v8
	s_addc_u32 s7, s59, 0
	s_and_b32 s34, s12, 3
	s_lshl_b32 s8, s11, 13
	v_lshl_or_b32 v15, v194, 6, v15
	v_and_b32_e32 v17, 32, v16
	v_bitop3_b32 v18, v15, s8, v17 bitop3:0xde
	s_lshl_b32 s8, s34, 12
	v_bitop3_b32 v196, v15, s8, v17 bitop3:0xde
	s_mov_b64 s[8:9], 0x80
	s_add_i32 m0, s69, 0x18000
	v_lshl_add_u64 v[6:7], v[6:7], 0, s[8:9]
	s_lshl_b32 s78, s11, 6
	s_lshl_b32 s79, s34, 5
	s_waitcnt vmcnt(2)
	s_barrier
	global_load_lds_dwordx4 v[6:7], off
	v_lshl_add_u64 v[4:5], v[4:5], 0, s[8:9]
	s_add_i32 m0, s69, 0x1a000
	s_add_i32 s80, s69, 0x8000
	s_add_i32 s81, s69, 0xa000
	global_load_lds_dwordx4 v[4:5], off
	v_lshl_add_u64 v[0:1], v[0:1], 0, s[8:9]
	s_mov_b32 m0, s80
	s_add_u32 s14, s74, 0x40080
	global_load_lds_dwordx4 v[0:1], off
	v_lshl_add_u64 v[0:1], v[2:3], 0, s[8:9]
	s_mov_b32 m0, s81
	s_addc_u32 s15, s75, 0
	global_load_lds_dwordx4 v[0:1], off
	s_add_i32 m0, s69, 0x1c000
	v_lshl_add_u64 v[0:1], s[14:15], 0, v[172:173]
	global_load_lds_dwordx4 v[0:1], off
	v_lshl_add_u64 v[0:1], s[14:15], 0, v[168:169]
	s_add_i32 m0, s69, 0x1e000
	s_lshl_b32 s84, s12, 9
	global_load_lds_dwordx4 v[0:1], off
	v_and_b32_e32 v0, 0x80, v16
	v_and_b32_e32 v1, 31, v8
	v_or3_b32 v197, v1, v0, s79
	v_lshlrev_b32_e32 v0, 14, v13
	v_and_b32_e32 v0, 0xffff8000, v0
	v_lshl_add_u32 v0, v12, 11, v0
	v_and_b32_e32 v1, 1, v13
	v_lshl_or_b32 v0, v1, 6, v0
	v_lshl_add_u32 v176, v14, 1, v0
	v_lshlrev_b32_e32 v0, 14, v9
	s_cmpk_lt_u32 s10, 0x100
	v_and_b32_e32 v0, 0xffff8000, v0
	s_waitcnt vmcnt(6)
	s_cselect_b64 s[12:13], -1, 0
	s_lshl_b32 s10, s11, 11
	s_lshl_b32 s11, s34, 9
	v_lshl_add_u32 v0, v10, 11, v0
	v_and_b32_e32 v1, 1, v9
	s_or_b32 s85, s10, s11
	v_lshl_or_b32 v0, v1, 6, v0
	v_bfe_u32 v195, v8, 4, 2
	s_add_i32 s85, s85, 0x22400
	v_mov_b32_e32 v177, v173
	v_lshl_add_u32 v178, v11, 1, v0
	v_mov_b32_e32 v179, v173
	v_mov_b64_e32 v[180:181], 0xb00
	v_mov_b64_e32 v[182:183], 0xaff
	s_movk_i32 s88, 0x1600
	s_add_i32 s89, s84, 0x22500
	s_add_i32 s90, 0, 0x10000
	s_add_i32 s91, 0, 0x14000
	v_add_u32_e32 v198, 0, v18
	v_mov_b32_e32 v199, 0x20400
	s_barrier
	s_mov_b32 s99, 0
	s_branch .LBB0_1603

.LBB0_1606:
	v_add_u32_e32 v76, s90, v196
	v_add_u32_e32 v160, s91, v196
	ds_read_b128 v[56:59], v76
	ds_read_b128 v[64:67], v76 offset:1024
	ds_read_b128 v[72:75], v76 offset:2048
	ds_read_b128 v[76:79], v76 offset:3072
	ds_read_b128 v[100:103], v160
	ds_read_b128 v[136:139], v160 offset:1024
	ds_read_b128 v[156:159], v160 offset:2048
	ds_read_b128 v[160:163], v160 offset:3072
	s_add_u32 s82, s46, 0xfffc0080
	s_addc_u32 s83, s47, -1
	s_and_b64 s[74:75], s[74:75], exec
	s_cselect_b32 s83, s35, s83
	s_cselect_b32 s82, s86, s82
	s_cselect_b32 s75, s15, s93
	s_cselect_b32 s74, s87, s92
	v_lshl_add_u64 v[192:193], s[46:47], 0, v[176:177]
	s_add_i32 m0, s69, 0xc000
	ds_read_b128 v[164:167], v198
	ds_read_b128 v[184:187], v198 offset:1024
	ds_read_b128 v[188:191], v198 offset:2048
	ds_read_b128 v[200:203], v198 offset:3072
	ds_read_b128 v[204:207], v198 offset:4096
	ds_read_b128 v[212:215], v198 offset:5120
	ds_read_b128 v[216:219], v198 offset:6144
	ds_read_b128 v[220:223], v198 offset:7168
	global_load_lds_dwordx4 v[192:193], off
	v_lshl_add_u64 v[192:193], s[46:47], 0, v[178:179]
	s_add_i32 m0, s69, 0xe000
	s_nop 0
	global_load_lds_dwordx4 v[192:193], off
	s_cmp_lg_u32 s99, 0
	s_cbranch_scc1 .Lrlx15a
	s_waitcnt vmcnt(8)
.Lrlx15a_done:
	s_waitcnt lgkmcnt(0)
	s_barrier
	s_setprio 1
	s_waitcnt lgkmcnt(0)
	v_mfma_f32_16x16x32_f16 v[152:155], v[56:59], v[164:167], v[152:155]
	v_mfma_f32_16x16x32_f16 v[144:147], v[72:75], v[164:167], v[144:147]
	v_mfma_f32_16x16x32_f16 v[132:135], v[56:59], v[188:191], v[132:135]
	v_mfma_f32_16x16x32_f16 v[124:127], v[72:75], v[188:191], v[124:127]
	v_mfma_f32_16x16x32_f16 v[116:119], v[56:59], v[204:207], v[116:119]
	v_mfma_f32_16x16x32_f16 v[108:111], v[72:75], v[204:207], v[108:111]
	v_mfma_f32_16x16x32_f16 v[96:99], v[56:59], v[216:219], v[96:99]
	v_mfma_f32_16x16x32_f16 v[88:91], v[72:75], v[216:219], v[88:91]
	v_mfma_f32_16x16x32_f16 v[152:155], v[64:67], v[184:187], v[152:155]
	v_mfma_f32_16x16x32_f16 v[144:147], v[76:79], v[184:187], v[144:147]
	v_mfma_f32_16x16x32_f16 v[132:135], v[64:67], v[200:203], v[132:135]
	v_mfma_f32_16x16x32_f16 v[124:127], v[76:79], v[200:203], v[124:127]
	v_mfma_f32_16x16x32_f16 v[116:119], v[64:67], v[212:215], v[116:119]
	v_mfma_f32_16x16x32_f16 v[108:111], v[76:79], v[212:215], v[108:111]
	v_mfma_f32_16x16x32_f16 v[96:99], v[64:67], v[220:223], v[96:99]
	v_mfma_f32_16x16x32_f16 v[88:91], v[76:79], v[220:223], v[88:91]
	s_setprio 0
	s_setprio 1
	v_mfma_f32_16x16x32_f16 v[148:151], v[100:103], v[164:167], v[148:151]
	v_mfma_f32_16x16x32_f16 v[140:143], v[156:159], v[164:167], v[140:143]
	v_mfma_f32_16x16x32_f16 v[128:131], v[100:103], v[188:191], v[128:131]
	v_mfma_f32_16x16x32_f16 v[120:123], v[156:159], v[188:191], v[120:123]
	v_mfma_f32_16x16x32_f16 v[112:115], v[100:103], v[204:207], v[112:115]
	v_mfma_f32_16x16x32_f16 v[104:107], v[156:159], v[204:207], v[104:107]
	v_mfma_f32_16x16x32_f16 v[92:95], v[100:103], v[216:219], v[92:95]
	v_mfma_f32_16x16x32_f16 v[84:87], v[156:159], v[216:219], v[84:87]
	v_mfma_f32_16x16x32_f16 v[148:151], v[136:139], v[184:187], v[148:151]
	v_mfma_f32_16x16x32_f16 v[140:143], v[160:163], v[184:187], v[140:143]
	v_mfma_f32_16x16x32_f16 v[128:131], v[136:139], v[200:203], v[128:131]
	v_mfma_f32_16x16x32_f16 v[120:123], v[160:163], v[200:203], v[120:123]
	v_mfma_f32_16x16x32_f16 v[112:115], v[136:139], v[212:215], v[112:115]
	v_mfma_f32_16x16x32_f16 v[104:107], v[160:163], v[212:215], v[104:107]
	v_mfma_f32_16x16x32_f16 v[92:95], v[136:139], v[220:223], v[92:95]
	v_mfma_f32_16x16x32_f16 v[84:87], v[160:163], v[220:223], v[84:87]
	s_setprio 0
	s_barrier
	s_add_i32 s95, s90, s67
	v_lshl_add_u64 v[192:193], s[74:75], 0, v[172:173]
	s_mov_b32 m0, s95
	ds_read_b128 v[164:167], v198 offset:16384
	ds_read_b128 v[184:187], v198 offset:17408
	ds_read_b128 v[188:191], v198 offset:18432
	ds_read_b128 v[200:203], v198 offset:19456
	ds_read_b128 v[204:207], v198 offset:20480
	ds_read_b128 v[212:215], v198 offset:21504
	ds_read_b128 v[216:219], v198 offset:22528
	ds_read_b128 v[220:223], v198 offset:23552
	global_load_lds_dwordx4 v[192:193], off
	s_add_i32 m0, s95, 0x2000
	s_add_u32 s96, s74, 0x40000
	v_lshl_add_u64 v[208:209], s[74:75], 0, v[168:169]
	s_addc_u32 s97, s75, 0
	s_add_i32 s95, s91, s67
	global_load_lds_dwordx4 v[208:209], off
	v_lshl_add_u64 v[210:211], s[96:97], 0, v[172:173]
	s_mov_b32 m0, s95
	v_lshl_add_u64 v[224:225], s[82:83], 0, v[170:171]
	global_load_lds_dwordx4 v[210:211], off
	v_lshl_add_u64 v[210:211], s[96:97], 0, v[168:169]
	s_add_i32 m0, s95, 0x2000
	s_nop 0
	global_load_lds_dwordx4 v[210:211], off
	v_lshl_add_u64 v[210:211], s[82:83], 0, v[174:175]
	s_mov_b32 m0, s69
	s_nop 0
	global_load_lds_dwordx4 v[210:211], off
	s_mov_b32 m0, s70
	s_nop 0
	global_load_lds_dwordx4 v[224:225], off
	s_cmp_lg_u32 s99, 0
	s_cbranch_scc1 .Lrlx15b
	s_waitcnt vmcnt(8)
.Lrlx15b_done:
	s_mov_b32 s99, 0
	s_waitcnt lgkmcnt(0)
	s_barrier
	s_setprio 1
	s_waitcnt lgkmcnt(0)
	v_mfma_f32_16x16x32_f16 v[80:83], v[56:59], v[164:167], v[80:83]
	v_mfma_f32_16x16x32_f16 v[60:63], v[72:75], v[164:167], v[60:63]
	v_mfma_f32_16x16x32_f16 v[44:47], v[56:59], v[188:191], v[44:47]
	v_mfma_f32_16x16x32_f16 v[36:39], v[72:75], v[188:191], v[36:39]
	v_mfma_f32_16x16x32_f16 v[28:31], v[56:59], v[204:207], v[28:31]
	v_mfma_f32_16x16x32_f16 v[20:23], v[72:75], v[204:207], v[20:23]
	v_mfma_f32_16x16x32_f16 v[12:15], v[56:59], v[216:219], v[12:15]
	v_mfma_f32_16x16x32_f16 v[4:7], v[72:75], v[216:219], v[4:7]
	v_mfma_f32_16x16x32_f16 v[80:83], v[64:67], v[184:187], v[80:83]
	v_mfma_f32_16x16x32_f16 v[60:63], v[76:79], v[184:187], v[60:63]
	v_mfma_f32_16x16x32_f16 v[44:47], v[64:67], v[200:203], v[44:47]
	v_mfma_f32_16x16x32_f16 v[36:39], v[76:79], v[200:203], v[36:39]
	v_mfma_f32_16x16x32_f16 v[28:31], v[64:67], v[212:215], v[28:31]
	v_mfma_f32_16x16x32_f16 v[20:23], v[76:79], v[212:215], v[20:23]
	v_mfma_f32_16x16x32_f16 v[12:15], v[64:67], v[220:223], v[12:15]
	v_mfma_f32_16x16x32_f16 v[4:7], v[76:79], v[220:223], v[4:7]
	s_setprio 0
	s_setprio 1
	v_mfma_f32_16x16x32_f16 v[48:51], v[156:159], v[164:167], v[48:51]
	v_mfma_f32_16x16x32_f16 v[40:43], v[100:103], v[188:191], v[40:43]
	v_mfma_f32_16x16x32_f16 v[32:35], v[156:159], v[188:191], v[32:35]
	v_mfma_f32_16x16x32_f16 v[24:27], v[100:103], v[204:207], v[24:27]
	v_mfma_f32_16x16x32_f16 v[16:19], v[156:159], v[204:207], v[16:19]
	v_mfma_f32_16x16x32_f16 v[8:11], v[100:103], v[216:219], v[8:11]
	v_mfma_f32_16x16x32_f16 v[0:3], v[156:159], v[216:219], v[0:3]
	v_mfma_f32_16x16x32_f16 v[56:59], v[100:103], v[164:167], v[68:71]
	v_mfma_f32_16x16x32_f16 v[48:51], v[160:163], v[184:187], v[48:51]
	v_mfma_f32_16x16x32_f16 v[40:43], v[136:139], v[200:203], v[40:43]
	v_mfma_f32_16x16x32_f16 v[32:35], v[160:163], v[200:203], v[32:35]
	v_mfma_f32_16x16x32_f16 v[24:27], v[136:139], v[212:215], v[24:27]
	v_mfma_f32_16x16x32_f16 v[16:19], v[160:163], v[212:215], v[16:19]
	v_mfma_f32_16x16x32_f16 v[8:11], v[136:139], v[220:223], v[8:11]
	v_mfma_f32_16x16x32_f16 v[0:3], v[160:163], v[220:223], v[0:3]
	v_mfma_f32_16x16x32_f16 v[56:59], v[136:139], v[184:187], v[56:59]
	s_setprio 0
	s_barrier
	s_add_i32 s95, 0, 0x18000
	s_add_i32 s96, 0, 0x1c000
	v_add_u32_e32 v76, s95, v196
	v_add_u32_e32 v160, s96, v196
	ds_read_b128 v[64:67], v76
	ds_read_b128 v[68:71], v76 offset:1024
	ds_read_b128 v[72:75], v76 offset:2048
	ds_read_b128 v[76:79], v76 offset:3072
	ds_read_b128 v[100:103], v160
	ds_read_b128 v[136:139], v160 offset:1024
	ds_read_b128 v[156:159], v160 offset:2048
	ds_read_b128 v[160:163], v160 offset:3072
	s_add_u32 s82, s82, 0x40000
	s_addc_u32 s83, s83, 0
	s_mov_b32 m0, s71
	v_lshl_add_u64 v[226:227], s[82:83], 0, v[174:175]
	ds_read_b128 v[164:167], v198 offset:32768
	ds_read_b128 v[184:187], v198 offset:33792
	ds_read_b128 v[188:191], v198 offset:34816
	ds_read_b128 v[200:203], v198 offset:35840
	ds_read_b128 v[204:207], v198 offset:36864
	ds_read_b128 v[212:215], v198 offset:37888
	ds_read_b128 v[216:219], v198 offset:38912
	ds_read_b128 v[220:223], v198 offset:39936
	global_load_lds_dwordx4 v[226:227], off
	v_lshl_add_u64 v[226:227], s[82:83], 0, v[170:171]
	s_mov_b32 m0, s72
	s_nop 0
	global_load_lds_dwordx4 v[226:227], off
	s_waitcnt vmcnt(8)
	s_waitcnt lgkmcnt(0)
	s_barrier
	s_setprio 1
	s_waitcnt lgkmcnt(0)
	v_mfma_f32_16x16x32_f16 v[152:155], v[64:67], v[164:167], v[152:155]
	v_mfma_f32_16x16x32_f16 v[144:147], v[72:75], v[164:167], v[144:147]
	v_mfma_f32_16x16x32_f16 v[132:135], v[64:67], v[188:191], v[132:135]
	v_mfma_f32_16x16x32_f16 v[124:127], v[72:75], v[188:191], v[124:127]
	v_mfma_f32_16x16x32_f16 v[116:119], v[64:67], v[204:207], v[116:119]
	v_mfma_f32_16x16x32_f16 v[108:111], v[72:75], v[204:207], v[108:111]
	v_mfma_f32_16x16x32_f16 v[96:99], v[64:67], v[216:219], v[96:99]
	v_mfma_f32_16x16x32_f16 v[88:91], v[72:75], v[216:219], v[88:91]
	v_mfma_f32_16x16x32_f16 v[152:155], v[68:71], v[184:187], v[152:155]
	v_mfma_f32_16x16x32_f16 v[144:147], v[76:79], v[184:187], v[144:147]
	v_mfma_f32_16x16x32_f16 v[132:135], v[68:71], v[200:203], v[132:135]
	v_mfma_f32_16x16x32_f16 v[124:127], v[76:79], v[200:203], v[124:127]
	v_mfma_f32_16x16x32_f16 v[116:119], v[68:71], v[212:215], v[116:119]
	v_mfma_f32_16x16x32_f16 v[108:111], v[76:79], v[212:215], v[108:111]
	v_mfma_f32_16x16x32_f16 v[96:99], v[68:71], v[220:223], v[96:99]
	v_mfma_f32_16x16x32_f16 v[88:91], v[76:79], v[220:223], v[88:91]
	s_setprio 0
	s_setprio 1
	v_mfma_f32_16x16x32_f16 v[148:151], v[100:103], v[164:167], v[148:151]
	v_mfma_f32_16x16x32_f16 v[140:143], v[156:159], v[164:167], v[140:143]
	v_mfma_f32_16x16x32_f16 v[128:131], v[100:103], v[188:191], v[128:131]
	v_mfma_f32_16x16x32_f16 v[120:123], v[156:159], v[188:191], v[120:123]
	v_mfma_f32_16x16x32_f16 v[112:115], v[100:103], v[204:207], v[112:115]
	v_mfma_f32_16x16x32_f16 v[104:107], v[156:159], v[204:207], v[104:107]
	v_mfma_f32_16x16x32_f16 v[92:95], v[100:103], v[216:219], v[92:95]
	v_mfma_f32_16x16x32_f16 v[84:87], v[156:159], v[216:219], v[84:87]
	v_mfma_f32_16x16x32_f16 v[148:151], v[136:139], v[184:187], v[148:151]
	v_mfma_f32_16x16x32_f16 v[140:143], v[160:163], v[184:187], v[140:143]
	v_mfma_f32_16x16x32_f16 v[128:131], v[136:139], v[200:203], v[128:131]
	v_mfma_f32_16x16x32_f16 v[120:123], v[160:163], v[200:203], v[120:123]
	v_mfma_f32_16x16x32_f16 v[112:115], v[136:139], v[212:215], v[112:115]
	v_mfma_f32_16x16x32_f16 v[104:107], v[160:163], v[212:215], v[104:107]
	v_mfma_f32_16x16x32_f16 v[92:95], v[136:139], v[220:223], v[92:95]
	v_mfma_f32_16x16x32_f16 v[84:87], v[160:163], v[220:223], v[84:87]
	s_setprio 0
	s_barrier
	s_add_i32 s82, s95, s67
	v_lshl_add_u64 v[192:193], v[192:193], 0, s[8:9]
	s_mov_b32 m0, s82
	ds_read_b128 v[164:167], v198 offset:49152
	ds_read_b128 v[184:187], v198 offset:50176
	ds_read_b128 v[188:191], v198 offset:51200
	ds_read_b128 v[200:203], v198 offset:52224
	ds_read_b128 v[204:207], v198 offset:53248
	ds_read_b128 v[212:215], v198 offset:54272
	ds_read_b128 v[216:219], v198 offset:55296
	ds_read_b128 v[220:223], v198 offset:56320
	global_load_lds_dwordx4 v[192:193], off
	s_add_i32 m0, s82, 0x2000
	s_add_u32 s74, s74, 0x40080
	v_lshl_add_u64 v[192:193], v[208:209], 0, s[8:9]
	s_addc_u32 s75, s75, 0
	s_add_i32 s82, s96, s67
	global_load_lds_dwordx4 v[192:193], off
	v_lshl_add_u64 v[192:193], s[74:75], 0, v[172:173]
	s_mov_b32 m0, s82
	s_nop 0
	global_load_lds_dwordx4 v[192:193], off
	v_lshl_add_u64 v[192:193], s[74:75], 0, v[168:169]
	s_add_i32 m0, s82, 0x2000
	s_nop 0
	global_load_lds_dwordx4 v[192:193], off
	v_lshl_add_u64 v[192:193], v[210:211], 0, s[8:9]
	s_mov_b32 m0, s80
	s_nop 0
	global_load_lds_dwordx4 v[192:193], off
	v_lshl_add_u64 v[192:193], v[224:225], 0, s[8:9]
	s_mov_b32 m0, s81
	s_nop 0
	global_load_lds_dwordx4 v[192:193], off
	s_waitcnt vmcnt(8)
	s_waitcnt lgkmcnt(0)
	s_barrier
	s_setprio 1
	s_waitcnt lgkmcnt(0)
	v_mfma_f32_16x16x32_f16 v[80:83], v[64:67], v[164:167], v[80:83]
	v_mfma_f32_16x16x32_f16 v[60:63], v[72:75], v[164:167], v[60:63]
	v_mfma_f32_16x16x32_f16 v[44:47], v[64:67], v[188:191], v[44:47]
	v_mfma_f32_16x16x32_f16 v[36:39], v[72:75], v[188:191], v[36:39]
	v_mfma_f32_16x16x32_f16 v[28:31], v[64:67], v[204:207], v[28:31]
	v_mfma_f32_16x16x32_f16 v[20:23], v[72:75], v[204:207], v[20:23]
	v_mfma_f32_16x16x32_f16 v[12:15], v[64:67], v[216:219], v[12:15]
	v_mfma_f32_16x16x32_f16 v[4:7], v[72:75], v[216:219], v[4:7]
	v_mfma_f32_16x16x32_f16 v[80:83], v[68:71], v[184:187], v[80:83]
	v_mfma_f32_16x16x32_f16 v[60:63], v[76:79], v[184:187], v[60:63]
	v_mfma_f32_16x16x32_f16 v[44:47], v[68:71], v[200:203], v[44:47]
	v_mfma_f32_16x16x32_f16 v[36:39], v[76:79], v[200:203], v[36:39]
	v_mfma_f32_16x16x32_f16 v[28:31], v[68:71], v[212:215], v[28:31]
	v_mfma_f32_16x16x32_f16 v[20:23], v[76:79], v[212:215], v[20:23]
	v_mfma_f32_16x16x32_f16 v[12:15], v[68:71], v[220:223], v[12:15]
	v_mfma_f32_16x16x32_f16 v[4:7], v[76:79], v[220:223], v[4:7]
	s_setprio 0
	s_setprio 1
	v_mfma_f32_16x16x32_f16 v[56:59], v[100:103], v[164:167], v[56:59]
	v_mfma_f32_16x16x32_f16 v[48:51], v[156:159], v[164:167], v[48:51]
	v_mfma_f32_16x16x32_f16 v[40:43], v[100:103], v[188:191], v[40:43]
	v_mfma_f32_16x16x32_f16 v[32:35], v[156:159], v[188:191], v[32:35]
	v_mfma_f32_16x16x32_f16 v[24:27], v[100:103], v[204:207], v[24:27]
	v_mfma_f32_16x16x32_f16 v[16:19], v[156:159], v[204:207], v[16:19]
	v_mfma_f32_16x16x32_f16 v[8:11], v[100:103], v[216:219], v[8:11]
	v_mfma_f32_16x16x32_f16 v[0:3], v[156:159], v[216:219], v[0:3]
	v_mfma_f32_16x16x32_f16 v[68:71], v[136:139], v[184:187], v[56:59]
	v_mfma_f32_16x16x32_f16 v[48:51], v[160:163], v[184:187], v[48:51]
	v_mfma_f32_16x16x32_f16 v[40:43], v[136:139], v[200:203], v[40:43]
	v_mfma_f32_16x16x32_f16 v[32:35], v[160:163], v[200:203], v[32:35]
	v_mfma_f32_16x16x32_f16 v[24:27], v[136:139], v[212:215], v[24:27]
	v_mfma_f32_16x16x32_f16 v[16:19], v[160:163], v[212:215], v[16:19]
	v_mfma_f32_16x16x32_f16 v[8:11], v[136:139], v[220:223], v[8:11]
	v_mfma_f32_16x16x32_f16 v[0:3], v[160:163], v[220:223], v[0:3]
	s_setprio 0
	s_barrier
	s_add_i32 s94, s94, 2
	s_add_u32 s46, s46, 0x100
	s_addc_u32 s47, s47, 0
	s_add_u32 s92, s92, 0x100
	s_addc_u32 s93, s93, 0
	s_cmp_gt_u32 s94, 13
	s_cbranch_scc1 .LBB0_1609

.LBB0_1611:
	s_cmp_eq_u32 s40, s66
	s_movk_i32 s15, 0x200
	s_cselect_b32 s15, s15, 0x300
	s_cmp_lg_u32 s40, s65
	v_mov_b32_e32 v64, v194
	v_mov_b32_e32 v65, v195
	s_cselect_b32 s15, s15, 0x100
	s_cmp_lg_u32 s40, s64
	s_cselect_b32 s15, s15, 0
	v_lshl_add_u32 v66, v65, 5, s85
	v_add_u32_e32 v184, s78, v64
	ds_read_b128 v[72:75], v66
	ds_read_b128 v[52:55], v66 offset:16
	ds_read_b128 v[76:79], v66 offset:256
	ds_read_b128 v[56:59], v66 offset:272
	ds_read_b128 v[202:205], v66 offset:128
	ds_read_b128 v[206:209], v66 offset:384
	ds_read_b128 v[160:163], v66 offset:144
	ds_read_b128 v[164:167], v66 offset:400
	s_lshl_b32 s35, s41, 7
	v_add_u32_e32 v64, s15, v184
	s_or_b32 s35, s35, s79
	v_lshl_add_u32 v64, v64, 3, v199
	v_lshl_add_u32 v190, v65, 3, s35
	ds_read2_b64 v[156:159], v64 offset1:16
	ds_read2_b64 v[136:139], v64 offset0:32 offset1:48
	ds_read2_b64 v[100:103], v64 offset0:128 offset1:144
	ds_read2_b64 v[64:67], v64 offset0:160 offset1:176
	s_waitcnt lgkmcnt(0)
	v_mov_b32_e32 v186, v202
	v_mov_b32_e32 v187, v72
	v_mov_b32_e32 v188, v206
	v_mov_b32_e32 v189, v76
	v_mov_b32_e32 v210, v148
	v_mov_b32_e32 v211, v152
	v_pk_fma_f32 v[212:213], v[186:187], v[156:157], v[188:189] op_sel:[0,1,0]
	v_mov_b32_e32 v76, v207
	v_pk_fma_f32 v[210:211], v[210:211], v[156:157], v[212:213] op_sel_hi:[1,0,1]
	v_mov_b32_e32 v152, v149
	v_mul_f32_e32 v72, 0xbfb8aa3b, v211
	v_exp_f32_e32 v72, v72
	v_mov_b32_e32 v202, v150
	v_lshl_add_u32 v200, s40, 8, v184
	v_ashrrev_i32_e32 v191, 31, v190
	v_add_f32_e32 v72, 1.0, v72
	v_rcp_f32_e32 v72, v72
	v_mov_b64_e32 v[184:185], s[42:43]
	v_mad_i64_i32 v[192:193], s[40:41], v200, s88, v[184:185]
	v_mul_f32_e32 v72, v211, v72
	v_mul_f32_e32 v201, v210, v72
	v_mov_b32_e32 v72, v203
	v_pk_fma_f32 v[148:149], v[72:73], v[156:157], v[76:77] op_sel:[0,1,0]
	v_mov_b32_e32 v203, v154
	v_pk_fma_f32 v[148:149], v[152:153], v[156:157], v[148:149] op_sel_hi:[1,0,1]
	v_mov_b32_e32 v153, v78
	v_mul_f32_e32 v152, 0xbfb8aa3b, v149
	v_exp_f32_e32 v152, v152
	v_mov_b32_e32 v78, v209
	v_mov_b32_e32 v154, v151
	s_andn2_b64 vcc, exec, s[10:11]
	v_add_f32_e32 v152, 1.0, v152
	v_rcp_f32_e32 v152, v152
	s_nop 0
	v_mul_f32_e32 v149, v149, v152
	v_mul_f32_e32 v210, v148, v149
	v_mov_b32_e32 v148, v204
	v_mov_b32_e32 v149, v74
	v_mov_b32_e32 v152, v208
	v_pk_fma_f32 v[206:207], v[148:149], v[156:157], v[152:153] op_sel:[0,1,0]
	s_nop 0
	v_pk_fma_f32 v[202:203], v[202:203], v[156:157], v[206:207] op_sel_hi:[1,0,1]
	s_nop 0
	v_mul_f32_e32 v74, 0xbfb8aa3b, v203
	v_exp_f32_e32 v74, v74
	s_nop 0
	v_add_f32_e32 v74, 1.0, v74
	v_rcp_f32_e32 v74, v74
	s_nop 0
	v_mul_f32_e32 v74, v203, v74
	v_mul_f32_e32 v206, v202, v74
	v_mov_b32_e32 v74, v205
	v_pk_fma_f32 v[150:151], v[74:75], v[156:157], v[78:79] op_sel:[0,1,0]
	v_mov_b32_e32 v202, v140
	v_pk_fma_f32 v[150:151], v[154:155], v[156:157], v[150:151] op_sel_hi:[1,0,1]
	v_mov_b32_e32 v155, v56
	v_mul_f32_e32 v154, 0xbfb8aa3b, v151
	v_exp_f32_e32 v154, v154
	v_mov_b32_e32 v203, v144
	v_mov_b32_e32 v56, v165
	v_mov_b32_e32 v144, v141
	v_add_f32_e32 v154, 1.0, v154
	v_rcp_f32_e32 v154, v154
	s_nop 0
	v_mul_f32_e32 v151, v151, v154
	v_mul_f32_e32 v207, v150, v151
	v_mov_b32_e32 v150, v160
	v_mov_b32_e32 v151, v52
	v_mov_b32_e32 v154, v164
	v_pk_fma_f32 v[204:205], v[150:151], v[156:157], v[154:155] op_sel:[0,1,0]
	v_mov_b32_e32 v160, v142
	v_pk_fma_f32 v[202:203], v[202:203], v[156:157], v[204:205] op_sel_hi:[1,0,1]
	s_nop 0
	v_mul_f32_e32 v52, 0xbfb8aa3b, v203
	v_exp_f32_e32 v52, v52
	s_nop 0
	v_add_f32_e32 v52, 1.0, v52
	v_rcp_f32_e32 v52, v52
	s_nop 0
	v_mul_f32_e32 v52, v203, v52
	v_mul_f32_e32 v202, v202, v52
	v_mov_b32_e32 v52, v161
	v_pk_fma_f32 v[140:141], v[52:53], v[156:157], v[56:57] op_sel:[0,1,0]
	v_mov_b32_e32 v161, v146
	v_pk_fma_f32 v[140:141], v[144:145], v[156:157], v[140:141] op_sel_hi:[1,0,1]
	v_mov_b32_e32 v145, v58
	v_mul_f32_e32 v144, 0xbfb8aa3b, v141
	v_exp_f32_e32 v144, v144
	v_mov_b32_e32 v58, v167
	v_mov_b32_e32 v146, v143
	v_add_f32_e32 v144, 1.0, v144
	v_rcp_f32_e32 v144, v144
	s_nop 0
	v_mul_f32_e32 v141, v141, v144
	v_mul_f32_e32 v203, v140, v141
	v_mov_b32_e32 v140, v162
	v_mov_b32_e32 v141, v54
	v_mov_b32_e32 v144, v166
	v_pk_fma_f32 v[164:165], v[140:141], v[156:157], v[144:145] op_sel:[0,1,0]
	s_nop 0
	v_pk_fma_f32 v[160:161], v[160:161], v[156:157], v[164:165] op_sel_hi:[1,0,1]
	s_nop 0
	v_mul_f32_e32 v54, 0xbfb8aa3b, v161
	v_exp_f32_e32 v54, v54
	s_nop 0
	v_add_f32_e32 v54, 1.0, v54
	v_rcp_f32_e32 v54, v54
	s_nop 0
	v_mul_f32_e32 v54, v161, v54
	v_mul_f32_e32 v164, v160, v54
	v_mov_b32_e32 v54, v163
	v_pk_fma_f32 v[142:143], v[54:55], v[156:157], v[58:59] op_sel:[0,1,0]
	v_cvt_pk_bf16_f32 v160, v201, v210
	v_cvt_pk_bf16_f32 v161, v206, v207
	v_cvt_pk_bf16_f32 v162, v202, v203
	s_nop 0
	v_pk_fma_f32 v[142:143], v[146:147], v[156:157], v[142:143] op_sel_hi:[1,0,1]
	v_mov_b32_e32 v157, v132
	v_mul_f32_e32 v146, 0xbfb8aa3b, v143
	v_exp_f32_e32 v146, v146
	v_mov_b32_e32 v132, v129
	v_add_f32_e32 v146, 1.0, v146
	v_rcp_f32_e32 v146, v146
	s_nop 0
	v_mul_f32_e32 v143, v143, v146
	v_mul_f32_e32 v156, v142, v143
	v_lshlrev_b64 v[142:143], 1, v[190:191]
	v_lshl_add_u64 v[146:147], v[192:193], 0, v[142:143]
	v_cvt_pk_bf16_f32 v163, v164, v156
	global_store_dwordx4 v[146:147], v[160:163], off
	v_mov_b32_e32 v156, v128
	v_add_u32_e32 v146, 16, v200
	v_pk_fma_f32 v[160:161], v[186:187], v[158:159], v[188:189] op_sel:[0,1,0]
	v_mad_i64_i32 v[146:147], s[40:41], v146, s88, v[184:185]
	v_pk_fma_f32 v[156:157], v[156:157], v[158:159], v[160:161] op_sel_hi:[1,0,1]
	s_nop 0
	v_mul_f32_e32 v128, 0xbfb8aa3b, v157
	v_exp_f32_e32 v128, v128
	s_nop 0
	v_add_f32_e32 v128, 1.0, v128
	v_rcp_f32_e32 v128, v128
	s_nop 0
	v_mul_f32_e32 v128, v157, v128
	v_mul_f32_e32 v156, v156, v128
	v_pk_fma_f32 v[128:129], v[72:73], v[158:159], v[76:77] op_sel:[0,1,0]
	s_nop 0
	v_pk_fma_f32 v[128:129], v[132:133], v[158:159], v[128:129] op_sel_hi:[1,0,1]
	s_nop 0
	v_mul_f32_e32 v132, 0xbfb8aa3b, v129
	v_exp_f32_e32 v132, v132
	s_nop 0
	v_add_f32_e32 v132, 1.0, v132
	v_rcp_f32_e32 v132, v132
	s_nop 0
	v_mul_f32_e32 v129, v129, v132
	v_mul_f32_e32 v157, v128, v129
	v_mov_b32_e32 v128, v130
	v_mov_b32_e32 v129, v134
	v_pk_fma_f32 v[132:133], v[148:149], v[158:159], v[152:153] op_sel:[0,1,0]
	v_mov_b32_e32 v134, v131
	v_pk_fma_f32 v[128:129], v[128:129], v[158:159], v[132:133] op_sel_hi:[1,0,1]
	s_nop 0
	v_mul_f32_e32 v130, 0xbfb8aa3b, v129
	v_exp_f32_e32 v130, v130
	s_nop 0
	v_add_f32_e32 v130, 1.0, v130
	v_rcp_f32_e32 v130, v130
	s_nop 0
	v_mul_f32_e32 v129, v129, v130
	v_mul_f32_e32 v132, v128, v129
	v_pk_fma_f32 v[128:129], v[74:75], v[158:159], v[78:79] op_sel:[0,1,0]
	s_nop 0
	v_pk_fma_f32 v[128:129], v[134:135], v[158:159], v[128:129] op_sel_hi:[1,0,1]
	s_nop 0
	v_mul_f32_e32 v130, 0xbfb8aa3b, v129
	v_exp_f32_e32 v130, v130
	s_nop 0
	v_add_f32_e32 v130, 1.0, v130
	v_rcp_f32_e32 v130, v130
	s_nop 0
	v_mul_f32_e32 v129, v129, v130
	v_mul_f32_e32 v133, v128, v129
	v_mov_b32_e32 v128, v120
	v_mov_b32_e32 v129, v124
	v_pk_fma_f32 v[130:131], v[150:151], v[158:159], v[154:155] op_sel:[0,1,0]
	v_mov_b32_e32 v124, v121
	v_pk_fma_f32 v[128:129], v[128:129], v[158:159], v[130:131] op_sel_hi:[1,0,1]
	s_nop 0
	v_mul_f32_e32 v120, 0xbfb8aa3b, v129
	v_exp_f32_e32 v120, v120
	s_nop 0
	v_add_f32_e32 v120, 1.0, v120
	v_rcp_f32_e32 v120, v120
	s_nop 0
	v_mul_f32_e32 v120, v129, v120
	v_mul_f32_e32 v128, v128, v120
	v_pk_fma_f32 v[120:121], v[52:53], v[158:159], v[56:57] op_sel:[0,1,0]
	s_nop 0
	v_pk_fma_f32 v[120:121], v[124:125], v[158:159], v[120:121] op_sel_hi:[1,0,1]
	s_nop 0
	v_mul_f32_e32 v124, 0xbfb8aa3b, v121
	v_exp_f32_e32 v124, v124
	s_nop 0
	v_add_f32_e32 v124, 1.0, v124
	v_rcp_f32_e32 v124, v124
	s_nop 0
	v_mul_f32_e32 v121, v121, v124
	v_mul_f32_e32 v129, v120, v121
	v_mov_b32_e32 v120, v122
	v_mov_b32_e32 v121, v126
	v_pk_fma_f32 v[124:125], v[140:141], v[158:159], v[144:145] op_sel:[0,1,0]
	v_mov_b32_e32 v126, v123
	v_pk_fma_f32 v[120:121], v[120:121], v[158:159], v[124:125] op_sel_hi:[1,0,1]
	v_lshl_add_u64 v[124:125], v[146:147], 0, v[142:143]
	v_mul_f32_e32 v122, 0xbfb8aa3b, v121
	v_exp_f32_e32 v122, v122
	s_nop 0
	v_add_f32_e32 v122, 1.0, v122
	v_rcp_f32_e32 v122, v122
	s_nop 0
	v_mul_f32_e32 v121, v121, v122
	v_mul_f32_e32 v130, v120, v121
	v_pk_fma_f32 v[120:121], v[54:55], v[158:159], v[58:59] op_sel:[0,1,0]
	s_nop 0
	v_pk_fma_f32 v[120:121], v[126:127], v[158:159], v[120:121] op_sel_hi:[1,0,1]
	s_nop 0
	v_mul_f32_e32 v122, 0xbfb8aa3b, v121
	v_exp_f32_e32 v122, v122
	s_nop 0
	v_add_f32_e32 v122, 1.0, v122
	v_rcp_f32_e32 v122, v122
	s_nop 0
	v_mul_f32_e32 v121, v121, v122
	v_mul_f32_e32 v123, v120, v121
	v_cvt_pk_bf16_f32 v120, v156, v157
	v_cvt_pk_bf16_f32 v121, v132, v133
	v_cvt_pk_bf16_f32 v122, v128, v129
	v_cvt_pk_bf16_f32 v123, v130, v123
	global_store_dwordx4 v[124:125], v[120:123], off
	v_pk_fma_f32 v[124:125], v[186:187], v[136:137], v[188:189] op_sel:[0,1,0]
	s_nop 0
	v_mov_b32_e32 v122, v112
	v_mov_b32_e32 v123, v116
	v_pk_fma_f32 v[122:123], v[122:123], v[136:137], v[124:125] op_sel_hi:[1,0,1]
	v_mov_b32_e32 v116, v113
	v_mul_f32_e32 v112, 0xbfb8aa3b, v123
	v_exp_f32_e32 v112, v112
	v_add_u32_e32 v120, 32, v200
	v_mad_i64_i32 v[120:121], s[40:41], v120, s88, v[184:185]
	v_add_f32_e32 v112, 1.0, v112
	v_rcp_f32_e32 v112, v112
	s_nop 0
	v_mul_f32_e32 v112, v123, v112
	v_mul_f32_e32 v122, v122, v112
	v_pk_fma_f32 v[112:113], v[72:73], v[136:137], v[76:77] op_sel:[0,1,0]
	s_nop 0
	v_pk_fma_f32 v[112:113], v[116:117], v[136:137], v[112:113] op_sel_hi:[1,0,1]
	s_nop 0
	v_mul_f32_e32 v116, 0xbfb8aa3b, v113
	v_exp_f32_e32 v116, v116
	s_nop 0
	v_add_f32_e32 v116, 1.0, v116
	v_rcp_f32_e32 v116, v116
	s_nop 0
	v_mul_f32_e32 v113, v113, v116
	v_mul_f32_e32 v123, v112, v113
	v_mov_b32_e32 v112, v114
	v_mov_b32_e32 v113, v118
	v_pk_fma_f32 v[116:117], v[148:149], v[136:137], v[152:153] op_sel:[0,1,0]
	v_mov_b32_e32 v118, v115
	v_pk_fma_f32 v[112:113], v[112:113], v[136:137], v[116:117] op_sel_hi:[1,0,1]
	s_nop 0
	v_mul_f32_e32 v114, 0xbfb8aa3b, v113
	v_exp_f32_e32 v114, v114
	s_nop 0
	v_add_f32_e32 v114, 1.0, v114
	v_rcp_f32_e32 v114, v114
	s_nop 0
	v_mul_f32_e32 v113, v113, v114
	v_mul_f32_e32 v116, v112, v113
	v_pk_fma_f32 v[112:113], v[74:75], v[136:137], v[78:79] op_sel:[0,1,0]
	s_nop 0
	v_pk_fma_f32 v[112:113], v[118:119], v[136:137], v[112:113] op_sel_hi:[1,0,1]
	s_nop 0
	v_mul_f32_e32 v114, 0xbfb8aa3b, v113
	v_exp_f32_e32 v114, v114
	s_nop 0
	v_add_f32_e32 v114, 1.0, v114
	v_rcp_f32_e32 v114, v114
	s_nop 0
	v_mul_f32_e32 v113, v113, v114
	v_mul_f32_e32 v117, v112, v113
	v_mov_b32_e32 v112, v104
	v_mov_b32_e32 v113, v108
	v_pk_fma_f32 v[114:115], v[150:151], v[136:137], v[154:155] op_sel:[0,1,0]
	v_mov_b32_e32 v108, v105
	v_pk_fma_f32 v[112:113], v[112:113], v[136:137], v[114:115] op_sel_hi:[1,0,1]
	s_nop 0
	v_mul_f32_e32 v104, 0xbfb8aa3b, v113
	v_exp_f32_e32 v104, v104
	s_nop 0
	v_add_f32_e32 v104, 1.0, v104
	v_rcp_f32_e32 v104, v104
	s_nop 0
	v_mul_f32_e32 v104, v113, v104
	v_mul_f32_e32 v112, v112, v104
	v_pk_fma_f32 v[104:105], v[52:53], v[136:137], v[56:57] op_sel:[0,1,0]
	s_nop 0
	v_pk_fma_f32 v[104:105], v[108:109], v[136:137], v[104:105] op_sel_hi:[1,0,1]
	s_nop 0
	v_mul_f32_e32 v108, 0xbfb8aa3b, v105
	v_exp_f32_e32 v108, v108
	s_nop 0
	v_add_f32_e32 v108, 1.0, v108
	v_rcp_f32_e32 v108, v108
	s_nop 0
	v_mul_f32_e32 v105, v105, v108
	v_mul_f32_e32 v113, v104, v105
	v_mov_b32_e32 v104, v106
	v_mov_b32_e32 v105, v110
	v_pk_fma_f32 v[108:109], v[140:141], v[136:137], v[144:145] op_sel:[0,1,0]
	v_mov_b32_e32 v110, v107
	v_pk_fma_f32 v[104:105], v[104:105], v[136:137], v[108:109] op_sel_hi:[1,0,1]
	v_lshl_add_u64 v[108:109], v[120:121], 0, v[142:143]
	v_mul_f32_e32 v106, 0xbfb8aa3b, v105
	v_exp_f32_e32 v106, v106
	s_nop 0
	v_add_f32_e32 v106, 1.0, v106
	v_rcp_f32_e32 v106, v106
	s_nop 0
	v_mul_f32_e32 v105, v105, v106
	v_mul_f32_e32 v114, v104, v105
	v_pk_fma_f32 v[104:105], v[54:55], v[136:137], v[58:59] op_sel:[0,1,0]
	s_nop 0
	v_pk_fma_f32 v[104:105], v[110:111], v[136:137], v[104:105] op_sel_hi:[1,0,1]
	s_nop 0
	v_mul_f32_e32 v106, 0xbfb8aa3b, v105
	v_exp_f32_e32 v106, v106
	s_nop 0
	v_add_f32_e32 v106, 1.0, v106
	v_rcp_f32_e32 v106, v106
	s_nop 0
	v_mul_f32_e32 v105, v105, v106
	v_mul_f32_e32 v107, v104, v105
	v_cvt_pk_bf16_f32 v104, v122, v123
	v_cvt_pk_bf16_f32 v105, v116, v117
	v_cvt_pk_bf16_f32 v106, v112, v113
	v_cvt_pk_bf16_f32 v107, v114, v107
	global_store_dwordx4 v[108:109], v[104:107], off
	v_pk_fma_f32 v[108:109], v[186:187], v[138:139], v[188:189] op_sel:[0,1,0]
	s_nop 0
	v_mov_b32_e32 v106, v92
	v_mov_b32_e32 v107, v96
	v_pk_fma_f32 v[106:107], v[106:107], v[138:139], v[108:109] op_sel_hi:[1,0,1]
	v_mov_b32_e32 v96, v93
	v_mul_f32_e32 v92, 0xbfb8aa3b, v107
	v_exp_f32_e32 v92, v92
	v_add_u32_e32 v104, 48, v200
	v_mad_i64_i32 v[104:105], s[40:41], v104, s88, v[184:185]
	v_add_f32_e32 v92, 1.0, v92
	v_rcp_f32_e32 v92, v92
	s_nop 0
	v_mul_f32_e32 v92, v107, v92
	v_mul_f32_e32 v106, v106, v92
	v_pk_fma_f32 v[92:93], v[72:73], v[138:139], v[76:77] op_sel:[0,1,0]
	s_nop 0
	v_pk_fma_f32 v[92:93], v[96:97], v[138:139], v[92:93] op_sel_hi:[1,0,1]
	s_nop 0
	v_mul_f32_e32 v96, 0xbfb8aa3b, v93
	v_exp_f32_e32 v96, v96
	s_nop 0
	v_add_f32_e32 v96, 1.0, v96
	v_rcp_f32_e32 v96, v96
	s_nop 0
	v_mul_f32_e32 v93, v93, v96
	v_mul_f32_e32 v107, v92, v93
	v_mov_b32_e32 v92, v94
	v_mov_b32_e32 v93, v98
	v_pk_fma_f32 v[96:97], v[148:149], v[138:139], v[152:153] op_sel:[0,1,0]
	v_mov_b32_e32 v98, v95
	v_pk_fma_f32 v[92:93], v[92:93], v[138:139], v[96:97] op_sel_hi:[1,0,1]
	s_nop 0
	v_mul_f32_e32 v94, 0xbfb8aa3b, v93
	v_exp_f32_e32 v94, v94
	s_nop 0
	v_add_f32_e32 v94, 1.0, v94
	v_rcp_f32_e32 v94, v94
	s_nop 0
	v_mul_f32_e32 v93, v93, v94
	v_mul_f32_e32 v96, v92, v93
	v_pk_fma_f32 v[92:93], v[74:75], v[138:139], v[78:79] op_sel:[0,1,0]
	s_nop 0
	v_pk_fma_f32 v[92:93], v[98:99], v[138:139], v[92:93] op_sel_hi:[1,0,1]
	s_nop 0
	v_mul_f32_e32 v94, 0xbfb8aa3b, v93
	v_exp_f32_e32 v94, v94
	s_nop 0
	v_add_f32_e32 v94, 1.0, v94
	v_rcp_f32_e32 v94, v94
	s_nop 0
	v_mul_f32_e32 v93, v93, v94
	v_mul_f32_e32 v97, v92, v93
	v_mov_b32_e32 v92, v84
	v_mov_b32_e32 v93, v88
	v_pk_fma_f32 v[94:95], v[150:151], v[138:139], v[154:155] op_sel:[0,1,0]
	v_mov_b32_e32 v88, v85
	v_pk_fma_f32 v[92:93], v[92:93], v[138:139], v[94:95] op_sel_hi:[1,0,1]
	s_nop 0
	v_mul_f32_e32 v84, 0xbfb8aa3b, v93
	v_exp_f32_e32 v84, v84
	s_nop 0
	v_add_f32_e32 v84, 1.0, v84
	v_rcp_f32_e32 v84, v84
	s_nop 0
	v_mul_f32_e32 v84, v93, v84
	v_mul_f32_e32 v92, v92, v84
	v_pk_fma_f32 v[84:85], v[52:53], v[138:139], v[56:57] op_sel:[0,1,0]
	s_nop 0
	v_pk_fma_f32 v[84:85], v[88:89], v[138:139], v[84:85] op_sel_hi:[1,0,1]
	s_nop 0
	v_mul_f32_e32 v88, 0xbfb8aa3b, v85
	v_exp_f32_e32 v88, v88
	s_nop 0
	v_add_f32_e32 v88, 1.0, v88
	v_rcp_f32_e32 v88, v88
	s_nop 0
	v_mul_f32_e32 v85, v85, v88
	v_mul_f32_e32 v93, v84, v85
	v_mov_b32_e32 v84, v86
	v_mov_b32_e32 v85, v90
	v_pk_fma_f32 v[88:89], v[140:141], v[138:139], v[144:145] op_sel:[0,1,0]
	v_mov_b32_e32 v90, v87
	v_pk_fma_f32 v[84:85], v[84:85], v[138:139], v[88:89] op_sel_hi:[1,0,1]
	v_lshl_add_u64 v[88:89], v[104:105], 0, v[142:143]
	v_mul_f32_e32 v86, 0xbfb8aa3b, v85
	v_exp_f32_e32 v86, v86
	s_nop 0
	v_add_f32_e32 v86, 1.0, v86
	v_rcp_f32_e32 v86, v86
	s_nop 0
	v_mul_f32_e32 v85, v85, v86
	v_mul_f32_e32 v94, v84, v85
	v_pk_fma_f32 v[84:85], v[54:55], v[138:139], v[58:59] op_sel:[0,1,0]
	s_nop 0
	v_pk_fma_f32 v[84:85], v[90:91], v[138:139], v[84:85] op_sel_hi:[1,0,1]
	s_nop 0
	v_mul_f32_e32 v86, 0xbfb8aa3b, v85
	v_exp_f32_e32 v86, v86
	s_nop 0
	v_add_f32_e32 v86, 1.0, v86
	v_rcp_f32_e32 v86, v86
	s_nop 0
	v_mul_f32_e32 v85, v85, v86
	v_mul_f32_e32 v87, v84, v85
	v_cvt_pk_bf16_f32 v84, v106, v107
	v_cvt_pk_bf16_f32 v85, v96, v97
	v_cvt_pk_bf16_f32 v86, v92, v93
	v_cvt_pk_bf16_f32 v87, v94, v87
	global_store_dwordx4 v[88:89], v[84:87], off
	v_pk_fma_f32 v[88:89], v[186:187], v[100:101], v[188:189] op_sel:[0,1,0]
	s_nop 0
	v_mov_b32_e32 v86, v68
	v_mov_b32_e32 v87, v80
	v_pk_fma_f32 v[86:87], v[86:87], v[100:101], v[88:89] op_sel_hi:[1,0,1]
	v_mov_b32_e32 v80, v69
	v_mul_f32_e32 v68, 0xbfb8aa3b, v87
	v_exp_f32_e32 v68, v68
	v_add_u32_e32 v84, 0x80, v200
	v_mad_i64_i32 v[84:85], s[40:41], v84, s88, v[184:185]
	v_add_f32_e32 v68, 1.0, v68
	v_rcp_f32_e32 v68, v68
	s_nop 0
	v_mul_f32_e32 v68, v87, v68
	v_mul_f32_e32 v86, v86, v68
	v_pk_fma_f32 v[68:69], v[72:73], v[100:101], v[76:77] op_sel:[0,1,0]
	s_nop 0
	v_pk_fma_f32 v[68:69], v[80:81], v[100:101], v[68:69] op_sel_hi:[1,0,1]
	s_nop 0
	v_mul_f32_e32 v80, 0xbfb8aa3b, v69
	v_exp_f32_e32 v80, v80
	s_nop 0
	v_add_f32_e32 v80, 1.0, v80
	v_rcp_f32_e32 v80, v80
	s_nop 0
	v_mul_f32_e32 v69, v69, v80
	v_mul_f32_e32 v87, v68, v69
	v_mov_b32_e32 v68, v70
	v_mov_b32_e32 v69, v82
	v_pk_fma_f32 v[80:81], v[148:149], v[100:101], v[152:153] op_sel:[0,1,0]
	v_mov_b32_e32 v82, v71
	v_pk_fma_f32 v[68:69], v[68:69], v[100:101], v[80:81] op_sel_hi:[1,0,1]
	s_nop 0
	v_mul_f32_e32 v70, 0xbfb8aa3b, v69
	v_exp_f32_e32 v70, v70
	s_nop 0
	v_add_f32_e32 v70, 1.0, v70
	v_rcp_f32_e32 v70, v70
	s_nop 0
	v_mul_f32_e32 v69, v69, v70
	v_mul_f32_e32 v80, v68, v69
	v_pk_fma_f32 v[68:69], v[74:75], v[100:101], v[78:79] op_sel:[0,1,0]
	s_nop 0
	v_pk_fma_f32 v[68:69], v[82:83], v[100:101], v[68:69] op_sel_hi:[1,0,1]
	s_nop 0
	v_mul_f32_e32 v70, 0xbfb8aa3b, v69
	v_exp_f32_e32 v70, v70
	s_nop 0
	v_add_f32_e32 v70, 1.0, v70
	v_rcp_f32_e32 v70, v70
	s_nop 0
	v_mul_f32_e32 v69, v69, v70
	v_mul_f32_e32 v81, v68, v69
	v_mov_b32_e32 v68, v48
	v_mov_b32_e32 v69, v60
	v_pk_fma_f32 v[70:71], v[150:151], v[100:101], v[154:155] op_sel:[0,1,0]
	v_mov_b32_e32 v60, v49
	v_pk_fma_f32 v[68:69], v[68:69], v[100:101], v[70:71] op_sel_hi:[1,0,1]
	s_nop 0
	v_mul_f32_e32 v48, 0xbfb8aa3b, v69
	v_exp_f32_e32 v48, v48
	s_nop 0
	v_add_f32_e32 v48, 1.0, v48
	v_rcp_f32_e32 v48, v48
	s_nop 0
	v_mul_f32_e32 v48, v69, v48
	v_mul_f32_e32 v68, v68, v48
	v_pk_fma_f32 v[48:49], v[52:53], v[100:101], v[56:57] op_sel:[0,1,0]
	s_nop 0
	v_pk_fma_f32 v[48:49], v[60:61], v[100:101], v[48:49] op_sel_hi:[1,0,1]
	s_nop 0
	v_mul_f32_e32 v60, 0xbfb8aa3b, v49
	v_exp_f32_e32 v60, v60
	s_nop 0
	v_add_f32_e32 v60, 1.0, v60
	v_rcp_f32_e32 v60, v60
	s_nop 0
	v_mul_f32_e32 v49, v49, v60
	v_mul_f32_e32 v69, v48, v49
	v_mov_b32_e32 v48, v50
	v_mov_b32_e32 v49, v62
	v_pk_fma_f32 v[60:61], v[140:141], v[100:101], v[144:145] op_sel:[0,1,0]
	v_mov_b32_e32 v62, v51
	v_pk_fma_f32 v[48:49], v[48:49], v[100:101], v[60:61] op_sel_hi:[1,0,1]
	v_lshl_add_u64 v[60:61], v[84:85], 0, v[142:143]
	v_mul_f32_e32 v50, 0xbfb8aa3b, v49
	v_exp_f32_e32 v50, v50
	s_nop 0
	v_add_f32_e32 v50, 1.0, v50
	v_rcp_f32_e32 v50, v50
	s_nop 0
	v_mul_f32_e32 v49, v49, v50
	v_mul_f32_e32 v70, v48, v49
	v_pk_fma_f32 v[48:49], v[54:55], v[100:101], v[58:59] op_sel:[0,1,0]
	s_nop 0
	v_pk_fma_f32 v[48:49], v[62:63], v[100:101], v[48:49] op_sel_hi:[1,0,1]
	s_nop 0
	v_mul_f32_e32 v50, 0xbfb8aa3b, v49
	v_exp_f32_e32 v50, v50
	s_nop 0
	v_add_f32_e32 v50, 1.0, v50
	v_rcp_f32_e32 v50, v50
	s_nop 0
	v_mul_f32_e32 v49, v49, v50
	v_mul_f32_e32 v51, v48, v49
	v_cvt_pk_bf16_f32 v48, v86, v87
	v_cvt_pk_bf16_f32 v49, v80, v81
	v_cvt_pk_bf16_f32 v50, v68, v69
	v_cvt_pk_bf16_f32 v51, v70, v51
	global_store_dwordx4 v[60:61], v[48:51], off
	v_pk_fma_f32 v[60:61], v[186:187], v[102:103], v[188:189] op_sel:[0,1,0]
	s_nop 0
	v_mov_b32_e32 v50, v40
	v_mov_b32_e32 v51, v44
	v_pk_fma_f32 v[50:51], v[50:51], v[102:103], v[60:61] op_sel_hi:[1,0,1]
	v_mov_b32_e32 v44, v41
	v_mul_f32_e32 v40, 0xbfb8aa3b, v51
	v_exp_f32_e32 v40, v40
	v_add_u32_e32 v48, 0x90, v200
	v_mad_i64_i32 v[48:49], s[40:41], v48, s88, v[184:185]
	v_add_f32_e32 v40, 1.0, v40
	v_rcp_f32_e32 v40, v40
	s_nop 0
	v_mul_f32_e32 v40, v51, v40
	v_mul_f32_e32 v50, v50, v40
	v_pk_fma_f32 v[40:41], v[72:73], v[102:103], v[76:77] op_sel:[0,1,0]
	s_nop 0
	v_pk_fma_f32 v[40:41], v[44:45], v[102:103], v[40:41] op_sel_hi:[1,0,1]
	s_nop 0
	v_mul_f32_e32 v44, 0xbfb8aa3b, v41
	v_exp_f32_e32 v44, v44
	s_nop 0
	v_add_f32_e32 v44, 1.0, v44
	v_rcp_f32_e32 v44, v44
	s_nop 0
	v_mul_f32_e32 v41, v41, v44
	v_mul_f32_e32 v51, v40, v41
	v_mov_b32_e32 v40, v42
	v_mov_b32_e32 v41, v46
	v_pk_fma_f32 v[44:45], v[148:149], v[102:103], v[152:153] op_sel:[0,1,0]
	v_mov_b32_e32 v46, v43
	v_pk_fma_f32 v[40:41], v[40:41], v[102:103], v[44:45] op_sel_hi:[1,0,1]
	s_nop 0
	v_mul_f32_e32 v42, 0xbfb8aa3b, v41
	v_exp_f32_e32 v42, v42
	s_nop 0
	v_add_f32_e32 v42, 1.0, v42
	v_rcp_f32_e32 v42, v42
	s_nop 0
	v_mul_f32_e32 v41, v41, v42
	v_mul_f32_e32 v44, v40, v41
	v_pk_fma_f32 v[40:41], v[74:75], v[102:103], v[78:79] op_sel:[0,1,0]
	s_nop 0
	v_pk_fma_f32 v[40:41], v[46:47], v[102:103], v[40:41] op_sel_hi:[1,0,1]
	s_nop 0
	v_mul_f32_e32 v42, 0xbfb8aa3b, v41
	v_exp_f32_e32 v42, v42
	s_nop 0
	v_add_f32_e32 v42, 1.0, v42
	v_rcp_f32_e32 v42, v42
	s_nop 0
	v_mul_f32_e32 v41, v41, v42
	v_mul_f32_e32 v45, v40, v41
	v_mov_b32_e32 v40, v32
	v_mov_b32_e32 v41, v36
	v_pk_fma_f32 v[42:43], v[150:151], v[102:103], v[154:155] op_sel:[0,1,0]
	v_mov_b32_e32 v36, v33
	v_pk_fma_f32 v[40:41], v[40:41], v[102:103], v[42:43] op_sel_hi:[1,0,1]
	s_nop 0
	v_mul_f32_e32 v32, 0xbfb8aa3b, v41
	v_exp_f32_e32 v32, v32
	s_nop 0
	v_add_f32_e32 v32, 1.0, v32
	v_rcp_f32_e32 v32, v32
	s_nop 0
	v_mul_f32_e32 v32, v41, v32
	v_mul_f32_e32 v40, v40, v32
	v_pk_fma_f32 v[32:33], v[52:53], v[102:103], v[56:57] op_sel:[0,1,0]
	s_nop 0
	v_pk_fma_f32 v[32:33], v[36:37], v[102:103], v[32:33] op_sel_hi:[1,0,1]
	s_nop 0
	v_mul_f32_e32 v36, 0xbfb8aa3b, v33
	v_exp_f32_e32 v36, v36
	s_nop 0
	v_add_f32_e32 v36, 1.0, v36
	v_rcp_f32_e32 v36, v36
	s_nop 0
	v_mul_f32_e32 v33, v33, v36
	v_mul_f32_e32 v41, v32, v33
	v_mov_b32_e32 v32, v34
	v_mov_b32_e32 v33, v38
	v_pk_fma_f32 v[36:37], v[140:141], v[102:103], v[144:145] op_sel:[0,1,0]
	v_mov_b32_e32 v38, v35
	v_pk_fma_f32 v[32:33], v[32:33], v[102:103], v[36:37] op_sel_hi:[1,0,1]
	v_lshl_add_u64 v[36:37], v[48:49], 0, v[142:143]
	v_mul_f32_e32 v34, 0xbfb8aa3b, v33
	v_exp_f32_e32 v34, v34
	s_nop 0
	v_add_f32_e32 v34, 1.0, v34
	v_rcp_f32_e32 v34, v34
	s_nop 0
	v_mul_f32_e32 v33, v33, v34
	v_mul_f32_e32 v42, v32, v33
	v_pk_fma_f32 v[32:33], v[54:55], v[102:103], v[58:59] op_sel:[0,1,0]
	s_nop 0
	v_pk_fma_f32 v[32:33], v[38:39], v[102:103], v[32:33] op_sel_hi:[1,0,1]
	s_nop 0
	v_mul_f32_e32 v34, 0xbfb8aa3b, v33
	v_exp_f32_e32 v34, v34
	s_nop 0
	v_add_f32_e32 v34, 1.0, v34
	v_rcp_f32_e32 v34, v34
	s_nop 0
	v_mul_f32_e32 v33, v33, v34
	v_mul_f32_e32 v35, v32, v33
	v_cvt_pk_bf16_f32 v32, v50, v51
	v_cvt_pk_bf16_f32 v33, v44, v45
	v_cvt_pk_bf16_f32 v34, v40, v41
	v_cvt_pk_bf16_f32 v35, v42, v35
	global_store_dwordx4 v[36:37], v[32:35], off
	v_pk_fma_f32 v[36:37], v[186:187], v[64:65], v[188:189] op_sel:[0,1,0]
	s_nop 0
	v_mov_b32_e32 v34, v24
	v_mov_b32_e32 v35, v28
	v_pk_fma_f32 v[34:35], v[34:35], v[64:65], v[36:37] op_sel_hi:[1,0,1]
	v_mov_b32_e32 v28, v25
	v_mul_f32_e32 v24, 0xbfb8aa3b, v35
	v_exp_f32_e32 v24, v24
	v_add_u32_e32 v32, 0xa0, v200
	v_mad_i64_i32 v[32:33], s[40:41], v32, s88, v[184:185]
	v_add_f32_e32 v24, 1.0, v24
	v_rcp_f32_e32 v24, v24
	s_nop 0
	v_mul_f32_e32 v24, v35, v24
	v_mul_f32_e32 v34, v34, v24
	v_pk_fma_f32 v[24:25], v[72:73], v[64:65], v[76:77] op_sel:[0,1,0]
	s_nop 0
	v_pk_fma_f32 v[24:25], v[28:29], v[64:65], v[24:25] op_sel_hi:[1,0,1]
	s_nop 0
	v_mul_f32_e32 v28, 0xbfb8aa3b, v25
	v_exp_f32_e32 v28, v28
	s_nop 0
	v_add_f32_e32 v28, 1.0, v28
	v_rcp_f32_e32 v28, v28
	s_nop 0
	v_mul_f32_e32 v25, v25, v28
	v_mul_f32_e32 v35, v24, v25
	v_mov_b32_e32 v24, v26
	v_mov_b32_e32 v25, v30
	v_pk_fma_f32 v[28:29], v[148:149], v[64:65], v[152:153] op_sel:[0,1,0]
	v_mov_b32_e32 v30, v27
	v_pk_fma_f32 v[24:25], v[24:25], v[64:65], v[28:29] op_sel_hi:[1,0,1]
	s_nop 0
	v_mul_f32_e32 v26, 0xbfb8aa3b, v25
	v_exp_f32_e32 v26, v26
	s_nop 0
	v_add_f32_e32 v26, 1.0, v26
	v_rcp_f32_e32 v26, v26
	s_nop 0
	v_mul_f32_e32 v25, v25, v26
	v_mul_f32_e32 v28, v24, v25
	v_pk_fma_f32 v[24:25], v[74:75], v[64:65], v[78:79] op_sel:[0,1,0]
	s_nop 0
	v_pk_fma_f32 v[24:25], v[30:31], v[64:65], v[24:25] op_sel_hi:[1,0,1]
	s_nop 0
	v_mul_f32_e32 v26, 0xbfb8aa3b, v25
	v_exp_f32_e32 v26, v26
	s_nop 0
	v_add_f32_e32 v26, 1.0, v26
	v_rcp_f32_e32 v26, v26
	s_nop 0
	v_mul_f32_e32 v25, v25, v26
	v_mul_f32_e32 v29, v24, v25
	v_mov_b32_e32 v24, v16
	v_mov_b32_e32 v25, v20
	v_pk_fma_f32 v[26:27], v[150:151], v[64:65], v[154:155] op_sel:[0,1,0]
	v_mov_b32_e32 v20, v17
	v_pk_fma_f32 v[24:25], v[24:25], v[64:65], v[26:27] op_sel_hi:[1,0,1]
	s_nop 0
	v_mul_f32_e32 v16, 0xbfb8aa3b, v25
	v_exp_f32_e32 v16, v16
	s_nop 0
	v_add_f32_e32 v16, 1.0, v16
	v_rcp_f32_e32 v16, v16
	s_nop 0
	v_mul_f32_e32 v16, v25, v16
	v_mul_f32_e32 v24, v24, v16
	v_pk_fma_f32 v[16:17], v[52:53], v[64:65], v[56:57] op_sel:[0,1,0]
	s_nop 0
	v_pk_fma_f32 v[16:17], v[20:21], v[64:65], v[16:17] op_sel_hi:[1,0,1]
	s_nop 0
	v_mul_f32_e32 v20, 0xbfb8aa3b, v17
	v_exp_f32_e32 v20, v20
	s_nop 0
	v_add_f32_e32 v20, 1.0, v20
	v_rcp_f32_e32 v20, v20
	s_nop 0
	v_mul_f32_e32 v17, v17, v20
	v_mul_f32_e32 v25, v16, v17
	v_mov_b32_e32 v16, v18
	v_mov_b32_e32 v17, v22
	v_pk_fma_f32 v[20:21], v[140:141], v[64:65], v[144:145] op_sel:[0,1,0]
	v_mov_b32_e32 v22, v19
	v_pk_fma_f32 v[16:17], v[16:17], v[64:65], v[20:21] op_sel_hi:[1,0,1]
	v_lshl_add_u64 v[20:21], v[32:33], 0, v[142:143]
	v_mul_f32_e32 v18, 0xbfb8aa3b, v17
	v_exp_f32_e32 v18, v18
	s_nop 0
	v_add_f32_e32 v18, 1.0, v18
	v_rcp_f32_e32 v18, v18
	s_nop 0
	v_mul_f32_e32 v17, v17, v18
	v_mul_f32_e32 v26, v16, v17
	v_pk_fma_f32 v[16:17], v[54:55], v[64:65], v[58:59] op_sel:[0,1,0]
	s_nop 0
	v_pk_fma_f32 v[16:17], v[22:23], v[64:65], v[16:17] op_sel_hi:[1,0,1]
	s_nop 0
	v_mul_f32_e32 v18, 0xbfb8aa3b, v17
	v_exp_f32_e32 v18, v18
	s_nop 0
	v_add_f32_e32 v18, 1.0, v18
	v_rcp_f32_e32 v18, v18
	s_nop 0
	v_mul_f32_e32 v17, v17, v18
	v_mul_f32_e32 v19, v16, v17
	v_cvt_pk_bf16_f32 v16, v34, v35
	v_cvt_pk_bf16_f32 v17, v28, v29
	v_cvt_pk_bf16_f32 v18, v24, v25
	v_cvt_pk_bf16_f32 v19, v26, v19
	global_store_dwordx4 v[20:21], v[16:19], off
	v_pk_fma_f32 v[20:21], v[186:187], v[66:67], v[188:189] op_sel:[0,1,0]
	s_nop 0
	v_mov_b32_e32 v18, v8
	v_mov_b32_e32 v19, v12
	v_pk_fma_f32 v[18:19], v[18:19], v[66:67], v[20:21] op_sel_hi:[1,0,1]
	v_mov_b32_e32 v12, v9
	v_mul_f32_e32 v8, 0xbfb8aa3b, v19
	v_exp_f32_e32 v8, v8
	v_add_u32_e32 v16, 0xb0, v200
	v_mad_i64_i32 v[16:17], s[40:41], v16, s88, v[184:185]
	v_add_f32_e32 v8, 1.0, v8
	v_rcp_f32_e32 v8, v8
	s_mov_b64 s[40:41], -1
	v_mul_f32_e32 v8, v19, v8
	v_mul_f32_e32 v18, v18, v8
	v_pk_fma_f32 v[8:9], v[72:73], v[66:67], v[76:77] op_sel:[0,1,0]
	s_nop 0
	v_pk_fma_f32 v[8:9], v[12:13], v[66:67], v[8:9] op_sel_hi:[1,0,1]
	s_nop 0
	v_mul_f32_e32 v12, 0xbfb8aa3b, v9
	v_exp_f32_e32 v12, v12
	s_nop 0
	v_add_f32_e32 v12, 1.0, v12
	v_rcp_f32_e32 v12, v12
	s_nop 0
	v_mul_f32_e32 v9, v9, v12
	v_mul_f32_e32 v19, v8, v9
	v_mov_b32_e32 v8, v10
	v_mov_b32_e32 v9, v14
	v_pk_fma_f32 v[12:13], v[148:149], v[66:67], v[152:153] op_sel:[0,1,0]
	v_mov_b32_e32 v14, v11
	v_pk_fma_f32 v[8:9], v[8:9], v[66:67], v[12:13] op_sel_hi:[1,0,1]
	s_nop 0
	v_mul_f32_e32 v10, 0xbfb8aa3b, v9
	v_exp_f32_e32 v10, v10
	s_nop 0
	v_add_f32_e32 v10, 1.0, v10
	v_rcp_f32_e32 v10, v10
	s_nop 0
	v_mul_f32_e32 v9, v9, v10
	v_mul_f32_e32 v12, v8, v9
	v_pk_fma_f32 v[8:9], v[74:75], v[66:67], v[78:79] op_sel:[0,1,0]
	s_nop 0
	v_pk_fma_f32 v[8:9], v[14:15], v[66:67], v[8:9] op_sel_hi:[1,0,1]
	s_nop 0
	v_mul_f32_e32 v10, 0xbfb8aa3b, v9
	v_exp_f32_e32 v10, v10
	s_nop 0
	v_add_f32_e32 v10, 1.0, v10
	v_rcp_f32_e32 v10, v10
	s_nop 0
	v_mul_f32_e32 v9, v9, v10
	v_mul_f32_e32 v13, v8, v9
	v_mov_b32_e32 v8, v0
	v_mov_b32_e32 v9, v4
	v_pk_fma_f32 v[10:11], v[150:151], v[66:67], v[154:155] op_sel:[0,1,0]
	v_mov_b32_e32 v4, v1
	v_pk_fma_f32 v[8:9], v[8:9], v[66:67], v[10:11] op_sel_hi:[1,0,1]
	s_nop 0
	v_mul_f32_e32 v0, 0xbfb8aa3b, v9
	v_exp_f32_e32 v0, v0
	s_nop 0
	v_add_f32_e32 v0, 1.0, v0
	v_rcp_f32_e32 v0, v0
	s_nop 0
	v_mul_f32_e32 v0, v9, v0
	v_mul_f32_e32 v8, v8, v0
	v_pk_fma_f32 v[0:1], v[52:53], v[66:67], v[56:57] op_sel:[0,1,0]
	s_nop 0
	v_pk_fma_f32 v[0:1], v[4:5], v[66:67], v[0:1] op_sel_hi:[1,0,1]
	s_nop 0
	v_mul_f32_e32 v4, 0xbfb8aa3b, v1
	v_exp_f32_e32 v4, v4
	s_nop 0
	v_add_f32_e32 v4, 1.0, v4
	v_rcp_f32_e32 v4, v4
	s_nop 0
	v_mul_f32_e32 v1, v1, v4
	v_mul_f32_e32 v9, v0, v1
	v_mov_b32_e32 v0, v2
	v_mov_b32_e32 v1, v6
	v_pk_fma_f32 v[4:5], v[140:141], v[66:67], v[144:145] op_sel:[0,1,0]
	v_mov_b32_e32 v6, v3
	v_pk_fma_f32 v[0:1], v[0:1], v[66:67], v[4:5] op_sel_hi:[1,0,1]
	v_lshl_add_u64 v[4:5], v[16:17], 0, v[142:143]
	v_mul_f32_e32 v2, 0xbfb8aa3b, v1
	v_exp_f32_e32 v2, v2
	s_nop 0
	v_add_f32_e32 v2, 1.0, v2
	v_rcp_f32_e32 v2, v2
	s_nop 0
	v_mul_f32_e32 v1, v1, v2
	v_mul_f32_e32 v10, v0, v1
	v_pk_fma_f32 v[0:1], v[54:55], v[66:67], v[58:59] op_sel:[0,1,0]
	s_nop 0
	v_pk_fma_f32 v[0:1], v[6:7], v[66:67], v[0:1] op_sel_hi:[1,0,1]
	s_nop 0
	v_mul_f32_e32 v2, 0xbfb8aa3b, v1
	v_exp_f32_e32 v2, v2
	s_nop 0
	v_add_f32_e32 v2, 1.0, v2
	v_rcp_f32_e32 v2, v2
	s_nop 0
	v_mul_f32_e32 v1, v1, v2
	v_mul_f32_e32 v3, v0, v1
	v_cvt_pk_bf16_f32 v0, v18, v19
	v_cvt_pk_bf16_f32 v1, v12, v13
	v_cvt_pk_bf16_f32 v2, v8, v9
	v_cvt_pk_bf16_f32 v3, v10, v3
	global_store_dwordx4 v[4:5], v[0:3], off
	s_mov_b32 s99, 1
	s_cbranch_vccnz .LBB0_1602
	s_andn2_b64 vcc, exec, s[0:1]
	s_cbranch_vccnz .LBB0_1601
	s_barrier
	s_branch .LBB0_1601

.LBB0_1673:
	v_readlane_b32 s0, v255, 32
	v_readlane_b32 s1, v255, 33
	s_and_b64 vcc, exec, s[0:1]
	s_cbranch_vccnz .LBB0_1713
	v_ashrrev_i32_e32 v2, 31, v0
	v_lshrrev_b32_e32 v2, 26, v2
	v_add_u32_e32 v2, v0, v2
	v_ashrrev_i32_e32 v137, 6, v2
	v_bfe_i32 v2, v0, 27, 1
	v_lshlrev_b32_e32 v1, 4, v0
	v_lshrrev_b32_e32 v2, 22, v2
	v_add_u32_e32 v2, v1, v2
	v_and_b32_e32 v2, 0xfffffc00, v2
	v_sub_u32_e32 v2, v1, v2
	v_lshrrev_b32_e32 v3, 4, v2
	v_bitop3_b32 v2, v3, v2, 32 bitop3:0x6c
	v_ashrrev_i32_e32 v4, 31, v2
	v_lshrrev_b32_e32 v4, 26, v4
	v_lshlrev_b32_e32 v3, 3, v137
	v_add_u32_e32 v4, v2, v4
	v_and_b32_e32 v3, -16, v3
	v_ashrrev_i32_e32 v149, 6, v4
	v_and_b32_e32 v4, 0xc0, v4
	v_add_u32_e32 v3, v149, v3
	v_lshlrev_b32_e32 v5, 5, v137
	v_sub_u32_e32 v2, v2, v4
	v_mov_b32_e32 v4, 1
	v_and_b32_e32 v147, 32, v5
	v_ashrrev_i16_sdwa v2, v4, sext(v2) dst_sel:DWORD dst_unused:UNUSED_PAD src0_sel:DWORD src1_sel:BYTE_0
	v_lshlrev_b32_e32 v5, 1, v3
	v_lshrrev_b32_e32 v6, 2, v3
	v_and_b32_e32 v7, 3, v149
	s_mov_b32 s6, 0xffffe0
	v_bfe_i32 v161, v2, 0, 16
	v_and_b32_e32 v5, 24, v5
	v_and_b32_e32 v6, 4, v6
	v_and_or_b32 v7, v3, s6, v7
	s_movk_i32 s11, 0xb00
	v_add_u32_e32 v2, v147, v161
	v_or3_b32 v5, v7, v6, v5
	v_mul_lo_u32 v3, v3, s11
	v_add_lshl_u32 v128, v2, v3, 1
	v_mul_u32_u24_e32 v3, 0xb00, v5
	v_add_u32_e32 v1, 0x2000, v1
	v_add_lshl_u32 v130, v3, v2, 1
	v_ashrrev_i32_e32 v2, 31, v1
	v_lshrrev_b32_e32 v2, 22, v2
	v_add_u32_e32 v2, v1, v2
	v_ashrrev_i32_e32 v163, 10, v2
	v_mul_i32_i24_e32 v2, 0x400, v163
	v_sub_u32_e32 v1, v1, v2
	v_lshrrev_b32_e32 v2, 4, v1
	v_bitop3_b32 v1, v2, v1, 32 bitop3:0x6c
	v_ashrrev_i32_e32 v3, 31, v1
	v_lshrrev_b32_e32 v3, 26, v3
	v_lshlrev_b32_e32 v2, 3, v163
	v_add_u32_e32 v3, v1, v3
	v_and_b32_e32 v2, -16, v2
	v_ashrrev_i32_e32 v165, 6, v3
	v_and_b32_e32 v3, 0xc0, v3
	v_add_u32_e32 v2, v165, v2
	v_lshlrev_b32_e32 v5, 5, v163
	v_sub_u32_e32 v1, v1, v3
	v_and_b32_e32 v167, 32, v5
	v_ashrrev_i16_sdwa v1, v4, sext(v1) dst_sel:DWORD dst_unused:UNUSED_PAD src0_sel:DWORD src1_sel:BYTE_0
	v_lshlrev_b32_e32 v3, 1, v2
	v_lshrrev_b32_e32 v4, 2, v2
	v_and_b32_e32 v5, 3, v165
	v_bfe_i32 v169, v1, 0, 16
	v_and_b32_e32 v3, 24, v3
	v_and_b32_e32 v4, 4, v4
	v_and_or_b32 v5, v2, s6, v5
	v_add_u32_e32 v1, v167, v169
	v_or3_b32 v3, v5, v4, v3
	v_mul_lo_u32 v2, v2, s11
	v_bfe_u32 v151, v0, 4, 2
	v_add_lshl_u32 v132, v1, v2, 1
	v_mul_u32_u24_e32 v2, 0xb00, v3
	v_and_b32_e32 v153, 15, v0
	v_add_lshl_u32 v134, v2, v1, 1
	v_mov_b32_e32 v1, v151
	v_mov_b32_e32 v0, v153
	s_add_u32 s0, s20, 0x1000
	v_lshlrev_b32_e32 v2, 3, v1
	v_mbcnt_lo_u32_b32 v1, -1, 0
	v_mbcnt_hi_u32_b32 v1, -1, v1
	v_and_b32_e32 v5, 64, v1
	v_xor_b32_e32 v4, 16, v1
	v_add_u32_e32 v5, 64, v5
	v_cmp_lt_i32_e32 vcc, v4, v5
	s_addc_u32 s1, s21, 0
	s_ashr_i32 s5, s10, 6
	s_ashr_i32 s12, s10, 8
	v_cndmask_b32_e32 v4, v1, v4, vcc
	s_and_b32 s4, s5, 3
	s_lshl_b32 s9, s5, 10
	s_lshl_b32 s15, s12, 6
	s_lshl_b32 s5, s80, 8
	v_lshlrev_b32_e32 v155, 2, v4
	v_xor_b32_e32 v4, 32, v1
	s_add_i32 s5, s5, s15
	v_cmp_lt_i32_e32 vcc, v4, v5
	v_add_u32_e32 v0, s5, v0
	v_ashrrev_i32_e32 v3, 31, v2
	v_cndmask_b32_e32 v1, v1, v4, vcc
	v_lshlrev_b32_e32 v157, 2, v1
	v_ashrrev_i32_e32 v1, 31, v0
	v_lshl_add_u64 v[6:7], v[2:3], 2, s[62:63]
	v_lshlrev_b64 v[4:5], 7, v[0:1]
	v_lshl_add_u64 v[4:5], v[6:7], 0, v[4:5]
	v_mov_b32_e32 v184, v0
	v_ashrrev_i32_e32 v185, 31, v184
	v_lshlrev_b64 v[184:185], 7, v[184:185]
	v_lshl_add_u64 v[184:185], v[6:7], 0, v[184:185]
	global_load_dwordx4 v[188:191], v[184:185], off offset:16
	global_load_dwordx4 v[192:195], v[184:185], off
	v_add_u32_e32 v184, 0x10, v0
	v_ashrrev_i32_e32 v185, 31, v184
	v_lshlrev_b64 v[184:185], 7, v[184:185]
	v_lshl_add_u64 v[184:185], v[6:7], 0, v[184:185]
	global_load_dwordx4 v[196:199], v[184:185], off offset:16
	global_load_dwordx4 v[200:203], v[184:185], off
	v_add_u32_e32 v184, 0x20, v0
	v_ashrrev_i32_e32 v185, 31, v184
	v_lshlrev_b64 v[184:185], 7, v[184:185]
	v_lshl_add_u64 v[184:185], v[6:7], 0, v[184:185]
	global_load_dwordx4 v[204:207], v[184:185], off offset:16
	global_load_dwordx4 v[208:211], v[184:185], off
	v_add_u32_e32 v184, 0x30, v0
	v_ashrrev_i32_e32 v185, 31, v184
	v_lshlrev_b64 v[184:185], 7, v[184:185]
	v_lshl_add_u64 v[184:185], v[6:7], 0, v[184:185]
	global_load_dwordx4 v[212:215], v[184:185], off offset:16
	global_load_dwordx4 v[216:219], v[184:185], off
	v_add_u32_e32 v184, 0x80, v0
	v_ashrrev_i32_e32 v185, 31, v184
	v_lshlrev_b64 v[184:185], 7, v[184:185]
	v_lshl_add_u64 v[184:185], v[6:7], 0, v[184:185]
	global_load_dwordx4 v[220:223], v[184:185], off offset:16
	global_load_dwordx4 v[224:227], v[184:185], off
	v_add_u32_e32 v184, 0x90, v0
	v_ashrrev_i32_e32 v185, 31, v184
	v_lshlrev_b64 v[184:185], 7, v[184:185]
	v_lshl_add_u64 v[184:185], v[6:7], 0, v[184:185]
	global_load_dwordx4 v[228:231], v[184:185], off offset:16
	global_load_dwordx4 v[232:235], v[184:185], off
	v_add_u32_e32 v184, 0xa0, v0
	v_ashrrev_i32_e32 v185, 31, v184
	v_lshlrev_b64 v[184:185], 7, v[184:185]
	v_lshl_add_u64 v[184:185], v[6:7], 0, v[184:185]
	global_load_dwordx4 v[236:239], v[184:185], off offset:16
	global_load_dwordx4 v[240:243], v[184:185], off
	v_add_u32_e32 v184, 0xb0, v0
	v_ashrrev_i32_e32 v185, 31, v184
	v_lshlrev_b64 v[184:185], 7, v[184:185]
	v_lshl_add_u64 v[184:185], v[6:7], 0, v[184:185]
	global_load_dwordx4 v[244:247], v[184:185], off offset:16
	global_load_dwordx4 v[248:251], v[184:185], off
	s_waitcnt vmcnt(0)
	v_mov_b32_e32 v8, v188
	v_mov_b32_e32 v9, v189
	v_mov_b32_e32 v10, v190
	v_mov_b32_e32 v11, v191
	v_mov_b32_e32 v12, v192
	v_mov_b32_e32 v13, v193
	v_mov_b32_e32 v14, v194
	v_mov_b32_e32 v15, v195
	v_add_u32_e32 v56, 0x90, v0
	v_ashrrev_i32_e32 v57, 31, v56
	v_add_u32_e32 v58, 0xa0, v0
	v_ashrrev_i32_e32 v59, 31, v58
	v_add_u32_e32 v60, 0xb0, v0
	v_ashrrev_i32_e32 v61, 31, v60
	s_lshl_b32 s66, s4, 5
	s_lshl_b32 s6, s79, 8
	s_or_b32 s6, s6, s66
	v_add_u32_e32 v2, s6, v2
	v_ashrrev_i32_e32 v3, 31, v2
	v_readlane_b32 s6, v255, 48
	v_readlane_b32 s7, v255, 49
	s_cmp_gt_i32 s80, 63
	v_readlane_b32 s34, v255, 44
	v_readlane_b32 s36, v255, 46
	v_readlane_b32 s35, v255, 45
	v_readlane_b32 s37, v255, 47
	s_mul_hi_i32 s14, s79, 0x160000
	s_mul_i32 s13, s80, 0x160000
	s_mul_hi_i32 s8, s80, 0x160000
	v_mov_b32_e32 v136, 0
	v_mov_b32_e32 v131, v136
	v_mov_b32_e32 v135, v136
	v_mov_b32_e32 v129, v136
	v_mov_b32_e32 v133, v136
	s_mov_b32 s5, 0
	v_mov_b32_e32 v5, v8
	v_mov_b32_e32 v4, v12
	v_mov_b32_e32 v16, v14
	v_mov_b32_e32 v17, v10
	v_pk_add_f32 v[4:5], v[4:5], v[16:17]
	v_add_f32_e32 v8, v13, v15
	v_add_f32_e32 v10, v9, v11
	v_mov_b32_e32 v9, v4
	v_mov_b32_e32 v11, v5
	v_pk_add_f32 v[4:5], v[8:9], v[10:11]
	ds_bpermute_b32 v9, v155, v5
	ds_bpermute_b32 v8, v155, v4
	s_waitcnt lgkmcnt(0)
	v_pk_add_f32 v[48:49], v[4:5], v[8:9]
	v_add_u32_e32 v4, 16, v0
	v_ashrrev_i32_e32 v5, 31, v4
	v_lshlrev_b64 v[8:9], 7, v[4:5]
	v_lshl_add_u64 v[12:13], v[6:7], 0, v[8:9]
	v_mov_b32_e32 v8, v196
	v_mov_b32_e32 v9, v197
	v_mov_b32_e32 v10, v198
	v_mov_b32_e32 v11, v199
	s_nop 0
	v_mov_b32_e32 v12, v200
	v_mov_b32_e32 v13, v201
	v_mov_b32_e32 v14, v202
	v_mov_b32_e32 v15, v203
	ds_bpermute_b32 v51, v157, v49
	ds_bpermute_b32 v50, v157, v48
	v_mov_b32_e32 v17, v8
	v_mov_b32_e32 v16, v12
	v_mov_b32_e32 v18, v14
	v_mov_b32_e32 v19, v10
	v_pk_add_f32 v[16:17], v[16:17], v[18:19]
	v_add_f32_e32 v8, v13, v15
	v_add_f32_e32 v10, v9, v11
	v_mov_b32_e32 v9, v16
	v_mov_b32_e32 v11, v17
	v_pk_add_f32 v[8:9], v[8:9], v[10:11]
	ds_bpermute_b32 v11, v155, v9
	ds_bpermute_b32 v10, v155, v8
	s_waitcnt lgkmcnt(0)
	v_pk_add_f32 v[52:53], v[8:9], v[10:11]
	v_add_u32_e32 v8, 32, v0
	v_ashrrev_i32_e32 v9, 31, v8
	v_lshlrev_b64 v[10:11], 7, v[8:9]
	v_lshl_add_u64 v[14:15], v[6:7], 0, v[10:11]
	v_mov_b32_e32 v10, v204
	v_mov_b32_e32 v11, v205
	v_mov_b32_e32 v12, v206
	v_mov_b32_e32 v13, v207
	s_nop 0
	v_mov_b32_e32 v14, v208
	v_mov_b32_e32 v15, v209
	v_mov_b32_e32 v16, v210
	v_mov_b32_e32 v17, v211
	ds_bpermute_b32 v55, v157, v53
	ds_bpermute_b32 v54, v157, v52
	v_mov_b32_e32 v19, v10
	v_mov_b32_e32 v18, v14
	v_mov_b32_e32 v20, v16
	v_mov_b32_e32 v21, v12
	v_pk_add_f32 v[18:19], v[18:19], v[20:21]
	v_add_f32_e32 v10, v15, v17
	v_add_f32_e32 v12, v11, v13
	v_mov_b32_e32 v11, v18
	v_mov_b32_e32 v13, v19
	v_pk_add_f32 v[10:11], v[10:11], v[12:13]
	ds_bpermute_b32 v13, v155, v11
	ds_bpermute_b32 v12, v155, v10
	s_waitcnt lgkmcnt(0)
	v_pk_add_f32 v[64:65], v[10:11], v[12:13]
	v_add_u32_e32 v10, 48, v0
	v_ashrrev_i32_e32 v11, 31, v10
	v_lshlrev_b64 v[12:13], 7, v[10:11]
	v_lshl_add_u64 v[16:17], v[6:7], 0, v[12:13]
	v_mov_b32_e32 v12, v212
	v_mov_b32_e32 v13, v213
	v_mov_b32_e32 v14, v214
	v_mov_b32_e32 v15, v215
	s_nop 0
	v_mov_b32_e32 v16, v216
	v_mov_b32_e32 v17, v217
	v_mov_b32_e32 v18, v218
	v_mov_b32_e32 v19, v219
	ds_bpermute_b32 v67, v157, v65
	ds_bpermute_b32 v66, v157, v64
	v_mov_b32_e32 v21, v12
	v_mov_b32_e32 v20, v16
	v_mov_b32_e32 v22, v18
	v_mov_b32_e32 v23, v14
	v_pk_add_f32 v[20:21], v[20:21], v[22:23]
	v_add_f32_e32 v12, v17, v19
	v_add_f32_e32 v14, v13, v15
	v_mov_b32_e32 v13, v20
	v_mov_b32_e32 v15, v21
	v_pk_add_f32 v[12:13], v[12:13], v[14:15]
	ds_bpermute_b32 v15, v155, v13
	ds_bpermute_b32 v14, v155, v12
	s_waitcnt lgkmcnt(0)
	v_pk_add_f32 v[68:69], v[12:13], v[14:15]
	v_add_u32_e32 v12, 0x80, v0
	v_ashrrev_i32_e32 v13, 31, v12
	v_lshlrev_b64 v[14:15], 7, v[12:13]
	v_lshl_add_u64 v[18:19], v[6:7], 0, v[14:15]
	v_mov_b32_e32 v14, v220
	v_mov_b32_e32 v15, v221
	v_mov_b32_e32 v16, v222
	v_mov_b32_e32 v17, v223
	s_nop 0
	v_mov_b32_e32 v18, v224
	v_mov_b32_e32 v19, v225
	v_mov_b32_e32 v20, v226
	v_mov_b32_e32 v21, v227
	v_lshlrev_b64 v[0:1], 11, v[0:1]
	v_lshl_add_u64 v[0:1], s[44:45], 0, v[0:1]
	ds_bpermute_b32 v71, v157, v69
	ds_bpermute_b32 v70, v157, v68
	v_mov_b32_e32 v23, v14
	v_mov_b32_e32 v22, v18
	v_mov_b32_e32 v24, v20
	v_mov_b32_e32 v25, v16
	v_pk_add_f32 v[22:23], v[22:23], v[24:25]
	v_add_f32_e32 v14, v19, v21
	v_add_f32_e32 v16, v15, v17
	v_mov_b32_e32 v15, v22
	v_mov_b32_e32 v17, v23
	v_pk_add_f32 v[14:15], v[14:15], v[16:17]
	ds_bpermute_b32 v17, v155, v15
	ds_bpermute_b32 v16, v155, v14
	s_waitcnt lgkmcnt(0)
	v_pk_add_f32 v[112:113], v[14:15], v[16:17]
	v_lshlrev_b64 v[14:15], 7, v[56:57]
	v_lshl_add_u64 v[18:19], v[6:7], 0, v[14:15]
	v_mov_b32_e32 v14, v228
	v_mov_b32_e32 v15, v229
	v_mov_b32_e32 v16, v230
	v_mov_b32_e32 v17, v231
	s_nop 0
	v_mov_b32_e32 v18, v232
	v_mov_b32_e32 v19, v233
	v_mov_b32_e32 v20, v234
	v_mov_b32_e32 v21, v235
	ds_bpermute_b32 v115, v157, v113
	ds_bpermute_b32 v114, v157, v112
	v_mov_b32_e32 v23, v14
	v_mov_b32_e32 v22, v18
	v_mov_b32_e32 v24, v20
	v_mov_b32_e32 v25, v16
	v_pk_add_f32 v[22:23], v[22:23], v[24:25]
	v_add_f32_e32 v14, v19, v21
	v_add_f32_e32 v16, v15, v17
	v_mov_b32_e32 v15, v22
	v_mov_b32_e32 v17, v23
	v_pk_add_f32 v[14:15], v[14:15], v[16:17]
	ds_bpermute_b32 v17, v155, v15
	ds_bpermute_b32 v16, v155, v14
	s_waitcnt lgkmcnt(0)
	v_pk_add_f32 v[116:117], v[14:15], v[16:17]
	v_lshlrev_b64 v[14:15], 7, v[58:59]
	v_lshl_add_u64 v[18:19], v[6:7], 0, v[14:15]
	v_mov_b32_e32 v14, v236
	v_mov_b32_e32 v15, v237
	v_mov_b32_e32 v16, v238
	v_mov_b32_e32 v17, v239
	s_nop 0
	v_mov_b32_e32 v18, v240
	v_mov_b32_e32 v19, v241
	v_mov_b32_e32 v20, v242
	v_mov_b32_e32 v21, v243
	ds_bpermute_b32 v119, v157, v117
	ds_bpermute_b32 v118, v157, v116
	v_mov_b32_e32 v23, v14
	v_mov_b32_e32 v22, v18
	v_mov_b32_e32 v24, v20
	v_mov_b32_e32 v25, v16
	v_pk_add_f32 v[22:23], v[22:23], v[24:25]
	v_add_f32_e32 v14, v19, v21
	v_add_f32_e32 v16, v15, v17
	v_mov_b32_e32 v15, v22
	v_mov_b32_e32 v17, v23
	v_pk_add_f32 v[14:15], v[14:15], v[16:17]
	ds_bpermute_b32 v17, v155, v15
	ds_bpermute_b32 v16, v155, v14
	s_waitcnt lgkmcnt(0)
	v_pk_add_f32 v[120:121], v[14:15], v[16:17]
	v_lshlrev_b64 v[14:15], 7, v[60:61]
	v_lshl_add_u64 v[6:7], v[6:7], 0, v[14:15]
	v_mov_b32_e32 v14, v244
	v_mov_b32_e32 v15, v245
	v_mov_b32_e32 v16, v246
	v_mov_b32_e32 v17, v247
	v_mov_b32_e32 v18, v248
	v_mov_b32_e32 v19, v249
	v_mov_b32_e32 v20, v250
	v_mov_b32_e32 v21, v251
	ds_bpermute_b32 v123, v157, v121
	ds_bpermute_b32 v122, v157, v120
	v_mov_b32_e32 v7, v14
	v_mov_b32_e32 v6, v18
	v_mov_b32_e32 v22, v20
	v_mov_b32_e32 v23, v16
	v_pk_add_f32 v[6:7], v[6:7], v[22:23]
	v_add_f32_e32 v14, v19, v21
	v_add_f32_e32 v16, v15, v17
	v_mov_b32_e32 v15, v6
	v_mov_b32_e32 v17, v7
	v_pk_add_f32 v[6:7], v[14:15], v[16:17]
	ds_bpermute_b32 v15, v155, v7
	ds_bpermute_b32 v14, v155, v6
	s_waitcnt lgkmcnt(0)
	v_pk_add_f32 v[124:125], v[6:7], v[14:15]
	v_lshlrev_b64 v[6:7], 2, v[2:3]
	v_lshlrev_b64 v[2:3], 1, v[2:3]
	v_lshl_add_u64 v[74:75], v[0:1], 0, v[2:3]
	v_lshlrev_b64 v[0:1], 11, v[4:5]
	v_lshl_add_u64 v[0:1], s[44:45], 0, v[0:1]
	v_lshl_add_u64 v[76:77], v[0:1], 0, v[2:3]
	v_lshlrev_b64 v[0:1], 11, v[8:9]
	v_lshl_add_u64 v[0:1], s[44:45], 0, v[0:1]
	v_lshl_add_u64 v[78:79], v[0:1], 0, v[2:3]
	v_lshlrev_b64 v[0:1], 11, v[10:11]
	v_lshl_add_u64 v[0:1], s[44:45], 0, v[0:1]
	v_lshl_add_u64 v[80:81], v[0:1], 0, v[2:3]
	v_lshlrev_b64 v[0:1], 11, v[12:13]
	v_lshl_add_u64 v[0:1], s[44:45], 0, v[0:1]
	v_lshl_add_u64 v[138:139], v[0:1], 0, v[2:3]
	v_lshlrev_b64 v[0:1], 11, v[56:57]
	v_lshl_add_u64 v[0:1], s[44:45], 0, v[0:1]
	v_lshl_add_u64 v[56:57], v[0:1], 0, v[2:3]
	v_lshlrev_b64 v[0:1], 11, v[58:59]
	v_lshl_add_u64 v[0:1], s[44:45], 0, v[0:1]
	v_lshl_add_u64 v[58:59], v[0:1], 0, v[2:3]
	v_lshlrev_b64 v[0:1], 11, v[60:61]
	v_lshl_add_u64 v[62:63], s[6:7], 0, v[6:7]
	v_lshl_add_u64 v[0:1], s[44:45], 0, v[0:1]
	s_cselect_b32 s7, s36, s34
	s_mul_i32 s34, s79, 0x160000
	v_lshl_add_u64 v[72:73], s[0:1], 0, v[6:7]
	v_lshl_add_u64 v[140:141], v[0:1], 0, v[2:3]
	s_cselect_b32 s6, s37, s35
	s_add_u32 s74, s7, s34
	global_load_dwordx4 v[36:39], v[62:63], off offset:16
	global_load_dwordx4 v[44:47], v[62:63], off
	global_load_dwordx4 v[32:35], v[72:73], off offset:16
	global_load_dwordx4 v[40:43], v[72:73], off
	global_load_dwordx4 v[28:31], v[74:75], off
	global_load_dwordx4 v[24:27], v[76:77], off
	global_load_dwordx4 v[20:23], v[78:79], off
	global_load_dwordx4 v[16:19], v[80:81], off
	global_load_dwordx4 v[12:15], v[138:139], off
	global_load_dwordx4 v[8:11], v[56:57], off
	global_load_dwordx4 v[4:7], v[58:59], off
	global_load_dwordx4 v[0:3], v[140:141], off
	global_load_dwordx4 v[100:103], v[62:63], off offset:528
	global_load_dwordx4 v[108:111], v[62:63], off offset:512
	global_load_dwordx4 v[96:99], v[72:73], off offset:528
	global_load_dwordx4 v[104:107], v[72:73], off offset:512
	global_load_dwordx4 v[92:95], v[74:75], off offset:256
	global_load_dwordx4 v[88:91], v[76:77], off offset:256
	global_load_dwordx4 v[84:87], v[78:79], off offset:256
	s_nop 0
	global_load_dwordx4 v[80:83], v[80:81], off offset:256
	s_nop 0
	global_load_dwordx4 v[76:79], v[138:139], off offset:256
	global_load_dwordx4 v[72:75], v[56:57], off offset:256
	global_load_dwordx4 v[60:63], v[58:59], off offset:256
	s_nop 0
	global_load_dwordx4 v[56:59], v[140:141], off offset:256
	s_addc_u32 s75, s6, s14
	s_add_i32 s67, s9, 0
	s_add_i32 m0, s67, 0x10000
	ds_bpermute_b32 v127, v157, v125
	global_load_lds_dwordx4 v130, s[74:75]
	s_add_i32 m0, s67, 0x12000
	s_add_u32 s6, s74, 0xb0000
	global_load_lds_dwordx4 v134, s[74:75]
	s_addc_u32 s7, s75, 0
	s_add_i32 m0, s67, 0x14000
	ds_bpermute_b32 v126, v157, v124
	global_load_lds_dwordx4 v130, s[6:7]
	s_add_i32 m0, s67, 0x16000
	s_add_u32 s40, s42, s13
	s_addc_u32 s41, s43, s8
	s_add_i32 s68, s67, 0x2000
	global_load_lds_dwordx4 v134, s[6:7]
	s_mov_b32 m0, s67
	s_add_u32 s6, s40, 0xb0000
	global_load_lds_dwordx4 v128, s[40:41]
	s_mov_b32 m0, s68
	s_addc_u32 s7, s41, 0
	s_add_i32 s69, s67, 0x4000
	global_load_lds_dwordx4 v132, s[40:41]
	s_mov_b32 m0, s69
	s_add_i32 s88, s67, 0x6000
	global_load_lds_dwordx4 v128, s[6:7]
	s_mov_b32 m0, s88
	s_cmp_eq_u32 s12, 1
	global_load_lds_dwordx4 v132, s[6:7]
	v_lshl_add_u64 v[138:139], s[74:75], 0, v[130:131]
	v_lshl_add_u64 v[140:141], s[74:75], 0, v[134:135]
	v_lshl_add_u64 v[142:143], s[40:41], 0, v[128:129]
	v_lshl_add_u64 v[144:145], s[40:41], 0, v[132:133]
	s_cselect_b64 s[6:7], -1, 0
	s_cmp_lg_u32 s12, 1
	s_cbranch_scc1 .LBB0_1676
	s_barrier

.LBB0_1920:
	s_add_u32 s6, s58, 0x375e000
	v_and_b32_e32 v192, 15, v8
	v_and_b32_e32 v15, 48, v8
	v_lshlrev_b32_e32 v16, 2, v8
	s_addc_u32 s7, s59, 0
	s_and_b32 s34, s11, 3
	s_lshl_b32 s8, s10, 13
	v_lshl_or_b32 v15, v192, 6, v15
	v_and_b32_e32 v17, 32, v16
	s_lshl_b32 s70, s10, 6
	v_bitop3_b32 v18, v15, s8, v17 bitop3:0xde
	s_lshl_b32 s71, s34, 5
	s_lshl_b32 s8, s34, 12
	v_bitop3_b32 v194, v15, s8, v17 bitop3:0xde
	s_add_u32 s8, s58, 0x3754000
	s_mov_b64 s[12:13], 0x80
	s_addc_u32 s9, s59, 0
	s_add_i32 m0, s41, 0x18000
	v_lshl_add_u64 v[6:7], v[6:7], 0, s[12:13]
	s_waitcnt vmcnt(2)
	s_barrier
	global_load_lds_dwordx4 v[6:7], off
	v_lshl_add_u64 v[4:5], v[4:5], 0, s[12:13]
	s_add_i32 m0, s41, 0x1a000
	s_add_i32 s72, s41, 0x8000
	s_add_i32 s73, s41, 0xa000
	global_load_lds_dwordx4 v[4:5], off
	v_lshl_add_u64 v[0:1], v[0:1], 0, s[12:13]
	s_mov_b32 m0, s72
	s_add_u32 s14, s96, 0x40080
	global_load_lds_dwordx4 v[0:1], off
	v_lshl_add_u64 v[0:1], v[2:3], 0, s[12:13]
	s_mov_b32 m0, s73
	s_addc_u32 s15, s97, 0
	global_load_lds_dwordx4 v[0:1], off
	s_add_i32 m0, s41, 0x1c000
	v_lshl_add_u64 v[0:1], s[14:15], 0, v[178:179]
	global_load_lds_dwordx4 v[0:1], off
	v_lshl_add_u64 v[0:1], s[14:15], 0, v[182:183]
	s_add_i32 m0, s41, 0x1e000
	s_lshl_b32 s78, s11, 9
	global_load_lds_dwordx4 v[0:1], off
	v_and_b32_e32 v0, 0x80, v16
	v_and_b32_e32 v1, 31, v8
	v_or3_b32 v195, v1, v0, s71
	v_lshlrev_b32_e32 v0, 14, v9
	v_and_b32_e32 v0, 0xffff8000, v0
	v_lshl_add_u32 v0, v10, 11, v0
	v_and_b32_e32 v1, 1, v9
	v_lshl_or_b32 v0, v1, 6, v0
	v_lshl_add_u32 v184, v11, 1, v0
	v_lshlrev_b32_e32 v0, 14, v12
	s_cmpk_lt_u32 s0, 0x100
	v_and_b32_e32 v0, 0xffff8000, v0
	s_waitcnt vmcnt(6)
	s_cselect_b64 s[14:15], -1, 0
	s_lshl_b32 s0, s10, 11
	s_lshl_b32 s10, s34, 9
	v_lshl_add_u32 v0, v13, 11, v0
	v_and_b32_e32 v1, 1, v12
	s_or_b32 s79, s0, s10
	v_lshl_or_b32 v0, v1, 6, v0
	v_bfe_u32 v193, v8, 4, 2
	s_add_i32 s79, s79, 0x22400
	v_mov_b32_e32 v185, v179
	v_lshl_add_u32 v186, v14, 1, v0
	v_mov_b32_e32 v187, v179
	v_mov_b64_e32 v[188:189], 0xa00
	v_mov_b64_e32 v[190:191], 0x9ff
	s_add_i32 s80, s78, 0x22500
	s_add_i32 s81, 0, 0x10000
	s_add_i32 s84, 0, 0x14000
	v_add_u32_e32 v196, 0, v18
	s_mov_b32 s34, 0x3e38aa3b
	v_mov_b32_e32 v197, 0x20400
	s_mov_b32 s85, 0
	s_barrier
	s_mov_b32 s99, 0
	s_branch .LBB0_1923

.LBB0_1926:
	v_add_u32_e32 v56, s81, v194
	v_add_u32_e32 v72, s84, v194
	ds_read_b128 v[40:43], v56
	ds_read_b128 v[44:47], v56 offset:1024
	ds_read_b128 v[48:51], v56 offset:2048
	ds_read_b128 v[56:59], v56 offset:3072
	ds_read_b128 v[60:63], v72
	ds_read_b128 v[64:67], v72 offset:1024
	ds_read_b128 v[68:71], v72 offset:2048
	ds_read_b128 v[72:75], v72 offset:3072
	s_add_u32 s92, s46, 0xfffc0080
	s_addc_u32 s93, s47, -1
	s_and_b64 s[86:87], s[96:97], exec
	s_cselect_b32 vcc_hi, s0, s93
	s_cselect_b32 vcc_lo, s37, s92
	s_cselect_b32 s97, s61, s75
	s_cselect_b32 s96, s66, s67
	v_lshl_add_u64 v[210:211], s[46:47], 0, v[184:185]
	s_add_i32 m0, s41, 0xc000
	ds_read_b128 v[100:103], v196
	ds_read_b128 v[136:139], v196 offset:1024
	ds_read_b128 v[172:175], v196 offset:2048
	ds_read_b128 v[198:201], v196 offset:3072
	ds_read_b128 v[202:205], v196 offset:4096
	ds_read_b128 v[206:209], v196 offset:5120
	ds_read_b128 v[212:215], v196 offset:6144
	ds_read_b128 v[216:219], v196 offset:7168
	global_load_lds_dwordx4 v[210:211], off
	v_lshl_add_u64 v[210:211], s[46:47], 0, v[186:187]
	s_add_i32 m0, s41, 0xe000
	s_nop 0
	global_load_lds_dwordx4 v[210:211], off
	s_cmp_lg_u32 s99, 0
	s_cbranch_scc1 .Lrlx18a
	s_waitcnt vmcnt(8)
.Lrlx18a_done:
	s_waitcnt lgkmcnt(0)
	s_barrier
	s_setprio 1
	s_waitcnt lgkmcnt(0)
	v_mfma_f32_16x16x32_f16 v[168:171], v[40:43], v[100:103], v[168:171]
	v_mfma_f32_16x16x32_f16 v[164:167], v[48:51], v[100:103], v[164:167]
	v_mfma_f32_16x16x32_f16 v[152:155], v[40:43], v[172:175], v[152:155]
	v_mfma_f32_16x16x32_f16 v[148:151], v[48:51], v[172:175], v[148:151]
	v_mfma_f32_16x16x32_f16 v[132:135], v[40:43], v[202:205], v[132:135]
	v_mfma_f32_16x16x32_f16 v[128:131], v[48:51], v[202:205], v[128:131]
	v_mfma_f32_16x16x32_f16 v[116:119], v[40:43], v[212:215], v[116:119]
	v_mfma_f32_16x16x32_f16 v[112:115], v[48:51], v[212:215], v[112:115]
	v_mfma_f32_16x16x32_f16 v[168:171], v[44:47], v[136:139], v[168:171]
	v_mfma_f32_16x16x32_f16 v[164:167], v[56:59], v[136:139], v[164:167]
	v_mfma_f32_16x16x32_f16 v[152:155], v[44:47], v[198:201], v[152:155]
	v_mfma_f32_16x16x32_f16 v[148:151], v[56:59], v[198:201], v[148:151]
	v_mfma_f32_16x16x32_f16 v[132:135], v[44:47], v[206:209], v[132:135]
	v_mfma_f32_16x16x32_f16 v[128:131], v[56:59], v[206:209], v[128:131]
	v_mfma_f32_16x16x32_f16 v[116:119], v[44:47], v[216:219], v[116:119]
	v_mfma_f32_16x16x32_f16 v[112:115], v[56:59], v[216:219], v[112:115]
	s_setprio 0
	s_setprio 1
	v_mfma_f32_16x16x32_f16 v[160:163], v[60:63], v[100:103], v[160:163]
	v_mfma_f32_16x16x32_f16 v[100:103], v[68:71], v[100:103], v[156:159]
	v_mfma_f32_16x16x32_f16 v[140:143], v[68:71], v[172:175], v[140:143]
	v_mfma_f32_16x16x32_f16 v[124:127], v[60:63], v[202:205], v[124:127]
	v_mfma_f32_16x16x32_f16 v[120:123], v[68:71], v[202:205], v[120:123]
	v_mfma_f32_16x16x32_f16 v[108:111], v[60:63], v[212:215], v[108:111]
	v_mfma_f32_16x16x32_f16 v[104:107], v[68:71], v[212:215], v[104:107]
	v_mfma_f32_16x16x32_f16 v[160:163], v[64:67], v[136:139], v[160:163]
	v_mfma_f32_16x16x32_f16 v[100:103], v[72:75], v[136:139], v[100:103]
	v_mfma_f32_16x16x32_f16 v[136:139], v[60:63], v[172:175], v[144:147]
	v_mfma_f32_16x16x32_f16 v[140:143], v[72:75], v[198:201], v[140:143]
	v_mfma_f32_16x16x32_f16 v[124:127], v[64:67], v[206:209], v[124:127]
	v_mfma_f32_16x16x32_f16 v[120:123], v[72:75], v[206:209], v[120:123]
	v_mfma_f32_16x16x32_f16 v[108:111], v[64:67], v[216:219], v[108:111]
	v_mfma_f32_16x16x32_f16 v[104:107], v[72:75], v[216:219], v[104:107]
	v_mfma_f32_16x16x32_f16 v[136:139], v[64:67], v[198:201], v[136:139]
	s_setprio 0
	s_barrier
	s_add_i32 s86, s81, s90
	v_lshl_add_u64 v[210:211], s[96:97], 0, v[178:179]
	s_mov_b32 m0, s86
	ds_read_b128 v[144:147], v196 offset:16384
	ds_read_b128 v[156:159], v196 offset:17408
	ds_read_b128 v[172:175], v196 offset:18432
	ds_read_b128 v[198:201], v196 offset:19456
	ds_read_b128 v[202:205], v196 offset:20480
	ds_read_b128 v[206:209], v196 offset:21504
	ds_read_b128 v[212:215], v196 offset:22528
	ds_read_b128 v[216:219], v196 offset:23552
	global_load_lds_dwordx4 v[210:211], off
	s_add_i32 m0, s86, 0x2000
	s_add_u32 s86, s96, 0x40000
	v_lshl_add_u64 v[228:229], s[96:97], 0, v[182:183]
	s_addc_u32 s87, s97, 0
	s_add_i32 s92, s84, s90
	global_load_lds_dwordx4 v[228:229], off
	v_lshl_add_u64 v[220:221], s[86:87], 0, v[178:179]
	s_mov_b32 m0, s92
	v_lshl_add_u64 v[230:231], vcc, 0, v[176:177]
	global_load_lds_dwordx4 v[220:221], off
	v_lshl_add_u64 v[220:221], s[86:87], 0, v[182:183]
	s_add_i32 m0, s92, 0x2000
	v_lshl_add_u64 v[232:233], vcc, 0, v[180:181]
	global_load_lds_dwordx4 v[220:221], off
	s_mov_b32 m0, s41
	s_nop 0
	global_load_lds_dwordx4 v[230:231], off
	s_mov_b32 m0, s91
	s_nop 0
	global_load_lds_dwordx4 v[232:233], off
	s_cmp_lg_u32 s99, 0
	s_cbranch_scc1 .Lrlx18b
	s_waitcnt vmcnt(8)
.Lrlx18b_done:
	s_mov_b32 s99, 0
	s_waitcnt lgkmcnt(0)
	s_barrier
	s_setprio 1
	s_waitcnt lgkmcnt(0)
	v_mfma_f32_16x16x32_f16 v[96:99], v[40:43], v[144:147], v[96:99]
	v_mfma_f32_16x16x32_f16 v[92:95], v[48:51], v[144:147], v[92:95]
	v_mfma_f32_16x16x32_f16 v[80:83], v[40:43], v[172:175], v[80:83]
	v_mfma_f32_16x16x32_f16 v[76:79], v[48:51], v[172:175], v[76:79]
	v_mfma_f32_16x16x32_f16 v[28:31], v[40:43], v[202:205], v[28:31]
	v_mfma_f32_16x16x32_f16 v[24:27], v[48:51], v[202:205], v[24:27]
	v_mfma_f32_16x16x32_f16 v[12:15], v[40:43], v[212:215], v[12:15]
	v_mfma_f32_16x16x32_f16 v[8:11], v[48:51], v[212:215], v[8:11]
	v_mfma_f32_16x16x32_f16 v[96:99], v[44:47], v[156:159], v[96:99]
	v_mfma_f32_16x16x32_f16 v[92:95], v[56:59], v[156:159], v[92:95]
	v_mfma_f32_16x16x32_f16 v[80:83], v[44:47], v[198:201], v[80:83]
	v_mfma_f32_16x16x32_f16 v[76:79], v[56:59], v[198:201], v[76:79]
	v_mfma_f32_16x16x32_f16 v[28:31], v[44:47], v[206:209], v[28:31]
	v_mfma_f32_16x16x32_f16 v[24:27], v[56:59], v[206:209], v[24:27]
	v_mfma_f32_16x16x32_f16 v[12:15], v[44:47], v[216:219], v[12:15]
	v_mfma_f32_16x16x32_f16 v[8:11], v[56:59], v[216:219], v[8:11]
	s_setprio 0
	s_setprio 1
	v_mfma_f32_16x16x32_f16 v[36:39], v[68:71], v[172:175], v[36:39]
	v_mfma_f32_16x16x32_f16 v[20:23], v[60:63], v[202:205], v[20:23]
	v_mfma_f32_16x16x32_f16 v[16:19], v[68:71], v[202:205], v[16:19]
	v_mfma_f32_16x16x32_f16 v[4:7], v[60:63], v[212:215], v[4:7]
	v_mfma_f32_16x16x32_f16 v[0:3], v[68:71], v[212:215], v[0:3]
	v_mfma_f32_16x16x32_f16 v[40:43], v[60:63], v[144:147], v[88:91]
	v_mfma_f32_16x16x32_f16 v[44:47], v[68:71], v[144:147], v[84:87]
	v_mfma_f32_16x16x32_f16 v[48:51], v[60:63], v[172:175], v[52:55]
	v_mfma_f32_16x16x32_f16 v[36:39], v[72:75], v[198:201], v[36:39]
	v_mfma_f32_16x16x32_f16 v[20:23], v[64:67], v[206:209], v[20:23]
	v_mfma_f32_16x16x32_f16 v[16:19], v[72:75], v[206:209], v[16:19]
	v_mfma_f32_16x16x32_f16 v[4:7], v[64:67], v[216:219], v[4:7]
	v_mfma_f32_16x16x32_f16 v[0:3], v[72:75], v[216:219], v[0:3]
	v_mfma_f32_16x16x32_f16 v[40:43], v[64:67], v[156:159], v[40:43]
	v_mfma_f32_16x16x32_f16 v[44:47], v[72:75], v[156:159], v[44:47]
	v_mfma_f32_16x16x32_f16 v[48:51], v[64:67], v[198:201], v[48:51]
	s_setprio 0
	s_barrier
	s_add_i32 s92, 0, 0x18000
	s_add_i32 s93, 0, 0x1c000
	v_add_u32_e32 v64, s92, v194
	v_add_u32_e32 v84, s93, v194
	ds_read_b128 v[52:55], v64
	ds_read_b128 v[56:59], v64 offset:1024
	ds_read_b128 v[60:63], v64 offset:2048
	ds_read_b128 v[64:67], v64 offset:3072
	ds_read_b128 v[68:71], v84
	ds_read_b128 v[72:75], v84 offset:1024
	ds_read_b128 v[172:175], v84 offset:2048
	ds_read_b128 v[198:201], v84 offset:3072
	s_add_u32 s86, vcc_lo, 0x40000
	s_addc_u32 s87, vcc_hi, 0
	s_mov_b32 m0, s64
	v_lshl_add_u64 v[144:145], s[86:87], 0, v[176:177]
	ds_read_b128 v[84:87], v196 offset:32768
	ds_read_b128 v[88:91], v196 offset:33792
	ds_read_b128 v[202:205], v196 offset:34816
	ds_read_b128 v[206:209], v196 offset:35840
	ds_read_b128 v[212:215], v196 offset:36864
	ds_read_b128 v[216:219], v196 offset:37888
	ds_read_b128 v[220:223], v196 offset:38912
	ds_read_b128 v[224:227], v196 offset:39936
	global_load_lds_dwordx4 v[144:145], off
	v_lshl_add_u64 v[144:145], s[86:87], 0, v[180:181]
	s_mov_b32 m0, s65
	s_nop 0
	global_load_lds_dwordx4 v[144:145], off
	s_waitcnt vmcnt(8)
	s_waitcnt lgkmcnt(0)
	s_barrier
	s_setprio 1
	s_waitcnt lgkmcnt(0)
	v_mfma_f32_16x16x32_f16 v[144:147], v[52:55], v[84:87], v[168:171]
	v_mfma_f32_16x16x32_f16 v[168:171], v[56:59], v[88:91], v[144:147]
	v_mfma_f32_16x16x32_f16 v[144:147], v[60:63], v[84:87], v[164:167]
	v_mfma_f32_16x16x32_f16 v[164:167], v[64:67], v[88:91], v[144:147]
	v_mfma_f32_16x16x32_f16 v[144:147], v[52:55], v[202:205], v[152:155]
	v_mfma_f32_16x16x32_f16 v[152:155], v[56:59], v[206:209], v[144:147]
	v_mfma_f32_16x16x32_f16 v[144:147], v[60:63], v[202:205], v[148:151]
	v_mfma_f32_16x16x32_f16 v[132:135], v[52:55], v[212:215], v[132:135]
	v_mfma_f32_16x16x32_f16 v[128:131], v[60:63], v[212:215], v[128:131]
	v_mfma_f32_16x16x32_f16 v[116:119], v[52:55], v[220:223], v[116:119]
	v_mfma_f32_16x16x32_f16 v[112:115], v[60:63], v[220:223], v[112:115]
	v_mfma_f32_16x16x32_f16 v[148:151], v[64:67], v[206:209], v[144:147]
	v_mfma_f32_16x16x32_f16 v[132:135], v[56:59], v[216:219], v[132:135]
	v_mfma_f32_16x16x32_f16 v[128:131], v[64:67], v[216:219], v[128:131]
	v_mfma_f32_16x16x32_f16 v[116:119], v[56:59], v[224:227], v[116:119]
	v_mfma_f32_16x16x32_f16 v[112:115], v[64:67], v[224:227], v[112:115]
	s_setprio 0
	s_setprio 1
	v_mfma_f32_16x16x32_f16 v[144:147], v[68:71], v[84:87], v[160:163]
	v_mfma_f32_16x16x32_f16 v[84:87], v[172:175], v[84:87], v[100:103]
	v_mfma_f32_16x16x32_f16 v[156:159], v[198:201], v[88:91], v[84:87]
	v_mfma_f32_16x16x32_f16 v[84:87], v[68:71], v[202:205], v[136:139]
	v_mfma_f32_16x16x32_f16 v[160:163], v[72:75], v[88:91], v[144:147]
	v_mfma_f32_16x16x32_f16 v[144:147], v[72:75], v[206:209], v[84:87]
	v_mfma_f32_16x16x32_f16 v[84:87], v[172:175], v[202:205], v[140:143]
	v_mfma_f32_16x16x32_f16 v[140:143], v[198:201], v[206:209], v[84:87]
	v_mfma_f32_16x16x32_f16 v[84:87], v[68:71], v[212:215], v[124:127]
	v_mfma_f32_16x16x32_f16 v[124:127], v[72:75], v[216:219], v[84:87]
	v_mfma_f32_16x16x32_f16 v[84:87], v[172:175], v[212:215], v[120:123]
	v_mfma_f32_16x16x32_f16 v[120:123], v[198:201], v[216:219], v[84:87]
	v_mfma_f32_16x16x32_f16 v[84:87], v[68:71], v[220:223], v[108:111]
	v_mfma_f32_16x16x32_f16 v[108:111], v[72:75], v[224:227], v[84:87]
	v_mfma_f32_16x16x32_f16 v[84:87], v[172:175], v[220:223], v[104:107]
	v_mfma_f32_16x16x32_f16 v[104:107], v[198:201], v[224:227], v[84:87]
	s_setprio 0
	s_barrier
	s_add_i32 s86, s92, s90
	v_lshl_add_u64 v[88:89], v[210:211], 0, s[12:13]
	s_mov_b32 m0, s86
	s_nop 1
	ds_read_b128 v[84:87], v196 offset:49152
	ds_read_b128 v[100:103], v196 offset:50176
	ds_read_b128 v[136:139], v196 offset:51200
	ds_read_b128 v[202:205], v196 offset:52224
	ds_read_b128 v[206:209], v196 offset:53248
	ds_read_b128 v[212:215], v196 offset:54272
	ds_read_b128 v[216:219], v196 offset:55296
	ds_read_b128 v[220:223], v196 offset:56320
	global_load_lds_dwordx4 v[88:89], off
	s_add_i32 m0, s86, 0x2000
	s_add_u32 s86, s96, 0x40080
	v_lshl_add_u64 v[88:89], v[228:229], 0, s[12:13]
	s_addc_u32 s87, s97, 0
	s_add_i32 s92, s93, s90
	global_load_lds_dwordx4 v[88:89], off
	v_lshl_add_u64 v[88:89], s[86:87], 0, v[178:179]
	s_mov_b32 m0, s92
	s_nop 0
	global_load_lds_dwordx4 v[88:89], off
	v_lshl_add_u64 v[88:89], s[86:87], 0, v[182:183]
	s_add_i32 m0, s92, 0x2000
	s_nop 0
	global_load_lds_dwordx4 v[88:89], off
	v_lshl_add_u64 v[88:89], v[230:231], 0, s[12:13]
	s_mov_b32 m0, s72
	s_nop 0
	global_load_lds_dwordx4 v[88:89], off
	v_lshl_add_u64 v[88:89], v[232:233], 0, s[12:13]
	s_mov_b32 m0, s73
	s_nop 0
	global_load_lds_dwordx4 v[88:89], off
	s_waitcnt vmcnt(8)
	s_waitcnt lgkmcnt(0)
	s_barrier
	s_setprio 1
	s_waitcnt lgkmcnt(0)
	v_mfma_f32_16x16x32_f16 v[88:91], v[52:55], v[84:87], v[96:99]
	v_mfma_f32_16x16x32_f16 v[96:99], v[56:59], v[100:103], v[88:91]
	v_mfma_f32_16x16x32_f16 v[88:91], v[60:63], v[84:87], v[92:95]
	v_mfma_f32_16x16x32_f16 v[80:83], v[52:55], v[136:139], v[80:83]
	v_mfma_f32_16x16x32_f16 v[76:79], v[60:63], v[136:139], v[76:79]
	v_mfma_f32_16x16x32_f16 v[28:31], v[52:55], v[206:209], v[28:31]
	v_mfma_f32_16x16x32_f16 v[24:27], v[60:63], v[206:209], v[24:27]
	v_mfma_f32_16x16x32_f16 v[12:15], v[52:55], v[216:219], v[12:15]
	v_mfma_f32_16x16x32_f16 v[8:11], v[60:63], v[216:219], v[8:11]
	v_mfma_f32_16x16x32_f16 v[92:95], v[64:67], v[100:103], v[88:91]
	v_mfma_f32_16x16x32_f16 v[80:83], v[56:59], v[202:205], v[80:83]
	v_mfma_f32_16x16x32_f16 v[76:79], v[64:67], v[202:205], v[76:79]
	v_mfma_f32_16x16x32_f16 v[28:31], v[56:59], v[212:215], v[28:31]
	v_mfma_f32_16x16x32_f16 v[24:27], v[64:67], v[212:215], v[24:27]
	v_mfma_f32_16x16x32_f16 v[12:15], v[56:59], v[220:223], v[12:15]
	v_mfma_f32_16x16x32_f16 v[8:11], v[64:67], v[220:223], v[8:11]
	s_setprio 0
	s_setprio 1
	v_mfma_f32_16x16x32_f16 v[40:43], v[68:71], v[84:87], v[40:43]
	v_mfma_f32_16x16x32_f16 v[88:91], v[72:75], v[100:103], v[40:43]
	v_mfma_f32_16x16x32_f16 v[40:43], v[172:175], v[84:87], v[44:47]
	v_mfma_f32_16x16x32_f16 v[84:87], v[198:201], v[100:103], v[40:43]
	v_mfma_f32_16x16x32_f16 v[40:43], v[68:71], v[136:139], v[48:51]
	v_mfma_f32_16x16x32_f16 v[36:39], v[172:175], v[136:139], v[36:39]
	v_mfma_f32_16x16x32_f16 v[20:23], v[68:71], v[206:209], v[20:23]
	v_mfma_f32_16x16x32_f16 v[16:19], v[172:175], v[206:209], v[16:19]
	v_mfma_f32_16x16x32_f16 v[4:7], v[68:71], v[216:219], v[4:7]
	v_mfma_f32_16x16x32_f16 v[0:3], v[172:175], v[216:219], v[0:3]
	v_mfma_f32_16x16x32_f16 v[52:55], v[72:75], v[202:205], v[40:43]
	v_mfma_f32_16x16x32_f16 v[36:39], v[198:201], v[202:205], v[36:39]
	v_mfma_f32_16x16x32_f16 v[20:23], v[72:75], v[212:215], v[20:23]
	v_mfma_f32_16x16x32_f16 v[16:19], v[198:201], v[212:215], v[16:19]
	v_mfma_f32_16x16x32_f16 v[4:7], v[72:75], v[220:223], v[4:7]
	v_mfma_f32_16x16x32_f16 v[0:3], v[198:201], v[220:223], v[0:3]
	s_setprio 0
	s_barrier
	s_add_i32 s83, s83, 2
	s_add_u32 s46, s46, 0x100
	s_addc_u32 s47, s47, 0
	s_add_u32 s67, s67, 0x100
	s_addc_u32 s75, s75, 0
	s_cmp_gt_u32 s83, 13
	s_cbranch_scc1 .LBB0_1929

.LBB0_2027:
	s_andn2_b64 vcc, exec, s[10:11]
	s_mov_b64 s[10:11], -1
	v_cvt_pk_bf16_f32 v0, v10, v12
	v_cvt_pk_bf16_f32 v1, v14, v17
	v_cvt_pk_bf16_f32 v2, v11, v13
	v_cvt_pk_bf16_f32 v3, v15, v16
	global_store_dwordx4 v[8:9], v[0:3], off offset:256
	s_mov_b32 s99, 1
	s_cbranch_vccnz .LBB0_1922
	s_andn2_b64 vcc, exec, s[4:5]
	s_cbranch_vccnz .LBB0_1921
	s_barrier
	s_branch .LBB0_1921

.LBB0_2361:
	v_readlane_b32 s0, v255, 32
	v_readlane_b32 s1, v255, 33
	s_and_b64 vcc, exec, s[0:1]
	s_cbranch_vccnz .LBB0_2397
	v_ashrrev_i32_e32 v2, 31, v0
	v_lshrrev_b32_e32 v2, 26, v2
	v_add_u32_e32 v2, v0, v2
	v_ashrrev_i32_e32 v137, 6, v2
	v_bfe_i32 v2, v0, 27, 1
	v_lshlrev_b32_e32 v1, 4, v0
	v_lshrrev_b32_e32 v2, 22, v2
	v_add_u32_e32 v2, v1, v2
	v_and_b32_e32 v2, 0xfffffc00, v2
	v_sub_u32_e32 v2, v1, v2
	v_lshrrev_b32_e32 v3, 4, v2
	v_bitop3_b32 v2, v3, v2, 32 bitop3:0x6c
	v_ashrrev_i32_e32 v4, 31, v2
	v_lshrrev_b32_e32 v4, 26, v4
	v_add_u32_e32 v4, v2, v4
	v_lshlrev_b32_e32 v3, 3, v137
	v_ashrrev_i32_e32 v147, 6, v4
	v_and_b32_e32 v4, 0xc0, v4
	v_and_b32_e32 v3, -16, v3
	v_sub_u32_e32 v2, v2, v4
	v_mov_b32_e32 v4, 1
	v_add_u32_e32 v3, v147, v3
	v_ashrrev_i16_sdwa v2, v4, sext(v2) dst_sel:DWORD dst_unused:UNUSED_PAD src0_sel:DWORD src1_sel:BYTE_0
	v_lshlrev_b32_e32 v5, 5, v137
	v_bfe_i32 v149, v2, 0, 16
	v_lshlrev_b32_e32 v2, 1, v3
	v_lshrrev_b32_e32 v6, 2, v3
	v_and_b32_e32 v7, 3, v147
	s_mov_b32 s6, 0x1fffe0
	v_and_b32_e32 v5, 32, v5
	v_and_b32_e32 v2, 24, v2
	v_and_b32_e32 v6, 4, v6
	v_and_or_b32 v7, v3, s6, v7
	v_or3_b32 v2, v7, v6, v2
	v_add_lshl_u32 v5, v5, v149, 1
	v_add_u32_e32 v1, 0x2000, v1
	v_lshl_add_u32 v130, v2, 11, v5
	v_ashrrev_i32_e32 v2, 31, v1
	v_lshrrev_b32_e32 v2, 22, v2
	v_add_u32_e32 v2, v1, v2
	v_ashrrev_i32_e32 v161, 10, v2
	v_mul_i32_i24_e32 v2, 0x400, v161
	v_sub_u32_e32 v1, v1, v2
	v_lshrrev_b32_e32 v2, 4, v1
	v_bitop3_b32 v1, v2, v1, 32 bitop3:0x6c
	v_lshl_add_u32 v128, v3, 11, v5
	v_ashrrev_i32_e32 v3, 31, v1
	v_lshrrev_b32_e32 v3, 26, v3
	v_add_u32_e32 v3, v1, v3
	v_lshlrev_b32_e32 v2, 3, v161
	v_ashrrev_i32_e32 v163, 6, v3
	v_and_b32_e32 v3, 0xc0, v3
	v_and_b32_e32 v2, -16, v2
	v_sub_u32_e32 v1, v1, v3
	v_add_u32_e32 v2, v163, v2
	v_ashrrev_i16_sdwa v1, v4, sext(v1) dst_sel:DWORD dst_unused:UNUSED_PAD src0_sel:DWORD src1_sel:BYTE_0
	v_lshlrev_b32_e32 v5, 5, v161
	v_bfe_i32 v165, v1, 0, 16
	v_lshlrev_b32_e32 v1, 1, v2
	v_lshrrev_b32_e32 v3, 2, v2
	v_and_b32_e32 v4, 3, v163
	v_and_b32_e32 v5, 32, v5
	v_and_b32_e32 v1, 24, v1
	v_and_b32_e32 v3, 4, v3
	v_and_or_b32 v4, v2, s6, v4
	v_bfe_u32 v151, v0, 4, 2
	v_or3_b32 v1, v4, v3, v1
	v_add_lshl_u32 v3, v5, v165, 1
	v_and_b32_e32 v153, 15, v0
	v_lshl_add_u32 v134, v1, 11, v3
	v_mov_b32_e32 v0, v153
	v_mov_b32_e32 v1, v151
	v_lshl_add_u32 v132, v2, 11, v3
	v_lshlrev_b32_e32 v2, 3, v1
	v_mbcnt_lo_u32_b32 v1, -1, 0
	v_mbcnt_hi_u32_b32 v1, -1, v1
	v_and_b32_e32 v5, 64, v1
	v_xor_b32_e32 v4, 16, v1
	v_add_u32_e32 v5, 64, v5
	s_add_u32 s0, s30, 0x1000
	v_cmp_lt_i32_e32 vcc, v4, v5
	s_addc_u32 s1, s31, 0
	s_ashr_i32 s5, s10, 6
	s_ashr_i32 s11, s10, 8
	v_cndmask_b32_e32 v4, v1, v4, vcc
	s_and_b32 s4, s5, 3
	s_lshl_b32 s9, s5, 10
	s_lshl_b32 s13, s11, 6
	s_lshl_b32 s5, s96, 8
	v_lshlrev_b32_e32 v155, 2, v4
	v_xor_b32_e32 v4, 32, v1
	s_add_i32 s5, s5, s13
	v_cmp_lt_i32_e32 vcc, v4, v5
	v_add_u32_e32 v0, s5, v0
	v_ashrrev_i32_e32 v3, 31, v2
	v_cndmask_b32_e32 v1, v1, v4, vcc
	v_lshlrev_b32_e32 v157, 2, v1
	v_ashrrev_i32_e32 v1, 31, v0
	v_lshl_add_u64 v[4:5], v[2:3], 2, s[76:77]
	v_lshlrev_b64 v[6:7], 7, v[0:1]
	v_lshl_add_u64 v[10:11], v[4:5], 0, v[6:7]
	v_mov_b32_e32 v184, v0
	v_ashrrev_i32_e32 v185, 31, v184
	v_lshlrev_b64 v[184:185], 7, v[184:185]
	v_lshl_add_u64 v[184:185], v[4:5], 0, v[184:185]
	global_load_dwordx4 v[188:191], v[184:185], off offset:16
	global_load_dwordx4 v[192:195], v[184:185], off
	v_add_u32_e32 v184, 0x10, v0
	v_ashrrev_i32_e32 v185, 31, v184
	v_lshlrev_b64 v[184:185], 7, v[184:185]
	v_lshl_add_u64 v[184:185], v[4:5], 0, v[184:185]
	global_load_dwordx4 v[196:199], v[184:185], off offset:16
	global_load_dwordx4 v[200:203], v[184:185], off
	v_add_u32_e32 v184, 0x20, v0
	v_ashrrev_i32_e32 v185, 31, v184
	v_lshlrev_b64 v[184:185], 7, v[184:185]
	v_lshl_add_u64 v[184:185], v[4:5], 0, v[184:185]
	global_load_dwordx4 v[204:207], v[184:185], off offset:16
	global_load_dwordx4 v[208:211], v[184:185], off
	v_add_u32_e32 v184, 0x30, v0
	v_ashrrev_i32_e32 v185, 31, v184
	v_lshlrev_b64 v[184:185], 7, v[184:185]
	v_lshl_add_u64 v[184:185], v[4:5], 0, v[184:185]
	global_load_dwordx4 v[212:215], v[184:185], off offset:16
	global_load_dwordx4 v[216:219], v[184:185], off
	v_add_u32_e32 v184, 0x80, v0
	v_ashrrev_i32_e32 v185, 31, v184
	v_lshlrev_b64 v[184:185], 7, v[184:185]
	v_lshl_add_u64 v[184:185], v[4:5], 0, v[184:185]
	global_load_dwordx4 v[220:223], v[184:185], off offset:16
	global_load_dwordx4 v[224:227], v[184:185], off
	v_add_u32_e32 v184, 0x90, v0
	v_ashrrev_i32_e32 v185, 31, v184
	v_lshlrev_b64 v[184:185], 7, v[184:185]
	v_lshl_add_u64 v[184:185], v[4:5], 0, v[184:185]
	global_load_dwordx4 v[228:231], v[184:185], off offset:16
	global_load_dwordx4 v[232:235], v[184:185], off
	v_add_u32_e32 v184, 0xa0, v0
	v_ashrrev_i32_e32 v185, 31, v184
	v_lshlrev_b64 v[184:185], 7, v[184:185]
	v_lshl_add_u64 v[184:185], v[4:5], 0, v[184:185]
	global_load_dwordx4 v[236:239], v[184:185], off offset:16
	global_load_dwordx4 v[240:243], v[184:185], off
	v_add_u32_e32 v184, 0xb0, v0
	v_ashrrev_i32_e32 v185, 31, v184
	v_lshlrev_b64 v[184:185], 7, v[184:185]
	v_lshl_add_u64 v[184:185], v[4:5], 0, v[184:185]
	global_load_dwordx4 v[244:247], v[184:185], off offset:16
	global_load_dwordx4 v[248:251], v[184:185], off
	s_waitcnt vmcnt(0)
	v_mov_b32_e32 v6, v188
	v_mov_b32_e32 v7, v189
	v_mov_b32_e32 v8, v190
	v_mov_b32_e32 v9, v191
	s_nop 0
	v_mov_b32_e32 v10, v192
	v_mov_b32_e32 v11, v193
	v_mov_b32_e32 v12, v194
	v_mov_b32_e32 v13, v195
	s_waitcnt vmcnt(3)
	v_add_u32_e32 v56, 0x90, v0
	v_ashrrev_i32_e32 v57, 31, v56
	v_add_u32_e32 v58, 0xa0, v0
	v_ashrrev_i32_e32 v59, 31, v58
	s_waitcnt vmcnt(2)
	v_add_u32_e32 v60, 0xb0, v0
	v_ashrrev_i32_e32 v61, 31, v60
	s_lshl_b32 s66, s4, 5
	s_lshl_b32 s6, s94, 8
	s_or_b32 s6, s6, s66
	v_add_u32_e32 v2, s6, v2
	v_ashrrev_i32_e32 v3, 31, v2
	s_ashr_i32 s97, s96, 31
	s_lshl_b64 s[6:7], s[96:97], 19
	v_readlane_b32 s14, v255, 34
	v_readlane_b32 s34, v255, 36
	s_cmp_gt_i32 s96, 63
	v_readlane_b32 s15, v255, 35
	v_readlane_b32 s35, v255, 37
	s_cselect_b32 s8, s35, s15
	s_cselect_b32 s12, s34, s14
	s_ashr_i32 s95, s94, 31
	s_lshl_b64 s[14:15], s[94:95], 19
	s_add_u32 s40, s12, s14
	s_addc_u32 s41, s8, s15
	s_add_i32 s67, s9, 0
	s_add_i32 m0, s67, 0x10000
	v_mov_b32_e32 v136, 0
	v_mov_b32_e32 v131, v136
	v_mov_b32_e32 v135, v136
	v_mov_b32_e32 v129, v136
	v_mov_b32_e32 v133, v136
	s_mov_b32 s5, 0
	v_mov_b32_e32 v15, v6
	v_mov_b32_e32 v14, v10
	v_mov_b32_e32 v16, v12
	v_mov_b32_e32 v17, v8
	v_pk_add_f32 v[14:15], v[14:15], v[16:17]
	v_add_f32_e32 v6, v11, v13
	v_add_f32_e32 v8, v7, v9
	v_mov_b32_e32 v7, v14
	v_mov_b32_e32 v9, v15
	v_pk_add_f32 v[6:7], v[6:7], v[8:9]
	ds_bpermute_b32 v9, v155, v7
	ds_bpermute_b32 v8, v155, v6
	s_waitcnt lgkmcnt(0)
	v_pk_add_f32 v[48:49], v[6:7], v[8:9]
	v_add_u32_e32 v6, 16, v0
	v_ashrrev_i32_e32 v7, 31, v6
	v_lshlrev_b64 v[8:9], 7, v[6:7]
	v_lshl_add_u64 v[12:13], v[4:5], 0, v[8:9]
	v_mov_b32_e32 v8, v196
	v_mov_b32_e32 v9, v197
	v_mov_b32_e32 v10, v198
	v_mov_b32_e32 v11, v199
	s_nop 0
	v_mov_b32_e32 v12, v200
	v_mov_b32_e32 v13, v201
	v_mov_b32_e32 v14, v202
	v_mov_b32_e32 v15, v203
	ds_bpermute_b32 v51, v157, v49
	ds_bpermute_b32 v50, v157, v48
	v_mov_b32_e32 v17, v8
	v_mov_b32_e32 v16, v12
	v_mov_b32_e32 v18, v14
	v_mov_b32_e32 v19, v10
	v_pk_add_f32 v[16:17], v[16:17], v[18:19]
	v_add_f32_e32 v8, v13, v15
	v_add_f32_e32 v10, v9, v11
	v_mov_b32_e32 v9, v16
	v_mov_b32_e32 v11, v17
	v_pk_add_f32 v[8:9], v[8:9], v[10:11]
	ds_bpermute_b32 v11, v155, v9
	ds_bpermute_b32 v10, v155, v8
	s_waitcnt lgkmcnt(0)
	v_pk_add_f32 v[52:53], v[8:9], v[10:11]
	v_add_u32_e32 v8, 32, v0
	v_ashrrev_i32_e32 v9, 31, v8
	v_lshlrev_b64 v[10:11], 7, v[8:9]
	v_lshl_add_u64 v[14:15], v[4:5], 0, v[10:11]
	v_mov_b32_e32 v10, v204
	v_mov_b32_e32 v11, v205
	v_mov_b32_e32 v12, v206
	v_mov_b32_e32 v13, v207
	s_nop 0
	v_mov_b32_e32 v14, v208
	v_mov_b32_e32 v15, v209
	v_mov_b32_e32 v16, v210
	v_mov_b32_e32 v17, v211
	ds_bpermute_b32 v55, v157, v53
	ds_bpermute_b32 v54, v157, v52
	v_mov_b32_e32 v19, v10
	v_mov_b32_e32 v18, v14
	v_mov_b32_e32 v20, v16
	v_mov_b32_e32 v21, v12
	v_pk_add_f32 v[18:19], v[18:19], v[20:21]
	v_add_f32_e32 v10, v15, v17
	v_add_f32_e32 v12, v11, v13
	v_mov_b32_e32 v11, v18
	v_mov_b32_e32 v13, v19
	v_pk_add_f32 v[10:11], v[10:11], v[12:13]
	ds_bpermute_b32 v13, v155, v11
	ds_bpermute_b32 v12, v155, v10
	s_waitcnt lgkmcnt(0)
	v_pk_add_f32 v[64:65], v[10:11], v[12:13]
	v_add_u32_e32 v10, 48, v0
	v_ashrrev_i32_e32 v11, 31, v10
	v_lshlrev_b64 v[12:13], 7, v[10:11]
	v_lshl_add_u64 v[16:17], v[4:5], 0, v[12:13]
	v_mov_b32_e32 v12, v212
	v_mov_b32_e32 v13, v213
	v_mov_b32_e32 v14, v214
	v_mov_b32_e32 v15, v215
	s_nop 0
	v_mov_b32_e32 v16, v216
	v_mov_b32_e32 v17, v217
	v_mov_b32_e32 v18, v218
	v_mov_b32_e32 v19, v219
	ds_bpermute_b32 v67, v157, v65
	ds_bpermute_b32 v66, v157, v64
	v_mov_b32_e32 v21, v12
	v_mov_b32_e32 v20, v16
	v_mov_b32_e32 v22, v18
	v_mov_b32_e32 v23, v14
	v_pk_add_f32 v[20:21], v[20:21], v[22:23]
	v_add_f32_e32 v12, v17, v19
	v_add_f32_e32 v14, v13, v15
	v_mov_b32_e32 v13, v20
	v_mov_b32_e32 v15, v21
	v_pk_add_f32 v[12:13], v[12:13], v[14:15]
	ds_bpermute_b32 v15, v155, v13
	ds_bpermute_b32 v14, v155, v12
	s_waitcnt lgkmcnt(0)
	v_pk_add_f32 v[68:69], v[12:13], v[14:15]
	v_add_u32_e32 v12, 0x80, v0
	v_ashrrev_i32_e32 v13, 31, v12
	v_lshlrev_b64 v[14:15], 7, v[12:13]
	v_lshl_add_u64 v[18:19], v[4:5], 0, v[14:15]
	v_mov_b32_e32 v14, v220
	v_mov_b32_e32 v15, v221
	v_mov_b32_e32 v16, v222
	v_mov_b32_e32 v17, v223
	s_nop 0
	v_mov_b32_e32 v18, v224
	v_mov_b32_e32 v19, v225
	v_mov_b32_e32 v20, v226
	v_mov_b32_e32 v21, v227
	v_lshlrev_b64 v[0:1], 11, v[0:1]
	v_lshl_add_u64 v[0:1], s[44:45], 0, v[0:1]
	ds_bpermute_b32 v71, v157, v69
	ds_bpermute_b32 v70, v157, v68
	v_mov_b32_e32 v23, v14
	v_mov_b32_e32 v22, v18
	v_mov_b32_e32 v24, v20
	v_mov_b32_e32 v25, v16
	v_pk_add_f32 v[22:23], v[22:23], v[24:25]
	v_add_f32_e32 v14, v19, v21
	v_add_f32_e32 v16, v15, v17
	v_mov_b32_e32 v15, v22
	v_mov_b32_e32 v17, v23
	v_pk_add_f32 v[14:15], v[14:15], v[16:17]
	ds_bpermute_b32 v17, v155, v15
	ds_bpermute_b32 v16, v155, v14
	s_waitcnt lgkmcnt(0)
	v_pk_add_f32 v[112:113], v[14:15], v[16:17]
	v_lshlrev_b64 v[14:15], 7, v[56:57]
	v_lshl_add_u64 v[18:19], v[4:5], 0, v[14:15]
	v_mov_b32_e32 v14, v228
	v_mov_b32_e32 v15, v229
	v_mov_b32_e32 v16, v230
	v_mov_b32_e32 v17, v231
	s_nop 0
	v_mov_b32_e32 v18, v232
	v_mov_b32_e32 v19, v233
	v_mov_b32_e32 v20, v234
	v_mov_b32_e32 v21, v235
	ds_bpermute_b32 v115, v157, v113
	ds_bpermute_b32 v114, v157, v112
	v_mov_b32_e32 v23, v14
	v_mov_b32_e32 v22, v18
	v_mov_b32_e32 v24, v20
	v_mov_b32_e32 v25, v16
	v_pk_add_f32 v[22:23], v[22:23], v[24:25]
	v_add_f32_e32 v14, v19, v21
	v_add_f32_e32 v16, v15, v17
	v_mov_b32_e32 v15, v22
	v_mov_b32_e32 v17, v23
	v_pk_add_f32 v[14:15], v[14:15], v[16:17]
	ds_bpermute_b32 v17, v155, v15
	ds_bpermute_b32 v16, v155, v14
	s_waitcnt lgkmcnt(0)
	v_pk_add_f32 v[116:117], v[14:15], v[16:17]
	v_lshlrev_b64 v[14:15], 7, v[58:59]
	v_lshl_add_u64 v[18:19], v[4:5], 0, v[14:15]
	v_mov_b32_e32 v14, v236
	v_mov_b32_e32 v15, v237
	v_mov_b32_e32 v16, v238
	v_mov_b32_e32 v17, v239
	s_nop 0
	v_mov_b32_e32 v18, v240
	v_mov_b32_e32 v19, v241
	v_mov_b32_e32 v20, v242
	v_mov_b32_e32 v21, v243
	ds_bpermute_b32 v119, v157, v117
	ds_bpermute_b32 v118, v157, v116
	v_mov_b32_e32 v23, v14
	v_mov_b32_e32 v22, v18
	v_mov_b32_e32 v24, v20
	v_mov_b32_e32 v25, v16
	v_pk_add_f32 v[22:23], v[22:23], v[24:25]
	v_add_f32_e32 v14, v19, v21
	v_add_f32_e32 v16, v15, v17
	v_mov_b32_e32 v15, v22
	v_mov_b32_e32 v17, v23
	v_pk_add_f32 v[14:15], v[14:15], v[16:17]
	ds_bpermute_b32 v17, v155, v15
	ds_bpermute_b32 v16, v155, v14
	s_waitcnt lgkmcnt(0)
	v_pk_add_f32 v[120:121], v[14:15], v[16:17]
	v_lshlrev_b64 v[14:15], 7, v[60:61]
	v_lshl_add_u64 v[4:5], v[4:5], 0, v[14:15]
	v_mov_b32_e32 v14, v244
	v_mov_b32_e32 v15, v245
	v_mov_b32_e32 v16, v246
	v_mov_b32_e32 v17, v247
	v_mov_b32_e32 v18, v248
	v_mov_b32_e32 v19, v249
	v_mov_b32_e32 v20, v250
	v_mov_b32_e32 v21, v251
	ds_bpermute_b32 v123, v157, v121
	ds_bpermute_b32 v122, v157, v120
	v_mov_b32_e32 v5, v14
	v_mov_b32_e32 v4, v18
	v_mov_b32_e32 v22, v20
	v_mov_b32_e32 v23, v16
	v_pk_add_f32 v[4:5], v[4:5], v[22:23]
	v_add_f32_e32 v14, v19, v21
	v_add_f32_e32 v16, v15, v17
	v_mov_b32_e32 v15, v4
	v_mov_b32_e32 v17, v5
	v_pk_add_f32 v[4:5], v[14:15], v[16:17]
	ds_bpermute_b32 v15, v155, v5
	ds_bpermute_b32 v14, v155, v4
	s_waitcnt lgkmcnt(0)
	v_pk_add_f32 v[124:125], v[4:5], v[14:15]
	v_lshlrev_b64 v[4:5], 2, v[2:3]
	v_lshlrev_b64 v[2:3], 1, v[2:3]
	v_lshl_add_u64 v[74:75], v[0:1], 0, v[2:3]
	v_lshlrev_b64 v[0:1], 11, v[6:7]
	v_lshl_add_u64 v[0:1], s[44:45], 0, v[0:1]
	v_lshl_add_u64 v[76:77], v[0:1], 0, v[2:3]
	v_lshlrev_b64 v[0:1], 11, v[8:9]
	v_lshl_add_u64 v[0:1], s[44:45], 0, v[0:1]
	v_lshl_add_u64 v[78:79], v[0:1], 0, v[2:3]
	v_lshlrev_b64 v[0:1], 11, v[10:11]
	v_lshl_add_u64 v[0:1], s[44:45], 0, v[0:1]
	v_lshl_add_u64 v[80:81], v[0:1], 0, v[2:3]
	v_lshlrev_b64 v[0:1], 11, v[12:13]
	v_lshl_add_u64 v[0:1], s[44:45], 0, v[0:1]
	v_lshl_add_u64 v[138:139], v[0:1], 0, v[2:3]
	v_lshlrev_b64 v[0:1], 11, v[56:57]
	v_lshl_add_u64 v[0:1], s[44:45], 0, v[0:1]
	v_lshl_add_u64 v[56:57], v[0:1], 0, v[2:3]
	v_lshlrev_b64 v[0:1], 11, v[58:59]
	v_lshl_add_u64 v[0:1], s[44:45], 0, v[0:1]
	v_lshl_add_u64 v[58:59], v[0:1], 0, v[2:3]
	v_lshlrev_b64 v[0:1], 11, v[60:61]
	v_lshl_add_u64 v[0:1], s[44:45], 0, v[0:1]
	v_lshl_add_u64 v[62:63], s[70:71], 0, v[4:5]
	v_lshl_add_u64 v[72:73], s[0:1], 0, v[4:5]
	v_lshl_add_u64 v[140:141], v[0:1], 0, v[2:3]
	global_load_dwordx4 v[36:39], v[62:63], off offset:16
	global_load_dwordx4 v[44:47], v[62:63], off
	global_load_dwordx4 v[32:35], v[72:73], off offset:16
	global_load_dwordx4 v[40:43], v[72:73], off
	global_load_dwordx4 v[28:31], v[74:75], off
	global_load_dwordx4 v[24:27], v[76:77], off
	global_load_dwordx4 v[20:23], v[78:79], off
	global_load_dwordx4 v[16:19], v[80:81], off
	global_load_dwordx4 v[12:15], v[138:139], off
	global_load_dwordx4 v[8:11], v[56:57], off
	global_load_dwordx4 v[4:7], v[58:59], off
	global_load_dwordx4 v[0:3], v[140:141], off
	global_load_dwordx4 v[100:103], v[62:63], off offset:528
	global_load_dwordx4 v[108:111], v[62:63], off offset:512
	global_load_dwordx4 v[96:99], v[72:73], off offset:528
	global_load_dwordx4 v[104:107], v[72:73], off offset:512
	global_load_dwordx4 v[92:95], v[74:75], off offset:256
	global_load_dwordx4 v[88:91], v[76:77], off offset:256
	global_load_dwordx4 v[84:87], v[78:79], off offset:256
	s_nop 0
	global_load_dwordx4 v[80:83], v[80:81], off offset:256
	s_nop 0
	global_load_dwordx4 v[76:79], v[138:139], off offset:256
	global_load_dwordx4 v[72:75], v[56:57], off offset:256
	global_load_dwordx4 v[60:63], v[58:59], off offset:256
	s_nop 0
	global_load_dwordx4 v[56:59], v[140:141], off offset:256
	ds_bpermute_b32 v127, v157, v125
	global_load_lds_dwordx4 v130, s[40:41]
	s_add_i32 m0, s67, 0x12000
	s_add_u32 s14, s40, 0x40000
	global_load_lds_dwordx4 v134, s[40:41]
	s_addc_u32 s15, s41, 0
	s_add_i32 m0, s67, 0x14000
	ds_bpermute_b32 v126, v157, v124
	global_load_lds_dwordx4 v130, s[14:15]
	s_add_i32 m0, s67, 0x16000
	s_add_u32 s74, s42, s6
	s_addc_u32 s75, s43, s7
	s_add_i32 s68, s67, 0x2000
	global_load_lds_dwordx4 v134, s[14:15]
	s_mov_b32 m0, s67
	s_add_u32 s6, s74, 0x40000
	global_load_lds_dwordx4 v128, s[74:75]
	s_mov_b32 m0, s68
	s_addc_u32 s7, s75, 0
	s_add_i32 s69, s67, 0x4000
	global_load_lds_dwordx4 v132, s[74:75]
	s_mov_b32 m0, s69
	s_add_i32 s90, s67, 0x6000
	global_load_lds_dwordx4 v128, s[6:7]
	s_mov_b32 m0, s90
	s_cmp_eq_u32 s11, 1
	global_load_lds_dwordx4 v132, s[6:7]
	v_lshl_add_u64 v[138:139], s[40:41], 0, v[130:131]
	v_lshl_add_u64 v[140:141], s[40:41], 0, v[134:135]
	v_lshl_add_u64 v[142:143], s[74:75], 0, v[128:129]
	v_lshl_add_u64 v[144:145], s[74:75], 0, v[132:133]
	s_cselect_b64 s[6:7], -1, 0
	s_cmp_lg_u32 s11, 1
	s_cbranch_scc1 .LBB0_2364
	s_barrier

.LBB0_2462:
	s_sext_i32_i16 s41, s4
	s_add_u32 s4, s58, 0x3768000
	s_addc_u32 s5, s59, 0
	s_add_u32 s6, s58, 0x3773000
	v_and_b32_e32 v194, 15, v9
	v_and_b32_e32 v15, 48, v9
	v_lshlrev_b32_e32 v16, 2, v9
	s_addc_u32 s7, s59, 0
	s_and_b32 s34, s12, 3
	s_lshl_b32 s8, s11, 13
	v_lshl_or_b32 v15, v194, 6, v15
	v_and_b32_e32 v17, 32, v16
	v_bitop3_b32 v18, v15, s8, v17 bitop3:0xde
	s_lshl_b32 s8, s34, 12
	v_bitop3_b32 v196, v15, s8, v17 bitop3:0xde
	s_mov_b64 s[8:9], 0x80
	s_add_i32 m0, s69, 0x18000
	v_lshl_add_u64 v[6:7], v[6:7], 0, s[8:9]
	s_lshl_b32 s78, s11, 6
	s_lshl_b32 s79, s34, 5
	s_waitcnt vmcnt(2)
	s_barrier
	global_load_lds_dwordx4 v[6:7], off
	v_lshl_add_u64 v[4:5], v[4:5], 0, s[8:9]
	s_add_i32 m0, s69, 0x1a000
	s_add_i32 s80, s69, 0x8000
	s_add_i32 s81, s69, 0xa000
	global_load_lds_dwordx4 v[4:5], off
	v_lshl_add_u64 v[0:1], v[0:1], 0, s[8:9]
	s_mov_b32 m0, s80
	s_add_u32 s14, s74, 0x40080
	global_load_lds_dwordx4 v[0:1], off
	v_lshl_add_u64 v[0:1], v[2:3], 0, s[8:9]
	s_mov_b32 m0, s81
	s_addc_u32 s15, s75, 0
	global_load_lds_dwordx4 v[0:1], off
	s_add_i32 m0, s69, 0x1c000
	v_lshl_add_u64 v[0:1], s[14:15], 0, v[172:173]
	global_load_lds_dwordx4 v[0:1], off
	v_lshl_add_u64 v[0:1], s[14:15], 0, v[168:169]
	s_add_i32 m0, s69, 0x1e000
	s_lshl_b32 s84, s12, 9
	global_load_lds_dwordx4 v[0:1], off
	v_and_b32_e32 v0, 0x80, v16
	v_and_b32_e32 v1, 31, v9
	v_or3_b32 v197, v1, v0, s79
	v_lshlrev_b32_e32 v0, 14, v13
	v_and_b32_e32 v0, 0xffff8000, v0
	v_lshl_add_u32 v0, v12, 11, v0
	v_and_b32_e32 v1, 1, v13
	v_lshl_or_b32 v0, v1, 6, v0
	v_lshl_add_u32 v176, v14, 1, v0
	v_lshlrev_b32_e32 v0, 14, v8
	s_cmpk_lt_u32 s10, 0x100
	v_and_b32_e32 v0, 0xffff8000, v0
	s_waitcnt vmcnt(6)
	s_cselect_b64 s[12:13], -1, 0
	s_lshl_b32 s10, s11, 11
	s_lshl_b32 s11, s34, 9
	v_lshl_add_u32 v0, v10, 11, v0
	v_and_b32_e32 v1, 1, v8
	s_or_b32 s85, s10, s11
	v_lshl_or_b32 v0, v1, 6, v0
	v_bfe_u32 v195, v9, 4, 2
	s_add_i32 s85, s85, 0x22400
	v_mov_b32_e32 v177, v173
	v_lshl_add_u32 v178, v11, 1, v0
	v_mov_b32_e32 v179, v173
	v_mov_b64_e32 v[180:181], 0xb00
	v_mov_b64_e32 v[182:183], 0xaff
	s_movk_i32 s88, 0x1600
	s_add_i32 s89, s84, 0x22500
	s_add_i32 s90, 0, 0x10000
	s_add_i32 s91, 0, 0x14000
	v_add_u32_e32 v198, 0, v18
	v_mov_b32_e32 v199, 0x20400
	s_barrier
	s_mov_b32 s99, 0
	s_branch .LBB0_2465

.LBB0_2473:
	s_cmp_eq_u32 s40, s66
	s_movk_i32 s15, 0x200
	s_cselect_b32 s15, s15, 0x300
	s_cmp_lg_u32 s40, s65
	v_mov_b32_e32 v64, v194
	v_mov_b32_e32 v65, v195
	s_cselect_b32 s15, s15, 0x100
	s_cmp_lg_u32 s40, s64
	s_cselect_b32 s15, s15, 0
	v_lshl_add_u32 v66, v65, 5, s85
	v_add_u32_e32 v184, s78, v64
	ds_read_b128 v[72:75], v66
	ds_read_b128 v[52:55], v66 offset:16
	ds_read_b128 v[76:79], v66 offset:256
	ds_read_b128 v[56:59], v66 offset:272
	ds_read_b128 v[202:205], v66 offset:128
	ds_read_b128 v[206:209], v66 offset:384
	ds_read_b128 v[160:163], v66 offset:144
	ds_read_b128 v[164:167], v66 offset:400
	s_lshl_b32 s35, s41, 7
	v_add_u32_e32 v64, s15, v184
	s_or_b32 s35, s35, s79
	v_lshl_add_u32 v64, v64, 3, v199
	v_lshl_add_u32 v190, v65, 3, s35
	ds_read2_b64 v[156:159], v64 offset1:16
	ds_read2_b64 v[136:139], v64 offset0:32 offset1:48
	ds_read2_b64 v[100:103], v64 offset0:128 offset1:144
	ds_read2_b64 v[64:67], v64 offset0:160 offset1:176
	s_waitcnt lgkmcnt(0)
	v_mov_b32_e32 v186, v202
	v_mov_b32_e32 v187, v72
	v_mov_b32_e32 v188, v206
	v_mov_b32_e32 v189, v76
	v_mov_b32_e32 v210, v148
	v_mov_b32_e32 v211, v152
	v_pk_fma_f32 v[212:213], v[186:187], v[156:157], v[188:189] op_sel:[0,1,0]
	v_mov_b32_e32 v76, v207
	v_pk_fma_f32 v[210:211], v[210:211], v[156:157], v[212:213] op_sel_hi:[1,0,1]
	v_mov_b32_e32 v152, v149
	v_mul_f32_e32 v72, 0xbfb8aa3b, v211
	v_exp_f32_e32 v72, v72
	v_mov_b32_e32 v202, v150
	v_lshl_add_u32 v200, s40, 8, v184
	v_ashrrev_i32_e32 v191, 31, v190
	v_add_f32_e32 v72, 1.0, v72
	v_rcp_f32_e32 v72, v72
	v_mov_b64_e32 v[184:185], s[42:43]
	v_mad_i64_i32 v[192:193], s[40:41], v200, s88, v[184:185]
	v_mul_f32_e32 v72, v211, v72
	v_mul_f32_e32 v201, v210, v72
	v_mov_b32_e32 v72, v203
	v_pk_fma_f32 v[148:149], v[72:73], v[156:157], v[76:77] op_sel:[0,1,0]
	v_mov_b32_e32 v203, v154
	v_pk_fma_f32 v[148:149], v[152:153], v[156:157], v[148:149] op_sel_hi:[1,0,1]
	v_mov_b32_e32 v153, v78
	v_mul_f32_e32 v152, 0xbfb8aa3b, v149
	v_exp_f32_e32 v152, v152
	v_mov_b32_e32 v78, v209
	v_mov_b32_e32 v154, v151
	s_andn2_b64 vcc, exec, s[10:11]
	v_add_f32_e32 v152, 1.0, v152
	v_rcp_f32_e32 v152, v152
	v_readlane_b32 s96, v255, 18
	v_readlane_b32 s97, v255, 19
	v_mul_f32_e32 v149, v149, v152
	v_mul_f32_e32 v210, v148, v149
	v_mov_b32_e32 v148, v204
	v_mov_b32_e32 v149, v74
	v_mov_b32_e32 v152, v208
	v_pk_fma_f32 v[206:207], v[148:149], v[156:157], v[152:153] op_sel:[0,1,0]
	s_nop 0
	v_pk_fma_f32 v[202:203], v[202:203], v[156:157], v[206:207] op_sel_hi:[1,0,1]
	s_nop 0
	v_mul_f32_e32 v74, 0xbfb8aa3b, v203
	v_exp_f32_e32 v74, v74
	s_nop 0
	v_add_f32_e32 v74, 1.0, v74
	v_rcp_f32_e32 v74, v74
	s_nop 0
	v_mul_f32_e32 v74, v203, v74
	v_mul_f32_e32 v206, v202, v74
	v_mov_b32_e32 v74, v205
	v_pk_fma_f32 v[150:151], v[74:75], v[156:157], v[78:79] op_sel:[0,1,0]
	v_mov_b32_e32 v202, v140
	v_pk_fma_f32 v[150:151], v[154:155], v[156:157], v[150:151] op_sel_hi:[1,0,1]
	v_mov_b32_e32 v155, v56
	v_mul_f32_e32 v154, 0xbfb8aa3b, v151
	v_exp_f32_e32 v154, v154
	v_mov_b32_e32 v203, v144
	v_mov_b32_e32 v56, v165
	v_mov_b32_e32 v144, v141
	v_add_f32_e32 v154, 1.0, v154
	v_rcp_f32_e32 v154, v154
	s_nop 0
	v_mul_f32_e32 v151, v151, v154
	v_mul_f32_e32 v207, v150, v151
	v_mov_b32_e32 v150, v160
	v_mov_b32_e32 v151, v52
	v_mov_b32_e32 v154, v164
	v_pk_fma_f32 v[204:205], v[150:151], v[156:157], v[154:155] op_sel:[0,1,0]
	v_mov_b32_e32 v160, v142
	v_pk_fma_f32 v[202:203], v[202:203], v[156:157], v[204:205] op_sel_hi:[1,0,1]
	s_nop 0
	v_mul_f32_e32 v52, 0xbfb8aa3b, v203
	v_exp_f32_e32 v52, v52
	s_nop 0
	v_add_f32_e32 v52, 1.0, v52
	v_rcp_f32_e32 v52, v52
	s_nop 0
	v_mul_f32_e32 v52, v203, v52
	v_mul_f32_e32 v202, v202, v52
	v_mov_b32_e32 v52, v161
	v_pk_fma_f32 v[140:141], v[52:53], v[156:157], v[56:57] op_sel:[0,1,0]
	v_mov_b32_e32 v161, v146
	v_pk_fma_f32 v[140:141], v[144:145], v[156:157], v[140:141] op_sel_hi:[1,0,1]
	v_mov_b32_e32 v145, v58
	v_mul_f32_e32 v144, 0xbfb8aa3b, v141
	v_exp_f32_e32 v144, v144
	v_mov_b32_e32 v58, v167
	v_mov_b32_e32 v146, v143
	v_add_f32_e32 v144, 1.0, v144
	v_rcp_f32_e32 v144, v144
	s_nop 0
	v_mul_f32_e32 v141, v141, v144
	v_mul_f32_e32 v203, v140, v141
	v_mov_b32_e32 v140, v162
	v_mov_b32_e32 v141, v54
	v_mov_b32_e32 v144, v166
	v_pk_fma_f32 v[164:165], v[140:141], v[156:157], v[144:145] op_sel:[0,1,0]
	s_nop 0
	v_pk_fma_f32 v[160:161], v[160:161], v[156:157], v[164:165] op_sel_hi:[1,0,1]
	s_nop 0
	v_mul_f32_e32 v54, 0xbfb8aa3b, v161
	v_exp_f32_e32 v54, v54
	s_nop 0
	v_add_f32_e32 v54, 1.0, v54
	v_rcp_f32_e32 v54, v54
	s_nop 0
	v_mul_f32_e32 v54, v161, v54
	v_mul_f32_e32 v164, v160, v54
	v_mov_b32_e32 v54, v163
	v_pk_fma_f32 v[142:143], v[54:55], v[156:157], v[58:59] op_sel:[0,1,0]
	v_cvt_pk_bf16_f32 v160, v201, v210
	v_cvt_pk_bf16_f32 v161, v206, v207
	v_cvt_pk_bf16_f32 v162, v202, v203
	s_nop 0
	v_pk_fma_f32 v[142:143], v[146:147], v[156:157], v[142:143] op_sel_hi:[1,0,1]
	v_mov_b32_e32 v157, v132
	v_mul_f32_e32 v146, 0xbfb8aa3b, v143
	v_exp_f32_e32 v146, v146
	v_mov_b32_e32 v132, v129
	v_add_f32_e32 v146, 1.0, v146
	v_rcp_f32_e32 v146, v146
	s_nop 0
	v_mul_f32_e32 v143, v143, v146
	v_mul_f32_e32 v156, v142, v143
	v_lshlrev_b64 v[142:143], 1, v[190:191]
	v_lshl_add_u64 v[146:147], v[192:193], 0, v[142:143]
	v_cvt_pk_bf16_f32 v163, v164, v156
	global_store_dwordx4 v[146:147], v[160:163], off
	v_mov_b32_e32 v156, v128
	v_add_u32_e32 v146, 16, v200
	v_pk_fma_f32 v[160:161], v[186:187], v[158:159], v[188:189] op_sel:[0,1,0]
	v_mad_i64_i32 v[146:147], s[40:41], v146, s88, v[184:185]
	v_pk_fma_f32 v[156:157], v[156:157], v[158:159], v[160:161] op_sel_hi:[1,0,1]
	s_nop 0
	v_mul_f32_e32 v128, 0xbfb8aa3b, v157
	v_exp_f32_e32 v128, v128
	s_nop 0
	v_add_f32_e32 v128, 1.0, v128
	v_rcp_f32_e32 v128, v128
	s_nop 0
	v_mul_f32_e32 v128, v157, v128
	v_mul_f32_e32 v156, v156, v128
	v_pk_fma_f32 v[128:129], v[72:73], v[158:159], v[76:77] op_sel:[0,1,0]
	s_nop 0
	v_pk_fma_f32 v[128:129], v[132:133], v[158:159], v[128:129] op_sel_hi:[1,0,1]
	s_nop 0
	v_mul_f32_e32 v132, 0xbfb8aa3b, v129
	v_exp_f32_e32 v132, v132
	s_nop 0
	v_add_f32_e32 v132, 1.0, v132
	v_rcp_f32_e32 v132, v132
	s_nop 0
	v_mul_f32_e32 v129, v129, v132
	v_mul_f32_e32 v157, v128, v129
	v_mov_b32_e32 v128, v130
	v_mov_b32_e32 v129, v134
	v_pk_fma_f32 v[132:133], v[148:149], v[158:159], v[152:153] op_sel:[0,1,0]
	v_mov_b32_e32 v134, v131
	v_pk_fma_f32 v[128:129], v[128:129], v[158:159], v[132:133] op_sel_hi:[1,0,1]
	s_nop 0
	v_mul_f32_e32 v130, 0xbfb8aa3b, v129
	v_exp_f32_e32 v130, v130
	s_nop 0
	v_add_f32_e32 v130, 1.0, v130
	v_rcp_f32_e32 v130, v130
	s_nop 0
	v_mul_f32_e32 v129, v129, v130
	v_mul_f32_e32 v132, v128, v129
	v_pk_fma_f32 v[128:129], v[74:75], v[158:159], v[78:79] op_sel:[0,1,0]
	s_nop 0
	v_pk_fma_f32 v[128:129], v[134:135], v[158:159], v[128:129] op_sel_hi:[1,0,1]
	s_nop 0
	v_mul_f32_e32 v130, 0xbfb8aa3b, v129
	v_exp_f32_e32 v130, v130
	s_nop 0
	v_add_f32_e32 v130, 1.0, v130
	v_rcp_f32_e32 v130, v130
	s_nop 0
	v_mul_f32_e32 v129, v129, v130
	v_mul_f32_e32 v133, v128, v129
	v_mov_b32_e32 v128, v120
	v_mov_b32_e32 v129, v124
	v_pk_fma_f32 v[130:131], v[150:151], v[158:159], v[154:155] op_sel:[0,1,0]
	v_mov_b32_e32 v124, v121
	v_pk_fma_f32 v[128:129], v[128:129], v[158:159], v[130:131] op_sel_hi:[1,0,1]
	s_nop 0
	v_mul_f32_e32 v120, 0xbfb8aa3b, v129
	v_exp_f32_e32 v120, v120
	s_nop 0
	v_add_f32_e32 v120, 1.0, v120
	v_rcp_f32_e32 v120, v120
	s_nop 0
	v_mul_f32_e32 v120, v129, v120
	v_mul_f32_e32 v128, v128, v120
	v_pk_fma_f32 v[120:121], v[52:53], v[158:159], v[56:57] op_sel:[0,1,0]
	s_nop 0
	v_pk_fma_f32 v[120:121], v[124:125], v[158:159], v[120:121] op_sel_hi:[1,0,1]
	s_nop 0
	v_mul_f32_e32 v124, 0xbfb8aa3b, v121
	v_exp_f32_e32 v124, v124
	s_nop 0
	v_add_f32_e32 v124, 1.0, v124
	v_rcp_f32_e32 v124, v124
	s_nop 0
	v_mul_f32_e32 v121, v121, v124
	v_mul_f32_e32 v129, v120, v121
	v_mov_b32_e32 v120, v122
	v_mov_b32_e32 v121, v126
	v_pk_fma_f32 v[124:125], v[140:141], v[158:159], v[144:145] op_sel:[0,1,0]
	v_mov_b32_e32 v126, v123
	v_pk_fma_f32 v[120:121], v[120:121], v[158:159], v[124:125] op_sel_hi:[1,0,1]
	v_lshl_add_u64 v[124:125], v[146:147], 0, v[142:143]
	v_mul_f32_e32 v122, 0xbfb8aa3b, v121
	v_exp_f32_e32 v122, v122
	s_nop 0
	v_add_f32_e32 v122, 1.0, v122
	v_rcp_f32_e32 v122, v122
	s_nop 0
	v_mul_f32_e32 v121, v121, v122
	v_mul_f32_e32 v130, v120, v121
	v_pk_fma_f32 v[120:121], v[54:55], v[158:159], v[58:59] op_sel:[0,1,0]
	s_nop 0
	v_pk_fma_f32 v[120:121], v[126:127], v[158:159], v[120:121] op_sel_hi:[1,0,1]
	s_nop 0
	v_mul_f32_e32 v122, 0xbfb8aa3b, v121
	v_exp_f32_e32 v122, v122
	s_nop 0
	v_add_f32_e32 v122, 1.0, v122
	v_rcp_f32_e32 v122, v122
	s_nop 0
	v_mul_f32_e32 v121, v121, v122
	v_mul_f32_e32 v123, v120, v121
	v_cvt_pk_bf16_f32 v120, v156, v157
	v_cvt_pk_bf16_f32 v121, v132, v133
	v_cvt_pk_bf16_f32 v122, v128, v129
	v_cvt_pk_bf16_f32 v123, v130, v123
	global_store_dwordx4 v[124:125], v[120:123], off
	v_pk_fma_f32 v[124:125], v[186:187], v[136:137], v[188:189] op_sel:[0,1,0]
	s_nop 0
	v_mov_b32_e32 v122, v112
	v_mov_b32_e32 v123, v116
	v_pk_fma_f32 v[122:123], v[122:123], v[136:137], v[124:125] op_sel_hi:[1,0,1]
	v_mov_b32_e32 v116, v113
	v_mul_f32_e32 v112, 0xbfb8aa3b, v123
	v_exp_f32_e32 v112, v112
	v_add_u32_e32 v120, 32, v200
	v_mad_i64_i32 v[120:121], s[40:41], v120, s88, v[184:185]
	v_add_f32_e32 v112, 1.0, v112
	v_rcp_f32_e32 v112, v112
	s_nop 0
	v_mul_f32_e32 v112, v123, v112
	v_mul_f32_e32 v122, v122, v112
	v_pk_fma_f32 v[112:113], v[72:73], v[136:137], v[76:77] op_sel:[0,1,0]
	s_nop 0
	v_pk_fma_f32 v[112:113], v[116:117], v[136:137], v[112:113] op_sel_hi:[1,0,1]
	s_nop 0
	v_mul_f32_e32 v116, 0xbfb8aa3b, v113
	v_exp_f32_e32 v116, v116
	s_nop 0
	v_add_f32_e32 v116, 1.0, v116
	v_rcp_f32_e32 v116, v116
	s_nop 0
	v_mul_f32_e32 v113, v113, v116
	v_mul_f32_e32 v123, v112, v113
	v_mov_b32_e32 v112, v114
	v_mov_b32_e32 v113, v118
	v_pk_fma_f32 v[116:117], v[148:149], v[136:137], v[152:153] op_sel:[0,1,0]
	v_mov_b32_e32 v118, v115
	v_pk_fma_f32 v[112:113], v[112:113], v[136:137], v[116:117] op_sel_hi:[1,0,1]
	s_nop 0
	v_mul_f32_e32 v114, 0xbfb8aa3b, v113
	v_exp_f32_e32 v114, v114
	s_nop 0
	v_add_f32_e32 v114, 1.0, v114
	v_rcp_f32_e32 v114, v114
	s_nop 0
	v_mul_f32_e32 v113, v113, v114
	v_mul_f32_e32 v116, v112, v113
	v_pk_fma_f32 v[112:113], v[74:75], v[136:137], v[78:79] op_sel:[0,1,0]
	s_nop 0
	v_pk_fma_f32 v[112:113], v[118:119], v[136:137], v[112:113] op_sel_hi:[1,0,1]
	s_nop 0
	v_mul_f32_e32 v114, 0xbfb8aa3b, v113
	v_exp_f32_e32 v114, v114
	s_nop 0
	v_add_f32_e32 v114, 1.0, v114
	v_rcp_f32_e32 v114, v114
	s_nop 0
	v_mul_f32_e32 v113, v113, v114
	v_mul_f32_e32 v117, v112, v113
	v_mov_b32_e32 v112, v104
	v_mov_b32_e32 v113, v108
	v_pk_fma_f32 v[114:115], v[150:151], v[136:137], v[154:155] op_sel:[0,1,0]
	v_mov_b32_e32 v108, v105
	v_pk_fma_f32 v[112:113], v[112:113], v[136:137], v[114:115] op_sel_hi:[1,0,1]
	s_nop 0
	v_mul_f32_e32 v104, 0xbfb8aa3b, v113
	v_exp_f32_e32 v104, v104
	s_nop 0
	v_add_f32_e32 v104, 1.0, v104
	v_rcp_f32_e32 v104, v104
	s_nop 0
	v_mul_f32_e32 v104, v113, v104
	v_mul_f32_e32 v112, v112, v104
	v_pk_fma_f32 v[104:105], v[52:53], v[136:137], v[56:57] op_sel:[0,1,0]
	s_nop 0
	v_pk_fma_f32 v[104:105], v[108:109], v[136:137], v[104:105] op_sel_hi:[1,0,1]
	s_nop 0
	v_mul_f32_e32 v108, 0xbfb8aa3b, v105
	v_exp_f32_e32 v108, v108
	s_nop 0
	v_add_f32_e32 v108, 1.0, v108
	v_rcp_f32_e32 v108, v108
	s_nop 0
	v_mul_f32_e32 v105, v105, v108
	v_mul_f32_e32 v113, v104, v105
	v_mov_b32_e32 v104, v106
	v_mov_b32_e32 v105, v110
	v_pk_fma_f32 v[108:109], v[140:141], v[136:137], v[144:145] op_sel:[0,1,0]
	v_mov_b32_e32 v110, v107
	v_pk_fma_f32 v[104:105], v[104:105], v[136:137], v[108:109] op_sel_hi:[1,0,1]
	v_lshl_add_u64 v[108:109], v[120:121], 0, v[142:143]
	v_mul_f32_e32 v106, 0xbfb8aa3b, v105
	v_exp_f32_e32 v106, v106
	s_nop 0
	v_add_f32_e32 v106, 1.0, v106
	v_rcp_f32_e32 v106, v106
	s_nop 0
	v_mul_f32_e32 v105, v105, v106
	v_mul_f32_e32 v114, v104, v105
	v_pk_fma_f32 v[104:105], v[54:55], v[136:137], v[58:59] op_sel:[0,1,0]
	s_nop 0
	v_pk_fma_f32 v[104:105], v[110:111], v[136:137], v[104:105] op_sel_hi:[1,0,1]
	s_nop 0
	v_mul_f32_e32 v106, 0xbfb8aa3b, v105
	v_exp_f32_e32 v106, v106
	s_nop 0
	v_add_f32_e32 v106, 1.0, v106
	v_rcp_f32_e32 v106, v106
	s_nop 0
	v_mul_f32_e32 v105, v105, v106
	v_mul_f32_e32 v107, v104, v105
	v_cvt_pk_bf16_f32 v104, v122, v123
	v_cvt_pk_bf16_f32 v105, v116, v117
	v_cvt_pk_bf16_f32 v106, v112, v113
	v_cvt_pk_bf16_f32 v107, v114, v107
	global_store_dwordx4 v[108:109], v[104:107], off
	v_pk_fma_f32 v[108:109], v[186:187], v[138:139], v[188:189] op_sel:[0,1,0]
	s_nop 0
	v_mov_b32_e32 v106, v92
	v_mov_b32_e32 v107, v96
	v_pk_fma_f32 v[106:107], v[106:107], v[138:139], v[108:109] op_sel_hi:[1,0,1]
	v_mov_b32_e32 v96, v93
	v_mul_f32_e32 v92, 0xbfb8aa3b, v107
	v_exp_f32_e32 v92, v92
	v_add_u32_e32 v104, 48, v200
	v_mad_i64_i32 v[104:105], s[40:41], v104, s88, v[184:185]
	v_add_f32_e32 v92, 1.0, v92
	v_rcp_f32_e32 v92, v92
	s_nop 0
	v_mul_f32_e32 v92, v107, v92
	v_mul_f32_e32 v106, v106, v92
	v_pk_fma_f32 v[92:93], v[72:73], v[138:139], v[76:77] op_sel:[0,1,0]
	s_nop 0
	v_pk_fma_f32 v[92:93], v[96:97], v[138:139], v[92:93] op_sel_hi:[1,0,1]
	s_nop 0
	v_mul_f32_e32 v96, 0xbfb8aa3b, v93
	v_exp_f32_e32 v96, v96
	s_nop 0
	v_add_f32_e32 v96, 1.0, v96
	v_rcp_f32_e32 v96, v96
	s_nop 0
	v_mul_f32_e32 v93, v93, v96
	v_mul_f32_e32 v107, v92, v93
	v_mov_b32_e32 v92, v94
	v_mov_b32_e32 v93, v98
	v_pk_fma_f32 v[96:97], v[148:149], v[138:139], v[152:153] op_sel:[0,1,0]
	v_mov_b32_e32 v98, v95
	v_pk_fma_f32 v[92:93], v[92:93], v[138:139], v[96:97] op_sel_hi:[1,0,1]
	s_nop 0
	v_mul_f32_e32 v94, 0xbfb8aa3b, v93
	v_exp_f32_e32 v94, v94
	s_nop 0
	v_add_f32_e32 v94, 1.0, v94
	v_rcp_f32_e32 v94, v94
	s_nop 0
	v_mul_f32_e32 v93, v93, v94
	v_mul_f32_e32 v96, v92, v93
	v_pk_fma_f32 v[92:93], v[74:75], v[138:139], v[78:79] op_sel:[0,1,0]
	s_nop 0
	v_pk_fma_f32 v[92:93], v[98:99], v[138:139], v[92:93] op_sel_hi:[1,0,1]
	s_nop 0
	v_mul_f32_e32 v94, 0xbfb8aa3b, v93
	v_exp_f32_e32 v94, v94
	s_nop 0
	v_add_f32_e32 v94, 1.0, v94
	v_rcp_f32_e32 v94, v94
	s_nop 0
	v_mul_f32_e32 v93, v93, v94
	v_mul_f32_e32 v97, v92, v93
	v_mov_b32_e32 v92, v84
	v_mov_b32_e32 v93, v88
	v_pk_fma_f32 v[94:95], v[150:151], v[138:139], v[154:155] op_sel:[0,1,0]
	v_mov_b32_e32 v88, v85
	v_pk_fma_f32 v[92:93], v[92:93], v[138:139], v[94:95] op_sel_hi:[1,0,1]
	s_nop 0
	v_mul_f32_e32 v84, 0xbfb8aa3b, v93
	v_exp_f32_e32 v84, v84
	s_nop 0
	v_add_f32_e32 v84, 1.0, v84
	v_rcp_f32_e32 v84, v84
	s_nop 0
	v_mul_f32_e32 v84, v93, v84
	v_mul_f32_e32 v92, v92, v84
	v_pk_fma_f32 v[84:85], v[52:53], v[138:139], v[56:57] op_sel:[0,1,0]
	s_nop 0
	v_pk_fma_f32 v[84:85], v[88:89], v[138:139], v[84:85] op_sel_hi:[1,0,1]
	s_nop 0
	v_mul_f32_e32 v88, 0xbfb8aa3b, v85
	v_exp_f32_e32 v88, v88
	s_nop 0
	v_add_f32_e32 v88, 1.0, v88
	v_rcp_f32_e32 v88, v88
	s_nop 0
	v_mul_f32_e32 v85, v85, v88
	v_mul_f32_e32 v93, v84, v85
	v_mov_b32_e32 v84, v86
	v_mov_b32_e32 v85, v90
	v_pk_fma_f32 v[88:89], v[140:141], v[138:139], v[144:145] op_sel:[0,1,0]
	v_mov_b32_e32 v90, v87
	v_pk_fma_f32 v[84:85], v[84:85], v[138:139], v[88:89] op_sel_hi:[1,0,1]
	v_lshl_add_u64 v[88:89], v[104:105], 0, v[142:143]
	v_mul_f32_e32 v86, 0xbfb8aa3b, v85
	v_exp_f32_e32 v86, v86
	s_nop 0
	v_add_f32_e32 v86, 1.0, v86
	v_rcp_f32_e32 v86, v86
	s_nop 0
	v_mul_f32_e32 v85, v85, v86
	v_mul_f32_e32 v94, v84, v85
	v_pk_fma_f32 v[84:85], v[54:55], v[138:139], v[58:59] op_sel:[0,1,0]
	s_nop 0
	v_pk_fma_f32 v[84:85], v[90:91], v[138:139], v[84:85] op_sel_hi:[1,0,1]
	s_nop 0
	v_mul_f32_e32 v86, 0xbfb8aa3b, v85
	v_exp_f32_e32 v86, v86
	s_nop 0
	v_add_f32_e32 v86, 1.0, v86
	v_rcp_f32_e32 v86, v86
	s_nop 0
	v_mul_f32_e32 v85, v85, v86
	v_mul_f32_e32 v87, v84, v85
	v_cvt_pk_bf16_f32 v84, v106, v107
	v_cvt_pk_bf16_f32 v85, v96, v97
	v_cvt_pk_bf16_f32 v86, v92, v93
	v_cvt_pk_bf16_f32 v87, v94, v87
	global_store_dwordx4 v[88:89], v[84:87], off
	v_pk_fma_f32 v[88:89], v[186:187], v[100:101], v[188:189] op_sel:[0,1,0]
	s_nop 0
	v_mov_b32_e32 v86, v68
	v_mov_b32_e32 v87, v80
	v_pk_fma_f32 v[86:87], v[86:87], v[100:101], v[88:89] op_sel_hi:[1,0,1]
	v_mov_b32_e32 v80, v69
	v_mul_f32_e32 v68, 0xbfb8aa3b, v87
	v_exp_f32_e32 v68, v68
	v_add_u32_e32 v84, 0x80, v200
	v_mad_i64_i32 v[84:85], s[40:41], v84, s88, v[184:185]
	v_add_f32_e32 v68, 1.0, v68
	v_rcp_f32_e32 v68, v68
	s_nop 0
	v_mul_f32_e32 v68, v87, v68
	v_mul_f32_e32 v86, v86, v68
	v_pk_fma_f32 v[68:69], v[72:73], v[100:101], v[76:77] op_sel:[0,1,0]
	s_nop 0
	v_pk_fma_f32 v[68:69], v[80:81], v[100:101], v[68:69] op_sel_hi:[1,0,1]
	s_nop 0
	v_mul_f32_e32 v80, 0xbfb8aa3b, v69
	v_exp_f32_e32 v80, v80
	s_nop 0
	v_add_f32_e32 v80, 1.0, v80
	v_rcp_f32_e32 v80, v80
	s_nop 0
	v_mul_f32_e32 v69, v69, v80
	v_mul_f32_e32 v87, v68, v69
	v_mov_b32_e32 v68, v70
	v_mov_b32_e32 v69, v82
	v_pk_fma_f32 v[80:81], v[148:149], v[100:101], v[152:153] op_sel:[0,1,0]
	v_mov_b32_e32 v82, v71
	v_pk_fma_f32 v[68:69], v[68:69], v[100:101], v[80:81] op_sel_hi:[1,0,1]
	s_nop 0
	v_mul_f32_e32 v70, 0xbfb8aa3b, v69
	v_exp_f32_e32 v70, v70
	s_nop 0
	v_add_f32_e32 v70, 1.0, v70
	v_rcp_f32_e32 v70, v70
	s_nop 0
	v_mul_f32_e32 v69, v69, v70
	v_mul_f32_e32 v80, v68, v69
	v_pk_fma_f32 v[68:69], v[74:75], v[100:101], v[78:79] op_sel:[0,1,0]
	s_nop 0
	v_pk_fma_f32 v[68:69], v[82:83], v[100:101], v[68:69] op_sel_hi:[1,0,1]
	s_nop 0
	v_mul_f32_e32 v70, 0xbfb8aa3b, v69
	v_exp_f32_e32 v70, v70
	s_nop 0
	v_add_f32_e32 v70, 1.0, v70
	v_rcp_f32_e32 v70, v70
	s_nop 0
	v_mul_f32_e32 v69, v69, v70
	v_mul_f32_e32 v81, v68, v69
	v_mov_b32_e32 v68, v48
	v_mov_b32_e32 v69, v60
	v_pk_fma_f32 v[70:71], v[150:151], v[100:101], v[154:155] op_sel:[0,1,0]
	v_mov_b32_e32 v60, v49
	v_pk_fma_f32 v[68:69], v[68:69], v[100:101], v[70:71] op_sel_hi:[1,0,1]
	s_nop 0
	v_mul_f32_e32 v48, 0xbfb8aa3b, v69
	v_exp_f32_e32 v48, v48
	s_nop 0
	v_add_f32_e32 v48, 1.0, v48
	v_rcp_f32_e32 v48, v48
	s_nop 0
	v_mul_f32_e32 v48, v69, v48
	v_mul_f32_e32 v68, v68, v48
	v_pk_fma_f32 v[48:49], v[52:53], v[100:101], v[56:57] op_sel:[0,1,0]
	s_nop 0
	v_pk_fma_f32 v[48:49], v[60:61], v[100:101], v[48:49] op_sel_hi:[1,0,1]
	s_nop 0
	v_mul_f32_e32 v60, 0xbfb8aa3b, v49
	v_exp_f32_e32 v60, v60
	s_nop 0
	v_add_f32_e32 v60, 1.0, v60
	v_rcp_f32_e32 v60, v60
	s_nop 0
	v_mul_f32_e32 v49, v49, v60
	v_mul_f32_e32 v69, v48, v49
	v_mov_b32_e32 v48, v50
	v_mov_b32_e32 v49, v62
	v_pk_fma_f32 v[60:61], v[140:141], v[100:101], v[144:145] op_sel:[0,1,0]
	v_mov_b32_e32 v62, v51
	v_pk_fma_f32 v[48:49], v[48:49], v[100:101], v[60:61] op_sel_hi:[1,0,1]
	v_lshl_add_u64 v[60:61], v[84:85], 0, v[142:143]
	v_mul_f32_e32 v50, 0xbfb8aa3b, v49
	v_exp_f32_e32 v50, v50
	s_nop 0
	v_add_f32_e32 v50, 1.0, v50
	v_rcp_f32_e32 v50, v50
	s_nop 0
	v_mul_f32_e32 v49, v49, v50
	v_mul_f32_e32 v70, v48, v49
	v_pk_fma_f32 v[48:49], v[54:55], v[100:101], v[58:59] op_sel:[0,1,0]
	s_nop 0
	v_pk_fma_f32 v[48:49], v[62:63], v[100:101], v[48:49] op_sel_hi:[1,0,1]
	s_nop 0
	v_mul_f32_e32 v50, 0xbfb8aa3b, v49
	v_exp_f32_e32 v50, v50
	s_nop 0
	v_add_f32_e32 v50, 1.0, v50
	v_rcp_f32_e32 v50, v50
	s_nop 0
	v_mul_f32_e32 v49, v49, v50
	v_mul_f32_e32 v51, v48, v49
	v_cvt_pk_bf16_f32 v48, v86, v87
	v_cvt_pk_bf16_f32 v49, v80, v81
	v_cvt_pk_bf16_f32 v50, v68, v69
	v_cvt_pk_bf16_f32 v51, v70, v51
	global_store_dwordx4 v[60:61], v[48:51], off
	v_pk_fma_f32 v[60:61], v[186:187], v[102:103], v[188:189] op_sel:[0,1,0]
	s_nop 0
	v_mov_b32_e32 v50, v40
	v_mov_b32_e32 v51, v44
	v_pk_fma_f32 v[50:51], v[50:51], v[102:103], v[60:61] op_sel_hi:[1,0,1]
	v_mov_b32_e32 v44, v41
	v_mul_f32_e32 v40, 0xbfb8aa3b, v51
	v_exp_f32_e32 v40, v40
	v_add_u32_e32 v48, 0x90, v200
	v_mad_i64_i32 v[48:49], s[40:41], v48, s88, v[184:185]
	v_add_f32_e32 v40, 1.0, v40
	v_rcp_f32_e32 v40, v40
	s_nop 0
	v_mul_f32_e32 v40, v51, v40
	v_mul_f32_e32 v50, v50, v40
	v_pk_fma_f32 v[40:41], v[72:73], v[102:103], v[76:77] op_sel:[0,1,0]
	s_nop 0
	v_pk_fma_f32 v[40:41], v[44:45], v[102:103], v[40:41] op_sel_hi:[1,0,1]
	s_nop 0
	v_mul_f32_e32 v44, 0xbfb8aa3b, v41
	v_exp_f32_e32 v44, v44
	s_nop 0
	v_add_f32_e32 v44, 1.0, v44
	v_rcp_f32_e32 v44, v44
	s_nop 0
	v_mul_f32_e32 v41, v41, v44
	v_mul_f32_e32 v51, v40, v41
	v_mov_b32_e32 v40, v42
	v_mov_b32_e32 v41, v46
	v_pk_fma_f32 v[44:45], v[148:149], v[102:103], v[152:153] op_sel:[0,1,0]
	v_mov_b32_e32 v46, v43
	v_pk_fma_f32 v[40:41], v[40:41], v[102:103], v[44:45] op_sel_hi:[1,0,1]
	s_nop 0
	v_mul_f32_e32 v42, 0xbfb8aa3b, v41
	v_exp_f32_e32 v42, v42
	s_nop 0
	v_add_f32_e32 v42, 1.0, v42
	v_rcp_f32_e32 v42, v42
	s_nop 0
	v_mul_f32_e32 v41, v41, v42
	v_mul_f32_e32 v44, v40, v41
	v_pk_fma_f32 v[40:41], v[74:75], v[102:103], v[78:79] op_sel:[0,1,0]
	s_nop 0
	v_pk_fma_f32 v[40:41], v[46:47], v[102:103], v[40:41] op_sel_hi:[1,0,1]
	s_nop 0
	v_mul_f32_e32 v42, 0xbfb8aa3b, v41
	v_exp_f32_e32 v42, v42
	s_nop 0
	v_add_f32_e32 v42, 1.0, v42
	v_rcp_f32_e32 v42, v42
	s_nop 0
	v_mul_f32_e32 v41, v41, v42
	v_mul_f32_e32 v45, v40, v41
	v_mov_b32_e32 v40, v32
	v_mov_b32_e32 v41, v36
	v_pk_fma_f32 v[42:43], v[150:151], v[102:103], v[154:155] op_sel:[0,1,0]
	v_mov_b32_e32 v36, v33
	v_pk_fma_f32 v[40:41], v[40:41], v[102:103], v[42:43] op_sel_hi:[1,0,1]
	s_nop 0
	v_mul_f32_e32 v32, 0xbfb8aa3b, v41
	v_exp_f32_e32 v32, v32
	s_nop 0
	v_add_f32_e32 v32, 1.0, v32
	v_rcp_f32_e32 v32, v32
	s_nop 0
	v_mul_f32_e32 v32, v41, v32
	v_mul_f32_e32 v40, v40, v32
	v_pk_fma_f32 v[32:33], v[52:53], v[102:103], v[56:57] op_sel:[0,1,0]
	s_nop 0
	v_pk_fma_f32 v[32:33], v[36:37], v[102:103], v[32:33] op_sel_hi:[1,0,1]
	s_nop 0
	v_mul_f32_e32 v36, 0xbfb8aa3b, v33
	v_exp_f32_e32 v36, v36
	s_nop 0
	v_add_f32_e32 v36, 1.0, v36
	v_rcp_f32_e32 v36, v36
	s_nop 0
	v_mul_f32_e32 v33, v33, v36
	v_mul_f32_e32 v41, v32, v33
	v_mov_b32_e32 v32, v34
	v_mov_b32_e32 v33, v38
	v_pk_fma_f32 v[36:37], v[140:141], v[102:103], v[144:145] op_sel:[0,1,0]
	v_mov_b32_e32 v38, v35
	v_pk_fma_f32 v[32:33], v[32:33], v[102:103], v[36:37] op_sel_hi:[1,0,1]
	v_lshl_add_u64 v[36:37], v[48:49], 0, v[142:143]
	v_mul_f32_e32 v34, 0xbfb8aa3b, v33
	v_exp_f32_e32 v34, v34
	s_nop 0
	v_add_f32_e32 v34, 1.0, v34
	v_rcp_f32_e32 v34, v34
	s_nop 0
	v_mul_f32_e32 v33, v33, v34
	v_mul_f32_e32 v42, v32, v33
	v_pk_fma_f32 v[32:33], v[54:55], v[102:103], v[58:59] op_sel:[0,1,0]
	s_nop 0
	v_pk_fma_f32 v[32:33], v[38:39], v[102:103], v[32:33] op_sel_hi:[1,0,1]
	s_nop 0
	v_mul_f32_e32 v34, 0xbfb8aa3b, v33
	v_exp_f32_e32 v34, v34
	s_nop 0
	v_add_f32_e32 v34, 1.0, v34
	v_rcp_f32_e32 v34, v34
	s_nop 0
	v_mul_f32_e32 v33, v33, v34
	v_mul_f32_e32 v35, v32, v33
	v_cvt_pk_bf16_f32 v32, v50, v51
	v_cvt_pk_bf16_f32 v33, v44, v45
	v_cvt_pk_bf16_f32 v34, v40, v41
	v_cvt_pk_bf16_f32 v35, v42, v35
	global_store_dwordx4 v[36:37], v[32:35], off
	v_pk_fma_f32 v[36:37], v[186:187], v[64:65], v[188:189] op_sel:[0,1,0]
	s_nop 0
	v_mov_b32_e32 v34, v24
	v_mov_b32_e32 v35, v28
	v_pk_fma_f32 v[34:35], v[34:35], v[64:65], v[36:37] op_sel_hi:[1,0,1]
	v_mov_b32_e32 v28, v25
	v_mul_f32_e32 v24, 0xbfb8aa3b, v35
	v_exp_f32_e32 v24, v24
	v_add_u32_e32 v32, 0xa0, v200
	v_mad_i64_i32 v[32:33], s[40:41], v32, s88, v[184:185]
	v_add_f32_e32 v24, 1.0, v24
	v_rcp_f32_e32 v24, v24
	s_nop 0
	v_mul_f32_e32 v24, v35, v24
	v_mul_f32_e32 v34, v34, v24
	v_pk_fma_f32 v[24:25], v[72:73], v[64:65], v[76:77] op_sel:[0,1,0]
	s_nop 0
	v_pk_fma_f32 v[24:25], v[28:29], v[64:65], v[24:25] op_sel_hi:[1,0,1]
	s_nop 0
	v_mul_f32_e32 v28, 0xbfb8aa3b, v25
	v_exp_f32_e32 v28, v28
	s_nop 0
	v_add_f32_e32 v28, 1.0, v28
	v_rcp_f32_e32 v28, v28
	s_nop 0
	v_mul_f32_e32 v25, v25, v28
	v_mul_f32_e32 v35, v24, v25
	v_mov_b32_e32 v24, v26
	v_mov_b32_e32 v25, v30
	v_pk_fma_f32 v[28:29], v[148:149], v[64:65], v[152:153] op_sel:[0,1,0]
	v_mov_b32_e32 v30, v27
	v_pk_fma_f32 v[24:25], v[24:25], v[64:65], v[28:29] op_sel_hi:[1,0,1]
	s_nop 0
	v_mul_f32_e32 v26, 0xbfb8aa3b, v25
	v_exp_f32_e32 v26, v26
	s_nop 0
	v_add_f32_e32 v26, 1.0, v26
	v_rcp_f32_e32 v26, v26
	s_nop 0
	v_mul_f32_e32 v25, v25, v26
	v_mul_f32_e32 v28, v24, v25
	v_pk_fma_f32 v[24:25], v[74:75], v[64:65], v[78:79] op_sel:[0,1,0]
	s_nop 0
	v_pk_fma_f32 v[24:25], v[30:31], v[64:65], v[24:25] op_sel_hi:[1,0,1]
	s_nop 0
	v_mul_f32_e32 v26, 0xbfb8aa3b, v25
	v_exp_f32_e32 v26, v26
	s_nop 0
	v_add_f32_e32 v26, 1.0, v26
	v_rcp_f32_e32 v26, v26
	s_nop 0
	v_mul_f32_e32 v25, v25, v26
	v_mul_f32_e32 v29, v24, v25
	v_mov_b32_e32 v24, v16
	v_mov_b32_e32 v25, v20
	v_pk_fma_f32 v[26:27], v[150:151], v[64:65], v[154:155] op_sel:[0,1,0]
	v_mov_b32_e32 v20, v17
	v_pk_fma_f32 v[24:25], v[24:25], v[64:65], v[26:27] op_sel_hi:[1,0,1]
	s_nop 0
	v_mul_f32_e32 v16, 0xbfb8aa3b, v25
	v_exp_f32_e32 v16, v16
	s_nop 0
	v_add_f32_e32 v16, 1.0, v16
	v_rcp_f32_e32 v16, v16
	s_nop 0
	v_mul_f32_e32 v16, v25, v16
	v_mul_f32_e32 v24, v24, v16
	v_pk_fma_f32 v[16:17], v[52:53], v[64:65], v[56:57] op_sel:[0,1,0]
	s_nop 0
	v_pk_fma_f32 v[16:17], v[20:21], v[64:65], v[16:17] op_sel_hi:[1,0,1]
	s_nop 0
	v_mul_f32_e32 v20, 0xbfb8aa3b, v17
	v_exp_f32_e32 v20, v20
	s_nop 0
	v_add_f32_e32 v20, 1.0, v20
	v_rcp_f32_e32 v20, v20
	s_nop 0
	v_mul_f32_e32 v17, v17, v20
	v_mul_f32_e32 v25, v16, v17
	v_mov_b32_e32 v16, v18
	v_mov_b32_e32 v17, v22
	v_pk_fma_f32 v[20:21], v[140:141], v[64:65], v[144:145] op_sel:[0,1,0]
	v_mov_b32_e32 v22, v19
	v_pk_fma_f32 v[16:17], v[16:17], v[64:65], v[20:21] op_sel_hi:[1,0,1]
	v_lshl_add_u64 v[20:21], v[32:33], 0, v[142:143]
	v_mul_f32_e32 v18, 0xbfb8aa3b, v17
	v_exp_f32_e32 v18, v18
	s_nop 0
	v_add_f32_e32 v18, 1.0, v18
	v_rcp_f32_e32 v18, v18
	s_nop 0
	v_mul_f32_e32 v17, v17, v18
	v_mul_f32_e32 v26, v16, v17
	v_pk_fma_f32 v[16:17], v[54:55], v[64:65], v[58:59] op_sel:[0,1,0]
	s_nop 0
	v_pk_fma_f32 v[16:17], v[22:23], v[64:65], v[16:17] op_sel_hi:[1,0,1]
	s_nop 0
	v_mul_f32_e32 v18, 0xbfb8aa3b, v17
	v_exp_f32_e32 v18, v18
	s_nop 0
	v_add_f32_e32 v18, 1.0, v18
	v_rcp_f32_e32 v18, v18
	s_nop 0
	v_mul_f32_e32 v17, v17, v18
	v_mul_f32_e32 v19, v16, v17
	v_cvt_pk_bf16_f32 v16, v34, v35
	v_cvt_pk_bf16_f32 v17, v28, v29
	v_cvt_pk_bf16_f32 v18, v24, v25
	v_cvt_pk_bf16_f32 v19, v26, v19
	global_store_dwordx4 v[20:21], v[16:19], off
	v_pk_fma_f32 v[20:21], v[186:187], v[66:67], v[188:189] op_sel:[0,1,0]
	s_nop 0
	v_mov_b32_e32 v18, v8
	v_mov_b32_e32 v19, v12
	v_pk_fma_f32 v[18:19], v[18:19], v[66:67], v[20:21] op_sel_hi:[1,0,1]
	v_mov_b32_e32 v12, v9
	v_mul_f32_e32 v8, 0xbfb8aa3b, v19
	v_exp_f32_e32 v8, v8
	v_add_u32_e32 v16, 0xb0, v200
	v_mad_i64_i32 v[16:17], s[40:41], v16, s88, v[184:185]
	v_add_f32_e32 v8, 1.0, v8
	v_rcp_f32_e32 v8, v8
	s_mov_b64 s[40:41], -1
	v_mul_f32_e32 v8, v19, v8
	v_mul_f32_e32 v18, v18, v8
	v_pk_fma_f32 v[8:9], v[72:73], v[66:67], v[76:77] op_sel:[0,1,0]
	s_nop 0
	v_pk_fma_f32 v[8:9], v[12:13], v[66:67], v[8:9] op_sel_hi:[1,0,1]
	s_nop 0
	v_mul_f32_e32 v12, 0xbfb8aa3b, v9
	v_exp_f32_e32 v12, v12
	s_nop 0
	v_add_f32_e32 v12, 1.0, v12
	v_rcp_f32_e32 v12, v12
	s_nop 0
	v_mul_f32_e32 v9, v9, v12
	v_mul_f32_e32 v19, v8, v9
	v_mov_b32_e32 v8, v10
	v_mov_b32_e32 v9, v14
	v_pk_fma_f32 v[12:13], v[148:149], v[66:67], v[152:153] op_sel:[0,1,0]
	v_mov_b32_e32 v14, v11
	v_pk_fma_f32 v[8:9], v[8:9], v[66:67], v[12:13] op_sel_hi:[1,0,1]
	s_nop 0
	v_mul_f32_e32 v10, 0xbfb8aa3b, v9
	v_exp_f32_e32 v10, v10
	s_nop 0
	v_add_f32_e32 v10, 1.0, v10
	v_rcp_f32_e32 v10, v10
	s_nop 0
	v_mul_f32_e32 v9, v9, v10
	v_mul_f32_e32 v12, v8, v9
	v_pk_fma_f32 v[8:9], v[74:75], v[66:67], v[78:79] op_sel:[0,1,0]
	s_nop 0
	v_pk_fma_f32 v[8:9], v[14:15], v[66:67], v[8:9] op_sel_hi:[1,0,1]
	s_nop 0
	v_mul_f32_e32 v10, 0xbfb8aa3b, v9
	v_exp_f32_e32 v10, v10
	s_nop 0
	v_add_f32_e32 v10, 1.0, v10
	v_rcp_f32_e32 v10, v10
	s_nop 0
	v_mul_f32_e32 v9, v9, v10
	v_mul_f32_e32 v13, v8, v9
	v_mov_b32_e32 v8, v0
	v_mov_b32_e32 v9, v4
	v_pk_fma_f32 v[10:11], v[150:151], v[66:67], v[154:155] op_sel:[0,1,0]
	v_mov_b32_e32 v4, v1
	v_pk_fma_f32 v[8:9], v[8:9], v[66:67], v[10:11] op_sel_hi:[1,0,1]
	s_nop 0
	v_mul_f32_e32 v0, 0xbfb8aa3b, v9
	v_exp_f32_e32 v0, v0
	s_nop 0
	v_add_f32_e32 v0, 1.0, v0
	v_rcp_f32_e32 v0, v0
	s_nop 0
	v_mul_f32_e32 v0, v9, v0
	v_mul_f32_e32 v8, v8, v0
	v_pk_fma_f32 v[0:1], v[52:53], v[66:67], v[56:57] op_sel:[0,1,0]
	s_nop 0
	v_pk_fma_f32 v[0:1], v[4:5], v[66:67], v[0:1] op_sel_hi:[1,0,1]
	s_nop 0
	v_mul_f32_e32 v4, 0xbfb8aa3b, v1
	v_exp_f32_e32 v4, v4
	s_nop 0
	v_add_f32_e32 v4, 1.0, v4
	v_rcp_f32_e32 v4, v4
	s_nop 0
	v_mul_f32_e32 v1, v1, v4
	v_mul_f32_e32 v9, v0, v1
	v_mov_b32_e32 v0, v2
	v_mov_b32_e32 v1, v6
	v_pk_fma_f32 v[4:5], v[140:141], v[66:67], v[144:145] op_sel:[0,1,0]
	v_mov_b32_e32 v6, v3
	v_pk_fma_f32 v[0:1], v[0:1], v[66:67], v[4:5] op_sel_hi:[1,0,1]
	v_lshl_add_u64 v[4:5], v[16:17], 0, v[142:143]
	v_mul_f32_e32 v2, 0xbfb8aa3b, v1
	v_exp_f32_e32 v2, v2
	s_nop 0
	v_add_f32_e32 v2, 1.0, v2
	v_rcp_f32_e32 v2, v2
	s_nop 0
	v_mul_f32_e32 v1, v1, v2
	v_mul_f32_e32 v10, v0, v1
	v_pk_fma_f32 v[0:1], v[54:55], v[66:67], v[58:59] op_sel:[0,1,0]
	s_nop 0
	v_pk_fma_f32 v[0:1], v[6:7], v[66:67], v[0:1] op_sel_hi:[1,0,1]
	s_nop 0
	v_mul_f32_e32 v2, 0xbfb8aa3b, v1
	v_exp_f32_e32 v2, v2
	s_nop 0
	v_add_f32_e32 v2, 1.0, v2
	v_rcp_f32_e32 v2, v2
	s_nop 0
	v_mul_f32_e32 v1, v1, v2
	v_mul_f32_e32 v3, v0, v1
	v_cvt_pk_bf16_f32 v0, v18, v19
	v_cvt_pk_bf16_f32 v1, v12, v13
	v_cvt_pk_bf16_f32 v2, v8, v9
	v_cvt_pk_bf16_f32 v3, v10, v3
	global_store_dwordx4 v[4:5], v[0:3], off
	s_mov_b32 s99, 1
	s_cbranch_vccnz .LBB0_2464
	s_andn2_b64 vcc, exec, s[0:1]
	s_cbranch_vccnz .LBB0_2463
	s_barrier
	s_branch .LBB0_2463

.LBB0_2536:
	v_readlane_b32 s0, v255, 32
	v_readlane_b32 s1, v255, 33
	s_and_b64 vcc, exec, s[0:1]
	s_cbranch_vccnz .LBB0_2576
	v_ashrrev_i32_e32 v2, 31, v0
	v_lshrrev_b32_e32 v2, 26, v2
	v_add_u32_e32 v2, v0, v2
	v_ashrrev_i32_e32 v137, 6, v2
	v_bfe_i32 v2, v0, 27, 1
	v_lshlrev_b32_e32 v1, 4, v0
	v_lshrrev_b32_e32 v2, 22, v2
	v_add_u32_e32 v2, v1, v2
	v_and_b32_e32 v2, 0xfffffc00, v2
	v_sub_u32_e32 v2, v1, v2
	v_lshrrev_b32_e32 v3, 4, v2
	v_bitop3_b32 v2, v3, v2, 32 bitop3:0x6c
	v_ashrrev_i32_e32 v4, 31, v2
	v_lshrrev_b32_e32 v4, 26, v4
	v_lshlrev_b32_e32 v3, 3, v137
	v_add_u32_e32 v4, v2, v4
	v_and_b32_e32 v3, -16, v3
	v_ashrrev_i32_e32 v149, 6, v4
	v_and_b32_e32 v4, 0xc0, v4
	v_add_u32_e32 v3, v149, v3
	v_lshlrev_b32_e32 v5, 5, v137
	v_sub_u32_e32 v2, v2, v4
	v_mov_b32_e32 v4, 1
	v_and_b32_e32 v147, 32, v5
	v_ashrrev_i16_sdwa v2, v4, sext(v2) dst_sel:DWORD dst_unused:UNUSED_PAD src0_sel:DWORD src1_sel:BYTE_0
	v_lshlrev_b32_e32 v5, 1, v3
	v_lshrrev_b32_e32 v6, 2, v3
	v_and_b32_e32 v7, 3, v149
	s_mov_b32 s6, 0xffffe0
	v_bfe_i32 v161, v2, 0, 16
	v_and_b32_e32 v5, 24, v5
	v_and_b32_e32 v6, 4, v6
	v_and_or_b32 v7, v3, s6, v7
	s_movk_i32 s11, 0xb00
	v_add_u32_e32 v2, v147, v161
	v_or3_b32 v5, v7, v6, v5
	v_mul_lo_u32 v3, v3, s11
	v_add_lshl_u32 v128, v2, v3, 1
	v_mul_u32_u24_e32 v3, 0xb00, v5
	v_add_u32_e32 v1, 0x2000, v1
	v_add_lshl_u32 v130, v3, v2, 1
	v_ashrrev_i32_e32 v2, 31, v1
	v_lshrrev_b32_e32 v2, 22, v2
	v_add_u32_e32 v2, v1, v2
	v_ashrrev_i32_e32 v163, 10, v2
	v_mul_i32_i24_e32 v2, 0x400, v163
	v_sub_u32_e32 v1, v1, v2
	v_lshrrev_b32_e32 v2, 4, v1
	v_bitop3_b32 v1, v2, v1, 32 bitop3:0x6c
	v_ashrrev_i32_e32 v3, 31, v1
	v_lshrrev_b32_e32 v3, 26, v3
	v_lshlrev_b32_e32 v2, 3, v163
	v_add_u32_e32 v3, v1, v3
	v_and_b32_e32 v2, -16, v2
	v_ashrrev_i32_e32 v165, 6, v3
	v_and_b32_e32 v3, 0xc0, v3
	v_add_u32_e32 v2, v165, v2
	v_lshlrev_b32_e32 v5, 5, v163
	v_sub_u32_e32 v1, v1, v3
	v_and_b32_e32 v167, 32, v5
	v_ashrrev_i16_sdwa v1, v4, sext(v1) dst_sel:DWORD dst_unused:UNUSED_PAD src0_sel:DWORD src1_sel:BYTE_0
	v_lshlrev_b32_e32 v3, 1, v2
	v_lshrrev_b32_e32 v4, 2, v2
	v_and_b32_e32 v5, 3, v165
	v_bfe_i32 v169, v1, 0, 16
	v_and_b32_e32 v3, 24, v3
	v_and_b32_e32 v4, 4, v4
	v_and_or_b32 v5, v2, s6, v5
	v_add_u32_e32 v1, v167, v169
	v_or3_b32 v3, v5, v4, v3
	v_mul_lo_u32 v2, v2, s11
	v_bfe_u32 v151, v0, 4, 2
	v_add_lshl_u32 v132, v1, v2, 1
	v_mul_u32_u24_e32 v2, 0xb00, v3
	v_and_b32_e32 v153, 15, v0
	v_add_lshl_u32 v134, v2, v1, 1
	v_mov_b32_e32 v0, v153
	v_mov_b32_e32 v1, v151
	s_add_u32 s0, s20, 0x2000
	v_lshlrev_b32_e32 v2, 3, v1
	v_mbcnt_lo_u32_b32 v1, -1, 0
	v_mbcnt_hi_u32_b32 v1, -1, v1
	v_and_b32_e32 v5, 64, v1
	v_xor_b32_e32 v4, 16, v1
	v_add_u32_e32 v5, 64, v5
	v_cmp_lt_i32_e32 vcc, v4, v5
	s_addc_u32 s1, s21, 0
	s_ashr_i32 s5, s10, 6
	s_ashr_i32 s12, s10, 8
	v_cndmask_b32_e32 v4, v1, v4, vcc
	s_and_b32 s4, s5, 3
	s_lshl_b32 s9, s5, 10
	s_lshl_b32 s15, s12, 6
	s_lshl_b32 s5, s80, 8
	v_lshlrev_b32_e32 v155, 2, v4
	v_xor_b32_e32 v4, 32, v1
	s_add_i32 s5, s5, s15
	v_cmp_lt_i32_e32 vcc, v4, v5
	v_add_u32_e32 v0, s5, v0
	v_ashrrev_i32_e32 v3, 31, v2
	v_cndmask_b32_e32 v1, v1, v4, vcc
	v_lshlrev_b32_e32 v157, 2, v1
	v_ashrrev_i32_e32 v1, 31, v0
	v_lshl_add_u64 v[4:5], v[2:3], 2, s[62:63]
	v_lshlrev_b64 v[6:7], 7, v[0:1]
	v_lshl_add_u64 v[10:11], v[4:5], 0, v[6:7]
	v_mov_b32_e32 v184, v0
	v_ashrrev_i32_e32 v185, 31, v184
	v_lshlrev_b64 v[184:185], 7, v[184:185]
	v_lshl_add_u64 v[184:185], v[4:5], 0, v[184:185]
	global_load_dwordx4 v[188:191], v[184:185], off offset:16
	global_load_dwordx4 v[192:195], v[184:185], off
	v_add_u32_e32 v184, 0x10, v0
	v_ashrrev_i32_e32 v185, 31, v184
	v_lshlrev_b64 v[184:185], 7, v[184:185]
	v_lshl_add_u64 v[184:185], v[4:5], 0, v[184:185]
	global_load_dwordx4 v[196:199], v[184:185], off offset:16
	global_load_dwordx4 v[200:203], v[184:185], off
	v_add_u32_e32 v184, 0x20, v0
	v_ashrrev_i32_e32 v185, 31, v184
	v_lshlrev_b64 v[184:185], 7, v[184:185]
	v_lshl_add_u64 v[184:185], v[4:5], 0, v[184:185]
	global_load_dwordx4 v[204:207], v[184:185], off offset:16
	global_load_dwordx4 v[208:211], v[184:185], off
	v_add_u32_e32 v184, 0x30, v0
	v_ashrrev_i32_e32 v185, 31, v184
	v_lshlrev_b64 v[184:185], 7, v[184:185]
	v_lshl_add_u64 v[184:185], v[4:5], 0, v[184:185]
	global_load_dwordx4 v[212:215], v[184:185], off offset:16
	global_load_dwordx4 v[216:219], v[184:185], off
	v_add_u32_e32 v184, 0x80, v0
	v_ashrrev_i32_e32 v185, 31, v184
	v_lshlrev_b64 v[184:185], 7, v[184:185]
	v_lshl_add_u64 v[184:185], v[4:5], 0, v[184:185]
	global_load_dwordx4 v[220:223], v[184:185], off offset:16
	global_load_dwordx4 v[224:227], v[184:185], off
	v_add_u32_e32 v184, 0x90, v0
	v_ashrrev_i32_e32 v185, 31, v184
	v_lshlrev_b64 v[184:185], 7, v[184:185]
	v_lshl_add_u64 v[184:185], v[4:5], 0, v[184:185]
	global_load_dwordx4 v[228:231], v[184:185], off offset:16
	global_load_dwordx4 v[232:235], v[184:185], off
	v_add_u32_e32 v184, 0xa0, v0
	v_ashrrev_i32_e32 v185, 31, v184
	v_lshlrev_b64 v[184:185], 7, v[184:185]
	v_lshl_add_u64 v[184:185], v[4:5], 0, v[184:185]
	global_load_dwordx4 v[236:239], v[184:185], off offset:16
	global_load_dwordx4 v[240:243], v[184:185], off
	v_add_u32_e32 v184, 0xb0, v0
	v_ashrrev_i32_e32 v185, 31, v184
	v_lshlrev_b64 v[184:185], 7, v[184:185]
	v_lshl_add_u64 v[184:185], v[4:5], 0, v[184:185]
	global_load_dwordx4 v[244:247], v[184:185], off offset:16
	global_load_dwordx4 v[248:251], v[184:185], off
	s_waitcnt vmcnt(0)
	v_mov_b32_e32 v6, v188
	v_mov_b32_e32 v7, v189
	v_mov_b32_e32 v8, v190
	v_mov_b32_e32 v9, v191
	s_nop 0
	v_mov_b32_e32 v10, v192
	v_mov_b32_e32 v11, v193
	v_mov_b32_e32 v12, v194
	v_mov_b32_e32 v13, v195
	v_add_u32_e32 v56, 0x90, v0
	v_ashrrev_i32_e32 v57, 31, v56
	v_add_u32_e32 v58, 0xa0, v0
	v_ashrrev_i32_e32 v59, 31, v58
	v_add_u32_e32 v60, 0xb0, v0
	v_ashrrev_i32_e32 v61, 31, v60
	s_lshl_b32 s66, s4, 5
	s_lshl_b32 s6, s79, 8
	s_or_b32 s6, s6, s66
	v_add_u32_e32 v2, s6, v2
	v_ashrrev_i32_e32 v3, 31, v2
	s_cmp_gt_i32 s80, 63
	v_readlane_b32 s34, v255, 44
	v_readlane_b32 s36, v255, 46
	v_readlane_b32 s35, v255, 45
	v_readlane_b32 s37, v255, 47
	s_cselect_b32 s7, s36, s34
	s_mul_i32 s34, s79, 0x160000
	s_cselect_b32 s6, s37, s35
	s_mul_hi_i32 s14, s79, 0x160000
	s_add_u32 s74, s7, s34
	s_addc_u32 s75, s6, s14
	s_add_i32 s67, s9, 0
	s_add_i32 m0, s67, 0x10000
	s_mul_i32 s13, s80, 0x160000
	s_mul_hi_i32 s8, s80, 0x160000
	v_mov_b32_e32 v136, 0
	v_mov_b32_e32 v131, v136
	v_mov_b32_e32 v135, v136
	v_mov_b32_e32 v129, v136
	v_mov_b32_e32 v133, v136
	s_mov_b32 s5, 0
	v_mov_b32_e32 v15, v6
	v_mov_b32_e32 v14, v10
	v_mov_b32_e32 v16, v12
	v_mov_b32_e32 v17, v8
	v_pk_add_f32 v[14:15], v[14:15], v[16:17]
	v_add_f32_e32 v6, v11, v13
	v_add_f32_e32 v8, v7, v9
	v_mov_b32_e32 v7, v14
	v_mov_b32_e32 v9, v15
	v_pk_add_f32 v[6:7], v[6:7], v[8:9]
	ds_bpermute_b32 v9, v155, v7
	ds_bpermute_b32 v8, v155, v6
	s_waitcnt lgkmcnt(0)
	v_pk_add_f32 v[48:49], v[6:7], v[8:9]
	v_add_u32_e32 v6, 16, v0
	v_ashrrev_i32_e32 v7, 31, v6
	v_lshlrev_b64 v[8:9], 7, v[6:7]
	v_lshl_add_u64 v[12:13], v[4:5], 0, v[8:9]
	v_mov_b32_e32 v8, v196
	v_mov_b32_e32 v9, v197
	v_mov_b32_e32 v10, v198
	v_mov_b32_e32 v11, v199
	s_nop 0
	v_mov_b32_e32 v12, v200
	v_mov_b32_e32 v13, v201
	v_mov_b32_e32 v14, v202
	v_mov_b32_e32 v15, v203
	ds_bpermute_b32 v51, v157, v49
	ds_bpermute_b32 v50, v157, v48
	v_mov_b32_e32 v17, v8
	v_mov_b32_e32 v16, v12
	v_mov_b32_e32 v18, v14
	v_mov_b32_e32 v19, v10
	v_pk_add_f32 v[16:17], v[16:17], v[18:19]
	v_add_f32_e32 v8, v13, v15
	v_add_f32_e32 v10, v9, v11
	v_mov_b32_e32 v9, v16
	v_mov_b32_e32 v11, v17
	v_pk_add_f32 v[8:9], v[8:9], v[10:11]
	ds_bpermute_b32 v11, v155, v9
	ds_bpermute_b32 v10, v155, v8
	s_waitcnt lgkmcnt(0)
	v_pk_add_f32 v[52:53], v[8:9], v[10:11]
	v_add_u32_e32 v8, 32, v0
	v_ashrrev_i32_e32 v9, 31, v8
	v_lshlrev_b64 v[10:11], 7, v[8:9]
	v_lshl_add_u64 v[14:15], v[4:5], 0, v[10:11]
	v_mov_b32_e32 v10, v204
	v_mov_b32_e32 v11, v205
	v_mov_b32_e32 v12, v206
	v_mov_b32_e32 v13, v207
	s_nop 0
	v_mov_b32_e32 v14, v208
	v_mov_b32_e32 v15, v209
	v_mov_b32_e32 v16, v210
	v_mov_b32_e32 v17, v211
	ds_bpermute_b32 v55, v157, v53
	ds_bpermute_b32 v54, v157, v52
	v_mov_b32_e32 v19, v10
	v_mov_b32_e32 v18, v14
	v_mov_b32_e32 v20, v16
	v_mov_b32_e32 v21, v12
	v_pk_add_f32 v[18:19], v[18:19], v[20:21]
	v_add_f32_e32 v10, v15, v17
	v_add_f32_e32 v12, v11, v13
	v_mov_b32_e32 v11, v18
	v_mov_b32_e32 v13, v19
	v_pk_add_f32 v[10:11], v[10:11], v[12:13]
	ds_bpermute_b32 v13, v155, v11
	ds_bpermute_b32 v12, v155, v10
	s_waitcnt lgkmcnt(0)
	v_pk_add_f32 v[64:65], v[10:11], v[12:13]
	v_add_u32_e32 v10, 48, v0
	v_ashrrev_i32_e32 v11, 31, v10
	v_lshlrev_b64 v[12:13], 7, v[10:11]
	v_lshl_add_u64 v[16:17], v[4:5], 0, v[12:13]
	v_mov_b32_e32 v12, v212
	v_mov_b32_e32 v13, v213
	v_mov_b32_e32 v14, v214
	v_mov_b32_e32 v15, v215
	s_nop 0
	v_mov_b32_e32 v16, v216
	v_mov_b32_e32 v17, v217
	v_mov_b32_e32 v18, v218
	v_mov_b32_e32 v19, v219
	ds_bpermute_b32 v67, v157, v65
	ds_bpermute_b32 v66, v157, v64
	v_mov_b32_e32 v21, v12
	v_mov_b32_e32 v20, v16
	v_mov_b32_e32 v22, v18
	v_mov_b32_e32 v23, v14
	v_pk_add_f32 v[20:21], v[20:21], v[22:23]
	v_add_f32_e32 v12, v17, v19
	v_add_f32_e32 v14, v13, v15
	v_mov_b32_e32 v13, v20
	v_mov_b32_e32 v15, v21
	v_pk_add_f32 v[12:13], v[12:13], v[14:15]
	ds_bpermute_b32 v15, v155, v13
	ds_bpermute_b32 v14, v155, v12
	s_waitcnt lgkmcnt(0)
	v_pk_add_f32 v[68:69], v[12:13], v[14:15]
	v_add_u32_e32 v12, 0x80, v0
	v_ashrrev_i32_e32 v13, 31, v12
	v_lshlrev_b64 v[14:15], 7, v[12:13]
	v_lshl_add_u64 v[18:19], v[4:5], 0, v[14:15]
	v_mov_b32_e32 v14, v220
	v_mov_b32_e32 v15, v221
	v_mov_b32_e32 v16, v222
	v_mov_b32_e32 v17, v223
	s_nop 0
	v_mov_b32_e32 v18, v224
	v_mov_b32_e32 v19, v225
	v_mov_b32_e32 v20, v226
	v_mov_b32_e32 v21, v227
	v_lshlrev_b64 v[0:1], 11, v[0:1]
	v_lshl_add_u64 v[0:1], s[44:45], 0, v[0:1]
	ds_bpermute_b32 v71, v157, v69
	ds_bpermute_b32 v70, v157, v68
	v_mov_b32_e32 v23, v14
	v_mov_b32_e32 v22, v18
	v_mov_b32_e32 v24, v20
	v_mov_b32_e32 v25, v16
	v_pk_add_f32 v[22:23], v[22:23], v[24:25]
	v_add_f32_e32 v14, v19, v21
	v_add_f32_e32 v16, v15, v17
	v_mov_b32_e32 v15, v22
	v_mov_b32_e32 v17, v23
	v_pk_add_f32 v[14:15], v[14:15], v[16:17]
	ds_bpermute_b32 v17, v155, v15
	ds_bpermute_b32 v16, v155, v14
	s_waitcnt lgkmcnt(0)
	v_pk_add_f32 v[112:113], v[14:15], v[16:17]
	v_lshlrev_b64 v[14:15], 7, v[56:57]
	v_lshl_add_u64 v[18:19], v[4:5], 0, v[14:15]
	v_mov_b32_e32 v14, v228
	v_mov_b32_e32 v15, v229
	v_mov_b32_e32 v16, v230
	v_mov_b32_e32 v17, v231
	s_nop 0
	v_mov_b32_e32 v18, v232
	v_mov_b32_e32 v19, v233
	v_mov_b32_e32 v20, v234
	v_mov_b32_e32 v21, v235
	ds_bpermute_b32 v115, v157, v113
	ds_bpermute_b32 v114, v157, v112
	v_mov_b32_e32 v23, v14
	v_mov_b32_e32 v22, v18
	v_mov_b32_e32 v24, v20
	v_mov_b32_e32 v25, v16
	v_pk_add_f32 v[22:23], v[22:23], v[24:25]
	v_add_f32_e32 v14, v19, v21
	v_add_f32_e32 v16, v15, v17
	v_mov_b32_e32 v15, v22
	v_mov_b32_e32 v17, v23
	v_pk_add_f32 v[14:15], v[14:15], v[16:17]
	ds_bpermute_b32 v17, v155, v15
	ds_bpermute_b32 v16, v155, v14
	s_waitcnt lgkmcnt(0)
	v_pk_add_f32 v[116:117], v[14:15], v[16:17]
	v_lshlrev_b64 v[14:15], 7, v[58:59]
	v_lshl_add_u64 v[18:19], v[4:5], 0, v[14:15]
	v_mov_b32_e32 v14, v236
	v_mov_b32_e32 v15, v237
	v_mov_b32_e32 v16, v238
	v_mov_b32_e32 v17, v239
	s_nop 0
	v_mov_b32_e32 v18, v240
	v_mov_b32_e32 v19, v241
	v_mov_b32_e32 v20, v242
	v_mov_b32_e32 v21, v243
	ds_bpermute_b32 v119, v157, v117
	ds_bpermute_b32 v118, v157, v116
	v_mov_b32_e32 v23, v14
	v_mov_b32_e32 v22, v18
	v_mov_b32_e32 v24, v20
	v_mov_b32_e32 v25, v16
	v_pk_add_f32 v[22:23], v[22:23], v[24:25]
	v_add_f32_e32 v14, v19, v21
	v_add_f32_e32 v16, v15, v17
	v_mov_b32_e32 v15, v22
	v_mov_b32_e32 v17, v23
	v_pk_add_f32 v[14:15], v[14:15], v[16:17]
	ds_bpermute_b32 v17, v155, v15
	ds_bpermute_b32 v16, v155, v14
	s_waitcnt lgkmcnt(0)
	v_pk_add_f32 v[120:121], v[14:15], v[16:17]
	v_lshlrev_b64 v[14:15], 7, v[60:61]
	v_lshl_add_u64 v[4:5], v[4:5], 0, v[14:15]
	v_mov_b32_e32 v14, v244
	v_mov_b32_e32 v15, v245
	v_mov_b32_e32 v16, v246
	v_mov_b32_e32 v17, v247
	v_mov_b32_e32 v18, v248
	v_mov_b32_e32 v19, v249
	v_mov_b32_e32 v20, v250
	v_mov_b32_e32 v21, v251
	ds_bpermute_b32 v123, v157, v121
	ds_bpermute_b32 v122, v157, v120
	v_mov_b32_e32 v5, v14
	v_mov_b32_e32 v4, v18
	v_mov_b32_e32 v22, v20
	v_mov_b32_e32 v23, v16
	v_pk_add_f32 v[4:5], v[4:5], v[22:23]
	v_add_f32_e32 v14, v19, v21
	v_add_f32_e32 v16, v15, v17
	v_mov_b32_e32 v15, v4
	v_mov_b32_e32 v17, v5
	v_pk_add_f32 v[4:5], v[14:15], v[16:17]
	ds_bpermute_b32 v15, v155, v5
	ds_bpermute_b32 v14, v155, v4
	s_waitcnt lgkmcnt(0)
	v_pk_add_f32 v[124:125], v[4:5], v[14:15]
	v_lshlrev_b64 v[4:5], 2, v[2:3]
	v_lshlrev_b64 v[2:3], 1, v[2:3]
	v_lshl_add_u64 v[74:75], v[0:1], 0, v[2:3]
	v_lshlrev_b64 v[0:1], 11, v[6:7]
	v_lshl_add_u64 v[0:1], s[44:45], 0, v[0:1]
	v_lshl_add_u64 v[76:77], v[0:1], 0, v[2:3]
	v_lshlrev_b64 v[0:1], 11, v[8:9]
	v_lshl_add_u64 v[0:1], s[44:45], 0, v[0:1]
	v_lshl_add_u64 v[78:79], v[0:1], 0, v[2:3]
	v_lshlrev_b64 v[0:1], 11, v[10:11]
	v_lshl_add_u64 v[0:1], s[44:45], 0, v[0:1]
	v_lshl_add_u64 v[80:81], v[0:1], 0, v[2:3]
	v_lshlrev_b64 v[0:1], 11, v[12:13]
	v_lshl_add_u64 v[0:1], s[44:45], 0, v[0:1]
	v_lshl_add_u64 v[138:139], v[0:1], 0, v[2:3]
	v_lshlrev_b64 v[0:1], 11, v[56:57]
	v_lshl_add_u64 v[0:1], s[44:45], 0, v[0:1]
	v_lshl_add_u64 v[56:57], v[0:1], 0, v[2:3]
	v_lshlrev_b64 v[0:1], 11, v[58:59]
	v_lshl_add_u64 v[0:1], s[44:45], 0, v[0:1]
	v_lshl_add_u64 v[58:59], v[0:1], 0, v[2:3]
	v_lshlrev_b64 v[0:1], 11, v[60:61]
	v_lshl_add_u64 v[0:1], s[44:45], 0, v[0:1]
	v_lshl_add_u64 v[62:63], s[72:73], 0, v[4:5]
	v_lshl_add_u64 v[72:73], s[0:1], 0, v[4:5]
	v_lshl_add_u64 v[140:141], v[0:1], 0, v[2:3]
	global_load_dwordx4 v[36:39], v[62:63], off offset:16
	global_load_dwordx4 v[44:47], v[62:63], off
	global_load_dwordx4 v[32:35], v[72:73], off offset:16
	global_load_dwordx4 v[40:43], v[72:73], off
	global_load_dwordx4 v[28:31], v[74:75], off
	global_load_dwordx4 v[24:27], v[76:77], off
	global_load_dwordx4 v[20:23], v[78:79], off
	global_load_dwordx4 v[16:19], v[80:81], off
	global_load_dwordx4 v[12:15], v[138:139], off
	global_load_dwordx4 v[8:11], v[56:57], off
	global_load_dwordx4 v[4:7], v[58:59], off
	global_load_dwordx4 v[0:3], v[140:141], off
	global_load_dwordx4 v[100:103], v[62:63], off offset:528
	global_load_dwordx4 v[108:111], v[62:63], off offset:512
	global_load_dwordx4 v[96:99], v[72:73], off offset:528
	global_load_dwordx4 v[104:107], v[72:73], off offset:512
	global_load_dwordx4 v[92:95], v[74:75], off offset:256
	global_load_dwordx4 v[88:91], v[76:77], off offset:256
	global_load_dwordx4 v[84:87], v[78:79], off offset:256
	s_nop 0
	global_load_dwordx4 v[80:83], v[80:81], off offset:256
	s_nop 0
	global_load_dwordx4 v[76:79], v[138:139], off offset:256
	global_load_dwordx4 v[72:75], v[56:57], off offset:256
	global_load_dwordx4 v[60:63], v[58:59], off offset:256
	s_nop 0
	global_load_dwordx4 v[56:59], v[140:141], off offset:256
	ds_bpermute_b32 v127, v157, v125
	global_load_lds_dwordx4 v130, s[74:75]
	s_add_i32 m0, s67, 0x12000
	s_add_u32 s6, s74, 0xb0000
	global_load_lds_dwordx4 v134, s[74:75]
	s_addc_u32 s7, s75, 0
	s_add_i32 m0, s67, 0x14000
	ds_bpermute_b32 v126, v157, v124
	global_load_lds_dwordx4 v130, s[6:7]
	s_add_i32 m0, s67, 0x16000
	s_add_u32 s40, s42, s13
	s_addc_u32 s41, s43, s8
	s_add_i32 s68, s67, 0x2000
	global_load_lds_dwordx4 v134, s[6:7]
	s_mov_b32 m0, s67
	s_add_u32 s6, s40, 0xb0000
	global_load_lds_dwordx4 v128, s[40:41]
	s_mov_b32 m0, s68
	s_addc_u32 s7, s41, 0
	s_add_i32 s69, s67, 0x4000
	global_load_lds_dwordx4 v132, s[40:41]
	s_mov_b32 m0, s69
	s_add_i32 s88, s67, 0x6000
	global_load_lds_dwordx4 v128, s[6:7]
	s_mov_b32 m0, s88
	s_cmp_eq_u32 s12, 1
	global_load_lds_dwordx4 v132, s[6:7]
	v_lshl_add_u64 v[138:139], s[74:75], 0, v[130:131]
	v_lshl_add_u64 v[140:141], s[74:75], 0, v[134:135]
	v_lshl_add_u64 v[142:143], s[40:41], 0, v[128:129]
	v_lshl_add_u64 v[144:145], s[40:41], 0, v[132:133]
	s_cselect_b64 s[6:7], -1, 0
	s_cmp_lg_u32 s12, 1
	s_cbranch_scc1 .LBB0_2539
	s_barrier

.LBB0_2784:
	s_add_u32 s6, s58, 0x3788000
	v_and_b32_e32 v192, 15, v8
	v_and_b32_e32 v15, 48, v8
	v_lshlrev_b32_e32 v16, 2, v8
	s_addc_u32 s7, s59, 0
	s_and_b32 s18, s11, 3
	s_lshl_b32 s8, s10, 13
	v_lshl_or_b32 v15, v192, 6, v15
	v_and_b32_e32 v17, 32, v16
	s_lshl_b32 s68, s10, 6
	v_bitop3_b32 v18, v15, s8, v17 bitop3:0xde
	s_lshl_b32 s69, s18, 5
	s_lshl_b32 s8, s18, 12
	v_bitop3_b32 v194, v15, s8, v17 bitop3:0xde
	s_add_u32 s8, s58, 0x377e000
	s_mov_b64 s[12:13], 0x80
	s_addc_u32 s9, s59, 0
	s_add_i32 m0, s41, 0x18000
	v_lshl_add_u64 v[6:7], v[6:7], 0, s[12:13]
	s_waitcnt vmcnt(2)
	s_barrier
	global_load_lds_dwordx4 v[6:7], off
	v_lshl_add_u64 v[4:5], v[4:5], 0, s[12:13]
	s_add_i32 m0, s41, 0x1a000
	s_add_i32 s70, s41, 0x8000
	s_add_i32 s71, s41, 0xa000
	global_load_lds_dwordx4 v[4:5], off
	v_lshl_add_u64 v[0:1], v[0:1], 0, s[12:13]
	s_mov_b32 m0, s70
	s_add_u32 s16, s52, 0x40080
	global_load_lds_dwordx4 v[0:1], off
	v_lshl_add_u64 v[0:1], v[2:3], 0, s[12:13]
	s_mov_b32 m0, s71
	s_addc_u32 s17, s53, 0
	global_load_lds_dwordx4 v[0:1], off
	s_add_i32 m0, s41, 0x1c000
	v_lshl_add_u64 v[0:1], s[16:17], 0, v[178:179]
	global_load_lds_dwordx4 v[0:1], off
	v_lshl_add_u64 v[0:1], s[16:17], 0, v[182:183]
	s_add_i32 m0, s41, 0x1e000
	s_lshl_b32 s72, s11, 9
	global_load_lds_dwordx4 v[0:1], off
	v_and_b32_e32 v0, 0x80, v16
	v_and_b32_e32 v1, 31, v8
	v_or3_b32 v195, v1, v0, s69
	v_lshlrev_b32_e32 v0, 14, v9
	v_and_b32_e32 v0, 0xffff8000, v0
	v_lshl_add_u32 v0, v10, 11, v0
	v_and_b32_e32 v1, 1, v9
	v_lshl_or_b32 v0, v1, 6, v0
	v_lshl_add_u32 v184, v11, 1, v0
	v_lshlrev_b32_e32 v0, 14, v12
	s_cmpk_lt_u32 s0, 0x100
	v_and_b32_e32 v0, 0xffff8000, v0
	s_waitcnt vmcnt(6)
	s_cselect_b64 s[16:17], -1, 0
	s_lshl_b32 s0, s10, 11
	s_lshl_b32 s10, s18, 9
	v_lshl_add_u32 v0, v13, 11, v0
	v_and_b32_e32 v1, 1, v12
	s_or_b32 s73, s0, s10
	v_lshl_or_b32 v0, v1, 6, v0
	v_bfe_u32 v193, v8, 4, 2
	s_add_i32 s73, s73, 0x22400
	v_mov_b32_e32 v185, v179
	v_lshl_add_u32 v186, v14, 1, v0
	v_mov_b32_e32 v187, v179
	v_mov_b64_e32 v[188:189], 0xa00
	v_mov_b64_e32 v[190:191], 0x9ff
	s_add_i32 s74, s72, 0x22500
	s_add_i32 s75, 0, 0x10000
	s_add_i32 s78, 0, 0x14000
	v_add_u32_e32 v196, 0, v18
	s_mov_b32 s18, 0x3e38aa3b
	v_mov_b32_e32 v197, 0x20400
	s_mov_b32 s79, 0
	s_barrier
	s_mov_b32 s99, 0
	s_branch .LBB0_2787

.LBB0_2790:
	v_add_u32_e32 v56, s75, v194
	v_add_u32_e32 v72, s78, v194
	ds_read_b128 v[40:43], v56
	ds_read_b128 v[44:47], v56 offset:1024
	ds_read_b128 v[48:51], v56 offset:2048
	ds_read_b128 v[56:59], v56 offset:3072
	ds_read_b128 v[60:63], v72
	ds_read_b128 v[64:67], v72 offset:1024
	ds_read_b128 v[68:71], v72 offset:2048
	ds_read_b128 v[72:75], v72 offset:3072
	s_add_u32 s54, s46, 0xfffc0080
	s_addc_u32 s55, s47, -1
	s_and_b64 s[52:53], s[52:53], exec
	s_cselect_b32 s55, s0, s55
	s_cselect_b32 s54, s25, s54
	s_cselect_b32 s53, s23, s80
	s_cselect_b32 s52, s37, s49
	v_lshl_add_u64 v[210:211], s[46:47], 0, v[184:185]
	s_add_i32 m0, s41, 0xc000
	ds_read_b128 v[100:103], v196
	ds_read_b128 v[136:139], v196 offset:1024
	ds_read_b128 v[172:175], v196 offset:2048
	ds_read_b128 v[198:201], v196 offset:3072
	ds_read_b128 v[202:205], v196 offset:4096
	ds_read_b128 v[206:209], v196 offset:5120
	ds_read_b128 v[212:215], v196 offset:6144
	ds_read_b128 v[216:219], v196 offset:7168
	global_load_lds_dwordx4 v[210:211], off
	v_lshl_add_u64 v[210:211], s[46:47], 0, v[186:187]
	s_add_i32 m0, s41, 0xe000
	s_nop 0
	global_load_lds_dwordx4 v[210:211], off
	s_cmp_lg_u32 s99, 0
	s_cbranch_scc1 .Lrlx26a
	s_waitcnt vmcnt(8)
.Lrlx26a_done:
	s_waitcnt lgkmcnt(0)
	s_barrier
	s_setprio 1
	s_waitcnt lgkmcnt(0)
	v_mfma_f32_16x16x32_f16 v[168:171], v[40:43], v[100:103], v[168:171]
	v_mfma_f32_16x16x32_f16 v[164:167], v[48:51], v[100:103], v[164:167]
	v_mfma_f32_16x16x32_f16 v[152:155], v[40:43], v[172:175], v[152:155]
	v_mfma_f32_16x16x32_f16 v[148:151], v[48:51], v[172:175], v[148:151]
	v_mfma_f32_16x16x32_f16 v[132:135], v[40:43], v[202:205], v[132:135]
	v_mfma_f32_16x16x32_f16 v[128:131], v[48:51], v[202:205], v[128:131]
	v_mfma_f32_16x16x32_f16 v[116:119], v[40:43], v[212:215], v[116:119]
	v_mfma_f32_16x16x32_f16 v[112:115], v[48:51], v[212:215], v[112:115]
	v_mfma_f32_16x16x32_f16 v[168:171], v[44:47], v[136:139], v[168:171]
	v_mfma_f32_16x16x32_f16 v[164:167], v[56:59], v[136:139], v[164:167]
	v_mfma_f32_16x16x32_f16 v[152:155], v[44:47], v[198:201], v[152:155]
	v_mfma_f32_16x16x32_f16 v[148:151], v[56:59], v[198:201], v[148:151]
	v_mfma_f32_16x16x32_f16 v[132:135], v[44:47], v[206:209], v[132:135]
	v_mfma_f32_16x16x32_f16 v[128:131], v[56:59], v[206:209], v[128:131]
	v_mfma_f32_16x16x32_f16 v[116:119], v[44:47], v[216:219], v[116:119]
	v_mfma_f32_16x16x32_f16 v[112:115], v[56:59], v[216:219], v[112:115]
	s_setprio 0
	s_setprio 1
	v_mfma_f32_16x16x32_f16 v[160:163], v[60:63], v[100:103], v[160:163]
	v_mfma_f32_16x16x32_f16 v[100:103], v[68:71], v[100:103], v[156:159]
	v_mfma_f32_16x16x32_f16 v[140:143], v[68:71], v[172:175], v[140:143]
	v_mfma_f32_16x16x32_f16 v[124:127], v[60:63], v[202:205], v[124:127]
	v_mfma_f32_16x16x32_f16 v[120:123], v[68:71], v[202:205], v[120:123]
	v_mfma_f32_16x16x32_f16 v[108:111], v[60:63], v[212:215], v[108:111]
	v_mfma_f32_16x16x32_f16 v[104:107], v[68:71], v[212:215], v[104:107]
	v_mfma_f32_16x16x32_f16 v[160:163], v[64:67], v[136:139], v[160:163]
	v_mfma_f32_16x16x32_f16 v[100:103], v[72:75], v[136:139], v[100:103]
	v_mfma_f32_16x16x32_f16 v[136:139], v[60:63], v[172:175], v[144:147]
	v_mfma_f32_16x16x32_f16 v[140:143], v[72:75], v[198:201], v[140:143]
	v_mfma_f32_16x16x32_f16 v[124:127], v[64:67], v[206:209], v[124:127]
	v_mfma_f32_16x16x32_f16 v[120:123], v[72:75], v[206:209], v[120:123]
	v_mfma_f32_16x16x32_f16 v[108:111], v[64:67], v[216:219], v[108:111]
	v_mfma_f32_16x16x32_f16 v[104:107], v[72:75], v[216:219], v[104:107]
	v_mfma_f32_16x16x32_f16 v[136:139], v[64:67], v[198:201], v[136:139]
	s_setprio 0
	s_barrier
	s_add_i32 s82, s75, s66
	v_lshl_add_u64 v[210:211], s[52:53], 0, v[178:179]
	s_mov_b32 m0, s82
	ds_read_b128 v[144:147], v196 offset:16384
	ds_read_b128 v[156:159], v196 offset:17408
	ds_read_b128 v[172:175], v196 offset:18432
	ds_read_b128 v[198:201], v196 offset:19456
	ds_read_b128 v[202:205], v196 offset:20480
	ds_read_b128 v[206:209], v196 offset:21504
	ds_read_b128 v[212:215], v196 offset:22528
	ds_read_b128 v[216:219], v196 offset:23552
	global_load_lds_dwordx4 v[210:211], off
	s_add_i32 m0, s82, 0x2000
	s_add_u32 s82, s52, 0x40000
	v_lshl_add_u64 v[228:229], s[52:53], 0, v[182:183]
	s_addc_u32 s83, s53, 0
	s_add_i32 s84, s78, s66
	global_load_lds_dwordx4 v[228:229], off
	v_lshl_add_u64 v[220:221], s[82:83], 0, v[178:179]
	s_mov_b32 m0, s84
	v_lshl_add_u64 v[230:231], s[54:55], 0, v[176:177]
	global_load_lds_dwordx4 v[220:221], off
	v_lshl_add_u64 v[220:221], s[82:83], 0, v[182:183]
	s_add_i32 m0, s84, 0x2000
	v_lshl_add_u64 v[232:233], s[54:55], 0, v[180:181]
	global_load_lds_dwordx4 v[220:221], off
	s_mov_b32 m0, s41
	s_nop 0
	global_load_lds_dwordx4 v[230:231], off
	s_mov_b32 m0, s67
	s_nop 0
	global_load_lds_dwordx4 v[232:233], off
	s_cmp_lg_u32 s99, 0
	s_cbranch_scc1 .Lrlx26b
	s_waitcnt vmcnt(8)
.Lrlx26b_done:
	s_mov_b32 s99, 0
	s_waitcnt lgkmcnt(0)
	s_barrier
	s_setprio 1
	s_waitcnt lgkmcnt(0)
	v_mfma_f32_16x16x32_f16 v[96:99], v[40:43], v[144:147], v[96:99]
	v_mfma_f32_16x16x32_f16 v[92:95], v[48:51], v[144:147], v[92:95]
	v_mfma_f32_16x16x32_f16 v[80:83], v[40:43], v[172:175], v[80:83]
	v_mfma_f32_16x16x32_f16 v[76:79], v[48:51], v[172:175], v[76:79]
	v_mfma_f32_16x16x32_f16 v[28:31], v[40:43], v[202:205], v[28:31]
	v_mfma_f32_16x16x32_f16 v[24:27], v[48:51], v[202:205], v[24:27]
	v_mfma_f32_16x16x32_f16 v[12:15], v[40:43], v[212:215], v[12:15]
	v_mfma_f32_16x16x32_f16 v[8:11], v[48:51], v[212:215], v[8:11]
	v_mfma_f32_16x16x32_f16 v[96:99], v[44:47], v[156:159], v[96:99]
	v_mfma_f32_16x16x32_f16 v[92:95], v[56:59], v[156:159], v[92:95]
	v_mfma_f32_16x16x32_f16 v[80:83], v[44:47], v[198:201], v[80:83]
	v_mfma_f32_16x16x32_f16 v[76:79], v[56:59], v[198:201], v[76:79]
	v_mfma_f32_16x16x32_f16 v[28:31], v[44:47], v[206:209], v[28:31]
	v_mfma_f32_16x16x32_f16 v[24:27], v[56:59], v[206:209], v[24:27]
	v_mfma_f32_16x16x32_f16 v[12:15], v[44:47], v[216:219], v[12:15]
	v_mfma_f32_16x16x32_f16 v[8:11], v[56:59], v[216:219], v[8:11]
	s_setprio 0
	s_setprio 1
	v_mfma_f32_16x16x32_f16 v[36:39], v[68:71], v[172:175], v[36:39]
	v_mfma_f32_16x16x32_f16 v[20:23], v[60:63], v[202:205], v[20:23]
	v_mfma_f32_16x16x32_f16 v[16:19], v[68:71], v[202:205], v[16:19]
	v_mfma_f32_16x16x32_f16 v[4:7], v[60:63], v[212:215], v[4:7]
	v_mfma_f32_16x16x32_f16 v[0:3], v[68:71], v[212:215], v[0:3]
	v_mfma_f32_16x16x32_f16 v[40:43], v[60:63], v[144:147], v[88:91]
	v_mfma_f32_16x16x32_f16 v[44:47], v[68:71], v[144:147], v[84:87]
	v_mfma_f32_16x16x32_f16 v[48:51], v[60:63], v[172:175], v[52:55]
	v_mfma_f32_16x16x32_f16 v[36:39], v[72:75], v[198:201], v[36:39]
	v_mfma_f32_16x16x32_f16 v[20:23], v[64:67], v[206:209], v[20:23]
	v_mfma_f32_16x16x32_f16 v[16:19], v[72:75], v[206:209], v[16:19]
	v_mfma_f32_16x16x32_f16 v[4:7], v[64:67], v[216:219], v[4:7]
	v_mfma_f32_16x16x32_f16 v[0:3], v[72:75], v[216:219], v[0:3]
	v_mfma_f32_16x16x32_f16 v[40:43], v[64:67], v[156:159], v[40:43]
	v_mfma_f32_16x16x32_f16 v[44:47], v[72:75], v[156:159], v[44:47]
	v_mfma_f32_16x16x32_f16 v[48:51], v[64:67], v[198:201], v[48:51]
	s_setprio 0
	s_barrier
	s_add_i32 s82, 0, 0x18000
	s_add_i32 s83, 0, 0x1c000
	v_add_u32_e32 v64, s82, v194
	v_add_u32_e32 v84, s83, v194
	ds_read_b128 v[52:55], v64
	ds_read_b128 v[56:59], v64 offset:1024
	ds_read_b128 v[60:63], v64 offset:2048
	ds_read_b128 v[64:67], v64 offset:3072
	ds_read_b128 v[68:71], v84
	ds_read_b128 v[72:75], v84 offset:1024
	ds_read_b128 v[172:175], v84 offset:2048
	ds_read_b128 v[198:201], v84 offset:3072
	s_add_u32 s54, s54, 0x40000
	s_addc_u32 s55, s55, 0
	s_mov_b32 m0, s64
	v_lshl_add_u64 v[144:145], s[54:55], 0, v[176:177]
	ds_read_b128 v[84:87], v196 offset:32768
	ds_read_b128 v[88:91], v196 offset:33792
	ds_read_b128 v[202:205], v196 offset:34816
	ds_read_b128 v[206:209], v196 offset:35840
	ds_read_b128 v[212:215], v196 offset:36864
	ds_read_b128 v[216:219], v196 offset:37888
	ds_read_b128 v[220:223], v196 offset:38912
	ds_read_b128 v[224:227], v196 offset:39936
	global_load_lds_dwordx4 v[144:145], off
	v_lshl_add_u64 v[144:145], s[54:55], 0, v[180:181]
	s_mov_b32 m0, s65
	s_nop 0
	global_load_lds_dwordx4 v[144:145], off
	s_waitcnt vmcnt(8)
	s_waitcnt lgkmcnt(0)
	s_barrier
	s_setprio 1
	s_waitcnt lgkmcnt(0)
	v_mfma_f32_16x16x32_f16 v[144:147], v[52:55], v[84:87], v[168:171]
	v_mfma_f32_16x16x32_f16 v[168:171], v[56:59], v[88:91], v[144:147]
	v_mfma_f32_16x16x32_f16 v[144:147], v[60:63], v[84:87], v[164:167]
	v_mfma_f32_16x16x32_f16 v[164:167], v[64:67], v[88:91], v[144:147]
	v_mfma_f32_16x16x32_f16 v[144:147], v[52:55], v[202:205], v[152:155]
	v_mfma_f32_16x16x32_f16 v[152:155], v[56:59], v[206:209], v[144:147]
	v_mfma_f32_16x16x32_f16 v[144:147], v[60:63], v[202:205], v[148:151]
	v_mfma_f32_16x16x32_f16 v[132:135], v[52:55], v[212:215], v[132:135]
	v_mfma_f32_16x16x32_f16 v[128:131], v[60:63], v[212:215], v[128:131]
	v_mfma_f32_16x16x32_f16 v[116:119], v[52:55], v[220:223], v[116:119]
	v_mfma_f32_16x16x32_f16 v[112:115], v[60:63], v[220:223], v[112:115]
	v_mfma_f32_16x16x32_f16 v[148:151], v[64:67], v[206:209], v[144:147]
	v_mfma_f32_16x16x32_f16 v[132:135], v[56:59], v[216:219], v[132:135]
	v_mfma_f32_16x16x32_f16 v[128:131], v[64:67], v[216:219], v[128:131]
	v_mfma_f32_16x16x32_f16 v[116:119], v[56:59], v[224:227], v[116:119]
	v_mfma_f32_16x16x32_f16 v[112:115], v[64:67], v[224:227], v[112:115]
	s_setprio 0
	s_setprio 1
	v_mfma_f32_16x16x32_f16 v[144:147], v[68:71], v[84:87], v[160:163]
	v_mfma_f32_16x16x32_f16 v[84:87], v[172:175], v[84:87], v[100:103]
	v_mfma_f32_16x16x32_f16 v[156:159], v[198:201], v[88:91], v[84:87]
	v_mfma_f32_16x16x32_f16 v[84:87], v[68:71], v[202:205], v[136:139]
	v_mfma_f32_16x16x32_f16 v[160:163], v[72:75], v[88:91], v[144:147]
	v_mfma_f32_16x16x32_f16 v[144:147], v[72:75], v[206:209], v[84:87]
	v_mfma_f32_16x16x32_f16 v[84:87], v[172:175], v[202:205], v[140:143]
	v_mfma_f32_16x16x32_f16 v[140:143], v[198:201], v[206:209], v[84:87]
	v_mfma_f32_16x16x32_f16 v[84:87], v[68:71], v[212:215], v[124:127]
	v_mfma_f32_16x16x32_f16 v[124:127], v[72:75], v[216:219], v[84:87]
	v_mfma_f32_16x16x32_f16 v[84:87], v[172:175], v[212:215], v[120:123]
	v_mfma_f32_16x16x32_f16 v[120:123], v[198:201], v[216:219], v[84:87]
	v_mfma_f32_16x16x32_f16 v[84:87], v[68:71], v[220:223], v[108:111]
	v_mfma_f32_16x16x32_f16 v[108:111], v[72:75], v[224:227], v[84:87]
	v_mfma_f32_16x16x32_f16 v[84:87], v[172:175], v[220:223], v[104:107]
	v_mfma_f32_16x16x32_f16 v[104:107], v[198:201], v[224:227], v[84:87]
	s_setprio 0
	s_barrier
	s_add_i32 s54, s82, s66
	v_lshl_add_u64 v[88:89], v[210:211], 0, s[12:13]
	s_mov_b32 m0, s54
	s_nop 1
	ds_read_b128 v[84:87], v196 offset:49152
	ds_read_b128 v[100:103], v196 offset:50176
	ds_read_b128 v[136:139], v196 offset:51200
	ds_read_b128 v[202:205], v196 offset:52224
	ds_read_b128 v[206:209], v196 offset:53248
	ds_read_b128 v[212:215], v196 offset:54272
	ds_read_b128 v[216:219], v196 offset:55296
	ds_read_b128 v[220:223], v196 offset:56320
	global_load_lds_dwordx4 v[88:89], off
	s_add_i32 m0, s54, 0x2000
	s_add_u32 s52, s52, 0x40080
	v_lshl_add_u64 v[88:89], v[228:229], 0, s[12:13]
	s_addc_u32 s53, s53, 0
	s_add_i32 s54, s83, s66
	global_load_lds_dwordx4 v[88:89], off
	v_lshl_add_u64 v[88:89], s[52:53], 0, v[178:179]
	s_mov_b32 m0, s54
	s_nop 0
	global_load_lds_dwordx4 v[88:89], off
	v_lshl_add_u64 v[88:89], s[52:53], 0, v[182:183]
	s_add_i32 m0, s54, 0x2000
	s_nop 0
	global_load_lds_dwordx4 v[88:89], off
	v_lshl_add_u64 v[88:89], v[230:231], 0, s[12:13]
	s_mov_b32 m0, s70
	s_nop 0
	global_load_lds_dwordx4 v[88:89], off
	v_lshl_add_u64 v[88:89], v[232:233], 0, s[12:13]
	s_mov_b32 m0, s71
	s_nop 0
	global_load_lds_dwordx4 v[88:89], off
	s_waitcnt vmcnt(8)
	s_waitcnt lgkmcnt(0)
	s_barrier
	s_setprio 1
	s_waitcnt lgkmcnt(0)
	v_mfma_f32_16x16x32_f16 v[88:91], v[52:55], v[84:87], v[96:99]
	v_mfma_f32_16x16x32_f16 v[96:99], v[56:59], v[100:103], v[88:91]
	v_mfma_f32_16x16x32_f16 v[88:91], v[60:63], v[84:87], v[92:95]
	v_mfma_f32_16x16x32_f16 v[80:83], v[52:55], v[136:139], v[80:83]
	v_mfma_f32_16x16x32_f16 v[76:79], v[60:63], v[136:139], v[76:79]
	v_mfma_f32_16x16x32_f16 v[28:31], v[52:55], v[206:209], v[28:31]
	v_mfma_f32_16x16x32_f16 v[24:27], v[60:63], v[206:209], v[24:27]
	v_mfma_f32_16x16x32_f16 v[12:15], v[52:55], v[216:219], v[12:15]
	v_mfma_f32_16x16x32_f16 v[8:11], v[60:63], v[216:219], v[8:11]
	v_mfma_f32_16x16x32_f16 v[92:95], v[64:67], v[100:103], v[88:91]
	v_mfma_f32_16x16x32_f16 v[80:83], v[56:59], v[202:205], v[80:83]
	v_mfma_f32_16x16x32_f16 v[76:79], v[64:67], v[202:205], v[76:79]
	v_mfma_f32_16x16x32_f16 v[28:31], v[56:59], v[212:215], v[28:31]
	v_mfma_f32_16x16x32_f16 v[24:27], v[64:67], v[212:215], v[24:27]
	v_mfma_f32_16x16x32_f16 v[12:15], v[56:59], v[220:223], v[12:15]
	v_mfma_f32_16x16x32_f16 v[8:11], v[64:67], v[220:223], v[8:11]
	s_setprio 0
	s_setprio 1
	v_mfma_f32_16x16x32_f16 v[40:43], v[68:71], v[84:87], v[40:43]
	v_mfma_f32_16x16x32_f16 v[88:91], v[72:75], v[100:103], v[40:43]
	v_mfma_f32_16x16x32_f16 v[40:43], v[172:175], v[84:87], v[44:47]
	v_mfma_f32_16x16x32_f16 v[84:87], v[198:201], v[100:103], v[40:43]
	v_mfma_f32_16x16x32_f16 v[40:43], v[68:71], v[136:139], v[48:51]
	v_mfma_f32_16x16x32_f16 v[36:39], v[172:175], v[136:139], v[36:39]
	v_mfma_f32_16x16x32_f16 v[20:23], v[68:71], v[206:209], v[20:23]
	v_mfma_f32_16x16x32_f16 v[16:19], v[172:175], v[206:209], v[16:19]
	v_mfma_f32_16x16x32_f16 v[4:7], v[68:71], v[216:219], v[4:7]
	v_mfma_f32_16x16x32_f16 v[0:3], v[172:175], v[216:219], v[0:3]
	v_mfma_f32_16x16x32_f16 v[52:55], v[72:75], v[202:205], v[40:43]
	v_mfma_f32_16x16x32_f16 v[36:39], v[198:201], v[202:205], v[36:39]
	v_mfma_f32_16x16x32_f16 v[20:23], v[72:75], v[212:215], v[20:23]
	v_mfma_f32_16x16x32_f16 v[16:19], v[198:201], v[212:215], v[16:19]
	v_mfma_f32_16x16x32_f16 v[4:7], v[72:75], v[220:223], v[4:7]
	v_mfma_f32_16x16x32_f16 v[0:3], v[198:201], v[220:223], v[0:3]
	s_setprio 0
	s_barrier
	s_add_i32 s81, s81, 2
	s_add_u32 s46, s46, 0x100
	s_addc_u32 s47, s47, 0
	s_add_u32 s49, s49, 0x100
	s_addc_u32 s80, s80, 0
	s_cmp_gt_u32 s81, 13
	s_cbranch_scc1 .LBB0_2793

.LBB0_3325:
	s_add_u32 s4, s58, 0x3792000
	s_addc_u32 s5, s59, 0
	s_add_u32 s8, s58, 0x379d000
	s_mov_b64 s[10:11], 0x80
	s_addc_u32 s9, s59, 0
	s_and_b32 s17, s12, 3
	s_add_i32 m0, s27, 0x18000
	v_lshl_add_u64 v[6:7], v[6:7], 0, s[10:11]
	s_lshl_b32 s55, s16, 6
	s_lshl_b32 s13, s16, 13
	s_lshl_b32 s60, s17, 5
	s_lshl_b32 s22, s17, 12
	s_waitcnt vmcnt(2)
	s_barrier
	global_load_lds_dwordx4 v[6:7], off
	v_lshl_add_u64 v[4:5], v[4:5], 0, s[10:11]
	s_add_i32 m0, s27, 0x1a000
	s_add_i32 s61, s27, 0x8000
	s_add_i32 s64, s27, 0xa000
	global_load_lds_dwordx4 v[4:5], off
	v_lshl_add_u64 v[0:1], v[0:1], 0, s[10:11]
	s_mov_b32 m0, s61
	s_add_u32 s18, s36, 0x40080
	global_load_lds_dwordx4 v[0:1], off
	v_lshl_add_u64 v[0:1], v[2:3], 0, s[10:11]
	s_mov_b32 m0, s64
	s_addc_u32 s19, s37, 0
	global_load_lds_dwordx4 v[0:1], off
	s_add_i32 m0, s27, 0x1c000
	v_lshl_add_u64 v[0:1], s[18:19], 0, v[164:165]
	global_load_lds_dwordx4 v[0:1], off
	v_lshl_add_u64 v[0:1], s[18:19], 0, v[160:161]
	s_add_i32 m0, s27, 0x1e000
	v_and_b32_e32 v182, 15, v9
	global_load_lds_dwordx4 v[0:1], off
	v_and_b32_e32 v0, 48, v9
	v_lshlrev_b32_e32 v1, 2, v9
	v_lshl_or_b32 v0, v182, 6, v0
	v_and_b32_e32 v2, 32, v1
	v_bitop3_b32 v3, v0, s13, v2 bitop3:0xde
	v_bitop3_b32 v184, v0, s22, v2 bitop3:0xde
	v_and_b32_e32 v0, 0x80, v1
	v_and_b32_e32 v1, 31, v9
	v_or3_b32 v185, v1, v0, s60
	v_lshlrev_b32_e32 v0, 14, v13
	v_and_b32_e32 v0, 0xffff8000, v0
	v_lshl_add_u32 v0, v12, 11, v0
	v_and_b32_e32 v1, 1, v13
	v_lshl_or_b32 v0, v1, 6, v0
	s_lshl_b32 s65, s12, 9
	v_lshl_add_u32 v168, v14, 1, v0
	v_lshlrev_b32_e32 v0, 14, v8
	s_cmpk_lt_u32 s7, 0x100
	v_and_b32_e32 v0, 0xffff8000, v0
	s_sext_i32_i16 s72, s6
	s_waitcnt vmcnt(6)
	s_cselect_b64 s[12:13], -1, 0
	s_lshl_b32 s6, s16, 11
	s_lshl_b32 s7, s17, 9
	v_lshl_add_u32 v0, v10, 11, v0
	v_and_b32_e32 v1, 1, v8
	s_or_b32 s66, s6, s7
	v_lshl_or_b32 v0, v1, 6, v0
	v_bfe_u32 v183, v9, 4, 2
	s_add_i32 s66, s66, 0x22400
	v_mov_b32_e32 v169, v165
	v_lshl_add_u32 v170, v11, 1, v0
	v_mov_b32_e32 v171, v165
	v_mov_b64_e32 v[172:173], 0xb00
	v_mov_b64_e32 v[174:175], 0xaff
	s_movk_i32 s67, 0x1600
	s_add_i32 s68, s65, 0x22500
	s_add_i32 s69, 0, 0x10000
	s_add_i32 s70, 0, 0x14000
	v_add_u32_e32 v186, 0, v3
	s_movk_i32 s71, 0x200
	v_mov_b32_e32 v187, 0x20400
	s_barrier
	s_mov_b32 s99, 0
	s_branch .LBB0_3328

.LBB0_3331:
	v_add_u32_e32 v128, s69, v184
	v_add_u32_e32 v176, s70, v184
	ds_read_b128 v[108:111], v128
	ds_read_b128 v[112:115], v128 offset:1024
	ds_read_b128 v[120:123], v128 offset:2048
	ds_read_b128 v[128:131], v128 offset:3072
	ds_read_b128 v[148:151], v176
	ds_read_b128 v[152:155], v176 offset:1024
	ds_read_b128 v[156:159], v176 offset:2048
	ds_read_b128 v[176:179], v176 offset:3072
	s_add_u32 s40, s34, 0xfffc0080
	s_addc_u32 s41, s35, -1
	s_and_b64 s[36:37], s[36:37], exec
	s_cselect_b32 s41, s19, s41
	s_cselect_b32 s40, s73, s40
	s_cselect_b32 s37, s17, s78
	s_cselect_b32 s36, s74, s75
	v_lshl_add_u64 v[180:181], s[34:35], 0, v[168:169]
	s_add_i32 m0, s27, 0xc000
	ds_read_b128 v[188:191], v186
	ds_read_b128 v[192:195], v186 offset:1024
	ds_read_b128 v[196:199], v186 offset:2048
	ds_read_b128 v[200:203], v186 offset:3072
	ds_read_b128 v[204:207], v186 offset:4096
	ds_read_b128 v[212:215], v186 offset:5120
	ds_read_b128 v[216:219], v186 offset:6144
	ds_read_b128 v[220:223], v186 offset:7168
	global_load_lds_dwordx4 v[180:181], off
	v_lshl_add_u64 v[180:181], s[34:35], 0, v[170:171]
	s_add_i32 m0, s27, 0xe000
	s_nop 0
	global_load_lds_dwordx4 v[180:181], off
	s_cmp_lg_u32 s99, 0
	s_cbranch_scc1 .Lrlx31a
	s_waitcnt vmcnt(8)
.Lrlx31a_done:
	s_waitcnt lgkmcnt(0)
	s_barrier
	s_setprio 1
	s_waitcnt lgkmcnt(0)
	v_mfma_f32_16x16x32_f16 v[144:147], v[108:111], v[188:191], v[144:147]
	v_mfma_f32_16x16x32_f16 v[136:139], v[120:123], v[188:191], v[136:139]
	v_mfma_f32_16x16x32_f16 v[124:127], v[108:111], v[196:199], v[124:127]
	v_mfma_f32_16x16x32_f16 v[100:103], v[120:123], v[196:199], v[100:103]
	v_mfma_f32_16x16x32_f16 v[92:95], v[108:111], v[204:207], v[92:95]
	v_mfma_f32_16x16x32_f16 v[84:87], v[120:123], v[204:207], v[84:87]
	v_mfma_f32_16x16x32_f16 v[76:79], v[108:111], v[216:219], v[76:79]
	v_mfma_f32_16x16x32_f16 v[68:71], v[120:123], v[216:219], v[68:71]
	v_mfma_f32_16x16x32_f16 v[144:147], v[112:115], v[192:195], v[144:147]
	v_mfma_f32_16x16x32_f16 v[136:139], v[128:131], v[192:195], v[136:139]
	v_mfma_f32_16x16x32_f16 v[124:127], v[112:115], v[200:203], v[124:127]
	v_mfma_f32_16x16x32_f16 v[100:103], v[128:131], v[200:203], v[100:103]
	v_mfma_f32_16x16x32_f16 v[92:95], v[112:115], v[212:215], v[92:95]
	v_mfma_f32_16x16x32_f16 v[84:87], v[128:131], v[212:215], v[84:87]
	v_mfma_f32_16x16x32_f16 v[76:79], v[112:115], v[220:223], v[76:79]
	v_mfma_f32_16x16x32_f16 v[68:71], v[128:131], v[220:223], v[68:71]
	s_setprio 0
	s_setprio 1
	v_mfma_f32_16x16x32_f16 v[140:143], v[148:151], v[188:191], v[140:143]
	v_mfma_f32_16x16x32_f16 v[132:135], v[156:159], v[188:191], v[132:135]
	v_mfma_f32_16x16x32_f16 v[116:119], v[148:151], v[196:199], v[116:119]
	v_mfma_f32_16x16x32_f16 v[96:99], v[156:159], v[196:199], v[96:99]
	v_mfma_f32_16x16x32_f16 v[88:91], v[148:151], v[204:207], v[88:91]
	v_mfma_f32_16x16x32_f16 v[80:83], v[156:159], v[204:207], v[80:83]
	v_mfma_f32_16x16x32_f16 v[72:75], v[148:151], v[216:219], v[72:75]
	v_mfma_f32_16x16x32_f16 v[64:67], v[156:159], v[216:219], v[64:67]
	v_mfma_f32_16x16x32_f16 v[140:143], v[152:155], v[192:195], v[140:143]
	v_mfma_f32_16x16x32_f16 v[132:135], v[176:179], v[192:195], v[132:135]
	v_mfma_f32_16x16x32_f16 v[116:119], v[152:155], v[200:203], v[116:119]
	v_mfma_f32_16x16x32_f16 v[96:99], v[176:179], v[200:203], v[96:99]
	v_mfma_f32_16x16x32_f16 v[88:91], v[152:155], v[212:215], v[88:91]
	v_mfma_f32_16x16x32_f16 v[80:83], v[176:179], v[212:215], v[80:83]
	v_mfma_f32_16x16x32_f16 v[72:75], v[152:155], v[220:223], v[72:75]
	v_mfma_f32_16x16x32_f16 v[64:67], v[176:179], v[220:223], v[64:67]
	s_setprio 0
	s_barrier
	s_add_i32 s80, s69, s49
	v_lshl_add_u64 v[180:181], s[36:37], 0, v[164:165]
	s_mov_b32 m0, s80
	ds_read_b128 v[188:191], v186 offset:16384
	ds_read_b128 v[192:195], v186 offset:17408
	ds_read_b128 v[196:199], v186 offset:18432
	ds_read_b128 v[200:203], v186 offset:19456
	ds_read_b128 v[204:207], v186 offset:20480
	ds_read_b128 v[212:215], v186 offset:21504
	ds_read_b128 v[216:219], v186 offset:22528
	ds_read_b128 v[220:223], v186 offset:23552
	global_load_lds_dwordx4 v[180:181], off
	s_add_i32 m0, s80, 0x2000
	s_add_u32 s80, s36, 0x40000
	v_lshl_add_u64 v[208:209], s[36:37], 0, v[160:161]
	s_addc_u32 s81, s37, 0
	s_add_i32 s82, s70, s49
	global_load_lds_dwordx4 v[208:209], off
	v_lshl_add_u64 v[210:211], s[80:81], 0, v[164:165]
	s_mov_b32 m0, s82
	v_lshl_add_u64 v[224:225], s[40:41], 0, v[162:163]
	global_load_lds_dwordx4 v[210:211], off
	v_lshl_add_u64 v[210:211], s[80:81], 0, v[160:161]
	s_add_i32 m0, s82, 0x2000
	s_nop 0
	global_load_lds_dwordx4 v[210:211], off
	v_lshl_add_u64 v[210:211], s[40:41], 0, v[166:167]
	s_mov_b32 m0, s27
	s_nop 0
	global_load_lds_dwordx4 v[210:211], off
	s_mov_b32 m0, s51
	s_nop 0
	global_load_lds_dwordx4 v[224:225], off
	s_cmp_lg_u32 s99, 0
	s_cbranch_scc1 .Lrlx31b
	s_waitcnt vmcnt(8)
.Lrlx31b_done:
	s_mov_b32 s99, 0
	s_waitcnt lgkmcnt(0)
	s_barrier
	s_setprio 1
	s_waitcnt lgkmcnt(0)
	v_mfma_f32_16x16x32_f16 v[60:63], v[108:111], v[188:191], v[60:63]
	v_mfma_f32_16x16x32_f16 v[52:55], v[120:123], v[188:191], v[52:55]
	v_mfma_f32_16x16x32_f16 v[44:47], v[108:111], v[196:199], v[44:47]
	v_mfma_f32_16x16x32_f16 v[36:39], v[120:123], v[196:199], v[36:39]
	v_mfma_f32_16x16x32_f16 v[28:31], v[108:111], v[204:207], v[28:31]
	v_mfma_f32_16x16x32_f16 v[20:23], v[120:123], v[204:207], v[20:23]
	v_mfma_f32_16x16x32_f16 v[12:15], v[108:111], v[216:219], v[12:15]
	v_mfma_f32_16x16x32_f16 v[4:7], v[120:123], v[216:219], v[4:7]
	v_mfma_f32_16x16x32_f16 v[60:63], v[112:115], v[192:195], v[60:63]
	v_mfma_f32_16x16x32_f16 v[52:55], v[128:131], v[192:195], v[52:55]
	v_mfma_f32_16x16x32_f16 v[44:47], v[112:115], v[200:203], v[44:47]
	v_mfma_f32_16x16x32_f16 v[36:39], v[128:131], v[200:203], v[36:39]
	v_mfma_f32_16x16x32_f16 v[28:31], v[112:115], v[212:215], v[28:31]
	v_mfma_f32_16x16x32_f16 v[20:23], v[128:131], v[212:215], v[20:23]
	v_mfma_f32_16x16x32_f16 v[12:15], v[112:115], v[220:223], v[12:15]
	v_mfma_f32_16x16x32_f16 v[4:7], v[128:131], v[220:223], v[4:7]
	s_setprio 0
	s_setprio 1
	v_mfma_f32_16x16x32_f16 v[56:59], v[148:151], v[188:191], v[56:59]
	v_mfma_f32_16x16x32_f16 v[48:51], v[156:159], v[188:191], v[48:51]
	v_mfma_f32_16x16x32_f16 v[40:43], v[148:151], v[196:199], v[40:43]
	v_mfma_f32_16x16x32_f16 v[32:35], v[156:159], v[196:199], v[32:35]
	v_mfma_f32_16x16x32_f16 v[24:27], v[148:151], v[204:207], v[24:27]
	v_mfma_f32_16x16x32_f16 v[16:19], v[156:159], v[204:207], v[16:19]
	v_mfma_f32_16x16x32_f16 v[8:11], v[148:151], v[216:219], v[8:11]
	v_mfma_f32_16x16x32_f16 v[0:3], v[156:159], v[216:219], v[0:3]
	v_mfma_f32_16x16x32_f16 v[56:59], v[152:155], v[192:195], v[56:59]
	v_mfma_f32_16x16x32_f16 v[48:51], v[176:179], v[192:195], v[48:51]
	v_mfma_f32_16x16x32_f16 v[40:43], v[152:155], v[200:203], v[40:43]
	v_mfma_f32_16x16x32_f16 v[32:35], v[176:179], v[200:203], v[32:35]
	v_mfma_f32_16x16x32_f16 v[24:27], v[152:155], v[212:215], v[24:27]
	v_mfma_f32_16x16x32_f16 v[16:19], v[176:179], v[212:215], v[16:19]
	v_mfma_f32_16x16x32_f16 v[8:11], v[152:155], v[220:223], v[8:11]
	v_mfma_f32_16x16x32_f16 v[0:3], v[176:179], v[220:223], v[0:3]
	s_setprio 0
	s_barrier
	s_add_i32 s80, 0, 0x18000
	s_add_i32 s81, 0, 0x1c000
	v_add_u32_e32 v128, s80, v184
	v_add_u32_e32 v176, s81, v184
	ds_read_b128 v[108:111], v128
	ds_read_b128 v[112:115], v128 offset:1024
	ds_read_b128 v[120:123], v128 offset:2048
	ds_read_b128 v[128:131], v128 offset:3072
	ds_read_b128 v[148:151], v176
	ds_read_b128 v[152:155], v176 offset:1024
	ds_read_b128 v[156:159], v176 offset:2048
	ds_read_b128 v[176:179], v176 offset:3072
	s_add_u32 s40, s40, 0x40000
	s_addc_u32 s41, s41, 0
	s_mov_b32 m0, s52
	v_lshl_add_u64 v[226:227], s[40:41], 0, v[166:167]
	ds_read_b128 v[188:191], v186 offset:32768
	ds_read_b128 v[192:195], v186 offset:33792
	ds_read_b128 v[196:199], v186 offset:34816
	ds_read_b128 v[200:203], v186 offset:35840
	ds_read_b128 v[204:207], v186 offset:36864
	ds_read_b128 v[212:215], v186 offset:37888
	ds_read_b128 v[216:219], v186 offset:38912
	ds_read_b128 v[220:223], v186 offset:39936
	global_load_lds_dwordx4 v[226:227], off
	v_lshl_add_u64 v[226:227], s[40:41], 0, v[162:163]
	s_mov_b32 m0, s53
	s_nop 0
	global_load_lds_dwordx4 v[226:227], off
	s_waitcnt vmcnt(8)
	s_waitcnt lgkmcnt(0)
	s_barrier
	s_setprio 1
	s_waitcnt lgkmcnt(0)
	v_mfma_f32_16x16x32_f16 v[144:147], v[108:111], v[188:191], v[144:147]
	v_mfma_f32_16x16x32_f16 v[136:139], v[120:123], v[188:191], v[136:139]
	v_mfma_f32_16x16x32_f16 v[124:127], v[108:111], v[196:199], v[124:127]
	v_mfma_f32_16x16x32_f16 v[100:103], v[120:123], v[196:199], v[100:103]
	v_mfma_f32_16x16x32_f16 v[92:95], v[108:111], v[204:207], v[92:95]
	v_mfma_f32_16x16x32_f16 v[84:87], v[120:123], v[204:207], v[84:87]
	v_mfma_f32_16x16x32_f16 v[76:79], v[108:111], v[216:219], v[76:79]
	v_mfma_f32_16x16x32_f16 v[68:71], v[120:123], v[216:219], v[68:71]
	v_mfma_f32_16x16x32_f16 v[144:147], v[112:115], v[192:195], v[144:147]
	v_mfma_f32_16x16x32_f16 v[136:139], v[128:131], v[192:195], v[136:139]
	v_mfma_f32_16x16x32_f16 v[124:127], v[112:115], v[200:203], v[124:127]
	v_mfma_f32_16x16x32_f16 v[100:103], v[128:131], v[200:203], v[100:103]
	v_mfma_f32_16x16x32_f16 v[92:95], v[112:115], v[212:215], v[92:95]
	v_mfma_f32_16x16x32_f16 v[84:87], v[128:131], v[212:215], v[84:87]
	v_mfma_f32_16x16x32_f16 v[76:79], v[112:115], v[220:223], v[76:79]
	v_mfma_f32_16x16x32_f16 v[68:71], v[128:131], v[220:223], v[68:71]
	s_setprio 0
	s_setprio 1
	v_mfma_f32_16x16x32_f16 v[140:143], v[148:151], v[188:191], v[140:143]
	v_mfma_f32_16x16x32_f16 v[132:135], v[156:159], v[188:191], v[132:135]
	v_mfma_f32_16x16x32_f16 v[116:119], v[148:151], v[196:199], v[116:119]
	v_mfma_f32_16x16x32_f16 v[96:99], v[156:159], v[196:199], v[96:99]
	v_mfma_f32_16x16x32_f16 v[88:91], v[148:151], v[204:207], v[88:91]
	v_mfma_f32_16x16x32_f16 v[80:83], v[156:159], v[204:207], v[80:83]
	v_mfma_f32_16x16x32_f16 v[72:75], v[148:151], v[216:219], v[72:75]
	v_mfma_f32_16x16x32_f16 v[64:67], v[156:159], v[216:219], v[64:67]
	v_mfma_f32_16x16x32_f16 v[140:143], v[152:155], v[192:195], v[140:143]
	v_mfma_f32_16x16x32_f16 v[132:135], v[176:179], v[192:195], v[132:135]
	v_mfma_f32_16x16x32_f16 v[116:119], v[152:155], v[200:203], v[116:119]
	v_mfma_f32_16x16x32_f16 v[96:99], v[176:179], v[200:203], v[96:99]
	v_mfma_f32_16x16x32_f16 v[88:91], v[152:155], v[212:215], v[88:91]
	v_mfma_f32_16x16x32_f16 v[80:83], v[176:179], v[212:215], v[80:83]
	v_mfma_f32_16x16x32_f16 v[72:75], v[152:155], v[220:223], v[72:75]
	v_mfma_f32_16x16x32_f16 v[64:67], v[176:179], v[220:223], v[64:67]
	s_setprio 0
	s_barrier
	s_add_i32 s40, s80, s49
	v_lshl_add_u64 v[180:181], v[180:181], 0, s[10:11]
	s_mov_b32 m0, s40
	ds_read_b128 v[188:191], v186 offset:49152
	ds_read_b128 v[192:195], v186 offset:50176
	ds_read_b128 v[196:199], v186 offset:51200
	ds_read_b128 v[200:203], v186 offset:52224
	ds_read_b128 v[204:207], v186 offset:53248
	ds_read_b128 v[212:215], v186 offset:54272
	ds_read_b128 v[216:219], v186 offset:55296
	ds_read_b128 v[220:223], v186 offset:56320
	global_load_lds_dwordx4 v[180:181], off
	s_add_i32 m0, s40, 0x2000
	s_add_u32 s36, s36, 0x40080
	v_lshl_add_u64 v[180:181], v[208:209], 0, s[10:11]
	s_addc_u32 s37, s37, 0
	s_add_i32 s40, s81, s49
	global_load_lds_dwordx4 v[180:181], off
	v_lshl_add_u64 v[180:181], s[36:37], 0, v[164:165]
	s_mov_b32 m0, s40
	s_nop 0
	global_load_lds_dwordx4 v[180:181], off
	v_lshl_add_u64 v[180:181], s[36:37], 0, v[160:161]
	s_add_i32 m0, s40, 0x2000
	s_nop 0
	global_load_lds_dwordx4 v[180:181], off
	v_lshl_add_u64 v[180:181], v[210:211], 0, s[10:11]
	s_mov_b32 m0, s61
	s_nop 0
	global_load_lds_dwordx4 v[180:181], off
	v_lshl_add_u64 v[180:181], v[224:225], 0, s[10:11]
	s_mov_b32 m0, s64
	s_nop 0
	global_load_lds_dwordx4 v[180:181], off
	s_waitcnt vmcnt(8)
	s_waitcnt lgkmcnt(0)
	s_barrier
	s_setprio 1
	s_waitcnt lgkmcnt(0)
	v_mfma_f32_16x16x32_f16 v[60:63], v[108:111], v[188:191], v[60:63]
	v_mfma_f32_16x16x32_f16 v[52:55], v[120:123], v[188:191], v[52:55]
	v_mfma_f32_16x16x32_f16 v[44:47], v[108:111], v[196:199], v[44:47]
	v_mfma_f32_16x16x32_f16 v[36:39], v[120:123], v[196:199], v[36:39]
	v_mfma_f32_16x16x32_f16 v[28:31], v[108:111], v[204:207], v[28:31]
	v_mfma_f32_16x16x32_f16 v[20:23], v[120:123], v[204:207], v[20:23]
	v_mfma_f32_16x16x32_f16 v[12:15], v[108:111], v[216:219], v[12:15]
	v_mfma_f32_16x16x32_f16 v[4:7], v[120:123], v[216:219], v[4:7]
	v_mfma_f32_16x16x32_f16 v[60:63], v[112:115], v[192:195], v[60:63]
	v_mfma_f32_16x16x32_f16 v[52:55], v[128:131], v[192:195], v[52:55]
	v_mfma_f32_16x16x32_f16 v[44:47], v[112:115], v[200:203], v[44:47]
	v_mfma_f32_16x16x32_f16 v[36:39], v[128:131], v[200:203], v[36:39]
	v_mfma_f32_16x16x32_f16 v[28:31], v[112:115], v[212:215], v[28:31]
	v_mfma_f32_16x16x32_f16 v[20:23], v[128:131], v[212:215], v[20:23]
	v_mfma_f32_16x16x32_f16 v[12:15], v[112:115], v[220:223], v[12:15]
	v_mfma_f32_16x16x32_f16 v[4:7], v[128:131], v[220:223], v[4:7]
	s_setprio 0
	s_setprio 1
	v_mfma_f32_16x16x32_f16 v[56:59], v[148:151], v[188:191], v[56:59]
	v_mfma_f32_16x16x32_f16 v[48:51], v[156:159], v[188:191], v[48:51]
	v_mfma_f32_16x16x32_f16 v[40:43], v[148:151], v[196:199], v[40:43]
	v_mfma_f32_16x16x32_f16 v[32:35], v[156:159], v[196:199], v[32:35]
	v_mfma_f32_16x16x32_f16 v[24:27], v[148:151], v[204:207], v[24:27]
	v_mfma_f32_16x16x32_f16 v[16:19], v[156:159], v[204:207], v[16:19]
	v_mfma_f32_16x16x32_f16 v[8:11], v[148:151], v[216:219], v[8:11]
	v_mfma_f32_16x16x32_f16 v[0:3], v[156:159], v[216:219], v[0:3]
	v_mfma_f32_16x16x32_f16 v[56:59], v[152:155], v[192:195], v[56:59]
	v_mfma_f32_16x16x32_f16 v[48:51], v[176:179], v[192:195], v[48:51]
	v_mfma_f32_16x16x32_f16 v[40:43], v[152:155], v[200:203], v[40:43]
	v_mfma_f32_16x16x32_f16 v[32:35], v[176:179], v[200:203], v[32:35]
	v_mfma_f32_16x16x32_f16 v[24:27], v[152:155], v[212:215], v[24:27]
	v_mfma_f32_16x16x32_f16 v[16:19], v[176:179], v[212:215], v[16:19]
	v_mfma_f32_16x16x32_f16 v[8:11], v[152:155], v[220:223], v[8:11]
	v_mfma_f32_16x16x32_f16 v[0:3], v[176:179], v[220:223], v[0:3]
	s_setprio 0
	s_barrier
	s_add_i32 s79, s79, 2
	s_add_u32 s34, s34, 0x100
	s_addc_u32 s35, s35, 0
	s_add_u32 s75, s75, 0x100
	s_addc_u32 s78, s78, 0
	s_cmp_gt_u32 s79, 13
	s_cbranch_scc1 .LBB0_3334

.LBB0_3336:
	s_cmp_eq_u32 s26, s48
	v_mov_b32_e32 v112, v182
	v_mov_b32_e32 v113, v183
	s_cselect_b32 s17, s71, 0x300
	s_cmp_lg_u32 s26, s47
	s_cselect_b32 s17, s17, 0x100
	v_lshl_add_u32 v114, v113, 5, s66
	s_cmp_lg_u32 s26, s46
	ds_read_b128 v[120:123], v114
	ds_read_b128 v[104:107], v114 offset:16
	ds_read_b128 v[128:131], v114 offset:256
	ds_read_b128 v[108:111], v114 offset:272
	ds_read_b128 v[190:193], v114 offset:128
	ds_read_b128 v[194:197], v114 offset:144
	ds_read_b128 v[198:201], v114 offset:384
	ds_read_b128 v[202:205], v114 offset:400
	s_cselect_b32 s17, s17, 0
	v_add_u32_e32 v176, s55, v112
	s_lshl_b32 s19, s72, 7
	v_add_u32_e32 v112, s17, v176
	s_or_b32 s19, s19, s60
	v_lshl_add_u32 v112, v112, 3, v187
	v_lshl_add_u32 v206, v113, 3, s19
	ds_read2_b64 v[156:159], v112 offset1:16
	ds_read2_b64 v[152:155], v112 offset0:32 offset1:48
	ds_read2_b64 v[148:151], v112 offset0:128 offset1:144
	ds_read2_b64 v[112:115], v112 offset0:160 offset1:176
	v_lshl_add_u32 v188, s26, 8, v176
	s_waitcnt lgkmcnt(0)
	v_mov_b32_e32 v176, v190
	v_mov_b32_e32 v177, v120
	v_mov_b32_e32 v178, v198
	v_mov_b32_e32 v179, v128
	v_mov_b32_e32 v180, v140
	v_mov_b32_e32 v181, v144
	v_pk_fma_f32 v[208:209], v[176:177], v[156:157], v[178:179] op_sel:[0,1,0]
	v_mov_b32_e32 v128, v199
	v_pk_fma_f32 v[180:181], v[180:181], v[156:157], v[208:209] op_sel_hi:[1,0,1]
	v_mov_b32_e32 v144, v141
	v_mul_f32_e32 v120, 0xbfb8aa3b, v181
	v_exp_f32_e32 v189, v120
	v_mov_b32_e32 v120, v191
	v_pk_fma_f32 v[140:141], v[120:121], v[156:157], v[128:129] op_sel:[0,1,0]
	v_mov_b32_e32 v208, v142
	v_pk_fma_f32 v[190:191], v[144:145], v[156:157], v[140:141] op_sel_hi:[1,0,1]
	v_add_f32_e32 v145, 1.0, v189
	v_mul_f32_e32 v140, 0xbfb8aa3b, v191
	v_exp_f32_e32 v144, v140
	v_rcp_f32_e32 v145, v145
	v_mov_b32_e32 v209, v146
	v_mov_b32_e32 v146, v143
	v_add_f32_e32 v144, 1.0, v144
	v_rcp_f32_e32 v144, v144
	v_mul_f32_e32 v145, v181, v145
	v_mul_f32_e32 v189, v180, v145
	v_mov_b32_e32 v145, v122
	v_mul_f32_e32 v191, v191, v144
	v_mov_b32_e32 v144, v192
	v_mov_b32_e32 v180, v200
	v_mov_b32_e32 v181, v130
	v_pk_fma_f32 v[210:211], v[144:145], v[156:157], v[180:181] op_sel:[0,1,0]
	v_mov_b32_e32 v130, v201
	v_pk_fma_f32 v[208:209], v[208:209], v[156:157], v[210:211] op_sel_hi:[1,0,1]
	v_mul_f32_e32 v210, v190, v191
	v_mul_f32_e32 v122, 0xbfb8aa3b, v209
	v_exp_f32_e32 v200, v122
	v_mov_b32_e32 v122, v193
	v_pk_fma_f32 v[142:143], v[122:123], v[156:157], v[130:131] op_sel:[0,1,0]
	v_mov_b32_e32 v190, v132
	v_pk_fma_f32 v[192:193], v[146:147], v[156:157], v[142:143] op_sel_hi:[1,0,1]
	v_add_f32_e32 v143, 1.0, v200
	v_mul_f32_e32 v142, 0xbfb8aa3b, v193
	v_exp_f32_e32 v142, v142
	v_rcp_f32_e32 v211, v143
	v_mov_b32_e32 v143, v104
	v_mov_b32_e32 v146, v202
	v_add_f32_e32 v142, 1.0, v142
	v_rcp_f32_e32 v212, v142
	v_mov_b32_e32 v142, v194
	v_mov_b32_e32 v147, v108
	v_mov_b32_e32 v191, v136
	v_pk_fma_f32 v[200:201], v[142:143], v[156:157], v[146:147] op_sel:[0,1,0]
	v_mul_f32_e32 v108, v209, v211
	v_pk_fma_f32 v[190:191], v[190:191], v[156:157], v[200:201] op_sel_hi:[1,0,1]
	v_mul_f32_e32 v200, v208, v108
	v_mul_f32_e32 v104, 0xbfb8aa3b, v191
	v_exp_f32_e32 v104, v104
	v_mov_b32_e32 v108, v203
	v_mov_b32_e32 v136, v133
	v_mul_f32_e32 v193, v193, v212
	v_add_f32_e32 v104, 1.0, v104
	v_rcp_f32_e32 v201, v104
	v_mov_b32_e32 v104, v195
	v_pk_fma_f32 v[132:133], v[104:105], v[156:157], v[108:109] op_sel:[0,1,0]
	v_mul_f32_e32 v202, v192, v193
	v_pk_fma_f32 v[194:195], v[136:137], v[156:157], v[132:133] op_sel_hi:[1,0,1]
	v_mul_f32_e32 v133, v191, v201
	v_mul_f32_e32 v132, 0xbfb8aa3b, v195
	v_exp_f32_e32 v132, v132
	v_mul_f32_e32 v201, v190, v133
	v_mov_b32_e32 v133, v106
	v_mov_b32_e32 v136, v204
	v_add_f32_e32 v132, 1.0, v132
	v_rcp_f32_e32 v203, v132
	v_mov_b32_e32 v132, v196
	v_mov_b32_e32 v137, v110
	v_mov_b32_e32 v190, v134
	v_mov_b32_e32 v191, v138
	v_pk_fma_f32 v[192:193], v[132:133], v[156:157], v[136:137] op_sel:[0,1,0]
	v_mov_b32_e32 v110, v205
	v_pk_fma_f32 v[190:191], v[190:191], v[156:157], v[192:193] op_sel_hi:[1,0,1]
	v_mov_b32_e32 v138, v135
	v_mul_f32_e32 v106, 0xbfb8aa3b, v191
	v_exp_f32_e32 v192, v106
	v_mov_b32_e32 v106, v197
	v_pk_fma_f32 v[134:135], v[106:107], v[156:157], v[110:111] op_sel:[0,1,0]
	v_ashrrev_i32_e32 v207, 31, v206
	v_pk_fma_f32 v[134:135], v[138:139], v[156:157], v[134:135] op_sel_hi:[1,0,1]
	v_add_f32_e32 v156, 1.0, v192
	v_mul_f32_e32 v138, 0xbfb8aa3b, v135
	v_exp_f32_e32 v138, v138
	v_rcp_f32_e32 v156, v156
	v_mov_b64_e32 v[140:141], s[42:43]
	v_mul_f32_e32 v139, v195, v203
	v_add_f32_e32 v138, 1.0, v138
	v_rcp_f32_e32 v138, v138
	v_mad_i64_i32 v[198:199], s[34:35], v188, s67, v[140:141]
	v_mul_f32_e32 v157, v194, v139
	v_mul_f32_e32 v135, v135, v138
	v_mul_f32_e32 v139, v191, v156
	v_mul_f32_e32 v193, v134, v135
	v_lshlrev_b64 v[134:135], 1, v[206:207]
	v_mul_f32_e32 v156, v190, v139
	v_lshl_add_u64 v[138:139], v[198:199], 0, v[134:135]
	v_cvt_pk_bf16_f32 v190, v189, v210
	v_cvt_pk_bf16_f32 v191, v200, v202
	v_cvt_pk_bf16_f32 v192, v201, v157
	v_cvt_pk_bf16_f32 v193, v156, v193
	global_store_dwordx4 v[138:139], v[190:193], off
	v_mov_b32_e32 v138, v116
	v_mov_b32_e32 v139, v124
	v_pk_fma_f32 v[156:157], v[176:177], v[158:159], v[178:179] op_sel:[0,1,0]
	v_mov_b32_e32 v124, v117
	v_pk_fma_f32 v[138:139], v[138:139], v[158:159], v[156:157] op_sel_hi:[1,0,1]
	s_andn2_b64 vcc, exec, s[6:7]
	v_mul_f32_e32 v116, 0xbfb8aa3b, v139
	v_exp_f32_e32 v156, v116
	v_pk_fma_f32 v[116:117], v[120:121], v[158:159], v[128:129] op_sel:[0,1,0]
	s_mov_b64 s[6:7], -1
	v_pk_fma_f32 v[116:117], v[124:125], v[158:159], v[116:117] op_sel_hi:[1,0,1]
	v_add_f32_e32 v156, 1.0, v156
	v_mul_f32_e32 v124, 0xbfb8aa3b, v117
	v_exp_f32_e32 v124, v124
	v_rcp_f32_e32 v156, v156
	v_add_u32_e32 v125, 16, v188
	v_add_f32_e32 v124, 1.0, v124
	v_rcp_f32_e32 v157, v124
	v_mul_f32_e32 v139, v139, v156
	v_mul_f32_e32 v189, v138, v139
	v_mov_b32_e32 v138, v118
	v_mul_f32_e32 v117, v117, v157
	v_mov_b32_e32 v139, v126
	v_pk_fma_f32 v[156:157], v[144:145], v[158:159], v[180:181] op_sel:[0,1,0]
	v_mov_b32_e32 v126, v119
	v_pk_fma_f32 v[138:139], v[138:139], v[158:159], v[156:157] op_sel_hi:[1,0,1]
	v_mul_f32_e32 v157, v116, v117
	v_mul_f32_e32 v118, 0xbfb8aa3b, v139
	v_exp_f32_e32 v156, v118
	v_pk_fma_f32 v[118:119], v[122:123], v[158:159], v[130:131] op_sel:[0,1,0]
	v_mov_b32_e32 v117, v100
	v_pk_fma_f32 v[118:119], v[126:127], v[158:159], v[118:119] op_sel_hi:[1,0,1]
	v_add_f32_e32 v116, 1.0, v156
	v_mul_f32_e32 v126, 0xbfb8aa3b, v119
	v_exp_f32_e32 v126, v126
	v_rcp_f32_e32 v156, v116
	v_mad_i64_i32 v[124:125], s[34:35], v125, s67, v[140:141]
	v_add_f32_e32 v116, 1.0, v126
	v_rcp_f32_e32 v190, v116
	v_mov_b32_e32 v116, v96
	v_pk_fma_f32 v[126:127], v[142:143], v[158:159], v[146:147] op_sel:[0,1,0]
	v_mul_f32_e32 v100, v139, v156
	v_pk_fma_f32 v[116:117], v[116:117], v[158:159], v[126:127] op_sel_hi:[1,0,1]
	v_mul_f32_e32 v126, v138, v100
	v_mul_f32_e32 v96, 0xbfb8aa3b, v117
	v_exp_f32_e32 v96, v96
	v_mov_b32_e32 v100, v97
	v_mul_f32_e32 v119, v119, v190
	v_mul_f32_e32 v118, v118, v119
	v_add_f32_e32 v96, 1.0, v96
	v_rcp_f32_e32 v127, v96
	v_pk_fma_f32 v[96:97], v[104:105], v[158:159], v[108:109] op_sel:[0,1,0]
	s_nop 0
	v_pk_fma_f32 v[96:97], v[100:101], v[158:159], v[96:97] op_sel_hi:[1,0,1]
	v_mul_f32_e32 v101, v117, v127
	v_mul_f32_e32 v100, 0xbfb8aa3b, v97
	v_exp_f32_e32 v100, v100
	v_mul_f32_e32 v119, v116, v101
	v_mov_b32_e32 v101, v102
	v_pk_fma_f32 v[116:117], v[132:133], v[158:159], v[136:137] op_sel:[0,1,0]
	v_add_f32_e32 v100, 1.0, v100
	v_rcp_f32_e32 v127, v100
	v_mov_b32_e32 v100, v98
	v_pk_fma_f32 v[100:101], v[100:101], v[158:159], v[116:117] op_sel_hi:[1,0,1]
	v_mov_b32_e32 v102, v99
	v_mul_f32_e32 v98, 0xbfb8aa3b, v101
	v_exp_f32_e32 v116, v98
	v_pk_fma_f32 v[98:99], v[106:107], v[158:159], v[110:111] op_sel:[0,1,0]
	v_mul_f32_e32 v97, v97, v127
	v_pk_fma_f32 v[98:99], v[102:103], v[158:159], v[98:99] op_sel_hi:[1,0,1]
	v_add_f32_e32 v103, 1.0, v116
	v_mul_f32_e32 v102, 0xbfb8aa3b, v99
	v_exp_f32_e32 v102, v102
	v_rcp_f32_e32 v103, v103
	v_mul_f32_e32 v116, v96, v97
	v_add_f32_e32 v102, 1.0, v102
	v_rcp_f32_e32 v102, v102
	v_mul_f32_e32 v96, v101, v103
	v_mul_f32_e32 v103, v100, v96
	v_lshl_add_u64 v[100:101], v[124:125], 0, v[134:135]
	v_mul_f32_e32 v96, v99, v102
	v_mul_f32_e32 v99, v98, v96
	v_cvt_pk_bf16_f32 v96, v189, v157
	v_cvt_pk_bf16_f32 v97, v126, v118
	v_cvt_pk_bf16_f32 v98, v119, v116
	v_cvt_pk_bf16_f32 v99, v103, v99
	global_store_dwordx4 v[100:101], v[96:99], off
	s_nop 1
	v_mov_b32_e32 v96, v88
	v_mov_b32_e32 v97, v92
	v_pk_fma_f32 v[98:99], v[176:177], v[152:153], v[178:179] op_sel:[0,1,0]
	v_mov_b32_e32 v92, v89
	v_pk_fma_f32 v[96:97], v[96:97], v[152:153], v[98:99] op_sel_hi:[1,0,1]
	s_nop 0
	v_mul_f32_e32 v88, 0xbfb8aa3b, v97
	v_exp_f32_e32 v98, v88
	v_pk_fma_f32 v[88:89], v[120:121], v[152:153], v[128:129] op_sel:[0,1,0]
	v_add_f32_e32 v98, 1.0, v98
	v_pk_fma_f32 v[88:89], v[92:93], v[152:153], v[88:89] op_sel_hi:[1,0,1]
	v_rcp_f32_e32 v98, v98
	v_mul_f32_e32 v92, 0xbfb8aa3b, v89
	v_exp_f32_e32 v92, v92
	v_add_u32_e32 v93, 32, v188
	v_mul_f32_e32 v97, v97, v98
	v_mul_f32_e32 v100, v96, v97
	v_add_f32_e32 v92, 1.0, v92
	v_rcp_f32_e32 v99, v92
	v_mov_b32_e32 v96, v90
	v_mov_b32_e32 v97, v94
	v_mov_b32_e32 v94, v91
	v_mul_f32_e32 v89, v89, v99
	v_pk_fma_f32 v[98:99], v[144:145], v[152:153], v[180:181] op_sel:[0,1,0]
	v_mad_i64_i32 v[92:93], s[34:35], v93, s67, v[140:141]
	v_pk_fma_f32 v[96:97], v[96:97], v[152:153], v[98:99] op_sel_hi:[1,0,1]
	v_mul_f32_e32 v99, v88, v89
	v_mul_f32_e32 v90, 0xbfb8aa3b, v97
	v_exp_f32_e32 v98, v90
	v_pk_fma_f32 v[90:91], v[122:123], v[152:153], v[130:131] op_sel:[0,1,0]
	v_mov_b32_e32 v89, v84
	v_pk_fma_f32 v[90:91], v[94:95], v[152:153], v[90:91] op_sel_hi:[1,0,1]
	v_add_f32_e32 v88, 1.0, v98
	v_mul_f32_e32 v94, 0xbfb8aa3b, v91
	v_exp_f32_e32 v94, v94
	v_rcp_f32_e32 v98, v88
	v_add_f32_e32 v88, 1.0, v94
	v_rcp_f32_e32 v101, v88
	v_mov_b32_e32 v88, v80
	v_pk_fma_f32 v[94:95], v[142:143], v[152:153], v[146:147] op_sel:[0,1,0]
	v_mul_f32_e32 v84, v97, v98
	v_pk_fma_f32 v[88:89], v[88:89], v[152:153], v[94:95] op_sel_hi:[1,0,1]
	v_mul_f32_e32 v94, v96, v84
	v_mul_f32_e32 v80, 0xbfb8aa3b, v89
	v_exp_f32_e32 v80, v80
	v_mov_b32_e32 v84, v81
	v_mul_f32_e32 v91, v91, v101
	v_mul_f32_e32 v90, v90, v91
	v_add_f32_e32 v80, 1.0, v80
	v_rcp_f32_e32 v95, v80
	v_pk_fma_f32 v[80:81], v[104:105], v[152:153], v[108:109] op_sel:[0,1,0]
	s_nop 0
	v_pk_fma_f32 v[80:81], v[84:85], v[152:153], v[80:81] op_sel_hi:[1,0,1]
	v_mul_f32_e32 v85, v89, v95
	v_mul_f32_e32 v84, 0xbfb8aa3b, v81
	v_exp_f32_e32 v84, v84
	v_mul_f32_e32 v91, v88, v85
	v_mov_b32_e32 v85, v86
	v_pk_fma_f32 v[88:89], v[132:133], v[152:153], v[136:137] op_sel:[0,1,0]
	v_add_f32_e32 v84, 1.0, v84
	v_rcp_f32_e32 v95, v84
	v_mov_b32_e32 v84, v82
	v_pk_fma_f32 v[84:85], v[84:85], v[152:153], v[88:89] op_sel_hi:[1,0,1]
	v_mov_b32_e32 v86, v83
	v_mul_f32_e32 v82, 0xbfb8aa3b, v85
	v_exp_f32_e32 v88, v82
	v_pk_fma_f32 v[82:83], v[106:107], v[152:153], v[110:111] op_sel:[0,1,0]
	v_mul_f32_e32 v81, v81, v95
	v_pk_fma_f32 v[82:83], v[86:87], v[152:153], v[82:83] op_sel_hi:[1,0,1]
	v_add_f32_e32 v87, 1.0, v88
	v_mul_f32_e32 v86, 0xbfb8aa3b, v83
	v_exp_f32_e32 v86, v86
	v_rcp_f32_e32 v87, v87
	v_mul_f32_e32 v88, v80, v81
	v_add_f32_e32 v86, 1.0, v86
	v_rcp_f32_e32 v86, v86
	v_mul_f32_e32 v80, v85, v87
	v_mul_f32_e32 v87, v84, v80
	v_lshl_add_u64 v[84:85], v[92:93], 0, v[134:135]
	v_mul_f32_e32 v80, v83, v86
	v_mul_f32_e32 v83, v82, v80
	v_cvt_pk_bf16_f32 v80, v100, v99
	v_cvt_pk_bf16_f32 v81, v94, v90
	v_cvt_pk_bf16_f32 v82, v91, v88
	v_cvt_pk_bf16_f32 v83, v87, v83
	global_store_dwordx4 v[84:85], v[80:83], off
	s_nop 1
	v_mov_b32_e32 v80, v72
	v_mov_b32_e32 v81, v76
	v_pk_fma_f32 v[82:83], v[176:177], v[154:155], v[178:179] op_sel:[0,1,0]
	v_mov_b32_e32 v76, v73
	v_pk_fma_f32 v[80:81], v[80:81], v[154:155], v[82:83] op_sel_hi:[1,0,1]
	s_nop 0
	v_mul_f32_e32 v72, 0xbfb8aa3b, v81
	v_exp_f32_e32 v82, v72
	v_pk_fma_f32 v[72:73], v[120:121], v[154:155], v[128:129] op_sel:[0,1,0]
	v_add_f32_e32 v82, 1.0, v82
	v_pk_fma_f32 v[72:73], v[76:77], v[154:155], v[72:73] op_sel_hi:[1,0,1]
	v_rcp_f32_e32 v82, v82
	v_mul_f32_e32 v76, 0xbfb8aa3b, v73
	v_exp_f32_e32 v76, v76
	v_add_u32_e32 v77, 48, v188
	v_mul_f32_e32 v81, v81, v82
	v_mul_f32_e32 v84, v80, v81
	v_add_f32_e32 v76, 1.0, v76
	v_rcp_f32_e32 v83, v76
	v_mov_b32_e32 v80, v74
	v_mov_b32_e32 v81, v78
	v_mov_b32_e32 v78, v75
	v_mul_f32_e32 v73, v73, v83
	v_pk_fma_f32 v[82:83], v[144:145], v[154:155], v[180:181] op_sel:[0,1,0]
	v_mad_i64_i32 v[76:77], s[34:35], v77, s67, v[140:141]
	v_pk_fma_f32 v[80:81], v[80:81], v[154:155], v[82:83] op_sel_hi:[1,0,1]
	v_mul_f32_e32 v83, v72, v73
	v_mul_f32_e32 v74, 0xbfb8aa3b, v81
	v_exp_f32_e32 v82, v74
	v_pk_fma_f32 v[74:75], v[122:123], v[154:155], v[130:131] op_sel:[0,1,0]
	v_mov_b32_e32 v73, v68
	v_pk_fma_f32 v[74:75], v[78:79], v[154:155], v[74:75] op_sel_hi:[1,0,1]
	v_add_f32_e32 v72, 1.0, v82
	v_mul_f32_e32 v78, 0xbfb8aa3b, v75
	v_exp_f32_e32 v78, v78
	v_rcp_f32_e32 v82, v72
	v_add_f32_e32 v72, 1.0, v78
	v_rcp_f32_e32 v85, v72
	v_mov_b32_e32 v72, v64
	v_pk_fma_f32 v[78:79], v[142:143], v[154:155], v[146:147] op_sel:[0,1,0]
	v_mul_f32_e32 v68, v81, v82
	v_pk_fma_f32 v[72:73], v[72:73], v[154:155], v[78:79] op_sel_hi:[1,0,1]
	v_mul_f32_e32 v78, v80, v68
	v_mul_f32_e32 v64, 0xbfb8aa3b, v73
	v_exp_f32_e32 v64, v64
	v_mov_b32_e32 v68, v65
	v_mul_f32_e32 v75, v75, v85
	v_mul_f32_e32 v74, v74, v75
	v_add_f32_e32 v64, 1.0, v64
	v_rcp_f32_e32 v79, v64
	v_pk_fma_f32 v[64:65], v[104:105], v[154:155], v[108:109] op_sel:[0,1,0]
	s_nop 0
	v_pk_fma_f32 v[64:65], v[68:69], v[154:155], v[64:65] op_sel_hi:[1,0,1]
	v_mul_f32_e32 v69, v73, v79
	v_mul_f32_e32 v68, 0xbfb8aa3b, v65
	v_exp_f32_e32 v68, v68
	v_mul_f32_e32 v75, v72, v69
	v_mov_b32_e32 v69, v70
	v_pk_fma_f32 v[72:73], v[132:133], v[154:155], v[136:137] op_sel:[0,1,0]
	v_add_f32_e32 v68, 1.0, v68
	v_rcp_f32_e32 v79, v68
	v_mov_b32_e32 v68, v66
	v_pk_fma_f32 v[68:69], v[68:69], v[154:155], v[72:73] op_sel_hi:[1,0,1]
	v_mov_b32_e32 v70, v67
	v_mul_f32_e32 v66, 0xbfb8aa3b, v69
	v_exp_f32_e32 v72, v66
	v_pk_fma_f32 v[66:67], v[106:107], v[154:155], v[110:111] op_sel:[0,1,0]
	v_mul_f32_e32 v65, v65, v79
	v_pk_fma_f32 v[66:67], v[70:71], v[154:155], v[66:67] op_sel_hi:[1,0,1]
	v_add_f32_e32 v71, 1.0, v72
	v_mul_f32_e32 v70, 0xbfb8aa3b, v67
	v_exp_f32_e32 v70, v70
	v_rcp_f32_e32 v71, v71
	v_mul_f32_e32 v72, v64, v65
	v_add_f32_e32 v70, 1.0, v70
	v_rcp_f32_e32 v70, v70
	v_mul_f32_e32 v64, v69, v71
	v_mul_f32_e32 v71, v68, v64
	v_lshl_add_u64 v[68:69], v[76:77], 0, v[134:135]
	v_mul_f32_e32 v64, v67, v70
	v_mul_f32_e32 v67, v66, v64
	v_cvt_pk_bf16_f32 v64, v84, v83
	v_cvt_pk_bf16_f32 v65, v78, v74
	v_cvt_pk_bf16_f32 v66, v75, v72
	v_cvt_pk_bf16_f32 v67, v71, v67
	global_store_dwordx4 v[68:69], v[64:67], off
	s_nop 1
	v_mov_b32_e32 v64, v56
	v_mov_b32_e32 v65, v60
	v_pk_fma_f32 v[66:67], v[176:177], v[148:149], v[178:179] op_sel:[0,1,0]
	v_mov_b32_e32 v60, v57
	v_pk_fma_f32 v[64:65], v[64:65], v[148:149], v[66:67] op_sel_hi:[1,0,1]
	s_nop 0
	v_mul_f32_e32 v56, 0xbfb8aa3b, v65
	v_exp_f32_e32 v66, v56
	v_pk_fma_f32 v[56:57], v[120:121], v[148:149], v[128:129] op_sel:[0,1,0]
	v_add_f32_e32 v66, 1.0, v66
	v_pk_fma_f32 v[56:57], v[60:61], v[148:149], v[56:57] op_sel_hi:[1,0,1]
	v_rcp_f32_e32 v66, v66
	v_mul_f32_e32 v60, 0xbfb8aa3b, v57
	v_exp_f32_e32 v60, v60
	v_add_u32_e32 v61, 0x80, v188
	v_mul_f32_e32 v65, v65, v66
	v_mul_f32_e32 v68, v64, v65
	v_add_f32_e32 v60, 1.0, v60
	v_rcp_f32_e32 v67, v60
	v_mov_b32_e32 v64, v58
	v_mov_b32_e32 v65, v62
	v_mov_b32_e32 v62, v59
	v_mul_f32_e32 v57, v57, v67
	v_pk_fma_f32 v[66:67], v[144:145], v[148:149], v[180:181] op_sel:[0,1,0]
	v_mad_i64_i32 v[60:61], s[34:35], v61, s67, v[140:141]
	v_pk_fma_f32 v[64:65], v[64:65], v[148:149], v[66:67] op_sel_hi:[1,0,1]
	v_mul_f32_e32 v67, v56, v57
	v_mul_f32_e32 v58, 0xbfb8aa3b, v65
	v_exp_f32_e32 v66, v58
	v_pk_fma_f32 v[58:59], v[122:123], v[148:149], v[130:131] op_sel:[0,1,0]
	v_mov_b32_e32 v57, v52
	v_pk_fma_f32 v[58:59], v[62:63], v[148:149], v[58:59] op_sel_hi:[1,0,1]
	v_add_f32_e32 v56, 1.0, v66
	v_mul_f32_e32 v62, 0xbfb8aa3b, v59
	v_exp_f32_e32 v62, v62
	v_rcp_f32_e32 v66, v56
	v_add_f32_e32 v56, 1.0, v62
	v_rcp_f32_e32 v69, v56
	v_mov_b32_e32 v56, v48
	v_pk_fma_f32 v[62:63], v[142:143], v[148:149], v[146:147] op_sel:[0,1,0]
	v_mul_f32_e32 v52, v65, v66
	v_pk_fma_f32 v[56:57], v[56:57], v[148:149], v[62:63] op_sel_hi:[1,0,1]
	v_mul_f32_e32 v62, v64, v52
	v_mul_f32_e32 v48, 0xbfb8aa3b, v57
	v_exp_f32_e32 v48, v48
	v_mov_b32_e32 v52, v49
	v_mul_f32_e32 v59, v59, v69
	v_mul_f32_e32 v58, v58, v59
	v_add_f32_e32 v48, 1.0, v48
	v_rcp_f32_e32 v63, v48
	v_pk_fma_f32 v[48:49], v[104:105], v[148:149], v[108:109] op_sel:[0,1,0]
	s_nop 0
	v_pk_fma_f32 v[48:49], v[52:53], v[148:149], v[48:49] op_sel_hi:[1,0,1]
	v_mul_f32_e32 v53, v57, v63
	v_mul_f32_e32 v52, 0xbfb8aa3b, v49
	v_exp_f32_e32 v52, v52
	v_mul_f32_e32 v59, v56, v53
	v_mov_b32_e32 v53, v54
	v_pk_fma_f32 v[56:57], v[132:133], v[148:149], v[136:137] op_sel:[0,1,0]
	v_add_f32_e32 v52, 1.0, v52
	v_rcp_f32_e32 v63, v52
	v_mov_b32_e32 v52, v50
	v_pk_fma_f32 v[52:53], v[52:53], v[148:149], v[56:57] op_sel_hi:[1,0,1]
	v_mov_b32_e32 v54, v51
	v_mul_f32_e32 v50, 0xbfb8aa3b, v53
	v_exp_f32_e32 v56, v50
	v_pk_fma_f32 v[50:51], v[106:107], v[148:149], v[110:111] op_sel:[0,1,0]
	v_mul_f32_e32 v49, v49, v63
	v_pk_fma_f32 v[50:51], v[54:55], v[148:149], v[50:51] op_sel_hi:[1,0,1]
	v_add_f32_e32 v55, 1.0, v56
	v_mul_f32_e32 v54, 0xbfb8aa3b, v51
	v_exp_f32_e32 v54, v54
	v_rcp_f32_e32 v55, v55
	v_mul_f32_e32 v56, v48, v49
	v_add_f32_e32 v54, 1.0, v54
	v_rcp_f32_e32 v54, v54
	v_mul_f32_e32 v48, v53, v55
	v_mul_f32_e32 v55, v52, v48
	v_lshl_add_u64 v[52:53], v[60:61], 0, v[134:135]
	v_mul_f32_e32 v48, v51, v54
	v_mul_f32_e32 v51, v50, v48
	v_cvt_pk_bf16_f32 v48, v68, v67
	v_cvt_pk_bf16_f32 v49, v62, v58
	v_cvt_pk_bf16_f32 v50, v59, v56
	v_cvt_pk_bf16_f32 v51, v55, v51
	global_store_dwordx4 v[52:53], v[48:51], off
	s_nop 1
	v_mov_b32_e32 v48, v40
	v_mov_b32_e32 v49, v44
	v_pk_fma_f32 v[50:51], v[176:177], v[150:151], v[178:179] op_sel:[0,1,0]
	v_mov_b32_e32 v44, v41
	v_pk_fma_f32 v[48:49], v[48:49], v[150:151], v[50:51] op_sel_hi:[1,0,1]
	s_nop 0
	v_mul_f32_e32 v40, 0xbfb8aa3b, v49
	v_exp_f32_e32 v50, v40
	v_pk_fma_f32 v[40:41], v[120:121], v[150:151], v[128:129] op_sel:[0,1,0]
	v_add_f32_e32 v50, 1.0, v50
	v_pk_fma_f32 v[40:41], v[44:45], v[150:151], v[40:41] op_sel_hi:[1,0,1]
	v_rcp_f32_e32 v50, v50
	v_mul_f32_e32 v44, 0xbfb8aa3b, v41
	v_exp_f32_e32 v44, v44
	v_add_u32_e32 v45, 0x90, v188
	v_mul_f32_e32 v49, v49, v50
	v_mul_f32_e32 v52, v48, v49
	v_add_f32_e32 v44, 1.0, v44
	v_rcp_f32_e32 v51, v44
	v_mov_b32_e32 v48, v42
	v_mov_b32_e32 v49, v46
	v_mov_b32_e32 v46, v43
	v_mul_f32_e32 v41, v41, v51
	v_pk_fma_f32 v[50:51], v[144:145], v[150:151], v[180:181] op_sel:[0,1,0]
	v_mad_i64_i32 v[44:45], s[34:35], v45, s67, v[140:141]
	v_pk_fma_f32 v[48:49], v[48:49], v[150:151], v[50:51] op_sel_hi:[1,0,1]
	v_mul_f32_e32 v51, v40, v41
	v_mul_f32_e32 v42, 0xbfb8aa3b, v49
	v_exp_f32_e32 v50, v42
	v_pk_fma_f32 v[42:43], v[122:123], v[150:151], v[130:131] op_sel:[0,1,0]
	v_mov_b32_e32 v41, v36
	v_pk_fma_f32 v[42:43], v[46:47], v[150:151], v[42:43] op_sel_hi:[1,0,1]
	v_add_f32_e32 v40, 1.0, v50
	v_mul_f32_e32 v46, 0xbfb8aa3b, v43
	v_exp_f32_e32 v46, v46
	v_rcp_f32_e32 v50, v40
	v_add_f32_e32 v40, 1.0, v46
	v_rcp_f32_e32 v53, v40
	v_mov_b32_e32 v40, v32
	v_pk_fma_f32 v[46:47], v[142:143], v[150:151], v[146:147] op_sel:[0,1,0]
	v_mul_f32_e32 v36, v49, v50
	v_pk_fma_f32 v[40:41], v[40:41], v[150:151], v[46:47] op_sel_hi:[1,0,1]
	v_mul_f32_e32 v46, v48, v36
	v_mul_f32_e32 v32, 0xbfb8aa3b, v41
	v_exp_f32_e32 v32, v32
	v_mov_b32_e32 v36, v33
	v_mul_f32_e32 v43, v43, v53
	v_mul_f32_e32 v42, v42, v43
	v_add_f32_e32 v32, 1.0, v32
	v_rcp_f32_e32 v47, v32
	v_pk_fma_f32 v[32:33], v[104:105], v[150:151], v[108:109] op_sel:[0,1,0]
	s_nop 0
	v_pk_fma_f32 v[32:33], v[36:37], v[150:151], v[32:33] op_sel_hi:[1,0,1]
	v_mul_f32_e32 v37, v41, v47
	v_mul_f32_e32 v36, 0xbfb8aa3b, v33
	v_exp_f32_e32 v36, v36
	v_mul_f32_e32 v43, v40, v37
	v_mov_b32_e32 v37, v38
	v_pk_fma_f32 v[40:41], v[132:133], v[150:151], v[136:137] op_sel:[0,1,0]
	v_add_f32_e32 v36, 1.0, v36
	v_rcp_f32_e32 v47, v36
	v_mov_b32_e32 v36, v34
	v_pk_fma_f32 v[36:37], v[36:37], v[150:151], v[40:41] op_sel_hi:[1,0,1]
	v_mov_b32_e32 v38, v35
	v_mul_f32_e32 v34, 0xbfb8aa3b, v37
	v_exp_f32_e32 v40, v34
	v_pk_fma_f32 v[34:35], v[106:107], v[150:151], v[110:111] op_sel:[0,1,0]
	v_mul_f32_e32 v33, v33, v47
	v_pk_fma_f32 v[34:35], v[38:39], v[150:151], v[34:35] op_sel_hi:[1,0,1]
	v_add_f32_e32 v39, 1.0, v40
	v_mul_f32_e32 v38, 0xbfb8aa3b, v35
	v_exp_f32_e32 v38, v38
	v_rcp_f32_e32 v39, v39
	v_mul_f32_e32 v40, v32, v33
	v_add_f32_e32 v38, 1.0, v38
	v_rcp_f32_e32 v38, v38
	v_mul_f32_e32 v32, v37, v39
	v_mul_f32_e32 v39, v36, v32
	v_lshl_add_u64 v[36:37], v[44:45], 0, v[134:135]
	v_mul_f32_e32 v32, v35, v38
	v_mul_f32_e32 v35, v34, v32
	v_cvt_pk_bf16_f32 v32, v52, v51
	v_cvt_pk_bf16_f32 v33, v46, v42
	v_cvt_pk_bf16_f32 v34, v43, v40
	v_cvt_pk_bf16_f32 v35, v39, v35
	global_store_dwordx4 v[36:37], v[32:35], off
	s_nop 1
	v_mov_b32_e32 v32, v24
	v_mov_b32_e32 v33, v28
	v_pk_fma_f32 v[34:35], v[176:177], v[112:113], v[178:179] op_sel:[0,1,0]
	v_mov_b32_e32 v28, v25
	v_pk_fma_f32 v[32:33], v[32:33], v[112:113], v[34:35] op_sel_hi:[1,0,1]
	s_nop 0
	v_mul_f32_e32 v24, 0xbfb8aa3b, v33
	v_exp_f32_e32 v34, v24
	v_pk_fma_f32 v[24:25], v[120:121], v[112:113], v[128:129] op_sel:[0,1,0]
	v_add_f32_e32 v34, 1.0, v34
	v_pk_fma_f32 v[24:25], v[28:29], v[112:113], v[24:25] op_sel_hi:[1,0,1]
	v_rcp_f32_e32 v34, v34
	v_mul_f32_e32 v28, 0xbfb8aa3b, v25
	v_exp_f32_e32 v28, v28
	v_add_u32_e32 v29, 0xa0, v188
	v_mul_f32_e32 v33, v33, v34
	v_mul_f32_e32 v36, v32, v33
	v_add_f32_e32 v28, 1.0, v28
	v_rcp_f32_e32 v35, v28
	v_mov_b32_e32 v32, v26
	v_mov_b32_e32 v33, v30
	v_mov_b32_e32 v30, v27
	v_mul_f32_e32 v25, v25, v35
	v_pk_fma_f32 v[34:35], v[144:145], v[112:113], v[180:181] op_sel:[0,1,0]
	v_mad_i64_i32 v[28:29], s[34:35], v29, s67, v[140:141]
	v_pk_fma_f32 v[32:33], v[32:33], v[112:113], v[34:35] op_sel_hi:[1,0,1]
	v_mul_f32_e32 v35, v24, v25
	v_mul_f32_e32 v26, 0xbfb8aa3b, v33
	v_exp_f32_e32 v34, v26
	v_pk_fma_f32 v[26:27], v[122:123], v[112:113], v[130:131] op_sel:[0,1,0]
	v_mov_b32_e32 v25, v20
	v_pk_fma_f32 v[26:27], v[30:31], v[112:113], v[26:27] op_sel_hi:[1,0,1]
	v_add_f32_e32 v24, 1.0, v34
	v_mul_f32_e32 v30, 0xbfb8aa3b, v27
	v_exp_f32_e32 v30, v30
	v_rcp_f32_e32 v34, v24
	v_add_f32_e32 v24, 1.0, v30
	v_rcp_f32_e32 v37, v24
	v_mov_b32_e32 v24, v16
	v_pk_fma_f32 v[30:31], v[142:143], v[112:113], v[146:147] op_sel:[0,1,0]
	v_mul_f32_e32 v20, v33, v34
	v_pk_fma_f32 v[24:25], v[24:25], v[112:113], v[30:31] op_sel_hi:[1,0,1]
	v_mul_f32_e32 v30, v32, v20
	v_mul_f32_e32 v16, 0xbfb8aa3b, v25
	v_exp_f32_e32 v16, v16
	v_mov_b32_e32 v20, v17
	v_mul_f32_e32 v27, v27, v37
	v_mul_f32_e32 v26, v26, v27
	v_add_f32_e32 v16, 1.0, v16
	v_rcp_f32_e32 v31, v16
	v_pk_fma_f32 v[16:17], v[104:105], v[112:113], v[108:109] op_sel:[0,1,0]
	s_nop 0
	v_pk_fma_f32 v[16:17], v[20:21], v[112:113], v[16:17] op_sel_hi:[1,0,1]
	v_mul_f32_e32 v21, v25, v31
	v_mul_f32_e32 v20, 0xbfb8aa3b, v17
	v_exp_f32_e32 v20, v20
	v_mul_f32_e32 v27, v24, v21
	v_mov_b32_e32 v21, v22
	v_pk_fma_f32 v[24:25], v[132:133], v[112:113], v[136:137] op_sel:[0,1,0]
	v_add_f32_e32 v20, 1.0, v20
	v_rcp_f32_e32 v31, v20
	v_mov_b32_e32 v20, v18
	v_pk_fma_f32 v[20:21], v[20:21], v[112:113], v[24:25] op_sel_hi:[1,0,1]
	v_mov_b32_e32 v22, v19
	v_mul_f32_e32 v18, 0xbfb8aa3b, v21
	v_exp_f32_e32 v24, v18
	v_pk_fma_f32 v[18:19], v[106:107], v[112:113], v[110:111] op_sel:[0,1,0]
	v_mul_f32_e32 v17, v17, v31
	v_pk_fma_f32 v[18:19], v[22:23], v[112:113], v[18:19] op_sel_hi:[1,0,1]
	v_add_f32_e32 v23, 1.0, v24
	v_mul_f32_e32 v22, 0xbfb8aa3b, v19
	v_exp_f32_e32 v22, v22
	v_rcp_f32_e32 v23, v23
	v_mul_f32_e32 v24, v16, v17
	v_add_f32_e32 v22, 1.0, v22
	v_rcp_f32_e32 v22, v22
	v_mul_f32_e32 v16, v21, v23
	v_mul_f32_e32 v23, v20, v16
	v_lshl_add_u64 v[20:21], v[28:29], 0, v[134:135]
	v_mul_f32_e32 v16, v19, v22
	v_mul_f32_e32 v19, v18, v16
	v_cvt_pk_bf16_f32 v16, v36, v35
	v_cvt_pk_bf16_f32 v17, v30, v26
	v_cvt_pk_bf16_f32 v18, v27, v24
	v_cvt_pk_bf16_f32 v19, v23, v19
	global_store_dwordx4 v[20:21], v[16:19], off
	s_nop 1
	v_mov_b32_e32 v16, v8
	v_mov_b32_e32 v17, v12
	v_pk_fma_f32 v[18:19], v[176:177], v[114:115], v[178:179] op_sel:[0,1,0]
	v_mov_b32_e32 v12, v9
	v_pk_fma_f32 v[16:17], v[16:17], v[114:115], v[18:19] op_sel_hi:[1,0,1]
	s_nop 0
	v_mul_f32_e32 v8, 0xbfb8aa3b, v17
	v_exp_f32_e32 v18, v8
	v_pk_fma_f32 v[8:9], v[120:121], v[114:115], v[128:129] op_sel:[0,1,0]
	v_add_f32_e32 v18, 1.0, v18
	v_pk_fma_f32 v[8:9], v[12:13], v[114:115], v[8:9] op_sel_hi:[1,0,1]
	v_rcp_f32_e32 v18, v18
	v_mul_f32_e32 v12, 0xbfb8aa3b, v9
	v_exp_f32_e32 v12, v12
	v_add_u32_e32 v13, 0xb0, v188
	v_mul_f32_e32 v17, v17, v18
	v_mul_f32_e32 v20, v16, v17
	v_add_f32_e32 v12, 1.0, v12
	v_rcp_f32_e32 v19, v12
	v_mov_b32_e32 v16, v10
	v_mov_b32_e32 v17, v14
	v_mov_b32_e32 v14, v11
	v_mul_f32_e32 v9, v9, v19
	v_pk_fma_f32 v[18:19], v[144:145], v[114:115], v[180:181] op_sel:[0,1,0]
	v_mad_i64_i32 v[12:13], s[34:35], v13, s67, v[140:141]
	v_pk_fma_f32 v[16:17], v[16:17], v[114:115], v[18:19] op_sel_hi:[1,0,1]
	v_mul_f32_e32 v19, v8, v9
	v_mul_f32_e32 v10, 0xbfb8aa3b, v17
	v_exp_f32_e32 v18, v10
	v_pk_fma_f32 v[10:11], v[122:123], v[114:115], v[130:131] op_sel:[0,1,0]
	v_mov_b32_e32 v9, v4
	v_pk_fma_f32 v[10:11], v[14:15], v[114:115], v[10:11] op_sel_hi:[1,0,1]
	v_add_f32_e32 v8, 1.0, v18
	v_mul_f32_e32 v14, 0xbfb8aa3b, v11
	v_exp_f32_e32 v14, v14
	v_rcp_f32_e32 v18, v8
	v_add_f32_e32 v8, 1.0, v14
	v_rcp_f32_e32 v21, v8
	v_mov_b32_e32 v8, v0
	v_pk_fma_f32 v[14:15], v[142:143], v[114:115], v[146:147] op_sel:[0,1,0]
	v_mul_f32_e32 v4, v17, v18
	v_pk_fma_f32 v[8:9], v[8:9], v[114:115], v[14:15] op_sel_hi:[1,0,1]
	v_mul_f32_e32 v14, v16, v4
	v_mul_f32_e32 v0, 0xbfb8aa3b, v9
	v_exp_f32_e32 v0, v0
	v_mov_b32_e32 v4, v1
	v_mul_f32_e32 v11, v11, v21
	v_mul_f32_e32 v10, v10, v11
	v_add_f32_e32 v0, 1.0, v0
	v_rcp_f32_e32 v15, v0
	v_pk_fma_f32 v[0:1], v[104:105], v[114:115], v[108:109] op_sel:[0,1,0]
	s_nop 0
	v_pk_fma_f32 v[0:1], v[4:5], v[114:115], v[0:1] op_sel_hi:[1,0,1]
	v_mul_f32_e32 v5, v9, v15
	v_mul_f32_e32 v4, 0xbfb8aa3b, v1
	v_exp_f32_e32 v4, v4
	v_mul_f32_e32 v11, v8, v5
	v_mov_b32_e32 v5, v6
	v_pk_fma_f32 v[8:9], v[132:133], v[114:115], v[136:137] op_sel:[0,1,0]
	v_add_f32_e32 v4, 1.0, v4
	v_rcp_f32_e32 v15, v4
	v_mov_b32_e32 v4, v2
	v_pk_fma_f32 v[4:5], v[4:5], v[114:115], v[8:9] op_sel_hi:[1,0,1]
	v_mov_b32_e32 v6, v3
	v_mul_f32_e32 v2, 0xbfb8aa3b, v5
	v_exp_f32_e32 v8, v2
	v_pk_fma_f32 v[2:3], v[106:107], v[114:115], v[110:111] op_sel:[0,1,0]
	v_mul_f32_e32 v1, v1, v15
	v_pk_fma_f32 v[2:3], v[6:7], v[114:115], v[2:3] op_sel_hi:[1,0,1]
	v_add_f32_e32 v7, 1.0, v8
	v_mul_f32_e32 v6, 0xbfb8aa3b, v3
	v_exp_f32_e32 v6, v6
	v_rcp_f32_e32 v7, v7
	v_mul_f32_e32 v8, v0, v1
	v_add_f32_e32 v6, 1.0, v6
	v_rcp_f32_e32 v6, v6
	v_mul_f32_e32 v0, v5, v7
	v_mul_f32_e32 v7, v4, v0
	v_lshl_add_u64 v[4:5], v[12:13], 0, v[134:135]
	v_mul_f32_e32 v0, v3, v6
	v_mul_f32_e32 v3, v2, v0
	v_cvt_pk_bf16_f32 v0, v20, v19
	v_cvt_pk_bf16_f32 v1, v14, v10
	v_cvt_pk_bf16_f32 v2, v11, v8
	v_cvt_pk_bf16_f32 v3, v7, v3
	global_store_dwordx4 v[4:5], v[0:3], off
	s_mov_b32 s99, 1
	s_cbranch_vccnz .LBB0_3327
	s_andn2_b64 vcc, exec, s[0:1]
	s_cbranch_vccnz .LBB0_3326
	s_barrier
	s_branch .LBB0_3326

	.amdhsa_kernel _Z14fwd_megakernel6Params
		.amdhsa_group_segment_fixed_size 0
		.amdhsa_private_segment_fixed_size 0
		.amdhsa_kernarg_size 400
		.amdhsa_user_sgpr_count 2
		.amdhsa_user_sgpr_dispatch_ptr 0
		.amdhsa_user_sgpr_queue_ptr 0
		.amdhsa_user_sgpr_kernarg_segment_ptr 1
		.amdhsa_user_sgpr_dispatch_id 0
		.amdhsa_user_sgpr_kernarg_preload_length 0
		.amdhsa_user_sgpr_kernarg_preload_offset 0
		.amdhsa_user_sgpr_private_segment_size 0
		.amdhsa_uses_dynamic_stack 0
		.amdhsa_enable_private_segment 0
		.amdhsa_system_sgpr_workgroup_id_x 1
		.amdhsa_system_sgpr_workgroup_id_y 0
		.amdhsa_system_sgpr_workgroup_id_z 0
		.amdhsa_system_sgpr_workgroup_info 0
		.amdhsa_system_vgpr_workitem_id 2
		.amdhsa_next_free_vgpr 256
		.amdhsa_next_free_sgpr 102
		.amdhsa_accum_offset 256
		.amdhsa_reserve_vcc 1
		.amdhsa_float_round_mode_32 0
		.amdhsa_float_round_mode_16_64 0
		.amdhsa_float_denorm_mode_32 3
		.amdhsa_float_denorm_mode_16_64 3
		.amdhsa_dx10_clamp 1
		.amdhsa_ieee_mode 1
		.amdhsa_fp16_overflow 0
		.amdhsa_tg_split 0
		.amdhsa_exception_fp_ieee_invalid_op 0
		.amdhsa_exception_fp_denorm_src 0
		.amdhsa_exception_fp_ieee_div_zero 0
		.amdhsa_exception_fp_ieee_overflow 0
		.amdhsa_exception_fp_ieee_underflow 0
		.amdhsa_exception_fp_ieee_inexact 0
		.amdhsa_exception_int_div_zero 0
	.end_amdhsa_kernel

amdhsa.kernels:
  - .agpr_count:     0
    .args:
      - .offset:         0
        .size:           144
        .value_kind:     by_value
      - .offset:         144
        .size:           4
        .value_kind:     hidden_block_count_x
      - .offset:         148
        .size:           4
        .value_kind:     hidden_block_count_y
      - .offset:         152
        .size:           4
        .value_kind:     hidden_block_count_z
      - .offset:         156
        .size:           2
        .value_kind:     hidden_group_size_x
      - .offset:         158
        .size:           2
        .value_kind:     hidden_group_size_y
      - .offset:         160
        .size:           2
        .value_kind:     hidden_group_size_z
      - .offset:         162
        .size:           2
        .value_kind:     hidden_remainder_x
      - .offset:         164
        .size:           2
        .value_kind:     hidden_remainder_y
      - .offset:         166
        .size:           2
        .value_kind:     hidden_remainder_z
      - .offset:         184
        .size:           8
        .value_kind:     hidden_global_offset_x
      - .offset:         192
        .size:           8
        .value_kind:     hidden_global_offset_y
      - .offset:         200
        .size:           8
        .value_kind:     hidden_global_offset_z
      - .offset:         208
        .size:           2
        .value_kind:     hidden_grid_dims
      - .offset:         232
        .size:           8
        .value_kind:     hidden_multigrid_sync_arg
      - .offset:         264
        .size:           4
        .value_kind:     hidden_dynamic_lds_size
    .group_segment_fixed_size: 0
    .kernarg_segment_align: 8
    .kernarg_segment_size: 400
    .language:       OpenCL C
    .language_version:
      - 2
      - 0
    .max_flat_workgroup_size: 512
    .name:           _Z14fwd_megakernel6Params
    .private_segment_fixed_size: 0
    .sgpr_count:     108
    .sgpr_spill_count: 62
    .symbol:         _Z14fwd_megakernel6Params.kd
    .uniform_work_group_size: 1
    .uses_dynamic_stack: false
    .vgpr_count:     256
    .vgpr_spill_count: 0
    .wavefront_size: 64
